# GEMM K-loops: in every load segment the LDS fragment reads are issued first, ahead of the scalar address/m0 setup and the LDS-DMA issue
# baseline (speedup 1.0000x reference)
; #define PG8_STAGE(bufoff, gbase, voff) do { _Pragma("unroll") for (int _i = 0; _i < 2; ++_i) \
;         __builtin_amdgcn_global_load_lds((const unsigned*)((const char*)(gbase) + (voff)[_i]), (LAS unsigned*)(lds + (bufoff) + ldsw + _i * 8192), 16, 0, 0); } while (0)
; #define PG8_LDA(dst, b, h) do { _Pragma("unroll") for (int m = 0; m < 4; ++m) _Pragma("unroll") for (int k = 0; k < 2; ++k) dst[m][k] = *(const LAS bf16x8*)(lds + PG8_SA(b, h) + aoff + m * 2048 + k * 1024); } while (0)
; #define PG8_LDB(dst, b, h) do { _Pragma("unroll") for (int n = 0; n < 2; ++n) _Pragma("unroll") for (int k = 0; k < 2; ++k) dst[n][k] = *(const LAS bf16x8*)(lds + PG8_SB(b, h) + boff + n * 2048 + k * 1024); } while (0)
; #define PG8_MMA(ai, bj, At, Bt) do { __builtin_amdgcn_s_setprio(1); _Pragma("unroll") for (int m = 0; m < 4; ++m) _Pragma("unroll") for (int n = 0; n < 2; ++n) _Pragma("unroll") for (int k = 0; k < 2; ++k) \
;         acc[ai][bj][m][n] = __builtin_amdgcn_mfma_f32_16x16x32_bf16(Bt[n][k], At[m][k], acc[ai][bj][m][n], 0, 0, 0); __builtin_amdgcn_s_setprio(0); } while (0)
; #define PG8_WAIT_V(n) asm volatile("s_waitcnt vmcnt(" #n ")" ::: "memory")
; #define PG8_WAIT_L(n) asm volatile("s_waitcnt lgkmcnt(" #n ")" ::: "memory")
; template <class Map, class Epi>
; DI void gemm_phase(LAS unsigned char* lds, const Map& MP, const Epi& E, const int nM, const int nN, const int K, const int lda, const int ldb) {
;     ...
;         for (int t = 0; t < nt; t += 2) {
;             const bool last = (t == nt - 2);
;             const char* a1 = cA + (size_t)(t + 1) * kstep;
;             const char* a2 = last ? nA : cA + (size_t)(t + 2) * kstep; const char* b2 = last ? nB : cB + (size_t)(t + 2) * kstep;
;             const char* a3 = a2 + kstep; const char* b3 = b2 + kstep;
;             PG8_LDB(B0, 0, 0); PG8_SCHED; PG8_LDA(At, 0, 0); PG8_STAGE(PG8_SA(1, 1), a1 + hstepA, voffA);
;             PG8_WAIT_L(8); PG8_BAR; PG8_WAIT_L(0); PG8_MMA(0, 0, At, B0); PG8_BAR; PG8_SCHED;
;             PG8_LDB(B1, 0, 1); PG8_STAGE(PG8_SB(0, 0), b2, voffB);
;             PG8_BAR; PG8_WAIT_L(0); PG8_MMA(0, 1, At, B1); PG8_BAR;
;             PG8_LDA(At, 0, 1); PG8_STAGE(PG8_SA(0, 0), a2, voffA);
;             PG8_BAR; PG8_WAIT_L(0); PG8_MMA(1, 0, At, B0); PG8_BAR; PG8_SCHED;
;             PG8_STAGE(PG8_SB(0, 1), b2 + hstepB, voffB);
;             PG8_WAIT_V(6); PG8_BAR; PG8_MMA(1, 1, At, B1); PG8_BAR;
.LBB1_229:
	ds_read_b128 v[160:163], v168
	ds_read_b128 v[170:173], v168 offset:1024
	ds_read_b128 v[174:177], v168 offset:2048
	ds_read_b128 v[178:181], v168 offset:3072
	ds_read_b128 v[182:185], v168 offset:4096
	ds_read_b128 v[186:189], v168 offset:5120
	ds_read_b128 v[190:193], v168 offset:6144
	ds_read_b128 v[198:201], v168 offset:7168
	s_add_u32 s26, s24, 0xfff80080
	s_addc_u32 s27, s25, -1
	s_cmp_eq_u32 s57, 4
	s_cselect_b32 s29, s17, s27
	s_cselect_b32 s28, s43, s26
	s_cselect_b32 s27, s53, s56
	s_cselect_b32 s26, s54, s55
	s_add_i32 m0, s2, 0xc000
	s_nop 0
	global_load_lds_dwordx4 v154, s[24:25]
	s_add_i32 m0, s2, 0xe000
	s_nop 0
	global_load_lds_dwordx4 v152, s[24:25]
	s_waitcnt lgkmcnt(8)
	s_barrier
	s_setprio 1
	s_waitcnt lgkmcnt(7)
	v_mfma_f32_16x16x32_bf16 v[140:143], v[72:75], v[160:163], v[140:143]
	v_mfma_f32_16x16x32_bf16 v[136:139], v[80:83], v[160:163], v[136:139]
	s_waitcnt lgkmcnt(5)
	v_mfma_f32_16x16x32_bf16 v[124:127], v[72:75], v[174:177], v[124:127]
	v_mfma_f32_16x16x32_bf16 v[120:123], v[80:83], v[174:177], v[120:123]
	s_waitcnt lgkmcnt(3)
	v_mfma_f32_16x16x32_bf16 v[108:111], v[72:75], v[182:185], v[108:111]
	v_mfma_f32_16x16x32_bf16 v[104:107], v[80:83], v[182:185], v[104:107]
	s_waitcnt lgkmcnt(1)
	v_mfma_f32_16x16x32_bf16 v[92:95], v[72:75], v[190:193], v[92:95]
	v_mfma_f32_16x16x32_bf16 v[88:91], v[80:83], v[190:193], v[88:91]
	v_mfma_f32_16x16x32_bf16 v[140:143], v[76:79], v[170:173], v[140:143]
	v_mfma_f32_16x16x32_bf16 v[136:139], v[84:87], v[170:173], v[136:139]
	v_mfma_f32_16x16x32_bf16 v[124:127], v[76:79], v[178:181], v[124:127]
	v_mfma_f32_16x16x32_bf16 v[120:123], v[84:87], v[178:181], v[120:123]
	v_mfma_f32_16x16x32_bf16 v[108:111], v[76:79], v[186:189], v[108:111]
	v_mfma_f32_16x16x32_bf16 v[104:107], v[84:87], v[186:189], v[104:107]
	s_waitcnt lgkmcnt(0)
	v_mfma_f32_16x16x32_bf16 v[92:95], v[76:79], v[198:201], v[92:95]
	v_mfma_f32_16x16x32_bf16 v[88:91], v[84:87], v[198:201], v[88:91]
	s_setprio 0
	s_barrier
	ds_read_b128 v[202:205], v169
	ds_read_b128 v[206:209], v169 offset:1024
	ds_read_b128 v[210:213], v169 offset:2048
	ds_read_b128 v[214:217], v169 offset:3072
	s_add_i32 s58, s48, s34
	v_lshl_add_u64 v[194:195], s[26:27], 0, v[148:149]
	s_mov_b32 m0, s58
	s_nop 0
	global_load_lds_dwordx4 v[194:195], off
	v_lshl_add_u64 v[218:219], s[26:27], 0, v[144:145]
	s_add_i32 m0, s58, 0x2000
	s_nop 0
	global_load_lds_dwordx4 v[218:219], off
	s_barrier
	s_setprio 1
	s_waitcnt lgkmcnt(3)
	v_mfma_f32_16x16x32_bf16 v[132:135], v[202:205], v[160:163], v[132:135]
	s_waitcnt lgkmcnt(1)
	v_mfma_f32_16x16x32_bf16 v[128:131], v[210:213], v[160:163], v[128:131]
	v_mfma_f32_16x16x32_bf16 v[116:119], v[202:205], v[174:177], v[116:119]
	v_mfma_f32_16x16x32_bf16 v[112:115], v[210:213], v[174:177], v[112:115]
	v_mfma_f32_16x16x32_bf16 v[100:103], v[202:205], v[182:185], v[100:103]
	v_mfma_f32_16x16x32_bf16 v[96:99], v[210:213], v[182:185], v[96:99]
	v_mfma_f32_16x16x32_bf16 v[68:71], v[202:205], v[190:193], v[68:71]
	v_mfma_f32_16x16x32_bf16 v[64:67], v[210:213], v[190:193], v[64:67]
	v_mfma_f32_16x16x32_bf16 v[132:135], v[206:209], v[170:173], v[132:135]
	s_mov_b32 m0, s2
	s_waitcnt lgkmcnt(0)
	v_mfma_f32_16x16x32_bf16 v[128:131], v[214:217], v[170:173], v[128:131]
	v_lshl_add_u64 v[220:221], s[28:29], 0, v[150:151]
	v_mfma_f32_16x16x32_bf16 v[116:119], v[206:209], v[178:181], v[116:119]
	v_mfma_f32_16x16x32_bf16 v[112:115], v[214:217], v[178:181], v[112:115]
	v_mfma_f32_16x16x32_bf16 v[100:103], v[206:209], v[186:189], v[100:103]
	v_mfma_f32_16x16x32_bf16 v[96:99], v[214:217], v[186:189], v[96:99]
	v_mfma_f32_16x16x32_bf16 v[68:71], v[206:209], v[198:201], v[68:71]
	v_mfma_f32_16x16x32_bf16 v[64:67], v[214:217], v[198:201], v[64:67]
	s_setprio 0
	s_barrier
	ds_read_b128 v[160:163], v168 offset:16384
	ds_read_b128 v[170:173], v168 offset:17408
	ds_read_b128 v[174:177], v168 offset:18432
	ds_read_b128 v[178:181], v168 offset:19456
	ds_read_b128 v[182:185], v168 offset:20480
	ds_read_b128 v[186:189], v168 offset:21504
	ds_read_b128 v[190:193], v168 offset:22528
	ds_read_b128 v[198:201], v168 offset:23552
	global_load_lds_dwordx4 v[220:221], off
	v_lshl_add_u64 v[222:223], s[28:29], 0, v[146:147]
	s_mov_b32 m0, s4
	s_nop 0
	global_load_lds_dwordx4 v[222:223], off
	s_waitcnt vmcnt(10)
	s_barrier
	s_setprio 1
	s_waitcnt lgkmcnt(7)
	v_mfma_f32_16x16x32_bf16 v[60:63], v[72:75], v[160:163], v[60:63]
	v_mfma_f32_16x16x32_bf16 v[56:59], v[80:83], v[160:163], v[56:59]
	s_waitcnt lgkmcnt(5)
	v_mfma_f32_16x16x32_bf16 v[44:47], v[72:75], v[174:177], v[44:47]
	v_mfma_f32_16x16x32_bf16 v[40:43], v[80:83], v[174:177], v[40:43]
	s_waitcnt lgkmcnt(3)
	v_mfma_f32_16x16x32_bf16 v[28:31], v[72:75], v[182:185], v[28:31]
	v_mfma_f32_16x16x32_bf16 v[24:27], v[80:83], v[182:185], v[24:27]
	s_waitcnt lgkmcnt(1)
	v_mfma_f32_16x16x32_bf16 v[12:15], v[72:75], v[190:193], v[12:15]
	v_mfma_f32_16x16x32_bf16 v[8:11], v[80:83], v[190:193], v[8:11]
	v_mfma_f32_16x16x32_bf16 v[60:63], v[76:79], v[170:173], v[60:63]
	v_mfma_f32_16x16x32_bf16 v[56:59], v[84:87], v[170:173], v[56:59]
	v_mfma_f32_16x16x32_bf16 v[44:47], v[76:79], v[178:181], v[44:47]
	v_mfma_f32_16x16x32_bf16 v[40:43], v[84:87], v[178:181], v[40:43]
	v_mfma_f32_16x16x32_bf16 v[28:31], v[76:79], v[186:189], v[28:31]
	v_mfma_f32_16x16x32_bf16 v[24:27], v[84:87], v[186:189], v[24:27]
	s_waitcnt lgkmcnt(0)
	v_mfma_f32_16x16x32_bf16 v[12:15], v[76:79], v[198:201], v[12:15]
	v_mfma_f32_16x16x32_bf16 v[8:11], v[84:87], v[198:201], v[8:11]
	s_setprio 0
	s_barrier
	s_add_u32 s58, s26, 0x20000
	s_addc_u32 s59, s27, 0
	s_add_i32 s60, s49, s34
	s_mov_b32 m0, s60
	s_nop 0
	global_load_lds_dwordx4 v148, s[58:59]
	s_add_i32 m0, s60, 0x2000
	s_nop 0
	global_load_lds_dwordx4 v144, s[58:59]
	s_waitcnt vmcnt(6)
	s_barrier
; #define PG8_STAGE(bufoff, gbase, voff) do { _Pragma("unroll") for (int _i = 0; _i < 2; ++_i) \
;         __builtin_amdgcn_global_load_lds((const unsigned*)((const char*)(gbase) + (voff)[_i]), (LAS unsigned*)(lds + (bufoff) + ldsw + _i * 8192), 16, 0, 0); } while (0)
; #define PG8_LDA(dst, b, h) do { _Pragma("unroll") for (int m = 0; m < 4; ++m) _Pragma("unroll") for (int k = 0; k < 2; ++k) dst[m][k] = *(const LAS bf16x8*)(lds + PG8_SA(b, h) + aoff + m * 2048 + k * 1024); } while (0)
; #define PG8_LDB(dst, b, h) do { _Pragma("unroll") for (int n = 0; n < 2; ++n) _Pragma("unroll") for (int k = 0; k < 2; ++k) dst[n][k] = *(const LAS bf16x8*)(lds + PG8_SB(b, h) + boff + n * 2048 + k * 1024); } while (0)
; #define PG8_MMA(ai, bj, At, Bt) do { __builtin_amdgcn_s_setprio(1); _Pragma("unroll") for (int m = 0; m < 4; ++m) _Pragma("unroll") for (int n = 0; n < 2; ++n) _Pragma("unroll") for (int k = 0; k < 2; ++k) \
;         acc[ai][bj][m][n] = __builtin_amdgcn_mfma_f32_16x16x32_bf16(Bt[n][k], At[m][k], acc[ai][bj][m][n], 0, 0, 0); __builtin_amdgcn_s_setprio(0); } while (0)
; #define PG8_WAIT_V(n) asm volatile("s_waitcnt vmcnt(" #n ")" ::: "memory")
; #define PG8_WAIT_L(n) asm volatile("s_waitcnt lgkmcnt(" #n ")" ::: "memory")
; #define PG8_BAR __builtin_amdgcn_s_barrier()
; #define PG8_SCHED __builtin_amdgcn_sched_barrier(0)
; template <class Map, class Epi>
; DI void gemm_phase(LAS unsigned char* lds, const Map& MP, const Epi& E, const int nM, const int nN, const int K, const int lda, const int ldb) {
;     ...
;             PG8_BAR; PG8_WAIT_L(0); PG8_MMA(1, 0, At, B0); PG8_BAR; PG8_SCHED;
;             PG8_STAGE(PG8_SB(0, 1), b2 + hstepB, voffB);
;             PG8_WAIT_V(6); PG8_BAR; PG8_MMA(1, 1, At, B1); PG8_BAR;
;             PG8_LDB(B0, 1, 0); PG8_SCHED; PG8_LDA(At, 1, 0); PG8_STAGE(PG8_SA(0, 1), a2 + hstepA, voffA);
;             PG8_WAIT_L(8); PG8_BAR; PG8_WAIT_L(0); PG8_MMA(0, 0, At, B0); PG8_BAR; PG8_SCHED;
;             PG8_LDB(B1, 1, 1); PG8_STAGE(PG8_SB(1, 0), b3, voffB);
;             PG8_BAR; PG8_WAIT_L(0); PG8_MMA(0, 1, At, B1); PG8_BAR;
;             PG8_LDA(At, 1, 1); PG8_STAGE(PG8_SA(1, 0), a3, voffA);
;             PG8_BAR; PG8_WAIT_L(0); PG8_MMA(1, 0, At, B0); PG8_BAR; PG8_SCHED;
;             PG8_STAGE(PG8_SB(1, 1), b3 + hstepB, voffB);
	s_setprio 1
	v_mfma_f32_16x16x32_bf16 v[52:55], v[202:205], v[160:163], v[52:55]
	v_mfma_f32_16x16x32_bf16 v[48:51], v[210:213], v[160:163], v[48:51]
	s_add_i32 s58, 0, 0x18000
	v_add_u32_e32 v84, s58, v166
	ds_read_b128 v[72:75], v84
	v_mfma_f32_16x16x32_bf16 v[36:39], v[202:205], v[174:177], v[36:39]
	v_mfma_f32_16x16x32_bf16 v[32:35], v[210:213], v[174:177], v[32:35]
	ds_read_b128 v[76:79], v84 offset:1024
	v_mfma_f32_16x16x32_bf16 v[20:23], v[202:205], v[182:185], v[20:23]
	v_mfma_f32_16x16x32_bf16 v[16:19], v[210:213], v[182:185], v[16:19]
	ds_read_b128 v[80:83], v84 offset:2048
	v_mfma_f32_16x16x32_bf16 v[4:7], v[202:205], v[190:193], v[4:7]
	v_mfma_f32_16x16x32_bf16 v[0:3], v[210:213], v[190:193], v[0:3]
	ds_read_b128 v[84:87], v84 offset:3072
	v_mfma_f32_16x16x32_bf16 v[52:55], v[206:209], v[170:173], v[52:55]
	v_mfma_f32_16x16x32_bf16 v[48:51], v[214:217], v[170:173], v[48:51]
	v_mfma_f32_16x16x32_bf16 v[36:39], v[206:209], v[178:181], v[36:39]
	v_mfma_f32_16x16x32_bf16 v[32:35], v[214:217], v[178:181], v[32:35]
	v_mfma_f32_16x16x32_bf16 v[20:23], v[206:209], v[186:189], v[20:23]
	v_mfma_f32_16x16x32_bf16 v[16:19], v[214:217], v[186:189], v[16:19]
	v_mfma_f32_16x16x32_bf16 v[4:7], v[206:209], v[198:201], v[4:7]
	v_mfma_f32_16x16x32_bf16 v[0:3], v[214:217], v[198:201], v[0:3]
	s_setprio 0
	s_barrier
	ds_read_b128 v[160:163], v168 offset:32768
	ds_read_b128 v[170:173], v168 offset:33792
	ds_read_b128 v[174:177], v168 offset:34816
	ds_read_b128 v[178:181], v168 offset:35840
	ds_read_b128 v[182:185], v168 offset:36864
	ds_read_b128 v[186:189], v168 offset:37888
	ds_read_b128 v[190:193], v168 offset:38912
	ds_read_b128 v[198:201], v168 offset:39936
	s_add_u32 s28, s28, 0x80000
	s_addc_u32 s29, s29, 0
	s_mov_b32 m0, s5
	s_nop 0
	global_load_lds_dwordx4 v150, s[28:29]
	s_mov_b32 m0, s23
	s_nop 0
	global_load_lds_dwordx4 v146, s[28:29]
	s_waitcnt lgkmcnt(8)
	s_barrier
	s_setprio 1
	s_waitcnt lgkmcnt(7)
	v_mfma_f32_16x16x32_bf16 v[140:143], v[72:75], v[160:163], v[140:143]
	v_mfma_f32_16x16x32_bf16 v[136:139], v[80:83], v[160:163], v[136:139]
	s_waitcnt lgkmcnt(5)
	v_mfma_f32_16x16x32_bf16 v[124:127], v[72:75], v[174:177], v[124:127]
	v_mfma_f32_16x16x32_bf16 v[120:123], v[80:83], v[174:177], v[120:123]
	s_waitcnt lgkmcnt(3)
	v_mfma_f32_16x16x32_bf16 v[108:111], v[72:75], v[182:185], v[108:111]
	v_mfma_f32_16x16x32_bf16 v[104:107], v[80:83], v[182:185], v[104:107]
	s_waitcnt lgkmcnt(1)
	v_mfma_f32_16x16x32_bf16 v[92:95], v[72:75], v[190:193], v[92:95]
	v_mfma_f32_16x16x32_bf16 v[88:91], v[80:83], v[190:193], v[88:91]
	v_mfma_f32_16x16x32_bf16 v[140:143], v[76:79], v[170:173], v[140:143]
	v_mfma_f32_16x16x32_bf16 v[136:139], v[84:87], v[170:173], v[136:139]
	v_mfma_f32_16x16x32_bf16 v[124:127], v[76:79], v[178:181], v[124:127]
	v_mfma_f32_16x16x32_bf16 v[120:123], v[84:87], v[178:181], v[120:123]
	v_mfma_f32_16x16x32_bf16 v[108:111], v[76:79], v[186:189], v[108:111]
	v_mfma_f32_16x16x32_bf16 v[104:107], v[84:87], v[186:189], v[104:107]
	s_waitcnt lgkmcnt(0)
	v_mfma_f32_16x16x32_bf16 v[92:95], v[76:79], v[198:201], v[92:95]
	v_mfma_f32_16x16x32_bf16 v[88:91], v[84:87], v[198:201], v[88:91]
	s_setprio 0
	s_barrier
	s_add_i32 s28, 0, 0x1c000
	v_add_u32_e32 v196, s28, v166
	ds_read_b128 v[202:205], v196
	ds_read_b128 v[206:209], v196 offset:1024
	ds_read_b128 v[210:213], v196 offset:2048
	ds_read_b128 v[214:217], v196 offset:3072
	s_add_i32 s29, s58, s34
	v_lshl_add_u64 v[194:195], v[194:195], 0, s[12:13]
	s_mov_b32 m0, s29
	s_nop 0
	global_load_lds_dwordx4 v[194:195], off
	v_lshl_add_u64 v[194:195], v[218:219], 0, s[12:13]
	s_add_i32 m0, s29, 0x2000
	s_nop 0
	global_load_lds_dwordx4 v[194:195], off
	s_barrier
	s_setprio 1
	s_waitcnt lgkmcnt(3)
	v_mfma_f32_16x16x32_bf16 v[132:135], v[202:205], v[160:163], v[132:135]
	s_waitcnt lgkmcnt(1)
	v_mfma_f32_16x16x32_bf16 v[128:131], v[210:213], v[160:163], v[128:131]
	v_mfma_f32_16x16x32_bf16 v[116:119], v[202:205], v[174:177], v[116:119]
	v_mfma_f32_16x16x32_bf16 v[112:115], v[210:213], v[174:177], v[112:115]
	v_mfma_f32_16x16x32_bf16 v[100:103], v[202:205], v[182:185], v[100:103]
	v_mfma_f32_16x16x32_bf16 v[96:99], v[210:213], v[182:185], v[96:99]
	v_mfma_f32_16x16x32_bf16 v[68:71], v[202:205], v[190:193], v[68:71]
	v_mfma_f32_16x16x32_bf16 v[64:67], v[210:213], v[190:193], v[64:67]
	v_mfma_f32_16x16x32_bf16 v[132:135], v[206:209], v[170:173], v[132:135]
	s_mov_b32 m0, s39
	s_waitcnt lgkmcnt(0)
	v_mfma_f32_16x16x32_bf16 v[128:131], v[214:217], v[170:173], v[128:131]
	v_lshl_add_u64 v[194:195], v[220:221], 0, s[12:13]
	v_mfma_f32_16x16x32_bf16 v[116:119], v[206:209], v[178:181], v[116:119]
	v_mfma_f32_16x16x32_bf16 v[112:115], v[214:217], v[178:181], v[112:115]
	v_mfma_f32_16x16x32_bf16 v[100:103], v[206:209], v[186:189], v[100:103]
	v_mfma_f32_16x16x32_bf16 v[96:99], v[214:217], v[186:189], v[96:99]
	v_mfma_f32_16x16x32_bf16 v[68:71], v[206:209], v[198:201], v[68:71]
	v_mfma_f32_16x16x32_bf16 v[64:67], v[214:217], v[198:201], v[64:67]
	s_setprio 0
	s_barrier
; #define PG8_STAGE(bufoff, gbase, voff) do { _Pragma("unroll") for (int _i = 0; _i < 2; ++_i) \
;         __builtin_amdgcn_global_load_lds((const unsigned*)((const char*)(gbase) + (voff)[_i]), (LAS unsigned*)(lds + (bufoff) + ldsw + _i * 8192), 16, 0, 0); } while (0)
; #define PG8_LDA(dst, b, h) do { _Pragma("unroll") for (int m = 0; m < 4; ++m) _Pragma("unroll") for (int k = 0; k < 2; ++k) dst[m][k] = *(const LAS bf16x8*)(lds + PG8_SA(b, h) + aoff + m * 2048 + k * 1024); } while (0)
; #define PG8_MMA(ai, bj, At, Bt) do { __builtin_amdgcn_s_setprio(1); _Pragma("unroll") for (int m = 0; m < 4; ++m) _Pragma("unroll") for (int n = 0; n < 2; ++n) _Pragma("unroll") for (int k = 0; k < 2; ++k) \
;         acc[ai][bj][m][n] = __builtin_amdgcn_mfma_f32_16x16x32_bf16(Bt[n][k], At[m][k], acc[ai][bj][m][n], 0, 0, 0); __builtin_amdgcn_s_setprio(0); } while (0)
; #define PG8_WAIT_V(n) asm volatile("s_waitcnt vmcnt(" #n ")" ::: "memory")
; #define PG8_WAIT_L(n) asm volatile("s_waitcnt lgkmcnt(" #n ")" ::: "memory")
; #define PG8_BAR __builtin_amdgcn_s_barrier()
; #define PG8_SCHED __builtin_amdgcn_sched_barrier(0)
;     DI void operator()(const f32x4 (&acc)[2][2][4][2], const Unit& u, int wr, int wc, int fr, int fq) const {
;         const int row0 = u.pm * BM + wr * 64 + fr, col0 = u.pn * BM + wc * 32 + 8 * fq;
;         f32x4 sc[2][2];
; #pragma unroll
;         for (int bj = 0; bj < 2; ++bj)
; #pragma unroll
;             for (int n = 0; n < 2; ++n) sc[bj][n] = scale ? *(const f32x4*)(scale + col0 + bj * HALF + 4 * n) : (f32x4){1.f, 1.f, 1.f, 1.f};
; template <class Map, class Epi>
; DI void gemm_phase(LAS unsigned char* lds, const Map& MP, const Epi& E, const int nM, const int nN, const int K, const int lda, const int ldb) {
;     ...
;             PG8_BAR; PG8_WAIT_L(0); PG8_MMA(0, 1, At, B1); PG8_BAR;
;             PG8_LDA(At, 1, 1); PG8_STAGE(PG8_SA(1, 0), a3, voffA);
;             PG8_BAR; PG8_WAIT_L(0); PG8_MMA(1, 0, At, B0); PG8_BAR; PG8_SCHED;
;             PG8_STAGE(PG8_SB(1, 1), b3 + hstepB, voffB);
;             PG8_WAIT_V(6); PG8_BAR; PG8_MMA(1, 1, At, B1); PG8_BAR;
;         }
	ds_read_b128 v[160:163], v168 offset:49152
	ds_read_b128 v[170:173], v168 offset:50176
	ds_read_b128 v[174:177], v168 offset:51200
	ds_read_b128 v[178:181], v168 offset:52224
	ds_read_b128 v[182:185], v168 offset:53248
	ds_read_b128 v[186:189], v168 offset:54272
	ds_read_b128 v[190:193], v168 offset:55296
	ds_read_b128 v[198:201], v168 offset:56320
	global_load_lds_dwordx4 v[194:195], off
	v_lshl_add_u64 v[194:195], v[222:223], 0, s[12:13]
	s_mov_b32 m0, s46
	s_nop 0
	global_load_lds_dwordx4 v[194:195], off
	s_waitcnt vmcnt(10)
	s_barrier
	s_setprio 1
	s_waitcnt lgkmcnt(7)
	v_mfma_f32_16x16x32_bf16 v[60:63], v[72:75], v[160:163], v[60:63]
	v_mfma_f32_16x16x32_bf16 v[56:59], v[80:83], v[160:163], v[56:59]
	s_waitcnt lgkmcnt(5)
	v_mfma_f32_16x16x32_bf16 v[44:47], v[72:75], v[174:177], v[44:47]
	v_mfma_f32_16x16x32_bf16 v[40:43], v[80:83], v[174:177], v[40:43]
	s_waitcnt lgkmcnt(3)
	v_mfma_f32_16x16x32_bf16 v[28:31], v[72:75], v[182:185], v[28:31]
	v_mfma_f32_16x16x32_bf16 v[24:27], v[80:83], v[182:185], v[24:27]
	s_waitcnt lgkmcnt(1)
	v_mfma_f32_16x16x32_bf16 v[12:15], v[72:75], v[190:193], v[12:15]
	v_mfma_f32_16x16x32_bf16 v[8:11], v[80:83], v[190:193], v[8:11]
	v_mfma_f32_16x16x32_bf16 v[60:63], v[76:79], v[170:173], v[60:63]
	v_mfma_f32_16x16x32_bf16 v[56:59], v[84:87], v[170:173], v[56:59]
	v_mfma_f32_16x16x32_bf16 v[44:47], v[76:79], v[178:181], v[44:47]
	v_mfma_f32_16x16x32_bf16 v[40:43], v[84:87], v[178:181], v[40:43]
	v_mfma_f32_16x16x32_bf16 v[28:31], v[76:79], v[186:189], v[28:31]
	v_mfma_f32_16x16x32_bf16 v[24:27], v[84:87], v[186:189], v[24:27]
	s_waitcnt lgkmcnt(0)
	v_mfma_f32_16x16x32_bf16 v[12:15], v[76:79], v[198:201], v[12:15]
	v_mfma_f32_16x16x32_bf16 v[8:11], v[84:87], v[198:201], v[8:11]
	s_setprio 0
	s_barrier
	s_add_u32 s26, s26, 0x20080
	s_addc_u32 s27, s27, 0
	s_add_i32 s28, s28, s34
	s_mov_b32 m0, s28
	s_nop 0
	global_load_lds_dwordx4 v148, s[26:27]
	s_add_i32 m0, s28, 0x2000
	s_nop 0
	global_load_lds_dwordx4 v144, s[26:27]
	s_waitcnt vmcnt(6)
	s_barrier
	s_setprio 1
	v_mfma_f32_16x16x32_bf16 v[52:55], v[202:205], v[160:163], v[52:55]
	v_mfma_f32_16x16x32_bf16 v[48:51], v[210:213], v[160:163], v[48:51]
	ds_read_b128 v[72:75], v167
	v_mfma_f32_16x16x32_bf16 v[36:39], v[202:205], v[174:177], v[36:39]
	v_mfma_f32_16x16x32_bf16 v[32:35], v[210:213], v[174:177], v[32:35]
	ds_read_b128 v[76:79], v167 offset:1024
	v_mfma_f32_16x16x32_bf16 v[20:23], v[202:205], v[182:185], v[20:23]
	v_mfma_f32_16x16x32_bf16 v[16:19], v[210:213], v[182:185], v[16:19]
	ds_read_b128 v[80:83], v167 offset:2048
	v_mfma_f32_16x16x32_bf16 v[4:7], v[202:205], v[190:193], v[4:7]
	v_mfma_f32_16x16x32_bf16 v[0:3], v[210:213], v[190:193], v[0:3]
	ds_read_b128 v[84:87], v167 offset:3072
	v_mfma_f32_16x16x32_bf16 v[52:55], v[206:209], v[170:173], v[52:55]
	s_add_i32 s57, s57, 2
	v_mfma_f32_16x16x32_bf16 v[48:51], v[214:217], v[170:173], v[48:51]
	s_add_u32 s55, s55, 0x100
	s_addc_u32 s56, s56, 0
	v_mfma_f32_16x16x32_bf16 v[36:39], v[206:209], v[178:181], v[36:39]
	s_add_u32 s24, s24, 0x100
	s_addc_u32 s25, s25, 0
	v_mfma_f32_16x16x32_bf16 v[32:35], v[214:217], v[178:181], v[32:35]
	s_cmp_gt_u32 s57, 5
	v_mfma_f32_16x16x32_bf16 v[20:23], v[206:209], v[186:189], v[20:23]
	v_mfma_f32_16x16x32_bf16 v[16:19], v[214:217], v[186:189], v[16:19]
	v_mfma_f32_16x16x32_bf16 v[4:7], v[206:209], v[198:201], v[4:7]
	v_mfma_f32_16x16x32_bf16 v[0:3], v[214:217], v[198:201], v[0:3]
	s_setprio 0
	s_barrier
	s_cbranch_scc0 .LBB1_229
	s_waitcnt lgkmcnt(0)
	s_lshl_b32 s17, s42, 8
	v_mov_b32_e32 v170, v164
	v_mov_b32_e32 v72, v165
	s_or_b32 s17, s17, s38
	v_mov_b32_e32 v80, 1.0
	v_lshl_add_u32 v160, v72, 3, s17
	v_ashrrev_i32_e32 v161, 31, v160
	v_cndmask_b32_e64 v72, 0, 1, s[14:15]
	v_lshl_add_u64 v[162:163], v[160:161], 2, s[8:9]
	v_cmp_ne_u32_e64 s[42:43], 1, v72
	s_andn2_b64 vcc, exec, s[14:15]
	v_mov_b32_e32 v84, 1.0
	v_mov_b32_e32 v85, 1.0
	v_mov_b32_e32 v86, 1.0
	v_mov_b32_e32 v87, 1.0
	s_cbranch_vccnz .LBB1_232
	global_load_dwordx4 v[84:87], v[162:163], off

; #define PG8_STAGE(bufoff, gbase, voff) do { _Pragma("unroll") for (int _i = 0; _i < 2; ++_i) \
;         __builtin_amdgcn_global_load_lds((const unsigned*)((const char*)(gbase) + (voff)[_i]), (LAS unsigned*)(lds + (bufoff) + ldsw + _i * 8192), 16, 0, 0); } while (0)
; #define PG8_LDA(dst, b, h) do { _Pragma("unroll") for (int m = 0; m < 4; ++m) _Pragma("unroll") for (int k = 0; k < 2; ++k) dst[m][k] = *(const LAS bf16x8*)(lds + PG8_SA(b, h) + aoff + m * 2048 + k * 1024); } while (0)
; #define PG8_LDB(dst, b, h) do { _Pragma("unroll") for (int n = 0; n < 2; ++n) _Pragma("unroll") for (int k = 0; k < 2; ++k) dst[n][k] = *(const LAS bf16x8*)(lds + PG8_SB(b, h) + boff + n * 2048 + k * 1024); } while (0)
; #define PG8_MMA(ai, bj, At, Bt) do { __builtin_amdgcn_s_setprio(1); _Pragma("unroll") for (int m = 0; m < 4; ++m) _Pragma("unroll") for (int n = 0; n < 2; ++n) _Pragma("unroll") for (int k = 0; k < 2; ++k) \
;         acc[ai][bj][m][n] = __builtin_amdgcn_mfma_f32_16x16x32_bf16(Bt[n][k], At[m][k], acc[ai][bj][m][n], 0, 0, 0); __builtin_amdgcn_s_setprio(0); } while (0)
; #define PG8_WAIT_V(n) asm volatile("s_waitcnt vmcnt(" #n ")" ::: "memory")
; #define PG8_WAIT_L(n) asm volatile("s_waitcnt lgkmcnt(" #n ")" ::: "memory")
; template <class Map, class Epi>
; DI void gemm_phase(LAS unsigned char* lds, const Map& MP, const Epi& E, const int nM, const int nN, const int K, const int lda, const int ldb) {
;     ...
;         for (int t = 0; t < nt; t += 2) {
;             const bool last = (t == nt - 2);
;             const char* a1 = cA + (size_t)(t + 1) * kstep;
;             const char* a2 = last ? nA : cA + (size_t)(t + 2) * kstep; const char* b2 = last ? nB : cB + (size_t)(t + 2) * kstep;
;             const char* a3 = a2 + kstep; const char* b3 = b2 + kstep;
;             PG8_LDB(B0, 0, 0); PG8_SCHED; PG8_LDA(At, 0, 0); PG8_STAGE(PG8_SA(1, 1), a1 + hstepA, voffA);
;             PG8_WAIT_L(8); PG8_BAR; PG8_WAIT_L(0); PG8_MMA(0, 0, At, B0); PG8_BAR; PG8_SCHED;
;             PG8_LDB(B1, 0, 1); PG8_STAGE(PG8_SB(0, 0), b2, voffB);
;             PG8_BAR; PG8_WAIT_L(0); PG8_MMA(0, 1, At, B1); PG8_BAR;
;             PG8_LDA(At, 0, 1); PG8_STAGE(PG8_SA(0, 0), a2, voffA);
;             PG8_BAR; PG8_WAIT_L(0); PG8_MMA(1, 0, At, B0); PG8_BAR; PG8_SCHED;
;             PG8_STAGE(PG8_SB(0, 1), b2 + hstepB, voffB);
;             PG8_WAIT_V(6); PG8_BAR; PG8_MMA(1, 1, At, B1); PG8_BAR;
.LBB1_380:
	ds_read_b128 v[96:99], v190
	ds_read_b128 v[100:103], v190 offset:1024
	ds_read_b128 v[108:111], v190 offset:2048
	ds_read_b128 v[112:115], v190 offset:3072
	ds_read_b128 v[160:163], v190 offset:4096
	ds_read_b128 v[164:167], v190 offset:5120
	ds_read_b128 v[198:201], v190 offset:6144
	ds_read_b128 v[202:205], v190 offset:7168
	s_add_u32 s28, s44, 0xfff80080
	s_addc_u32 s29, s45, -1
	s_cmp_eq_u32 vcc_hi, 28
	s_cselect_b32 s47, s23, s29
	s_cselect_b32 s46, s61, s28
	s_cselect_b32 s29, s21, vcc_lo
	s_cselect_b32 s28, s58, s59
	s_add_i32 m0, s38, 0xc000
	s_nop 0
	global_load_lds_dwordx4 v178, s[44:45]
	s_add_i32 m0, s38, 0xe000
	s_nop 0
	global_load_lds_dwordx4 v176, s[44:45]
	s_waitcnt lgkmcnt(8)
	s_barrier
	s_setprio 1
	s_waitcnt lgkmcnt(7)
	v_mfma_f32_16x16x32_bf16 v[148:151], v[80:83], v[96:99], v[148:151]
	v_mfma_f32_16x16x32_bf16 v[144:147], v[88:91], v[96:99], v[144:147]
	s_waitcnt lgkmcnt(5)
	v_mfma_f32_16x16x32_bf16 v[136:139], v[80:83], v[108:111], v[136:139]
	v_mfma_f32_16x16x32_bf16 v[128:131], v[88:91], v[108:111], v[128:131]
	s_waitcnt lgkmcnt(3)
	v_mfma_f32_16x16x32_bf16 v[120:123], v[80:83], v[160:163], v[120:123]
	v_mfma_f32_16x16x32_bf16 v[104:107], v[88:91], v[160:163], v[104:107]
	s_waitcnt lgkmcnt(1)
	v_mfma_f32_16x16x32_bf16 v[76:79], v[80:83], v[198:201], v[76:79]
	v_mfma_f32_16x16x32_bf16 v[72:75], v[88:91], v[198:201], v[72:75]
	v_mfma_f32_16x16x32_bf16 v[148:151], v[84:87], v[100:103], v[148:151]
	v_mfma_f32_16x16x32_bf16 v[144:147], v[92:95], v[100:103], v[144:147]
	v_mfma_f32_16x16x32_bf16 v[136:139], v[84:87], v[112:115], v[136:139]
	v_mfma_f32_16x16x32_bf16 v[128:131], v[92:95], v[112:115], v[128:131]
	v_mfma_f32_16x16x32_bf16 v[120:123], v[84:87], v[164:167], v[120:123]
	v_mfma_f32_16x16x32_bf16 v[104:107], v[92:95], v[164:167], v[104:107]
	s_waitcnt lgkmcnt(0)
	v_mfma_f32_16x16x32_bf16 v[76:79], v[84:87], v[202:205], v[76:79]
	v_mfma_f32_16x16x32_bf16 v[72:75], v[92:95], v[202:205], v[72:75]
	s_setprio 0
	s_barrier
	ds_read_b128 v[206:209], v191
	ds_read_b128 v[210:213], v191 offset:1024
	ds_read_b128 v[214:217], v191 offset:2048
	ds_read_b128 v[218:221], v191 offset:3072
	s_add_i32 s68, s5, s37
	v_lshl_add_u64 v[184:185], s[28:29], 0, v[172:173]
	s_mov_b32 m0, s68
	s_nop 0
	global_load_lds_dwordx4 v[184:185], off
	v_lshl_add_u64 v[194:195], s[28:29], 0, v[168:169]
	s_add_i32 m0, s68, 0x2000
	s_nop 0
	global_load_lds_dwordx4 v[194:195], off
	s_barrier
	s_setprio 1
	s_waitcnt lgkmcnt(3)
	v_mfma_f32_16x16x32_bf16 v[156:159], v[206:209], v[96:99], v[156:159]
	s_waitcnt lgkmcnt(1)
	v_mfma_f32_16x16x32_bf16 v[96:99], v[214:217], v[96:99], v[152:155]
	v_mfma_f32_16x16x32_bf16 v[156:159], v[210:213], v[100:103], v[156:159]
	s_waitcnt lgkmcnt(0)
	v_mfma_f32_16x16x32_bf16 v[96:99], v[218:221], v[100:103], v[96:99]
	v_mfma_f32_16x16x32_bf16 v[100:103], v[206:209], v[108:111], v[140:143]
	v_mfma_f32_16x16x32_bf16 v[108:111], v[214:217], v[108:111], v[132:135]
	v_mfma_f32_16x16x32_bf16 v[116:119], v[214:217], v[160:163], v[116:119]
	v_mfma_f32_16x16x32_bf16 v[68:71], v[206:209], v[198:201], v[68:71]
	v_mfma_f32_16x16x32_bf16 v[64:67], v[214:217], v[198:201], v[64:67]
	s_mov_b32 m0, s38
	v_mfma_f32_16x16x32_bf16 v[100:103], v[210:213], v[112:115], v[100:103]
	v_lshl_add_u64 v[226:227], s[46:47], 0, v[174:175]
	v_mfma_f32_16x16x32_bf16 v[108:111], v[218:221], v[112:115], v[108:111]
	v_mfma_f32_16x16x32_bf16 v[112:115], v[206:209], v[160:163], v[124:127]
	v_mfma_f32_16x16x32_bf16 v[116:119], v[218:221], v[164:167], v[116:119]
	v_mfma_f32_16x16x32_bf16 v[68:71], v[210:213], v[202:205], v[68:71]
	v_mfma_f32_16x16x32_bf16 v[64:67], v[218:221], v[202:205], v[64:67]
	v_mfma_f32_16x16x32_bf16 v[112:115], v[210:213], v[164:167], v[112:115]
	s_setprio 0
	s_barrier
	ds_read_b128 v[124:127], v190 offset:16384
	ds_read_b128 v[132:135], v190 offset:17408
	ds_read_b128 v[140:143], v190 offset:18432
	ds_read_b128 v[152:155], v190 offset:19456
	ds_read_b128 v[160:163], v190 offset:20480
	ds_read_b128 v[164:167], v190 offset:21504
	ds_read_b128 v[198:201], v190 offset:22528
	ds_read_b128 v[202:205], v190 offset:23552
	global_load_lds_dwordx4 v[226:227], off
	v_lshl_add_u64 v[234:235], s[46:47], 0, v[170:171]
	s_mov_b32 m0, s39
	s_nop 0
	global_load_lds_dwordx4 v[234:235], off
	s_waitcnt vmcnt(10)
	s_barrier
	s_setprio 1
	s_waitcnt lgkmcnt(7)
	v_mfma_f32_16x16x32_bf16 v[60:63], v[80:83], v[124:127], v[60:63]
	v_mfma_f32_16x16x32_bf16 v[48:51], v[88:91], v[124:127], v[48:51]
	s_waitcnt lgkmcnt(5)
	v_mfma_f32_16x16x32_bf16 v[40:43], v[80:83], v[140:143], v[40:43]
	v_mfma_f32_16x16x32_bf16 v[32:35], v[88:91], v[140:143], v[32:35]
	s_waitcnt lgkmcnt(3)
	v_mfma_f32_16x16x32_bf16 v[24:27], v[80:83], v[160:163], v[24:27]
	v_mfma_f32_16x16x32_bf16 v[16:19], v[88:91], v[160:163], v[16:19]
	s_waitcnt lgkmcnt(1)
	v_mfma_f32_16x16x32_bf16 v[12:15], v[80:83], v[198:201], v[12:15]
	v_mfma_f32_16x16x32_bf16 v[8:11], v[88:91], v[198:201], v[8:11]
	v_mfma_f32_16x16x32_bf16 v[60:63], v[84:87], v[132:135], v[60:63]
	v_mfma_f32_16x16x32_bf16 v[48:51], v[92:95], v[132:135], v[48:51]
	v_mfma_f32_16x16x32_bf16 v[40:43], v[84:87], v[152:155], v[40:43]
	v_mfma_f32_16x16x32_bf16 v[32:35], v[92:95], v[152:155], v[32:35]
	v_mfma_f32_16x16x32_bf16 v[24:27], v[84:87], v[164:167], v[24:27]
	v_mfma_f32_16x16x32_bf16 v[16:19], v[92:95], v[164:167], v[16:19]
	s_waitcnt lgkmcnt(0)
	v_mfma_f32_16x16x32_bf16 v[12:15], v[84:87], v[202:205], v[12:15]
	v_mfma_f32_16x16x32_bf16 v[8:11], v[92:95], v[202:205], v[8:11]
	s_setprio 0
	s_barrier
	s_add_u32 s68, s28, 0x80000
	s_addc_u32 s69, s29, 0
	s_add_i32 s70, s2, s37
	s_mov_b32 m0, s70
	s_nop 0
	global_load_lds_dwordx4 v172, s[68:69]
	s_add_i32 m0, s70, 0x2000
	s_nop 0
	global_load_lds_dwordx4 v168, s[68:69]
	s_waitcnt vmcnt(6)
	s_barrier
; #define PG8_STAGE(bufoff, gbase, voff) do { _Pragma("unroll") for (int _i = 0; _i < 2; ++_i) \
;         __builtin_amdgcn_global_load_lds((const unsigned*)((const char*)(gbase) + (voff)[_i]), (LAS unsigned*)(lds + (bufoff) + ldsw + _i * 8192), 16, 0, 0); } while (0)
; #define PG8_LDA(dst, b, h) do { _Pragma("unroll") for (int m = 0; m < 4; ++m) _Pragma("unroll") for (int k = 0; k < 2; ++k) dst[m][k] = *(const LAS bf16x8*)(lds + PG8_SA(b, h) + aoff + m * 2048 + k * 1024); } while (0)
; #define PG8_LDB(dst, b, h) do { _Pragma("unroll") for (int n = 0; n < 2; ++n) _Pragma("unroll") for (int k = 0; k < 2; ++k) dst[n][k] = *(const LAS bf16x8*)(lds + PG8_SB(b, h) + boff + n * 2048 + k * 1024); } while (0)
; #define PG8_MMA(ai, bj, At, Bt) do { __builtin_amdgcn_s_setprio(1); _Pragma("unroll") for (int m = 0; m < 4; ++m) _Pragma("unroll") for (int n = 0; n < 2; ++n) _Pragma("unroll") for (int k = 0; k < 2; ++k) \
;         acc[ai][bj][m][n] = __builtin_amdgcn_mfma_f32_16x16x32_bf16(Bt[n][k], At[m][k], acc[ai][bj][m][n], 0, 0, 0); __builtin_amdgcn_s_setprio(0); } while (0)
; #define PG8_WAIT_V(n) asm volatile("s_waitcnt vmcnt(" #n ")" ::: "memory")
; #define PG8_WAIT_L(n) asm volatile("s_waitcnt lgkmcnt(" #n ")" ::: "memory")
; #define PG8_BAR __builtin_amdgcn_s_barrier()
; #define PG8_SCHED __builtin_amdgcn_sched_barrier(0)
; template <class Map, class Epi>
; DI void gemm_phase(LAS unsigned char* lds, const Map& MP, const Epi& E, const int nM, const int nN, const int K, const int lda, const int ldb) {
;     ...
;             PG8_BAR; PG8_WAIT_L(0); PG8_MMA(1, 0, At, B0); PG8_BAR; PG8_SCHED;
;             PG8_STAGE(PG8_SB(0, 1), b2 + hstepB, voffB);
;             PG8_WAIT_V(6); PG8_BAR; PG8_MMA(1, 1, At, B1); PG8_BAR;
;             PG8_LDB(B0, 1, 0); PG8_SCHED; PG8_LDA(At, 1, 0); PG8_STAGE(PG8_SA(0, 1), a2 + hstepA, voffA);
;             PG8_WAIT_L(8); PG8_BAR; PG8_WAIT_L(0); PG8_MMA(0, 0, At, B0); PG8_BAR; PG8_SCHED;
;             PG8_LDB(B1, 1, 1); PG8_STAGE(PG8_SB(1, 0), b3, voffB);
;             PG8_BAR; PG8_WAIT_L(0); PG8_MMA(0, 1, At, B1); PG8_BAR;
;             PG8_LDA(At, 1, 1); PG8_STAGE(PG8_SA(1, 0), a3, voffA);
;             PG8_BAR; PG8_WAIT_L(0); PG8_MMA(1, 0, At, B0); PG8_BAR; PG8_SCHED;
;             PG8_STAGE(PG8_SB(1, 1), b3 + hstepB, voffB);
	s_setprio 1
	v_mfma_f32_16x16x32_bf16 v[56:59], v[206:209], v[124:127], v[56:59]
	v_mfma_f32_16x16x32_bf16 v[52:55], v[214:217], v[124:127], v[52:55]
	s_add_i32 s68, 0, 0x18000
	v_add_u32_e32 v92, s68, v188
	ds_read_b128 v[80:83], v92
	v_mfma_f32_16x16x32_bf16 v[44:47], v[206:209], v[140:143], v[44:47]
	v_mfma_f32_16x16x32_bf16 v[36:39], v[214:217], v[140:143], v[36:39]
	ds_read_b128 v[84:87], v92 offset:1024
	v_mfma_f32_16x16x32_bf16 v[28:31], v[206:209], v[160:163], v[28:31]
	v_mfma_f32_16x16x32_bf16 v[20:23], v[214:217], v[160:163], v[20:23]
	ds_read_b128 v[88:91], v92 offset:2048
	v_mfma_f32_16x16x32_bf16 v[4:7], v[206:209], v[198:201], v[4:7]
	v_mfma_f32_16x16x32_bf16 v[0:3], v[214:217], v[198:201], v[0:3]
	ds_read_b128 v[92:95], v92 offset:3072
	v_mfma_f32_16x16x32_bf16 v[56:59], v[210:213], v[132:135], v[56:59]
	v_mfma_f32_16x16x32_bf16 v[52:55], v[218:221], v[132:135], v[52:55]
	v_mfma_f32_16x16x32_bf16 v[44:47], v[210:213], v[152:155], v[44:47]
	v_mfma_f32_16x16x32_bf16 v[36:39], v[218:221], v[152:155], v[36:39]
	v_mfma_f32_16x16x32_bf16 v[28:31], v[210:213], v[164:167], v[28:31]
	v_mfma_f32_16x16x32_bf16 v[20:23], v[218:221], v[164:167], v[20:23]
	v_mfma_f32_16x16x32_bf16 v[4:7], v[210:213], v[202:205], v[4:7]
	v_mfma_f32_16x16x32_bf16 v[0:3], v[218:221], v[202:205], v[0:3]
	s_setprio 0
	s_barrier
	ds_read_b128 v[124:127], v190 offset:32768
	ds_read_b128 v[132:135], v190 offset:33792
	ds_read_b128 v[160:163], v190 offset:34816
	ds_read_b128 v[164:167], v190 offset:35840
	ds_read_b128 v[198:201], v190 offset:36864
	ds_read_b128 v[202:205], v190 offset:37888
	ds_read_b128 v[206:209], v190 offset:38912
	ds_read_b128 v[210:213], v190 offset:39936
	s_add_u32 s46, s46, 0x80000
	s_addc_u32 s47, s47, 0
	s_mov_b32 m0, s56
	s_nop 0
	global_load_lds_dwordx4 v174, s[46:47]
	s_mov_b32 m0, s57
	s_nop 0
	global_load_lds_dwordx4 v170, s[46:47]
	s_waitcnt lgkmcnt(8)
	s_barrier
	s_setprio 1
	s_waitcnt lgkmcnt(7)
	v_mfma_f32_16x16x32_bf16 v[140:143], v[80:83], v[124:127], v[148:151]
	s_waitcnt lgkmcnt(6)
	v_mfma_f32_16x16x32_bf16 v[148:151], v[84:87], v[132:135], v[140:143]
	v_mfma_f32_16x16x32_bf16 v[140:143], v[88:91], v[124:127], v[144:147]
	s_waitcnt lgkmcnt(5)
	v_mfma_f32_16x16x32_bf16 v[136:139], v[80:83], v[160:163], v[136:139]
	v_mfma_f32_16x16x32_bf16 v[128:131], v[88:91], v[160:163], v[128:131]
	s_waitcnt lgkmcnt(3)
	v_mfma_f32_16x16x32_bf16 v[120:123], v[80:83], v[198:201], v[120:123]
	v_mfma_f32_16x16x32_bf16 v[104:107], v[88:91], v[198:201], v[104:107]
	s_waitcnt lgkmcnt(1)
	v_mfma_f32_16x16x32_bf16 v[76:79], v[80:83], v[206:209], v[76:79]
	v_mfma_f32_16x16x32_bf16 v[72:75], v[88:91], v[206:209], v[72:75]
	v_mfma_f32_16x16x32_bf16 v[144:147], v[92:95], v[132:135], v[140:143]
	v_mfma_f32_16x16x32_bf16 v[136:139], v[84:87], v[164:167], v[136:139]
	v_mfma_f32_16x16x32_bf16 v[128:131], v[92:95], v[164:167], v[128:131]
	v_mfma_f32_16x16x32_bf16 v[120:123], v[84:87], v[202:205], v[120:123]
	v_mfma_f32_16x16x32_bf16 v[104:107], v[92:95], v[202:205], v[104:107]
	s_waitcnt lgkmcnt(0)
	v_mfma_f32_16x16x32_bf16 v[76:79], v[84:87], v[210:213], v[76:79]
	v_mfma_f32_16x16x32_bf16 v[72:75], v[92:95], v[210:213], v[72:75]
	s_setprio 0
	s_barrier
	s_add_i32 s46, 0, 0x1c000
	v_add_u32_e32 v140, s46, v188
	ds_read_b128 v[214:217], v140
	ds_read_b128 v[218:221], v140 offset:1024
	ds_read_b128 v[222:225], v140 offset:2048
	ds_read_b128 v[230:233], v140 offset:3072
	s_add_i32 s47, s68, s37
	v_lshl_add_u64 v[140:141], v[184:185], 0, s[14:15]
	s_mov_b32 m0, s47
	s_nop 0
	global_load_lds_dwordx4 v[140:141], off
	v_lshl_add_u64 v[140:141], v[194:195], 0, s[14:15]
	s_add_i32 m0, s47, 0x2000
	s_nop 0
	global_load_lds_dwordx4 v[140:141], off
	s_barrier
	s_setprio 1
	s_waitcnt lgkmcnt(1)
	v_mfma_f32_16x16x32_bf16 v[96:99], v[222:225], v[124:127], v[96:99]
	v_mfma_f32_16x16x32_bf16 v[140:143], v[214:217], v[124:127], v[156:159]
	s_waitcnt lgkmcnt(0)
	v_mfma_f32_16x16x32_bf16 v[152:155], v[230:233], v[132:135], v[96:99]
	v_mfma_f32_16x16x32_bf16 v[96:99], v[214:217], v[160:163], v[100:103]
	v_mfma_f32_16x16x32_bf16 v[156:159], v[218:221], v[132:135], v[140:143]
	v_mfma_f32_16x16x32_bf16 v[140:143], v[218:221], v[164:167], v[96:99]
	v_mfma_f32_16x16x32_bf16 v[96:99], v[222:225], v[160:163], v[108:111]
	v_mfma_f32_16x16x32_bf16 v[132:135], v[230:233], v[164:167], v[96:99]
	v_mfma_f32_16x16x32_bf16 v[96:99], v[214:217], v[198:201], v[112:115]
	s_mov_b32 m0, s62
	v_mfma_f32_16x16x32_bf16 v[124:127], v[218:221], v[202:205], v[96:99]
	v_lshl_add_u64 v[184:185], v[226:227], 0, s[14:15]
	v_mfma_f32_16x16x32_bf16 v[96:99], v[222:225], v[198:201], v[116:119]
	v_mfma_f32_16x16x32_bf16 v[68:71], v[214:217], v[206:209], v[68:71]
	v_mfma_f32_16x16x32_bf16 v[64:67], v[222:225], v[206:209], v[64:67]
	v_mfma_f32_16x16x32_bf16 v[116:119], v[230:233], v[202:205], v[96:99]
	v_mfma_f32_16x16x32_bf16 v[68:71], v[218:221], v[210:213], v[68:71]
	v_mfma_f32_16x16x32_bf16 v[64:67], v[230:233], v[210:213], v[64:67]
	s_setprio 0
	s_barrier
	ds_read_b128 v[96:99], v190 offset:49152
	ds_read_b128 v[100:103], v190 offset:50176
	ds_read_b128 v[108:111], v190 offset:51200
	ds_read_b128 v[112:115], v190 offset:52224
	ds_read_b128 v[160:163], v190 offset:53248
	ds_read_b128 v[164:167], v190 offset:54272
	ds_read_b128 v[198:201], v190 offset:55296
	ds_read_b128 v[202:205], v190 offset:56320
	global_load_lds_dwordx4 v[184:185], off
	v_lshl_add_u64 v[184:185], v[234:235], 0, s[14:15]
	s_mov_b32 m0, s63
	s_nop 0
	global_load_lds_dwordx4 v[184:185], off
	s_waitcnt vmcnt(10)
	s_barrier
; #define PG8_STAGE(bufoff, gbase, voff) do { _Pragma("unroll") for (int _i = 0; _i < 2; ++_i) \
;         __builtin_amdgcn_global_load_lds((const unsigned*)((const char*)(gbase) + (voff)[_i]), (LAS unsigned*)(lds + (bufoff) + ldsw + _i * 8192), 16, 0, 0); } while (0)
; #define PG8_LDA(dst, b, h) do { _Pragma("unroll") for (int m = 0; m < 4; ++m) _Pragma("unroll") for (int k = 0; k < 2; ++k) dst[m][k] = *(const LAS bf16x8*)(lds + PG8_SA(b, h) + aoff + m * 2048 + k * 1024); } while (0)
; #define PG8_MMA(ai, bj, At, Bt) do { __builtin_amdgcn_s_setprio(1); _Pragma("unroll") for (int m = 0; m < 4; ++m) _Pragma("unroll") for (int n = 0; n < 2; ++n) _Pragma("unroll") for (int k = 0; k < 2; ++k) \
;         acc[ai][bj][m][n] = __builtin_amdgcn_mfma_f32_16x16x32_bf16(Bt[n][k], At[m][k], acc[ai][bj][m][n], 0, 0, 0); __builtin_amdgcn_s_setprio(0); } while (0)
; #define PG8_WAIT_V(n) asm volatile("s_waitcnt vmcnt(" #n ")" ::: "memory")
; #define PG8_WAIT_L(n) asm volatile("s_waitcnt lgkmcnt(" #n ")" ::: "memory")
; #define PG8_BAR __builtin_amdgcn_s_barrier()
; #define PG8_SCHED __builtin_amdgcn_sched_barrier(0)
; template <class Map, class Epi>
; DI void gemm_phase(LAS unsigned char* lds, const Map& MP, const Epi& E, const int nM, const int nN, const int K, const int lda, const int ldb) {
;     ...
;             PG8_BAR; PG8_WAIT_L(0); PG8_MMA(0, 1, At, B1); PG8_BAR;
;             PG8_LDA(At, 1, 1); PG8_STAGE(PG8_SA(1, 0), a3, voffA);
;             PG8_BAR; PG8_WAIT_L(0); PG8_MMA(1, 0, At, B0); PG8_BAR; PG8_SCHED;
;             PG8_STAGE(PG8_SB(1, 1), b3 + hstepB, voffB);
;             PG8_WAIT_V(6); PG8_BAR; PG8_MMA(1, 1, At, B1); PG8_BAR;
;         }
	s_setprio 1
	s_waitcnt lgkmcnt(7)
	v_mfma_f32_16x16x32_bf16 v[60:63], v[80:83], v[96:99], v[60:63]
	v_mfma_f32_16x16x32_bf16 v[48:51], v[88:91], v[96:99], v[48:51]
	s_waitcnt lgkmcnt(5)
	v_mfma_f32_16x16x32_bf16 v[40:43], v[80:83], v[108:111], v[40:43]
	v_mfma_f32_16x16x32_bf16 v[32:35], v[88:91], v[108:111], v[32:35]
	s_waitcnt lgkmcnt(3)
	v_mfma_f32_16x16x32_bf16 v[24:27], v[80:83], v[160:163], v[24:27]
	v_mfma_f32_16x16x32_bf16 v[16:19], v[88:91], v[160:163], v[16:19]
	s_waitcnt lgkmcnt(1)
	v_mfma_f32_16x16x32_bf16 v[12:15], v[80:83], v[198:201], v[12:15]
	v_mfma_f32_16x16x32_bf16 v[8:11], v[88:91], v[198:201], v[8:11]
	v_mfma_f32_16x16x32_bf16 v[60:63], v[84:87], v[100:103], v[60:63]
	v_mfma_f32_16x16x32_bf16 v[48:51], v[92:95], v[100:103], v[48:51]
	v_mfma_f32_16x16x32_bf16 v[40:43], v[84:87], v[112:115], v[40:43]
	v_mfma_f32_16x16x32_bf16 v[32:35], v[92:95], v[112:115], v[32:35]
	v_mfma_f32_16x16x32_bf16 v[24:27], v[84:87], v[164:167], v[24:27]
	v_mfma_f32_16x16x32_bf16 v[16:19], v[92:95], v[164:167], v[16:19]
	s_waitcnt lgkmcnt(0)
	v_mfma_f32_16x16x32_bf16 v[12:15], v[84:87], v[202:205], v[12:15]
	v_mfma_f32_16x16x32_bf16 v[8:11], v[92:95], v[202:205], v[8:11]
	s_setprio 0
	s_barrier
	s_add_u32 s28, s28, 0x80080
	s_addc_u32 s29, s29, 0
	s_add_i32 s46, s46, s37
	s_mov_b32 m0, s46
	s_nop 0
	global_load_lds_dwordx4 v172, s[28:29]
	s_add_i32 m0, s46, 0x2000
	s_nop 0
	global_load_lds_dwordx4 v168, s[28:29]
	s_waitcnt vmcnt(6)
	s_barrier
	s_setprio 1
	v_mfma_f32_16x16x32_bf16 v[56:59], v[214:217], v[96:99], v[56:59]
	v_mfma_f32_16x16x32_bf16 v[52:55], v[222:225], v[96:99], v[52:55]
	ds_read_b128 v[80:83], v189
	v_mfma_f32_16x16x32_bf16 v[44:47], v[214:217], v[108:111], v[44:47]
	v_mfma_f32_16x16x32_bf16 v[36:39], v[222:225], v[108:111], v[36:39]
	ds_read_b128 v[84:87], v189 offset:1024
	v_mfma_f32_16x16x32_bf16 v[28:31], v[214:217], v[160:163], v[28:31]
	v_mfma_f32_16x16x32_bf16 v[20:23], v[222:225], v[160:163], v[20:23]
	ds_read_b128 v[88:91], v189 offset:2048
	v_mfma_f32_16x16x32_bf16 v[4:7], v[214:217], v[198:201], v[4:7]
	v_mfma_f32_16x16x32_bf16 v[0:3], v[222:225], v[198:201], v[0:3]
	ds_read_b128 v[92:95], v189 offset:3072
	v_mfma_f32_16x16x32_bf16 v[56:59], v[218:221], v[100:103], v[56:59]
	s_add_i32 vcc_hi, vcc_hi, 2
	v_mfma_f32_16x16x32_bf16 v[52:55], v[230:233], v[100:103], v[52:55]
	s_add_u32 s59, s59, 0x100
	s_addc_u32 vcc_lo, vcc_lo, 0
	v_mfma_f32_16x16x32_bf16 v[44:47], v[218:221], v[112:115], v[44:47]
	s_add_u32 s44, s44, 0x100
	s_addc_u32 s45, s45, 0
	v_mfma_f32_16x16x32_bf16 v[36:39], v[230:233], v[112:115], v[36:39]
	s_cmp_gt_u32 vcc_hi, 29
	v_mfma_f32_16x16x32_bf16 v[28:31], v[218:221], v[164:167], v[28:31]
	v_mfma_f32_16x16x32_bf16 v[20:23], v[230:233], v[164:167], v[20:23]
	v_mfma_f32_16x16x32_bf16 v[4:7], v[218:221], v[202:205], v[4:7]
	v_mfma_f32_16x16x32_bf16 v[0:3], v[230:233], v[202:205], v[0:3]
	s_setprio 0
	s_barrier
	s_cbranch_scc0 .LBB1_380
; DI float silu_mul(float g, float v) { return g * v * __builtin_amdgcn_rcpf(1.0f + __builtin_amdgcn_exp2f(-LOG2E * g)); }
;     DI void operator()(const f32x4 (&acc)[2][2][4][2], const Unit& u, int wr, int wc, int fr, int fq) const {
;         const int row0 = u.pm * BM + wr * 64 + fr, ch0 = u.pn * 128 + wc * 32 + 8 * fq;
;         f32x4 w0[2], w1[2], w2[2], bb[2];
; #pragma unroll
;         for (int n = 0; n < 2; ++n) { w0[n] = *(const f32x4*)(cw + ch0 + 4 * n); w1[n] = *(const f32x4*)(cw + DFF + ch0 + 4 * n); w2[n] = *(const f32x4*)(cw + 2 * DFF + ch0 + 4 * n); bb[n] = *(const f32x4*)(cb + ch0 + 4 * n); }
; #pragma unroll
;         for (int ai = 0; ai < 2; ++ai)
; #pragma unroll
;             for (int m = 0; m < 4; ++m) {
;                 const bool efirst = (m == 0) && (fr == 0), elast = (m == 3) && (fr == 15);
;                 const int row = row0 + ai * HALF + m * 16;
;                 f32x4 gc[2];
; #pragma unroll
;                 for (int n = 0; n < 2; ++n) {
;                     const f32x4 g = acc[ai][0][m][n];
;                     const f32x4 gprev = acc[ai][0][m > 0 ? m - 1 : 0][n], gnext = acc[ai][0][m < 3 ? m + 1 : 3][n];
;                     f32x4 up, dn;
; #pragma unroll
;                     for (int e = 0; e < 4; ++e) {
;                         const float pu = (m > 0 && fr == 15) ? gprev[e] : g[e];
;                         const float pd = (m < 3 && fr == 0) ? gnext[e] : g[e];
;                         up[e] = dpp_ror1(pu); dn[e] = dpp_ror15(pd);
;                     }
;                     if (efirst) up = (f32x4){0.f, 0.f, 0.f, 0.f};
;                     if (elast) dn = (f32x4){0.f, 0.f, 0.f, 0.f};
;                     gc[n] = w0[n] * up + w1[n] * g + w2[n] * dn + bb[n];
;                 }
;                 if (efirst || elast) {
;                     const size_t eo = (size_t)((row >> 6) * 2 + (elast ? 1 : 0)) * DFF + ch0;
; #pragma unroll
;                     for (int n = 0; n < 2; ++n) { *(f32x4*)(EP + eo + 4 * n) = gc[n]; *(f32x4*)(ER + eo + 4 * n) = acc[ai][0][m][n]; *(f32x4*)(EV + eo + 4 * n) = acc[ai][1][m][n]; }
;                 } else {
;                     const f32x4 v0 = acc[ai][1][m][0], v1 = acc[ai][1][m][1];
;                     u32x4 o;
;                     o[0] = pack2(silu_mul(gc[0][0], v0[0]), silu_mul(gc[0][1], v0[1])); o[1] = pack2(silu_mul(gc[0][2], v0[2]), silu_mul(gc[0][3], v0[3]));
	s_waitcnt lgkmcnt(0)
	s_lshl_b32 s23, s43, 7
	v_mov_b32_e32 v194, v186
	v_mov_b32_e32 v80, v187
	s_or_b32 s23, s23, s67
	v_mov_b32_e32 v160, 0
	v_lshl_add_u32 v184, v80, 3, s23
	v_ashrrev_i32_e32 v185, 31, v184
	v_lshlrev_b64 v[80:81], 2, v[184:185]
	v_lshl_add_u64 v[84:85], s[52:53], 0, v[80:81]
	v_lshl_add_u64 v[88:89], s[16:17], 0, v[80:81]
	v_lshl_add_u64 v[92:93], s[18:19], 0, v[80:81]
	v_lshl_add_u64 v[112:113], s[54:55], 0, v[80:81]
	global_load_dwordx4 v[80:83], v[84:85], off offset:16
	global_load_dwordx4 v[96:99], v[84:85], off
	s_nop 0
	global_load_dwordx4 v[84:87], v[88:89], off offset:16
	global_load_dwordx4 v[100:103], v[88:89], off
	s_nop 0
	global_load_dwordx4 v[88:91], v[92:93], off offset:16
	global_load_dwordx4 v[108:111], v[92:93], off
	s_nop 0
	global_load_dwordx4 v[92:95], v[112:113], off offset:16
	s_nop 0
	global_load_dwordx4 v[112:115], v[112:113], off
	v_cmp_eq_u32_e32 vcc, 0, v194
	v_mov_b32_e32 v164, 0
	v_mov_b32_e32 v195, 0
	v_cndmask_b32_e32 v161, v148, v136, vcc
	v_cndmask_b32_e32 v162, v149, v137, vcc
	v_cndmask_b32_e32 v163, v150, v138, vcc
	v_mov_b32_dpp v160, v161 row_ror:15 row_mask:0xf bank_mask:0xf
	v_mov_b32_e32 v161, 0
	v_mov_b32_e32 v166, 0
	v_mov_b32_e32 v167, 0
	v_mov_b32_dpp v161, v162 row_ror:15 row_mask:0xf bank_mask:0xf
	v_mov_b32_e32 v162, 0
	v_mov_b32_dpp v164, v150 row_ror:1 row_mask:0xf bank_mask:0xf
	v_cndmask_b32_e32 v165, v151, v139, vcc
	v_mov_b32_dpp v162, v163 row_ror:15 row_mask:0xf bank_mask:0xf
	v_mov_b32_dpp v195, v151 row_ror:1 row_mask:0xf bank_mask:0xf
	v_mov_b32_e32 v163, 0
	v_mov_b32_dpp v166, v148 row_ror:1 row_mask:0xf bank_mask:0xf
	v_mov_b32_dpp v167, v149 row_ror:1 row_mask:0xf bank_mask:0xf
	v_mov_b32_dpp v163, v165 row_ror:15 row_mask:0xf bank_mask:0xf
	v_cndmask_b32_e64 v165, v195, 0, vcc
	v_cndmask_b32_e64 v164, v164, 0, vcc
	v_cndmask_b32_e64 v167, v167, 0, vcc
	v_cndmask_b32_e64 v166, v166, 0, vcc
	v_mov_b32_e32 v195, 0
	v_mov_b32_e32 v196, 0
	v_mov_b32_e32 v198, 0
	v_mov_b32_e32 v200, 0
	v_mov_b32_dpp v195, v144 row_ror:1 row_mask:0xf bank_mask:0xf
	v_mov_b32_dpp v196, v145 row_ror:1 row_mask:0xf bank_mask:0xf
	v_mov_b32_dpp v198, v146 row_ror:1 row_mask:0xf bank_mask:0xf
	v_cndmask_b32_e32 v199, v147, v131, vcc
	v_mov_b32_dpp v200, v147 row_ror:1 row_mask:0xf bank_mask:0xf
	v_cndmask_b32_e64 v198, v198, 0, vcc
	v_cndmask_b32_e64 v201, v196, 0, vcc
	s_lshl_b32 s21, s42, 8
	s_add_i32 s21, s21, s49
	v_add_u32_e32 v193, s21, v194
	v_cmp_ne_u32_e64 s[46:47], 0, v194
	s_waitcnt vmcnt(0)
	v_pk_mul_f32 v[164:165], v[98:99], v[164:165]
	v_pk_mul_f32 v[166:167], v[96:97], v[166:167]
	v_pk_fma_f32 v[164:165], v[150:151], v[102:103], v[164:165]
	v_pk_fma_f32 v[166:167], v[148:149], v[100:101], v[166:167]
	v_pk_fma_f32 v[162:163], v[110:111], v[162:163], v[164:165]
	v_cndmask_b32_e32 v165, v144, v128, vcc
	v_mov_b32_e32 v164, 0
	v_pk_fma_f32 v[160:161], v[108:109], v[160:161], v[166:167]
	v_cndmask_b32_e32 v166, v145, v129, vcc
	v_mov_b32_dpp v164, v165 row_ror:15 row_mask:0xf bank_mask:0xf
	v_mov_b32_e32 v165, 0
	v_cndmask_b32_e32 v167, v146, v130, vcc
	v_pk_add_f32 v[162:163], v[114:115], v[162:163]
	v_mov_b32_dpp v165, v166 row_ror:15 row_mask:0xf bank_mask:0xf
	v_mov_b32_e32 v166, 0
	v_pk_add_f32 v[160:161], v[112:113], v[160:161]
	s_nop 0
	v_mov_b32_dpp v166, v167 row_ror:15 row_mask:0xf bank_mask:0xf
	v_mov_b32_e32 v167, 0
	s_nop 1
	v_mov_b32_dpp v167, v199 row_ror:15 row_mask:0xf bank_mask:0xf
	v_cndmask_b32_e64 v199, v200, 0, vcc
	v_cndmask_b32_e64 v200, v195, 0, vcc
	v_pk_mul_f32 v[200:201], v[80:81], v[200:201]
	v_pk_mul_f32 v[198:199], v[82:83], v[198:199]
	v_pk_fma_f32 v[200:201], v[144:145], v[84:85], v[200:201]
	v_pk_fma_f32 v[198:199], v[146:147], v[86:87], v[198:199]
	v_pk_fma_f32 v[164:165], v[88:89], v[164:165], v[200:201]
	v_pk_fma_f32 v[166:167], v[90:91], v[166:167], v[198:199]
	v_pk_add_f32 v[164:165], v[92:93], v[164:165]
	v_pk_add_f32 v[166:167], v[94:95], v[166:167]
	s_and_saveexec_b64 s[28:29], s[46:47]
	s_xor_b64 s[28:29], exec, s[28:29]
	s_cbranch_execz .LBB1_383
	v_mul_f32_e32 v195, 0xbfb8aa3b, v160
	v_exp_f32_e32 v195, v195
	v_mul_f32_e32 v196, 0xbfb8aa3b, v161
	v_exp_f32_e32 v196, v196
	v_pk_mul_f32 v[160:161], v[156:157], v[160:161]
	v_add_f32_e32 v195, 1.0, v195
	v_rcp_f32_e32 v198, v195
	v_add_f32_e32 v196, 1.0, v196
	v_mul_f32_e32 v195, 0xbfb8aa3b, v162
	v_rcp_f32_e32 v199, v196
	v_exp_f32_e32 v195, v195
	v_mul_f32_e32 v196, 0xbfb8aa3b, v163
	v_exp_f32_e32 v196, v196
	v_pk_mul_f32 v[160:161], v[160:161], v[198:199]
	v_add_f32_e32 v195, 1.0, v195
	v_rcp_f32_e32 v200, v195
	v_add_f32_e32 v195, 1.0, v196
	v_rcp_f32_e32 v201, v195
	v_cvt_pk_bf16_f32 v160, v160, v161
	v_mul_f32_e32 v161, 0xbfb8aa3b, v164
	v_exp_f32_e32 v195, v161
	v_mul_f32_e32 v161, 0xbfb8aa3b, v165
	v_exp_f32_e32 v196, v161
	v_pk_mul_f32 v[162:163], v[158:159], v[162:163]
	v_pk_mul_f32 v[164:165], v[152:153], v[164:165]
	v_pk_mul_f32 v[162:163], v[162:163], v[200:201]
	s_nop 0
	v_cvt_pk_bf16_f32 v161, v162, v163
	v_add_f32_e32 v162, 1.0, v195
	v_mul_f32_e32 v195, 0xbfb8aa3b, v166
	v_add_f32_e32 v163, 1.0, v196
	v_exp_f32_e32 v195, v195
	v_mul_f32_e32 v196, 0xbfb8aa3b, v167
	v_exp_f32_e32 v196, v196
	v_rcp_f32_e32 v162, v162
	v_add_f32_e32 v195, 1.0, v195
	v_rcp_f32_e32 v198, v195
	v_add_f32_e32 v195, 1.0, v196
	v_rcp_f32_e32 v163, v163
	v_rcp_f32_e32 v199, v195
	v_pk_mul_f32 v[166:167], v[154:155], v[166:167]
	v_pk_mul_f32 v[162:163], v[164:165], v[162:163]
	v_pk_mul_f32 v[164:165], v[166:167], v[198:199]
	v_cvt_pk_bf16_f32 v162, v162, v163
	v_cvt_pk_bf16_f32 v163, v164, v165
	v_mov_b64_e32 v[164:165], s[6:7]
	v_mad_i64_i32 v[164:165], s[42:43], v193, s30, v[164:165]
	v_lshl_add_u64 v[164:165], v[184:185], 1, v[164:165]
	global_store_dwordx4 v[164:165], v[160:163], off

; #define PG8_STAGE(bufoff, gbase, voff) do { _Pragma("unroll") for (int _i = 0; _i < 2; ++_i) \
;         __builtin_amdgcn_global_load_lds((const unsigned*)((const char*)(gbase) + (voff)[_i]), (LAS unsigned*)(lds + (bufoff) + ldsw + _i * 8192), 16, 0, 0); } while (0)
; #define PG8_LDA(dst, b, h) do { _Pragma("unroll") for (int m = 0; m < 4; ++m) _Pragma("unroll") for (int k = 0; k < 2; ++k) dst[m][k] = *(const LAS bf16x8*)(lds + PG8_SA(b, h) + aoff + m * 2048 + k * 1024); } while (0)
; #define PG8_LDB(dst, b, h) do { _Pragma("unroll") for (int n = 0; n < 2; ++n) _Pragma("unroll") for (int k = 0; k < 2; ++k) dst[n][k] = *(const LAS bf16x8*)(lds + PG8_SB(b, h) + boff + n * 2048 + k * 1024); } while (0)
; #define PG8_MMA(ai, bj, At, Bt) do { __builtin_amdgcn_s_setprio(1); _Pragma("unroll") for (int m = 0; m < 4; ++m) _Pragma("unroll") for (int n = 0; n < 2; ++n) _Pragma("unroll") for (int k = 0; k < 2; ++k) \
;         acc[ai][bj][m][n] = __builtin_amdgcn_mfma_f32_16x16x32_bf16(Bt[n][k], At[m][k], acc[ai][bj][m][n], 0, 0, 0); __builtin_amdgcn_s_setprio(0); } while (0)
; #define PG8_WAIT_V(n) asm volatile("s_waitcnt vmcnt(" #n ")" ::: "memory")
; #define PG8_WAIT_L(n) asm volatile("s_waitcnt lgkmcnt(" #n ")" ::: "memory")
; template <class Map, class Epi>
; DI void gemm_phase(LAS unsigned char* lds, const Map& MP, const Epi& E, const int nM, const int nN, const int K, const int lda, const int ldb) {
;     ...
;         for (int t = 0; t < nt; t += 2) {
;             const bool last = (t == nt - 2);
;             const char* a1 = cA + (size_t)(t + 1) * kstep;
;             const char* a2 = last ? nA : cA + (size_t)(t + 2) * kstep; const char* b2 = last ? nB : cB + (size_t)(t + 2) * kstep;
;             const char* a3 = a2 + kstep; const char* b3 = b2 + kstep;
;             PG8_LDB(B0, 0, 0); PG8_SCHED; PG8_LDA(At, 0, 0); PG8_STAGE(PG8_SA(1, 1), a1 + hstepA, voffA);
;             PG8_WAIT_L(8); PG8_BAR; PG8_WAIT_L(0); PG8_MMA(0, 0, At, B0); PG8_BAR; PG8_SCHED;
;             PG8_LDB(B1, 0, 1); PG8_STAGE(PG8_SB(0, 0), b2, voffB);
;             PG8_BAR; PG8_WAIT_L(0); PG8_MMA(0, 1, At, B1); PG8_BAR;
;             PG8_LDA(At, 0, 1); PG8_STAGE(PG8_SA(0, 0), a2, voffA);
;             PG8_BAR; PG8_WAIT_L(0); PG8_MMA(1, 0, At, B0); PG8_BAR; PG8_SCHED;
;             PG8_STAGE(PG8_SB(0, 1), b2 + hstepB, voffB);
;             PG8_WAIT_V(6); PG8_BAR; PG8_MMA(1, 1, At, B1); PG8_BAR;
.LBB1_550:
	ds_read_b128 v[168:171], v150
	ds_read_b128 v[172:175], v150 offset:1024
	ds_read_b128 v[176:179], v150 offset:2048
	ds_read_b128 v[180:183], v150 offset:3072
	ds_read_b128 v[184:187], v150 offset:4096
	ds_read_b128 v[188:191], v150 offset:5120
	ds_read_b128 v[192:195], v150 offset:6144
	ds_read_b128 v[198:201], v150 offset:7168
	s_add_u32 s10, s8, 0x100
	s_addc_u32 s11, s9, 0
	s_cmpk_eq_i32 s3, 0x54
	s_cselect_b32 s15, s43, s11
	s_cselect_b32 s14, s42, s10
	s_cselect_b32 s13, s7, s38
	s_cselect_b32 s12, s6, s5
	s_add_i32 m0, s24, 0xc000
	s_nop 0
	global_load_lds_dwordx4 v138, s[8:9]
	s_add_i32 m0, s24, 0xe000
	s_nop 0
	global_load_lds_dwordx4 v136, s[8:9]
	s_waitcnt lgkmcnt(8)
	s_barrier
	s_setprio 1
	s_waitcnt lgkmcnt(7)
	v_mfma_f32_16x16x32_bf16 v[124:127], v[152:155], v[168:171], v[124:127]
	v_mfma_f32_16x16x32_bf16 v[120:123], v[160:163], v[168:171], v[120:123]
	s_waitcnt lgkmcnt(5)
	v_mfma_f32_16x16x32_bf16 v[108:111], v[152:155], v[176:179], v[108:111]
	v_mfma_f32_16x16x32_bf16 v[104:107], v[160:163], v[176:179], v[104:107]
	s_waitcnt lgkmcnt(3)
	v_mfma_f32_16x16x32_bf16 v[92:95], v[152:155], v[184:187], v[92:95]
	v_mfma_f32_16x16x32_bf16 v[88:91], v[160:163], v[184:187], v[88:91]
	s_waitcnt lgkmcnt(1)
	v_mfma_f32_16x16x32_bf16 v[76:79], v[152:155], v[192:195], v[76:79]
	v_mfma_f32_16x16x32_bf16 v[72:75], v[160:163], v[192:195], v[72:75]
	v_mfma_f32_16x16x32_bf16 v[124:127], v[156:159], v[172:175], v[124:127]
	v_mfma_f32_16x16x32_bf16 v[120:123], v[164:167], v[172:175], v[120:123]
	v_mfma_f32_16x16x32_bf16 v[108:111], v[156:159], v[180:183], v[108:111]
	v_mfma_f32_16x16x32_bf16 v[104:107], v[164:167], v[180:183], v[104:107]
	v_mfma_f32_16x16x32_bf16 v[92:95], v[156:159], v[188:191], v[92:95]
	v_mfma_f32_16x16x32_bf16 v[88:91], v[164:167], v[188:191], v[88:91]
	s_waitcnt lgkmcnt(0)
	v_mfma_f32_16x16x32_bf16 v[76:79], v[156:159], v[198:201], v[76:79]
	v_mfma_f32_16x16x32_bf16 v[72:75], v[164:167], v[198:201], v[72:75]
	s_setprio 0
	s_barrier
	ds_read_b128 v[202:205], v151
	ds_read_b128 v[206:209], v151 offset:1024
	ds_read_b128 v[210:213], v151 offset:2048
	ds_read_b128 v[214:217], v151 offset:3072
	s_add_i32 s8, s35, s22
	v_lshl_add_u64 v[144:145], s[12:13], 0, v[132:133]
	s_mov_b32 m0, s8
	s_nop 0
	global_load_lds_dwordx4 v[144:145], off
	v_lshl_add_u64 v[218:219], s[12:13], 0, v[128:129]
	s_add_i32 m0, s8, 0x2000
	s_nop 0
	global_load_lds_dwordx4 v[218:219], off
	s_barrier
	s_setprio 1
	s_waitcnt lgkmcnt(3)
	v_mfma_f32_16x16x32_bf16 v[116:119], v[202:205], v[168:171], v[116:119]
	s_waitcnt lgkmcnt(1)
	v_mfma_f32_16x16x32_bf16 v[112:115], v[210:213], v[168:171], v[112:115]
	v_mfma_f32_16x16x32_bf16 v[100:103], v[202:205], v[176:179], v[100:103]
	v_mfma_f32_16x16x32_bf16 v[96:99], v[210:213], v[176:179], v[96:99]
	v_mfma_f32_16x16x32_bf16 v[84:87], v[202:205], v[184:187], v[84:87]
	v_mfma_f32_16x16x32_bf16 v[80:83], v[210:213], v[184:187], v[80:83]
	v_mfma_f32_16x16x32_bf16 v[68:71], v[202:205], v[192:195], v[68:71]
	v_mfma_f32_16x16x32_bf16 v[64:67], v[210:213], v[192:195], v[64:67]
	v_mfma_f32_16x16x32_bf16 v[116:119], v[206:209], v[172:175], v[116:119]
	s_mov_b32 m0, s24
	s_waitcnt lgkmcnt(0)
	v_mfma_f32_16x16x32_bf16 v[112:115], v[214:217], v[172:175], v[112:115]
	v_lshl_add_u64 v[220:221], s[14:15], 0, v[134:135]
	v_mfma_f32_16x16x32_bf16 v[100:103], v[206:209], v[180:183], v[100:103]
	v_mfma_f32_16x16x32_bf16 v[96:99], v[214:217], v[180:183], v[96:99]
	v_mfma_f32_16x16x32_bf16 v[84:87], v[206:209], v[188:191], v[84:87]
	v_mfma_f32_16x16x32_bf16 v[80:83], v[214:217], v[188:191], v[80:83]
	v_mfma_f32_16x16x32_bf16 v[68:71], v[206:209], v[198:201], v[68:71]
	v_mfma_f32_16x16x32_bf16 v[64:67], v[214:217], v[198:201], v[64:67]
	s_setprio 0
	s_barrier
	ds_read_b128 v[168:171], v150 offset:16384
	ds_read_b128 v[172:175], v150 offset:17408
	ds_read_b128 v[176:179], v150 offset:18432
	ds_read_b128 v[180:183], v150 offset:19456
	ds_read_b128 v[184:187], v150 offset:20480
	ds_read_b128 v[188:191], v150 offset:21504
	ds_read_b128 v[192:195], v150 offset:22528
	ds_read_b128 v[198:201], v150 offset:23552
	global_load_lds_dwordx4 v[220:221], off
	v_lshl_add_u64 v[222:223], s[14:15], 0, v[130:131]
	s_mov_b32 m0, s25
	s_nop 0
	global_load_lds_dwordx4 v[222:223], off
	s_waitcnt vmcnt(10)
	s_barrier
	s_setprio 1
	s_waitcnt lgkmcnt(7)
	v_mfma_f32_16x16x32_bf16 v[60:63], v[152:155], v[168:171], v[60:63]
	v_mfma_f32_16x16x32_bf16 v[56:59], v[160:163], v[168:171], v[56:59]
	s_waitcnt lgkmcnt(5)
	v_mfma_f32_16x16x32_bf16 v[44:47], v[152:155], v[176:179], v[44:47]
	v_mfma_f32_16x16x32_bf16 v[40:43], v[160:163], v[176:179], v[40:43]
	s_waitcnt lgkmcnt(3)
	v_mfma_f32_16x16x32_bf16 v[28:31], v[152:155], v[184:187], v[28:31]
	v_mfma_f32_16x16x32_bf16 v[24:27], v[160:163], v[184:187], v[24:27]
	s_waitcnt lgkmcnt(1)
	v_mfma_f32_16x16x32_bf16 v[12:15], v[152:155], v[192:195], v[12:15]
	v_mfma_f32_16x16x32_bf16 v[8:11], v[160:163], v[192:195], v[8:11]
	v_mfma_f32_16x16x32_bf16 v[60:63], v[156:159], v[172:175], v[60:63]
	v_mfma_f32_16x16x32_bf16 v[56:59], v[164:167], v[172:175], v[56:59]
	v_mfma_f32_16x16x32_bf16 v[44:47], v[156:159], v[180:183], v[44:47]
	v_mfma_f32_16x16x32_bf16 v[40:43], v[164:167], v[180:183], v[40:43]
	v_mfma_f32_16x16x32_bf16 v[28:31], v[156:159], v[188:191], v[28:31]
	v_mfma_f32_16x16x32_bf16 v[24:27], v[164:167], v[188:191], v[24:27]
	s_waitcnt lgkmcnt(0)
	v_mfma_f32_16x16x32_bf16 v[12:15], v[156:159], v[198:201], v[12:15]
	v_mfma_f32_16x16x32_bf16 v[8:11], v[164:167], v[198:201], v[8:11]
	s_setprio 0
	s_barrier
; #define PG8_STAGE(bufoff, gbase, voff) do { _Pragma("unroll") for (int _i = 0; _i < 2; ++_i) \
;         __builtin_amdgcn_global_load_lds((const unsigned*)((const char*)(gbase) + (voff)[_i]), (LAS unsigned*)(lds + (bufoff) + ldsw + _i * 8192), 16, 0, 0); } while (0)
; #define PG8_LDA(dst, b, h) do { _Pragma("unroll") for (int m = 0; m < 4; ++m) _Pragma("unroll") for (int k = 0; k < 2; ++k) dst[m][k] = *(const LAS bf16x8*)(lds + PG8_SA(b, h) + aoff + m * 2048 + k * 1024); } while (0)
; #define PG8_LDB(dst, b, h) do { _Pragma("unroll") for (int n = 0; n < 2; ++n) _Pragma("unroll") for (int k = 0; k < 2; ++k) dst[n][k] = *(const LAS bf16x8*)(lds + PG8_SB(b, h) + boff + n * 2048 + k * 1024); } while (0)
; #define PG8_MMA(ai, bj, At, Bt) do { __builtin_amdgcn_s_setprio(1); _Pragma("unroll") for (int m = 0; m < 4; ++m) _Pragma("unroll") for (int n = 0; n < 2; ++n) _Pragma("unroll") for (int k = 0; k < 2; ++k) \
;         acc[ai][bj][m][n] = __builtin_amdgcn_mfma_f32_16x16x32_bf16(Bt[n][k], At[m][k], acc[ai][bj][m][n], 0, 0, 0); __builtin_amdgcn_s_setprio(0); } while (0)
; #define PG8_WAIT_V(n) asm volatile("s_waitcnt vmcnt(" #n ")" ::: "memory")
; #define PG8_WAIT_L(n) asm volatile("s_waitcnt lgkmcnt(" #n ")" ::: "memory")
; #define PG8_BAR __builtin_amdgcn_s_barrier()
; #define PG8_SCHED __builtin_amdgcn_sched_barrier(0)
; template <class Map, class Epi>
; DI void gemm_phase(LAS unsigned char* lds, const Map& MP, const Epi& E, const int nM, const int nN, const int K, const int lda, const int ldb) {
;     ...
;             PG8_STAGE(PG8_SB(0, 1), b2 + hstepB, voffB);
;             PG8_WAIT_V(6); PG8_BAR; PG8_MMA(1, 1, At, B1); PG8_BAR;
;             PG8_LDB(B0, 1, 0); PG8_SCHED; PG8_LDA(At, 1, 0); PG8_STAGE(PG8_SA(0, 1), a2 + hstepA, voffA);
;             PG8_WAIT_L(8); PG8_BAR; PG8_WAIT_L(0); PG8_MMA(0, 0, At, B0); PG8_BAR; PG8_SCHED;
;             PG8_LDB(B1, 1, 1); PG8_STAGE(PG8_SB(1, 0), b3, voffB);
;             PG8_BAR; PG8_WAIT_L(0); PG8_MMA(0, 1, At, B1); PG8_BAR;
;             PG8_LDA(At, 1, 1); PG8_STAGE(PG8_SA(1, 0), a3, voffA);
;             PG8_BAR; PG8_WAIT_L(0); PG8_MMA(1, 0, At, B0); PG8_BAR; PG8_SCHED;
	s_add_u32 s8, s12, 0x160000
	s_addc_u32 s9, s13, 0
	s_add_i32 s39, s36, s22
	s_mov_b32 m0, s39
	s_nop 0
	global_load_lds_dwordx4 v132, s[8:9]
	s_add_i32 m0, s39, 0x2000
	s_nop 0
	global_load_lds_dwordx4 v128, s[8:9]
	s_waitcnt vmcnt(6)
	s_barrier
	s_setprio 1
	v_mfma_f32_16x16x32_bf16 v[52:55], v[202:205], v[168:171], v[52:55]
	v_mfma_f32_16x16x32_bf16 v[48:51], v[210:213], v[168:171], v[48:51]
	s_add_i32 s39, 0, 0x18000
	v_add_u32_e32 v164, s39, v148
	ds_read_b128 v[152:155], v164
	v_mfma_f32_16x16x32_bf16 v[36:39], v[202:205], v[176:179], v[36:39]
	v_mfma_f32_16x16x32_bf16 v[32:35], v[210:213], v[176:179], v[32:35]
	ds_read_b128 v[156:159], v164 offset:1024
	v_mfma_f32_16x16x32_bf16 v[20:23], v[202:205], v[184:187], v[20:23]
	v_mfma_f32_16x16x32_bf16 v[16:19], v[210:213], v[184:187], v[16:19]
	ds_read_b128 v[160:163], v164 offset:2048
	v_mfma_f32_16x16x32_bf16 v[4:7], v[202:205], v[192:195], v[4:7]
	v_mfma_f32_16x16x32_bf16 v[0:3], v[210:213], v[192:195], v[0:3]
	ds_read_b128 v[164:167], v164 offset:3072
	v_mfma_f32_16x16x32_bf16 v[52:55], v[206:209], v[172:175], v[52:55]
	v_mfma_f32_16x16x32_bf16 v[48:51], v[214:217], v[172:175], v[48:51]
	v_mfma_f32_16x16x32_bf16 v[36:39], v[206:209], v[180:183], v[36:39]
	v_mfma_f32_16x16x32_bf16 v[32:35], v[214:217], v[180:183], v[32:35]
	v_mfma_f32_16x16x32_bf16 v[20:23], v[206:209], v[188:191], v[20:23]
	v_mfma_f32_16x16x32_bf16 v[16:19], v[214:217], v[188:191], v[16:19]
	v_mfma_f32_16x16x32_bf16 v[4:7], v[206:209], v[198:201], v[4:7]
	v_mfma_f32_16x16x32_bf16 v[0:3], v[214:217], v[198:201], v[0:3]
	s_setprio 0
	s_barrier
	ds_read_b128 v[168:171], v150 offset:32768
	ds_read_b128 v[172:175], v150 offset:33792
	ds_read_b128 v[176:179], v150 offset:34816
	ds_read_b128 v[180:183], v150 offset:35840
	ds_read_b128 v[184:187], v150 offset:36864
	ds_read_b128 v[188:191], v150 offset:37888
	ds_read_b128 v[192:195], v150 offset:38912
	ds_read_b128 v[198:201], v150 offset:39936
	s_add_u32 s8, s14, 0x160000
	s_addc_u32 s9, s15, 0
	s_mov_b32 m0, s26
	s_nop 0
	global_load_lds_dwordx4 v134, s[8:9]
	s_mov_b32 m0, s27
	s_nop 0
	global_load_lds_dwordx4 v130, s[8:9]
	s_waitcnt lgkmcnt(8)
	s_barrier
	s_setprio 1
	s_waitcnt lgkmcnt(7)
	v_mfma_f32_16x16x32_bf16 v[124:127], v[152:155], v[168:171], v[124:127]
	v_mfma_f32_16x16x32_bf16 v[120:123], v[160:163], v[168:171], v[120:123]
	s_waitcnt lgkmcnt(5)
	v_mfma_f32_16x16x32_bf16 v[108:111], v[152:155], v[176:179], v[108:111]
	v_mfma_f32_16x16x32_bf16 v[104:107], v[160:163], v[176:179], v[104:107]
	s_waitcnt lgkmcnt(3)
	v_mfma_f32_16x16x32_bf16 v[92:95], v[152:155], v[184:187], v[92:95]
	v_mfma_f32_16x16x32_bf16 v[88:91], v[160:163], v[184:187], v[88:91]
	s_waitcnt lgkmcnt(1)
	v_mfma_f32_16x16x32_bf16 v[76:79], v[152:155], v[192:195], v[76:79]
	v_mfma_f32_16x16x32_bf16 v[72:75], v[160:163], v[192:195], v[72:75]
	v_mfma_f32_16x16x32_bf16 v[124:127], v[156:159], v[172:175], v[124:127]
	v_mfma_f32_16x16x32_bf16 v[120:123], v[164:167], v[172:175], v[120:123]
	v_mfma_f32_16x16x32_bf16 v[108:111], v[156:159], v[180:183], v[108:111]
	v_mfma_f32_16x16x32_bf16 v[104:107], v[164:167], v[180:183], v[104:107]
	v_mfma_f32_16x16x32_bf16 v[92:95], v[156:159], v[188:191], v[92:95]
	v_mfma_f32_16x16x32_bf16 v[88:91], v[164:167], v[188:191], v[88:91]
	s_waitcnt lgkmcnt(0)
	v_mfma_f32_16x16x32_bf16 v[76:79], v[156:159], v[198:201], v[76:79]
	v_mfma_f32_16x16x32_bf16 v[72:75], v[164:167], v[198:201], v[72:75]
	s_setprio 0
	s_barrier
	s_add_i32 s14, 0, 0x1c000
	v_add_u32_e32 v196, s14, v148
	ds_read_b128 v[202:205], v196
	ds_read_b128 v[206:209], v196 offset:1024
	ds_read_b128 v[210:213], v196 offset:2048
	ds_read_b128 v[214:217], v196 offset:3072
	s_add_i32 s8, s39, s22
	v_lshl_add_u64 v[144:145], v[144:145], 0, s[52:53]
	s_mov_b32 m0, s8
	s_nop 0
	global_load_lds_dwordx4 v[144:145], off
	v_lshl_add_u64 v[144:145], v[218:219], 0, s[52:53]
	s_add_i32 m0, s8, 0x2000
	s_nop 0
	global_load_lds_dwordx4 v[144:145], off
	s_barrier
	s_setprio 1
	s_waitcnt lgkmcnt(3)
	v_mfma_f32_16x16x32_bf16 v[116:119], v[202:205], v[168:171], v[116:119]
	s_waitcnt lgkmcnt(1)
	v_mfma_f32_16x16x32_bf16 v[112:115], v[210:213], v[168:171], v[112:115]
	v_mfma_f32_16x16x32_bf16 v[100:103], v[202:205], v[176:179], v[100:103]
	v_mfma_f32_16x16x32_bf16 v[96:99], v[210:213], v[176:179], v[96:99]
	v_mfma_f32_16x16x32_bf16 v[84:87], v[202:205], v[184:187], v[84:87]
	v_mfma_f32_16x16x32_bf16 v[80:83], v[210:213], v[184:187], v[80:83]
	v_mfma_f32_16x16x32_bf16 v[68:71], v[202:205], v[192:195], v[68:71]
	v_mfma_f32_16x16x32_bf16 v[64:67], v[210:213], v[192:195], v[64:67]
	v_mfma_f32_16x16x32_bf16 v[116:119], v[206:209], v[172:175], v[116:119]
	s_mov_b32 m0, s30
	s_waitcnt lgkmcnt(0)
	v_mfma_f32_16x16x32_bf16 v[112:115], v[214:217], v[172:175], v[112:115]
	v_lshl_add_u64 v[144:145], v[220:221], 0, s[52:53]
	v_mfma_f32_16x16x32_bf16 v[100:103], v[206:209], v[180:183], v[100:103]
	v_mfma_f32_16x16x32_bf16 v[96:99], v[214:217], v[180:183], v[96:99]
	v_mfma_f32_16x16x32_bf16 v[84:87], v[206:209], v[188:191], v[84:87]
	v_mfma_f32_16x16x32_bf16 v[80:83], v[214:217], v[188:191], v[80:83]
	v_mfma_f32_16x16x32_bf16 v[68:71], v[206:209], v[198:201], v[68:71]
	v_mfma_f32_16x16x32_bf16 v[64:67], v[214:217], v[198:201], v[64:67]
	s_setprio 0
	s_barrier
	ds_read_b128 v[168:171], v150 offset:49152
	ds_read_b128 v[172:175], v150 offset:50176
	ds_read_b128 v[176:179], v150 offset:51200
	ds_read_b128 v[180:183], v150 offset:52224
	ds_read_b128 v[184:187], v150 offset:53248
	ds_read_b128 v[188:191], v150 offset:54272
	ds_read_b128 v[192:195], v150 offset:55296
	ds_read_b128 v[198:201], v150 offset:56320
	global_load_lds_dwordx4 v[144:145], off
	v_lshl_add_u64 v[144:145], v[222:223], 0, s[52:53]
	s_mov_b32 m0, s31
	s_nop 0
	global_load_lds_dwordx4 v[144:145], off
	s_waitcnt vmcnt(10)
	s_barrier
; DI unsigned pack2(float a, float b) { f32x2 v = {a, b}; hwbf16x2 r = __builtin_convertvector(v, hwbf16x2); return __builtin_bit_cast(unsigned, r); }
; DI float bflo(unsigned w) { return __uint_as_float(w << 16); }
; DI float bfhi(unsigned w) { return __uint_as_float(w & 0xffff0000u); }
; #define PG8_STAGE(bufoff, gbase, voff) do { _Pragma("unroll") for (int _i = 0; _i < 2; ++_i) \
;         __builtin_amdgcn_global_load_lds((const unsigned*)((const char*)(gbase) + (voff)[_i]), (LAS unsigned*)(lds + (bufoff) + ldsw + _i * 8192), 16, 0, 0); } while (0)
; #define PG8_WAIT_V(n) asm volatile("s_waitcnt vmcnt(" #n ")" ::: "memory")
; #define PG8_WAIT_L(n) asm volatile("s_waitcnt lgkmcnt(" #n ")" ::: "memory")
;     DI void operator()(const f32x4 (&acc)[2][2][4][2], const Unit& u, int wr, int wc, int fr, int fq) const {
;     ...
;         for (int ai = 0; ai < 2; ++ai)
; #pragma unroll
;             for (int m = 0; m < 4; ++m) { const size_t ro = (size_t)(row0 + ai * HALF + m * 16) * D + col0;
; #pragma unroll
;                 for (int bj = 0; bj < 2; ++bj) {
;                     f32x4 x0, x1;
;                     if constexpr (IB) { const u32x4 w = *(const u32x4*)((const bf16_t*)Xin + ro + bj * HALF);
;                         x0 = (f32x4){bflo(w[0]), bfhi(w[0]), bflo(w[1]), bfhi(w[1])}; x1 = (f32x4){bflo(w[2]), bfhi(w[2]), bflo(w[3]), bfhi(w[3])}; }
;                     else { x0 = *(const f32x4*)((const float*)Xin + ro + bj * HALF); x1 = *(const f32x4*)((const float*)Xin + ro + bj * HALF + 4); }
;                     x0 += acc[ai][bj][m][0] * sc[bj][0]; x1 += acc[ai][bj][m][1] * sc[bj][1];
;                     if constexpr (OB) { u32x4 o; o[0] = pack2(x0[0], x0[1]); o[1] = pack2(x0[2], x0[3]); o[2] = pack2(x1[0], x1[1]); o[3] = pack2(x1[2], x1[3]);
;                         *(u32x4*)((bf16_t*)Xout + ro + bj * HALF) = o; }
;                     else { *(f32x4*)((float*)Xout + ro + bj * HALF) = x0; *(f32x4*)((float*)Xout + ro + bj * HALF + 4) = x1; } } }
; template <class Map, class Epi>
; DI void gemm_phase(LAS unsigned char* lds, const Map& MP, const Epi& E, const int nM, const int nN, const int K, const int lda, const int ldb) {
;     ...
;             PG8_BAR; PG8_WAIT_L(0); PG8_MMA(1, 0, At, B0); PG8_BAR; PG8_SCHED;
;             PG8_STAGE(PG8_SB(1, 1), b3 + hstepB, voffB);
;             PG8_WAIT_V(6); PG8_BAR; PG8_MMA(1, 1, At, B1); PG8_BAR;
	s_setprio 1
	s_waitcnt lgkmcnt(7)
	v_mfma_f32_16x16x32_bf16 v[60:63], v[152:155], v[168:171], v[60:63]
	v_mfma_f32_16x16x32_bf16 v[56:59], v[160:163], v[168:171], v[56:59]
	s_waitcnt lgkmcnt(5)
	v_mfma_f32_16x16x32_bf16 v[44:47], v[152:155], v[176:179], v[44:47]
	v_mfma_f32_16x16x32_bf16 v[40:43], v[160:163], v[176:179], v[40:43]
	s_waitcnt lgkmcnt(3)
	v_mfma_f32_16x16x32_bf16 v[28:31], v[152:155], v[184:187], v[28:31]
	v_mfma_f32_16x16x32_bf16 v[24:27], v[160:163], v[184:187], v[24:27]
	s_waitcnt lgkmcnt(1)
	v_mfma_f32_16x16x32_bf16 v[12:15], v[152:155], v[192:195], v[12:15]
	v_mfma_f32_16x16x32_bf16 v[8:11], v[160:163], v[192:195], v[8:11]
	v_mfma_f32_16x16x32_bf16 v[60:63], v[156:159], v[172:175], v[60:63]
	v_mfma_f32_16x16x32_bf16 v[56:59], v[164:167], v[172:175], v[56:59]
	v_mfma_f32_16x16x32_bf16 v[44:47], v[156:159], v[180:183], v[44:47]
	v_mfma_f32_16x16x32_bf16 v[40:43], v[164:167], v[180:183], v[40:43]
	v_mfma_f32_16x16x32_bf16 v[28:31], v[156:159], v[188:191], v[28:31]
	v_mfma_f32_16x16x32_bf16 v[24:27], v[164:167], v[188:191], v[24:27]
	s_waitcnt lgkmcnt(0)
	v_mfma_f32_16x16x32_bf16 v[12:15], v[156:159], v[198:201], v[12:15]
	v_mfma_f32_16x16x32_bf16 v[8:11], v[164:167], v[198:201], v[8:11]
	s_setprio 0
	s_barrier
	s_add_u32 s8, s12, 0x160080
	s_addc_u32 s9, s13, 0
	s_add_i32 s12, s14, s22
	s_mov_b32 m0, s12
	s_nop 0
	global_load_lds_dwordx4 v132, s[8:9]
	s_add_i32 m0, s12, 0x2000
	s_nop 0
	global_load_lds_dwordx4 v128, s[8:9]
	s_waitcnt vmcnt(6)
	s_barrier
	s_setprio 1
	v_mfma_f32_16x16x32_bf16 v[52:55], v[202:205], v[168:171], v[52:55]
	v_mfma_f32_16x16x32_bf16 v[48:51], v[210:213], v[168:171], v[48:51]
	ds_read_b128 v[152:155], v149
	v_mfma_f32_16x16x32_bf16 v[36:39], v[202:205], v[176:179], v[36:39]
	v_mfma_f32_16x16x32_bf16 v[32:35], v[210:213], v[176:179], v[32:35]
	ds_read_b128 v[156:159], v149 offset:1024
	v_mfma_f32_16x16x32_bf16 v[20:23], v[202:205], v[184:187], v[20:23]
	v_mfma_f32_16x16x32_bf16 v[16:19], v[210:213], v[184:187], v[16:19]
	ds_read_b128 v[160:163], v149 offset:2048
	v_mfma_f32_16x16x32_bf16 v[4:7], v[202:205], v[192:195], v[4:7]
	v_mfma_f32_16x16x32_bf16 v[0:3], v[210:213], v[192:195], v[0:3]
	ds_read_b128 v[164:167], v149 offset:3072
	v_mfma_f32_16x16x32_bf16 v[52:55], v[206:209], v[172:175], v[52:55]
	s_add_i32 s3, s3, 2
	v_mfma_f32_16x16x32_bf16 v[48:51], v[214:217], v[172:175], v[48:51]
	s_add_u32 s5, s5, 0x100
	s_addc_u32 s38, s38, 0
	v_mfma_f32_16x16x32_bf16 v[36:39], v[206:209], v[180:183], v[36:39]
	s_cmpk_gt_u32 s3, 0x55
	v_mfma_f32_16x16x32_bf16 v[32:35], v[214:217], v[180:183], v[32:35]
	s_mov_b64 s[8:9], s[10:11]
	v_mfma_f32_16x16x32_bf16 v[20:23], v[206:209], v[188:191], v[20:23]
	v_mfma_f32_16x16x32_bf16 v[16:19], v[214:217], v[188:191], v[16:19]
	v_mfma_f32_16x16x32_bf16 v[4:7], v[206:209], v[198:201], v[4:7]
	v_mfma_f32_16x16x32_bf16 v[0:3], v[214:217], v[198:201], v[0:3]
	s_setprio 0
	s_barrier
	s_cbranch_scc0 .LBB1_550
	s_waitcnt lgkmcnt(0)
	v_mov_b32_e32 v144, v146
	v_mov_b32_e32 v152, v147
	s_lshl_b32 s2, s2, 8
	s_add_i32 s2, s2, s29
	s_lshl_b32 s3, s4, 8
	v_add_u32_e32 v152, s2, v152
	s_or_b32 s3, s3, s54
	v_ashrrev_i32_e32 v153, 31, v152
	v_lshl_add_u32 v144, v144, 3, s3
	v_lshlrev_b64 v[152:153], 12, v[152:153]
	v_ashrrev_i32_e32 v145, 31, v144
	v_lshl_add_u64 v[152:153], s[46:47], 0, v[152:153]
	v_lshl_add_u64 v[144:145], v[144:145], 1, v[152:153]
	global_load_dwordx4 v[160:163], v[144:145], off
	global_load_dwordx4 v[164:167], v[144:145], off offset:256
	s_mov_b64 s[98:99], 0x10000
	v_lshl_add_u64 v[154:155], v[144:145], 0, s[98:99]
	global_load_dwordx4 v[168:171], v[154:155], off
	global_load_dwordx4 v[172:175], v[154:155], off offset:256
	s_mov_b64 s[98:99], 0x20000
	v_lshl_add_u64 v[154:155], v[144:145], 0, s[98:99]
	global_load_dwordx4 v[176:179], v[154:155], off
	global_load_dwordx4 v[180:183], v[154:155], off offset:256
	s_mov_b64 s[98:99], 0x30000
	v_lshl_add_u64 v[154:155], v[144:145], 0, s[98:99]
	global_load_dwordx4 v[184:187], v[154:155], off
	global_load_dwordx4 v[188:191], v[154:155], off offset:256
	s_mov_b64 s[98:99], 0x80000
	v_lshl_add_u64 v[154:155], v[144:145], 0, s[98:99]
	global_load_dwordx4 v[192:195], v[154:155], off
	global_load_dwordx4 v[198:201], v[154:155], off offset:256
	s_mov_b64 s[98:99], 0x90000
	v_lshl_add_u64 v[154:155], v[144:145], 0, s[98:99]
	global_load_dwordx4 v[202:205], v[154:155], off
	global_load_dwordx4 v[206:209], v[154:155], off offset:256
	s_mov_b64 s[98:99], 0xa0000
	v_lshl_add_u64 v[154:155], v[144:145], 0, s[98:99]
	global_load_dwordx4 v[210:213], v[154:155], off
	global_load_dwordx4 v[214:217], v[154:155], off offset:256
	s_mov_b64 s[98:99], 0xb0000
	v_lshl_add_u64 v[154:155], v[144:145], 0, s[98:99]
	global_load_dwordx4 v[248:251], v[154:155], off
	global_load_dwordx4 v[252:255], v[154:155], off offset:256
	s_waitcnt vmcnt(15)
	s_nop 1
	v_mov_b32_e32 v152, v160
	v_mov_b32_e32 v153, v161
	v_mov_b32_e32 v154, v162
	v_mov_b32_e32 v155, v163
	s_mov_b64 s[2:3], 0x10000
	s_mov_b32 s4, s37
	s_mov_b64 s[10:11], s[6:7]
	s_mov_b64 s[8:9], s[42:43]
	s_waitcnt lgkmcnt(0)
	v_lshlrev_b32_e32 v156, 16, v152
	v_and_b32_e32 v157, 0xffff0000, v152
	v_lshlrev_b32_e32 v152, 16, v153
	v_and_b32_e32 v153, 0xffff0000, v153
	v_lshlrev_b32_e32 v158, 16, v154
	v_and_b32_e32 v159, 0xffff0000, v154
	v_lshlrev_b32_e32 v154, 16, v155
	v_and_b32_e32 v155, 0xffff0000, v155
	v_pk_add_f32 v[126:127], v[126:127], v[152:153]
	v_pk_add_f32 v[124:125], v[124:125], v[156:157]
	v_pk_add_f32 v[152:153], v[122:123], v[154:155]
	v_pk_add_f32 v[122:123], v[120:121], v[158:159]
	v_cvt_pk_bf16_f32 v120, v124, v125
	v_cvt_pk_bf16_f32 v121, v126, v127
	v_cvt_pk_bf16_f32 v122, v122, v123
	v_cvt_pk_bf16_f32 v123, v152, v153
	global_store_dwordx4 v[144:145], v[120:123], off
	s_waitcnt vmcnt(15)
; DI unsigned pack2(float a, float b) { f32x2 v = {a, b}; hwbf16x2 r = __builtin_convertvector(v, hwbf16x2); return __builtin_bit_cast(unsigned, r); }
; DI float bflo(unsigned w) { return __uint_as_float(w << 16); }
; DI float bfhi(unsigned w) { return __uint_as_float(w & 0xffff0000u); }
;     DI void operator()(const f32x4 (&acc)[2][2][4][2], const Unit& u, int wr, int wc, int fr, int fq) const {
;     ...
;         for (int ai = 0; ai < 2; ++ai)
; #pragma unroll
;             for (int m = 0; m < 4; ++m) { const size_t ro = (size_t)(row0 + ai * HALF + m * 16) * D + col0;
; #pragma unroll
;                 for (int bj = 0; bj < 2; ++bj) {
;                     f32x4 x0, x1;
;                     if constexpr (IB) { const u32x4 w = *(const u32x4*)((const bf16_t*)Xin + ro + bj * HALF);
;                         x0 = (f32x4){bflo(w[0]), bfhi(w[0]), bflo(w[1]), bfhi(w[1])}; x1 = (f32x4){bflo(w[2]), bfhi(w[2]), bflo(w[3]), bfhi(w[3])}; }
;                     else { x0 = *(const f32x4*)((const float*)Xin + ro + bj * HALF); x1 = *(const f32x4*)((const float*)Xin + ro + bj * HALF + 4); }
;                     x0 += acc[ai][bj][m][0] * sc[bj][0]; x1 += acc[ai][bj][m][1] * sc[bj][1];
;                     if constexpr (OB) { u32x4 o; o[0] = pack2(x0[0], x0[1]); o[1] = pack2(x0[2], x0[3]); o[2] = pack2(x1[0], x1[1]); o[3] = pack2(x1[2], x1[3]);
;                         *(u32x4*)((bf16_t*)Xout + ro + bj * HALF) = o; }
;                     else { *(f32x4*)((float*)Xout + ro + bj * HALF) = x0; *(f32x4*)((float*)Xout + ro + bj * HALF + 4) = x1; } } }
	s_nop 1
	v_mov_b32_e32 v120, v164
	v_mov_b32_e32 v121, v165
	v_mov_b32_e32 v122, v166
	v_mov_b32_e32 v123, v167
	s_waitcnt lgkmcnt(0)
	v_lshlrev_b32_e32 v124, 16, v120
	v_and_b32_e32 v125, 0xffff0000, v120
	v_lshlrev_b32_e32 v120, 16, v121
	v_and_b32_e32 v121, 0xffff0000, v121
	v_lshlrev_b32_e32 v126, 16, v122
	v_and_b32_e32 v127, 0xffff0000, v122
	v_lshlrev_b32_e32 v122, 16, v123
	v_and_b32_e32 v123, 0xffff0000, v123
	v_pk_add_f32 v[116:117], v[116:117], v[124:125]
	v_pk_add_f32 v[118:119], v[118:119], v[120:121]
	v_pk_add_f32 v[120:121], v[114:115], v[122:123]
	v_pk_add_f32 v[114:115], v[112:113], v[126:127]
	v_cvt_pk_bf16_f32 v112, v116, v117
	v_lshl_add_u64 v[116:117], v[144:145], 0, s[2:3]
	s_mov_b32 s2, 0x10000
	v_cvt_pk_bf16_f32 v113, v118, v119
	v_add_co_u32_e32 v118, vcc, s2, v144
	v_cvt_pk_bf16_f32 v114, v114, v115
	v_cvt_pk_bf16_f32 v115, v120, v121
	v_addc_co_u32_e32 v119, vcc, 0, v145, vcc
	global_store_dwordx4 v[144:145], v[112:115], off offset:256
	s_waitcnt vmcnt(15)
	s_nop 1
	v_mov_b32_e32 v112, v168
	v_mov_b32_e32 v113, v169
	v_mov_b32_e32 v114, v170
	v_mov_b32_e32 v115, v171
	s_mov_b64 s[2:3], 0x20000
	s_waitcnt lgkmcnt(0)
	v_lshlrev_b32_e32 v120, 16, v112
	v_and_b32_e32 v121, 0xffff0000, v112
	v_lshlrev_b32_e32 v112, 16, v113
	v_and_b32_e32 v113, 0xffff0000, v113
	v_lshlrev_b32_e32 v122, 16, v114
	v_and_b32_e32 v123, 0xffff0000, v114
	v_lshlrev_b32_e32 v114, 16, v115
	v_and_b32_e32 v115, 0xffff0000, v115
	v_pk_add_f32 v[110:111], v[110:111], v[112:113]
	v_pk_add_f32 v[108:109], v[108:109], v[120:121]
	v_pk_add_f32 v[112:113], v[106:107], v[114:115]
	v_pk_add_f32 v[106:107], v[104:105], v[122:123]
	v_cvt_pk_bf16_f32 v104, v108, v109
	v_cvt_pk_bf16_f32 v105, v110, v111
	v_cvt_pk_bf16_f32 v106, v106, v107
	v_cvt_pk_bf16_f32 v107, v112, v113
	global_store_dwordx4 v[118:119], v[104:107], off
	s_waitcnt vmcnt(15)
	s_nop 1
	v_mov_b32_e32 v104, v172
	v_mov_b32_e32 v105, v173
	v_mov_b32_e32 v106, v174
	v_mov_b32_e32 v107, v175
	s_waitcnt lgkmcnt(0)
	v_lshlrev_b32_e32 v108, 16, v104
	v_and_b32_e32 v109, 0xffff0000, v104
	v_lshlrev_b32_e32 v104, 16, v105
	v_and_b32_e32 v105, 0xffff0000, v105
	v_lshlrev_b32_e32 v110, 16, v106
	v_and_b32_e32 v111, 0xffff0000, v106
	v_lshlrev_b32_e32 v106, 16, v107
	v_and_b32_e32 v107, 0xffff0000, v107
	v_pk_add_f32 v[100:101], v[100:101], v[108:109]
	v_pk_add_f32 v[102:103], v[102:103], v[104:105]
	v_pk_add_f32 v[104:105], v[98:99], v[106:107]
	v_pk_add_f32 v[98:99], v[96:97], v[110:111]
	v_cvt_pk_bf16_f32 v96, v100, v101
	v_lshl_add_u64 v[100:101], v[144:145], 0, s[2:3]
	s_mov_b32 s2, 0x20000
	v_cvt_pk_bf16_f32 v97, v102, v103
	v_add_co_u32_e32 v102, vcc, s2, v144
	v_cvt_pk_bf16_f32 v98, v98, v99
	v_cvt_pk_bf16_f32 v99, v104, v105
	v_addc_co_u32_e32 v103, vcc, 0, v145, vcc
	global_store_dwordx4 v[116:117], v[96:99], off offset:256
	s_waitcnt vmcnt(15)
	s_nop 1
	v_mov_b32_e32 v96, v176
	v_mov_b32_e32 v97, v177
	v_mov_b32_e32 v98, v178
	v_mov_b32_e32 v99, v179
	s_mov_b64 s[2:3], 0x30000
	s_waitcnt lgkmcnt(0)
	v_lshlrev_b32_e32 v104, 16, v96
	v_and_b32_e32 v105, 0xffff0000, v96
	v_lshlrev_b32_e32 v96, 16, v97
	v_and_b32_e32 v97, 0xffff0000, v97
	v_lshlrev_b32_e32 v106, 16, v98
	v_and_b32_e32 v107, 0xffff0000, v98
	v_lshlrev_b32_e32 v98, 16, v99
	v_and_b32_e32 v99, 0xffff0000, v99
	v_pk_add_f32 v[94:95], v[94:95], v[96:97]
	v_pk_add_f32 v[92:93], v[92:93], v[104:105]
	v_pk_add_f32 v[96:97], v[90:91], v[98:99]
	v_pk_add_f32 v[90:91], v[88:89], v[106:107]
	v_cvt_pk_bf16_f32 v88, v92, v93
	v_cvt_pk_bf16_f32 v89, v94, v95
	v_cvt_pk_bf16_f32 v90, v90, v91
	v_cvt_pk_bf16_f32 v91, v96, v97
	global_store_dwordx4 v[102:103], v[88:91], off
	s_waitcnt vmcnt(15)
	s_nop 1
	v_mov_b32_e32 v88, v180
	v_mov_b32_e32 v89, v181
	v_mov_b32_e32 v90, v182
	v_mov_b32_e32 v91, v183
	s_waitcnt lgkmcnt(0)
	v_lshlrev_b32_e32 v92, 16, v88
	v_and_b32_e32 v93, 0xffff0000, v88
	v_lshlrev_b32_e32 v88, 16, v89
	v_and_b32_e32 v89, 0xffff0000, v89
	v_lshlrev_b32_e32 v94, 16, v90
	v_and_b32_e32 v95, 0xffff0000, v90
	v_lshlrev_b32_e32 v90, 16, v91
	v_and_b32_e32 v91, 0xffff0000, v91
	v_pk_add_f32 v[86:87], v[86:87], v[88:89]
	v_pk_add_f32 v[84:85], v[84:85], v[92:93]
	v_pk_add_f32 v[88:89], v[82:83], v[90:91]
	v_pk_add_f32 v[82:83], v[80:81], v[94:95]
	v_cvt_pk_bf16_f32 v80, v84, v85
	v_cvt_pk_bf16_f32 v81, v86, v87
	v_cvt_pk_bf16_f32 v82, v82, v83
	v_cvt_pk_bf16_f32 v83, v88, v89
	global_store_dwordx4 v[100:101], v[80:83], off offset:256
	s_nop 1
	v_lshl_add_u64 v[80:81], v[144:145], 0, s[2:3]
	s_mov_b32 s2, 0x30000
	v_add_co_u32_e32 v86, vcc, s2, v144
	s_mov_b64 s[2:3], 0x80000
	s_nop 0
	v_addc_co_u32_e32 v87, vcc, 0, v145, vcc
	s_waitcnt vmcnt(15)
	s_nop 1
	v_mov_b32_e32 v82, v184
	v_mov_b32_e32 v83, v185
	v_mov_b32_e32 v84, v186
	v_mov_b32_e32 v85, v187
	s_waitcnt lgkmcnt(0)
	v_lshlrev_b32_e32 v88, 16, v82
	v_and_b32_e32 v89, 0xffff0000, v82
	v_lshlrev_b32_e32 v82, 16, v83
	v_and_b32_e32 v83, 0xffff0000, v83
	v_lshlrev_b32_e32 v90, 16, v84
	v_and_b32_e32 v91, 0xffff0000, v84
	v_lshlrev_b32_e32 v84, 16, v85
	v_and_b32_e32 v85, 0xffff0000, v85
	v_pk_add_f32 v[78:79], v[78:79], v[82:83]
	v_pk_add_f32 v[76:77], v[76:77], v[88:89]
	v_pk_add_f32 v[82:83], v[74:75], v[84:85]
	v_pk_add_f32 v[74:75], v[72:73], v[90:91]
	v_cvt_pk_bf16_f32 v72, v76, v77
	v_cvt_pk_bf16_f32 v73, v78, v79
	v_cvt_pk_bf16_f32 v74, v74, v75
	v_cvt_pk_bf16_f32 v75, v82, v83
	global_store_dwordx4 v[86:87], v[72:75], off
	s_waitcnt vmcnt(15)
	s_nop 1
	v_mov_b32_e32 v72, v188
	v_mov_b32_e32 v73, v189
	v_mov_b32_e32 v74, v190
	v_mov_b32_e32 v75, v191
	s_waitcnt lgkmcnt(0)
; DI unsigned pack2(float a, float b) { f32x2 v = {a, b}; hwbf16x2 r = __builtin_convertvector(v, hwbf16x2); return __builtin_bit_cast(unsigned, r); }
; DI float bflo(unsigned w) { return __uint_as_float(w << 16); }
; DI float bfhi(unsigned w) { return __uint_as_float(w & 0xffff0000u); }
;     DI void operator()(const f32x4 (&acc)[2][2][4][2], const Unit& u, int wr, int wc, int fr, int fq) const {
;     ...
;         for (int ai = 0; ai < 2; ++ai)
; #pragma unroll
;             for (int m = 0; m < 4; ++m) { const size_t ro = (size_t)(row0 + ai * HALF + m * 16) * D + col0;
; #pragma unroll
;                 for (int bj = 0; bj < 2; ++bj) {
;                     f32x4 x0, x1;
;                     if constexpr (IB) { const u32x4 w = *(const u32x4*)((const bf16_t*)Xin + ro + bj * HALF);
;                         x0 = (f32x4){bflo(w[0]), bfhi(w[0]), bflo(w[1]), bfhi(w[1])}; x1 = (f32x4){bflo(w[2]), bfhi(w[2]), bflo(w[3]), bfhi(w[3])}; }
;                     else { x0 = *(const f32x4*)((const float*)Xin + ro + bj * HALF); x1 = *(const f32x4*)((const float*)Xin + ro + bj * HALF + 4); }
;                     x0 += acc[ai][bj][m][0] * sc[bj][0]; x1 += acc[ai][bj][m][1] * sc[bj][1];
;                     if constexpr (OB) { u32x4 o; o[0] = pack2(x0[0], x0[1]); o[1] = pack2(x0[2], x0[3]); o[2] = pack2(x1[0], x1[1]); o[3] = pack2(x1[2], x1[3]);
;                         *(u32x4*)((bf16_t*)Xout + ro + bj * HALF) = o; }
;                     else { *(f32x4*)((float*)Xout + ro + bj * HALF) = x0; *(f32x4*)((float*)Xout + ro + bj * HALF + 4) = x1; } } }
	v_lshlrev_b32_e32 v76, 16, v72
	v_and_b32_e32 v77, 0xffff0000, v72
	v_lshlrev_b32_e32 v72, 16, v73
	v_and_b32_e32 v73, 0xffff0000, v73
	v_lshlrev_b32_e32 v78, 16, v74
	v_and_b32_e32 v79, 0xffff0000, v74
	v_lshlrev_b32_e32 v74, 16, v75
	v_and_b32_e32 v75, 0xffff0000, v75
	v_pk_add_f32 v[70:71], v[70:71], v[72:73]
	v_pk_add_f32 v[68:69], v[68:69], v[76:77]
	v_pk_add_f32 v[72:73], v[66:67], v[74:75]
	v_pk_add_f32 v[66:67], v[64:65], v[78:79]
	v_cvt_pk_bf16_f32 v64, v68, v69
	v_cvt_pk_bf16_f32 v65, v70, v71
	v_cvt_pk_bf16_f32 v66, v66, v67
	v_cvt_pk_bf16_f32 v67, v72, v73
	global_store_dwordx4 v[80:81], v[64:67], off offset:256
	s_nop 1
	v_lshl_add_u64 v[64:65], v[144:145], 0, s[2:3]
	s_mov_b32 s2, 0x80000
	v_add_co_u32_e32 v70, vcc, s2, v144
	s_mov_b64 s[2:3], 0x90000
	s_nop 0
	v_addc_co_u32_e32 v71, vcc, 0, v145, vcc
	s_waitcnt vmcnt(15)
	s_nop 1
	v_mov_b32_e32 v66, v192
	v_mov_b32_e32 v67, v193
	v_mov_b32_e32 v68, v194
	v_mov_b32_e32 v69, v195
	s_waitcnt lgkmcnt(0)
	v_lshlrev_b32_e32 v72, 16, v66
	v_and_b32_e32 v73, 0xffff0000, v66
	v_lshlrev_b32_e32 v66, 16, v67
	v_and_b32_e32 v67, 0xffff0000, v67
	v_lshlrev_b32_e32 v74, 16, v68
	v_and_b32_e32 v75, 0xffff0000, v68
	v_lshlrev_b32_e32 v68, 16, v69
	v_and_b32_e32 v69, 0xffff0000, v69
	v_pk_add_f32 v[62:63], v[62:63], v[66:67]
	v_pk_add_f32 v[60:61], v[60:61], v[72:73]
	v_pk_add_f32 v[66:67], v[58:59], v[68:69]
	v_pk_add_f32 v[58:59], v[56:57], v[74:75]
	v_cvt_pk_bf16_f32 v56, v60, v61
	v_cvt_pk_bf16_f32 v57, v62, v63
	v_cvt_pk_bf16_f32 v58, v58, v59
	v_cvt_pk_bf16_f32 v59, v66, v67
	global_store_dwordx4 v[70:71], v[56:59], off
	s_waitcnt vmcnt(15)
	s_nop 1
	v_mov_b32_e32 v56, v198
	v_mov_b32_e32 v57, v199
	v_mov_b32_e32 v58, v200
	v_mov_b32_e32 v59, v201
	s_waitcnt lgkmcnt(0)
	v_lshlrev_b32_e32 v60, 16, v56
	v_and_b32_e32 v61, 0xffff0000, v56
	v_lshlrev_b32_e32 v56, 16, v57
	v_and_b32_e32 v57, 0xffff0000, v57
	v_lshlrev_b32_e32 v62, 16, v58
	v_and_b32_e32 v63, 0xffff0000, v58
	v_lshlrev_b32_e32 v58, 16, v59
	v_and_b32_e32 v59, 0xffff0000, v59
	v_pk_add_f32 v[54:55], v[54:55], v[56:57]
	v_pk_add_f32 v[52:53], v[52:53], v[60:61]
	v_pk_add_f32 v[56:57], v[50:51], v[58:59]
	v_pk_add_f32 v[50:51], v[48:49], v[62:63]
	v_cvt_pk_bf16_f32 v48, v52, v53
	v_cvt_pk_bf16_f32 v49, v54, v55
	v_cvt_pk_bf16_f32 v50, v50, v51
	v_cvt_pk_bf16_f32 v51, v56, v57
	global_store_dwordx4 v[64:65], v[48:51], off offset:256
	s_nop 1
	v_lshl_add_u64 v[48:49], v[144:145], 0, s[2:3]
	s_mov_b32 s2, 0x90000
	v_add_co_u32_e32 v54, vcc, s2, v144
	s_mov_b64 s[2:3], 0xa0000
	s_nop 0
	v_addc_co_u32_e32 v55, vcc, 0, v145, vcc
	s_waitcnt vmcnt(15)
	s_nop 1
	v_mov_b32_e32 v50, v202
	v_mov_b32_e32 v51, v203
	v_mov_b32_e32 v52, v204
	v_mov_b32_e32 v53, v205
	s_waitcnt lgkmcnt(0)
	v_lshlrev_b32_e32 v56, 16, v50
	v_and_b32_e32 v57, 0xffff0000, v50
	v_lshlrev_b32_e32 v50, 16, v51
	v_and_b32_e32 v51, 0xffff0000, v51
	v_lshlrev_b32_e32 v58, 16, v52
	v_and_b32_e32 v59, 0xffff0000, v52
	v_lshlrev_b32_e32 v52, 16, v53
	v_and_b32_e32 v53, 0xffff0000, v53
	v_pk_add_f32 v[46:47], v[46:47], v[50:51]
	v_pk_add_f32 v[44:45], v[44:45], v[56:57]
	v_pk_add_f32 v[50:51], v[42:43], v[52:53]
	v_pk_add_f32 v[42:43], v[40:41], v[58:59]
	v_cvt_pk_bf16_f32 v40, v44, v45
	v_cvt_pk_bf16_f32 v41, v46, v47
	v_cvt_pk_bf16_f32 v42, v42, v43
	v_cvt_pk_bf16_f32 v43, v50, v51
	global_store_dwordx4 v[54:55], v[40:43], off
	s_waitcnt vmcnt(15)
	s_nop 1
	v_mov_b32_e32 v40, v206
	v_mov_b32_e32 v41, v207
	v_mov_b32_e32 v42, v208
	v_mov_b32_e32 v43, v209
	s_waitcnt lgkmcnt(0)
; DI unsigned pack2(float a, float b) { f32x2 v = {a, b}; hwbf16x2 r = __builtin_convertvector(v, hwbf16x2); return __builtin_bit_cast(unsigned, r); }
; DI float bflo(unsigned w) { return __uint_as_float(w << 16); }
; DI float bfhi(unsigned w) { return __uint_as_float(w & 0xffff0000u); }
; #define PG8_WAIT_V(n) asm volatile("s_waitcnt vmcnt(" #n ")" ::: "memory")
; #define PG8_BAR __builtin_amdgcn_s_barrier()
;     DI void operator()(const f32x4 (&acc)[2][2][4][2], const Unit& u, int wr, int wc, int fr, int fq) const {
;     ...
;         for (int ai = 0; ai < 2; ++ai)
; #pragma unroll
;             for (int m = 0; m < 4; ++m) { const size_t ro = (size_t)(row0 + ai * HALF + m * 16) * D + col0;
; #pragma unroll
;                 for (int bj = 0; bj < 2; ++bj) {
;                     f32x4 x0, x1;
;                     if constexpr (IB) { const u32x4 w = *(const u32x4*)((const bf16_t*)Xin + ro + bj * HALF);
;                         x0 = (f32x4){bflo(w[0]), bfhi(w[0]), bflo(w[1]), bfhi(w[1])}; x1 = (f32x4){bflo(w[2]), bfhi(w[2]), bflo(w[3]), bfhi(w[3])}; }
;                     else { x0 = *(const f32x4*)((const float*)Xin + ro + bj * HALF); x1 = *(const f32x4*)((const float*)Xin + ro + bj * HALF + 4); }
;                     x0 += acc[ai][bj][m][0] * sc[bj][0]; x1 += acc[ai][bj][m][1] * sc[bj][1];
;                     if constexpr (OB) { u32x4 o; o[0] = pack2(x0[0], x0[1]); o[1] = pack2(x0[2], x0[3]); o[2] = pack2(x1[0], x1[1]); o[3] = pack2(x1[2], x1[3]);
;                         *(u32x4*)((bf16_t*)Xout + ro + bj * HALF) = o; }
;                     else { *(f32x4*)((float*)Xout + ro + bj * HALF) = x0; *(f32x4*)((float*)Xout + ro + bj * HALF + 4) = x1; } } }
; template <class Map, class Epi>
; DI void gemm_phase(LAS unsigned char* lds, const Map& MP, const Epi& E, const int nM, const int nN, const int K, const int lda, const int ldb) {
;     ...
;         cur = nxt; cA = nA; cB = nB; ++ui;
;     }
;     PG8_WAIT_V(0);
;     if (wr == 0) PG8_BAR;
;     PG8_BAR;
	v_lshlrev_b32_e32 v44, 16, v40
	v_and_b32_e32 v45, 0xffff0000, v40
	v_lshlrev_b32_e32 v40, 16, v41
	v_and_b32_e32 v41, 0xffff0000, v41
	v_lshlrev_b32_e32 v46, 16, v42
	v_and_b32_e32 v47, 0xffff0000, v42
	v_lshlrev_b32_e32 v42, 16, v43
	v_and_b32_e32 v43, 0xffff0000, v43
	v_pk_add_f32 v[38:39], v[38:39], v[40:41]
	v_pk_add_f32 v[36:37], v[36:37], v[44:45]
	v_pk_add_f32 v[40:41], v[34:35], v[42:43]
	v_pk_add_f32 v[34:35], v[32:33], v[46:47]
	v_cvt_pk_bf16_f32 v32, v36, v37
	v_cvt_pk_bf16_f32 v33, v38, v39
	v_cvt_pk_bf16_f32 v34, v34, v35
	v_cvt_pk_bf16_f32 v35, v40, v41
	global_store_dwordx4 v[48:49], v[32:35], off offset:256
	s_nop 1
	v_lshl_add_u64 v[32:33], v[144:145], 0, s[2:3]
	s_mov_b32 s2, 0xa0000
	v_add_co_u32_e32 v38, vcc, s2, v144
	s_mov_b64 s[2:3], 0xb0000
	s_nop 0
	v_addc_co_u32_e32 v39, vcc, 0, v145, vcc
	s_waitcnt vmcnt(15)
	s_nop 1
	v_mov_b32_e32 v34, v210
	v_mov_b32_e32 v35, v211
	v_mov_b32_e32 v36, v212
	v_mov_b32_e32 v37, v213
	s_waitcnt lgkmcnt(0)
	v_lshlrev_b32_e32 v40, 16, v34
	v_and_b32_e32 v41, 0xffff0000, v34
	v_lshlrev_b32_e32 v34, 16, v35
	v_and_b32_e32 v35, 0xffff0000, v35
	v_lshlrev_b32_e32 v42, 16, v36
	v_and_b32_e32 v43, 0xffff0000, v36
	v_lshlrev_b32_e32 v36, 16, v37
	v_and_b32_e32 v37, 0xffff0000, v37
	v_pk_add_f32 v[30:31], v[30:31], v[34:35]
	v_pk_add_f32 v[28:29], v[28:29], v[40:41]
	v_pk_add_f32 v[34:35], v[26:27], v[36:37]
	v_pk_add_f32 v[26:27], v[24:25], v[42:43]
	v_cvt_pk_bf16_f32 v24, v28, v29
	v_cvt_pk_bf16_f32 v25, v30, v31
	v_cvt_pk_bf16_f32 v26, v26, v27
	v_cvt_pk_bf16_f32 v27, v34, v35
	global_store_dwordx4 v[38:39], v[24:27], off
	s_waitcnt vmcnt(15)
	s_nop 1
	v_mov_b32_e32 v24, v214
	v_mov_b32_e32 v25, v215
	v_mov_b32_e32 v26, v216
	v_mov_b32_e32 v27, v217
	s_waitcnt lgkmcnt(0)
	v_lshlrev_b32_e32 v28, 16, v24
	v_and_b32_e32 v29, 0xffff0000, v24
	v_lshlrev_b32_e32 v24, 16, v25
	v_and_b32_e32 v25, 0xffff0000, v25
	v_lshlrev_b32_e32 v30, 16, v26
	v_and_b32_e32 v31, 0xffff0000, v26
	v_lshlrev_b32_e32 v26, 16, v27
	v_and_b32_e32 v27, 0xffff0000, v27
	v_pk_add_f32 v[22:23], v[22:23], v[24:25]
	v_pk_add_f32 v[20:21], v[20:21], v[28:29]
	v_pk_add_f32 v[24:25], v[18:19], v[26:27]
	v_pk_add_f32 v[18:19], v[16:17], v[30:31]
	v_cvt_pk_bf16_f32 v16, v20, v21
	v_cvt_pk_bf16_f32 v17, v22, v23
	v_cvt_pk_bf16_f32 v18, v18, v19
	v_cvt_pk_bf16_f32 v19, v24, v25
	global_store_dwordx4 v[32:33], v[16:19], off offset:256
	s_nop 1
	v_lshl_add_u64 v[16:17], v[144:145], 0, s[2:3]
	s_mov_b32 s2, 0xb0000
	v_add_co_u32_e32 v22, vcc, s2, v144
	s_mov_b32 s2, s55
	s_nop 0
	v_addc_co_u32_e32 v23, vcc, 0, v145, vcc
	s_waitcnt vmcnt(15)
	s_nop 1
	v_mov_b32_e32 v18, v248
	v_mov_b32_e32 v19, v249
	v_mov_b32_e32 v20, v250
	v_mov_b32_e32 v21, v251
	s_and_b64 vcc, exec, s[40:41]
	s_waitcnt lgkmcnt(0)
	v_lshlrev_b32_e32 v24, 16, v18
	v_and_b32_e32 v25, 0xffff0000, v18
	v_lshlrev_b32_e32 v18, 16, v19
	v_and_b32_e32 v19, 0xffff0000, v19
	v_lshlrev_b32_e32 v26, 16, v20
	v_and_b32_e32 v27, 0xffff0000, v20
	v_lshlrev_b32_e32 v20, 16, v21
	v_and_b32_e32 v21, 0xffff0000, v21
	v_pk_add_f32 v[14:15], v[14:15], v[18:19]
	v_pk_add_f32 v[12:13], v[12:13], v[24:25]
	v_pk_add_f32 v[18:19], v[10:11], v[20:21]
	v_pk_add_f32 v[10:11], v[8:9], v[26:27]
	v_cvt_pk_bf16_f32 v8, v12, v13
	v_cvt_pk_bf16_f32 v9, v14, v15
	v_cvt_pk_bf16_f32 v10, v10, v11
	v_cvt_pk_bf16_f32 v11, v18, v19
	global_store_dwordx4 v[22:23], v[8:11], off
	s_waitcnt vmcnt(15)
	s_nop 1
	v_mov_b32_e32 v8, v252
	v_mov_b32_e32 v9, v253
	v_mov_b32_e32 v10, v254
	v_mov_b32_e32 v11, v255
	s_waitcnt lgkmcnt(0)
	v_lshlrev_b32_e32 v12, 16, v8
	v_and_b32_e32 v13, 0xffff0000, v8
	v_lshlrev_b32_e32 v8, 16, v9
	v_and_b32_e32 v9, 0xffff0000, v9
	v_lshlrev_b32_e32 v14, 16, v10
	v_and_b32_e32 v15, 0xffff0000, v10
	v_lshlrev_b32_e32 v10, 16, v11
	v_and_b32_e32 v11, 0xffff0000, v11
	v_pk_add_f32 v[6:7], v[6:7], v[8:9]
	v_pk_add_f32 v[4:5], v[4:5], v[12:13]
	v_pk_add_f32 v[8:9], v[2:3], v[10:11]
	v_pk_add_f32 v[2:3], v[0:1], v[14:15]
	v_cvt_pk_bf16_f32 v0, v4, v5
	v_cvt_pk_bf16_f32 v1, v6, v7
	v_cvt_pk_bf16_f32 v2, v2, v3
	v_cvt_pk_bf16_f32 v3, v8, v9
	global_store_dwordx4 v[16:17], v[0:3], off offset:256
	s_cbranch_vccz .LBB1_543
	s_waitcnt vmcnt(0)
	s_cmpk_gt_u32 s17, 0xff
	s_cbranch_scc1 .LBB1_554
	s_barrier

; #define PG8_STAGE(bufoff, gbase, voff) do { _Pragma("unroll") for (int _i = 0; _i < 2; ++_i) \
;         __builtin_amdgcn_global_load_lds((const unsigned*)((const char*)(gbase) + (voff)[_i]), (LAS unsigned*)(lds + (bufoff) + ldsw + _i * 8192), 16, 0, 0); } while (0)
; #define PG8_LDA(dst, b, h) do { _Pragma("unroll") for (int m = 0; m < 4; ++m) _Pragma("unroll") for (int k = 0; k < 2; ++k) dst[m][k] = *(const LAS bf16x8*)(lds + PG8_SA(b, h) + aoff + m * 2048 + k * 1024); } while (0)
; #define PG8_LDB(dst, b, h) do { _Pragma("unroll") for (int n = 0; n < 2; ++n) _Pragma("unroll") for (int k = 0; k < 2; ++k) dst[n][k] = *(const LAS bf16x8*)(lds + PG8_SB(b, h) + boff + n * 2048 + k * 1024); } while (0)
; #define PG8_MMA(ai, bj, At, Bt) do { __builtin_amdgcn_s_setprio(1); _Pragma("unroll") for (int m = 0; m < 4; ++m) _Pragma("unroll") for (int n = 0; n < 2; ++n) _Pragma("unroll") for (int k = 0; k < 2; ++k) \
;         acc[ai][bj][m][n] = __builtin_amdgcn_mfma_f32_16x16x32_bf16(Bt[n][k], At[m][k], acc[ai][bj][m][n], 0, 0, 0); __builtin_amdgcn_s_setprio(0); } while (0)
; #define PG8_WAIT_L(n) asm volatile("s_waitcnt lgkmcnt(" #n ")" ::: "memory")
; #define PG8_BAR __builtin_amdgcn_s_barrier()
; #define PG8_SCHED __builtin_amdgcn_sched_barrier(0)
; template <class Map, class Epi>
; DI void gemm_phase(LAS unsigned char* lds, const Map& MP, const Epi& E, const int nM, const int nN, const int K, const int lda, const int ldb) {
;     ...
;             PG8_LDB(B0, 0, 0); PG8_SCHED; PG8_LDA(At, 0, 0); PG8_STAGE(PG8_SA(1, 1), a1 + hstepA, voffA);
;             PG8_WAIT_L(8); PG8_BAR; PG8_WAIT_L(0); PG8_MMA(0, 0, At, B0); PG8_BAR; PG8_SCHED;
;             PG8_LDB(B1, 0, 1); PG8_STAGE(PG8_SB(0, 0), b2, voffB);
;             PG8_BAR; PG8_WAIT_L(0); PG8_MMA(0, 1, At, B1); PG8_BAR;
;             PG8_LDA(At, 0, 1); PG8_STAGE(PG8_SA(0, 0), a2, voffA);
;             PG8_BAR; PG8_WAIT_L(0); PG8_MMA(1, 0, At, B0); PG8_BAR; PG8_SCHED;
.LBB1_693:
	ds_read_b128 v[166:169], v148
	ds_read_b128 v[170:173], v148 offset:1024
	ds_read_b128 v[174:177], v148 offset:2048
	ds_read_b128 v[178:181], v148 offset:3072
	ds_read_b128 v[182:185], v148 offset:4096
	ds_read_b128 v[186:189], v148 offset:5120
	ds_read_b128 v[190:193], v148 offset:6144
	ds_read_b128 v[198:201], v148 offset:7168
	s_add_u32 s3, s20, 0xfff80080
	s_addc_u32 s22, s21, -1
	s_cmp_eq_u32 s54, 28
	s_cselect_b32 s25, s15, s22
	s_cselect_b32 s24, s48, s3
	s_cselect_b32 s23, s13, s53
	s_cselect_b32 s22, s49, s52
	s_add_i32 m0, s31, 0xc000
	s_nop 0
	global_load_lds_dwordx4 v138, s[20:21]
	s_add_i32 m0, s31, 0xe000
	s_nop 0
	global_load_lds_dwordx4 v136, s[20:21]
	s_waitcnt lgkmcnt(8)
	s_barrier
	s_setprio 1
	s_waitcnt lgkmcnt(7)
	v_mfma_f32_16x16x32_bf16 v[124:127], v[150:153], v[166:169], v[124:127]
	v_mfma_f32_16x16x32_bf16 v[120:123], v[158:161], v[166:169], v[120:123]
	s_waitcnt lgkmcnt(5)
	v_mfma_f32_16x16x32_bf16 v[116:119], v[150:153], v[174:177], v[116:119]
	v_mfma_f32_16x16x32_bf16 v[112:115], v[158:161], v[174:177], v[112:115]
	s_waitcnt lgkmcnt(3)
	v_mfma_f32_16x16x32_bf16 v[100:103], v[150:153], v[182:185], v[100:103]
	v_mfma_f32_16x16x32_bf16 v[96:99], v[158:161], v[182:185], v[96:99]
	s_waitcnt lgkmcnt(1)
	v_mfma_f32_16x16x32_bf16 v[84:87], v[150:153], v[190:193], v[84:87]
	v_mfma_f32_16x16x32_bf16 v[80:83], v[158:161], v[190:193], v[80:83]
	v_mfma_f32_16x16x32_bf16 v[124:127], v[154:157], v[170:173], v[124:127]
	v_mfma_f32_16x16x32_bf16 v[120:123], v[162:165], v[170:173], v[120:123]
	v_mfma_f32_16x16x32_bf16 v[116:119], v[154:157], v[178:181], v[116:119]
	v_mfma_f32_16x16x32_bf16 v[112:115], v[162:165], v[178:181], v[112:115]
	v_mfma_f32_16x16x32_bf16 v[100:103], v[154:157], v[186:189], v[100:103]
	v_mfma_f32_16x16x32_bf16 v[96:99], v[162:165], v[186:189], v[96:99]
	s_waitcnt lgkmcnt(0)
	v_mfma_f32_16x16x32_bf16 v[84:87], v[154:157], v[198:201], v[84:87]
	v_mfma_f32_16x16x32_bf16 v[80:83], v[162:165], v[198:201], v[80:83]
	s_setprio 0
	s_barrier
	ds_read_b128 v[202:205], v149
	ds_read_b128 v[206:209], v149 offset:1024
	ds_read_b128 v[210:213], v149 offset:2048
	ds_read_b128 v[214:217], v149 offset:3072
	s_add_i32 s3, s44, s29
	v_lshl_add_u64 v[194:195], s[22:23], 0, v[132:133]
	s_mov_b32 m0, s3
	s_nop 0
	global_load_lds_dwordx4 v[194:195], off
	v_lshl_add_u64 v[218:219], s[22:23], 0, v[128:129]
	s_add_i32 m0, s3, 0x2000
	s_nop 0
	global_load_lds_dwordx4 v[218:219], off
	s_barrier
	s_setprio 1
	s_waitcnt lgkmcnt(3)
	v_mfma_f32_16x16x32_bf16 v[108:111], v[202:205], v[166:169], v[108:111]
	s_waitcnt lgkmcnt(1)
	v_mfma_f32_16x16x32_bf16 v[104:107], v[210:213], v[166:169], v[104:107]
	v_mfma_f32_16x16x32_bf16 v[92:95], v[202:205], v[174:177], v[92:95]
	v_mfma_f32_16x16x32_bf16 v[88:91], v[210:213], v[174:177], v[88:91]
	v_mfma_f32_16x16x32_bf16 v[76:79], v[202:205], v[182:185], v[76:79]
	v_mfma_f32_16x16x32_bf16 v[72:75], v[210:213], v[182:185], v[72:75]
	v_mfma_f32_16x16x32_bf16 v[68:71], v[202:205], v[190:193], v[68:71]
	v_mfma_f32_16x16x32_bf16 v[64:67], v[210:213], v[190:193], v[64:67]
	v_mfma_f32_16x16x32_bf16 v[108:111], v[206:209], v[170:173], v[108:111]
	s_mov_b32 m0, s31
	s_waitcnt lgkmcnt(0)
	v_mfma_f32_16x16x32_bf16 v[104:107], v[214:217], v[170:173], v[104:107]
	v_lshl_add_u64 v[220:221], s[24:25], 0, v[134:135]
	v_mfma_f32_16x16x32_bf16 v[92:95], v[206:209], v[178:181], v[92:95]
	v_mfma_f32_16x16x32_bf16 v[88:91], v[214:217], v[178:181], v[88:91]
	v_mfma_f32_16x16x32_bf16 v[76:79], v[206:209], v[186:189], v[76:79]
	v_mfma_f32_16x16x32_bf16 v[72:75], v[214:217], v[186:189], v[72:75]
	v_mfma_f32_16x16x32_bf16 v[68:71], v[206:209], v[198:201], v[68:71]
	v_mfma_f32_16x16x32_bf16 v[64:67], v[214:217], v[198:201], v[64:67]
	s_setprio 0
	s_barrier
	ds_read_b128 v[166:169], v148 offset:16384
	ds_read_b128 v[170:173], v148 offset:17408
	ds_read_b128 v[174:177], v148 offset:18432
	ds_read_b128 v[178:181], v148 offset:19456
	ds_read_b128 v[182:185], v148 offset:20480
	ds_read_b128 v[186:189], v148 offset:21504
	ds_read_b128 v[190:193], v148 offset:22528
	ds_read_b128 v[198:201], v148 offset:23552
	global_load_lds_dwordx4 v[220:221], off
	v_lshl_add_u64 v[222:223], s[24:25], 0, v[130:131]
	s_mov_b32 m0, s11
	s_nop 0
	global_load_lds_dwordx4 v[222:223], off
	s_waitcnt vmcnt(10)
	s_barrier
	s_setprio 1
	s_waitcnt lgkmcnt(7)
	v_mfma_f32_16x16x32_bf16 v[60:63], v[150:153], v[166:169], v[60:63]
	v_mfma_f32_16x16x32_bf16 v[56:59], v[158:161], v[166:169], v[56:59]
	s_waitcnt lgkmcnt(5)
	v_mfma_f32_16x16x32_bf16 v[52:55], v[150:153], v[174:177], v[52:55]
	v_mfma_f32_16x16x32_bf16 v[48:51], v[158:161], v[174:177], v[48:51]
	s_waitcnt lgkmcnt(3)
	v_mfma_f32_16x16x32_bf16 v[36:39], v[150:153], v[182:185], v[36:39]
	v_mfma_f32_16x16x32_bf16 v[32:35], v[158:161], v[182:185], v[32:35]
	s_waitcnt lgkmcnt(1)
	v_mfma_f32_16x16x32_bf16 v[20:23], v[150:153], v[190:193], v[20:23]
	v_mfma_f32_16x16x32_bf16 v[16:19], v[158:161], v[190:193], v[16:19]
	v_mfma_f32_16x16x32_bf16 v[60:63], v[154:157], v[170:173], v[60:63]
	v_mfma_f32_16x16x32_bf16 v[56:59], v[162:165], v[170:173], v[56:59]
	v_mfma_f32_16x16x32_bf16 v[52:55], v[154:157], v[178:181], v[52:55]
	v_mfma_f32_16x16x32_bf16 v[48:51], v[162:165], v[178:181], v[48:51]
	v_mfma_f32_16x16x32_bf16 v[36:39], v[154:157], v[186:189], v[36:39]
	v_mfma_f32_16x16x32_bf16 v[32:35], v[162:165], v[186:189], v[32:35]
	s_waitcnt lgkmcnt(0)
	v_mfma_f32_16x16x32_bf16 v[20:23], v[154:157], v[198:201], v[20:23]
	v_mfma_f32_16x16x32_bf16 v[16:19], v[162:165], v[198:201], v[16:19]
	s_setprio 0
	s_barrier
; #define PG8_STAGE(bufoff, gbase, voff) do { _Pragma("unroll") for (int _i = 0; _i < 2; ++_i) \
;         __builtin_amdgcn_global_load_lds((const unsigned*)((const char*)(gbase) + (voff)[_i]), (LAS unsigned*)(lds + (bufoff) + ldsw + _i * 8192), 16, 0, 0); } while (0)
; #define PG8_LDA(dst, b, h) do { _Pragma("unroll") for (int m = 0; m < 4; ++m) _Pragma("unroll") for (int k = 0; k < 2; ++k) dst[m][k] = *(const LAS bf16x8*)(lds + PG8_SA(b, h) + aoff + m * 2048 + k * 1024); } while (0)
; #define PG8_LDB(dst, b, h) do { _Pragma("unroll") for (int n = 0; n < 2; ++n) _Pragma("unroll") for (int k = 0; k < 2; ++k) dst[n][k] = *(const LAS bf16x8*)(lds + PG8_SB(b, h) + boff + n * 2048 + k * 1024); } while (0)
; #define PG8_MMA(ai, bj, At, Bt) do { __builtin_amdgcn_s_setprio(1); _Pragma("unroll") for (int m = 0; m < 4; ++m) _Pragma("unroll") for (int n = 0; n < 2; ++n) _Pragma("unroll") for (int k = 0; k < 2; ++k) \
;         acc[ai][bj][m][n] = __builtin_amdgcn_mfma_f32_16x16x32_bf16(Bt[n][k], At[m][k], acc[ai][bj][m][n], 0, 0, 0); __builtin_amdgcn_s_setprio(0); } while (0)
; #define PG8_WAIT_V(n) asm volatile("s_waitcnt vmcnt(" #n ")" ::: "memory")
; #define PG8_WAIT_L(n) asm volatile("s_waitcnt lgkmcnt(" #n ")" ::: "memory")
; #define PG8_BAR __builtin_amdgcn_s_barrier()
; #define PG8_SCHED __builtin_amdgcn_sched_barrier(0)
; template <class Map, class Epi>
; DI void gemm_phase(LAS unsigned char* lds, const Map& MP, const Epi& E, const int nM, const int nN, const int K, const int lda, const int ldb) {
;     ...
;             PG8_STAGE(PG8_SB(0, 1), b2 + hstepB, voffB);
;             PG8_WAIT_V(6); PG8_BAR; PG8_MMA(1, 1, At, B1); PG8_BAR;
;             PG8_LDB(B0, 1, 0); PG8_SCHED; PG8_LDA(At, 1, 0); PG8_STAGE(PG8_SA(0, 1), a2 + hstepA, voffA);
;             PG8_WAIT_L(8); PG8_BAR; PG8_WAIT_L(0); PG8_MMA(0, 0, At, B0); PG8_BAR; PG8_SCHED;
;             PG8_LDB(B1, 1, 1); PG8_STAGE(PG8_SB(1, 0), b3, voffB);
;             PG8_BAR; PG8_WAIT_L(0); PG8_MMA(0, 1, At, B1); PG8_BAR;
;             PG8_LDA(At, 1, 1); PG8_STAGE(PG8_SA(1, 0), a3, voffA);
;             PG8_BAR; PG8_WAIT_L(0); PG8_MMA(1, 0, At, B0); PG8_BAR; PG8_SCHED;
	s_add_u32 s56, s22, 0x80000
	s_addc_u32 s57, s23, 0
	s_add_i32 s3, s45, s29
	s_mov_b32 m0, s3
	s_nop 0
	global_load_lds_dwordx4 v132, s[56:57]
	s_add_i32 m0, s3, 0x2000
	s_nop 0
	global_load_lds_dwordx4 v128, s[56:57]
	s_waitcnt vmcnt(6)
	s_barrier
	s_setprio 1
	v_mfma_f32_16x16x32_bf16 v[44:47], v[202:205], v[166:169], v[44:47]
	v_mfma_f32_16x16x32_bf16 v[40:43], v[210:213], v[166:169], v[40:43]
	s_add_i32 s3, 0, 0x18000
	v_add_u32_e32 v162, s3, v146
	ds_read_b128 v[150:153], v162
	v_mfma_f32_16x16x32_bf16 v[28:31], v[202:205], v[174:177], v[28:31]
	v_mfma_f32_16x16x32_bf16 v[24:27], v[210:213], v[174:177], v[24:27]
	ds_read_b128 v[154:157], v162 offset:1024
	v_mfma_f32_16x16x32_bf16 v[12:15], v[202:205], v[182:185], v[12:15]
	v_mfma_f32_16x16x32_bf16 v[8:11], v[210:213], v[182:185], v[8:11]
	ds_read_b128 v[158:161], v162 offset:2048
	v_mfma_f32_16x16x32_bf16 v[4:7], v[202:205], v[190:193], v[4:7]
	v_mfma_f32_16x16x32_bf16 v[0:3], v[210:213], v[190:193], v[0:3]
	ds_read_b128 v[162:165], v162 offset:3072
	v_mfma_f32_16x16x32_bf16 v[44:47], v[206:209], v[170:173], v[44:47]
	v_mfma_f32_16x16x32_bf16 v[40:43], v[214:217], v[170:173], v[40:43]
	v_mfma_f32_16x16x32_bf16 v[28:31], v[206:209], v[178:181], v[28:31]
	v_mfma_f32_16x16x32_bf16 v[24:27], v[214:217], v[178:181], v[24:27]
	v_mfma_f32_16x16x32_bf16 v[12:15], v[206:209], v[186:189], v[12:15]
	v_mfma_f32_16x16x32_bf16 v[8:11], v[214:217], v[186:189], v[8:11]
	v_mfma_f32_16x16x32_bf16 v[4:7], v[206:209], v[198:201], v[4:7]
	v_mfma_f32_16x16x32_bf16 v[0:3], v[214:217], v[198:201], v[0:3]
	s_setprio 0
	s_barrier
	ds_read_b128 v[166:169], v148 offset:32768
	ds_read_b128 v[170:173], v148 offset:33792
	ds_read_b128 v[174:177], v148 offset:34816
	ds_read_b128 v[178:181], v148 offset:35840
	ds_read_b128 v[182:185], v148 offset:36864
	ds_read_b128 v[186:189], v148 offset:37888
	ds_read_b128 v[190:193], v148 offset:38912
	ds_read_b128 v[198:201], v148 offset:39936
	s_add_u32 s24, s24, 0x80000
	s_addc_u32 s25, s25, 0
	s_mov_b32 m0, s34
	s_nop 0
	global_load_lds_dwordx4 v134, s[24:25]
	s_mov_b32 m0, s35
	s_nop 0
	global_load_lds_dwordx4 v130, s[24:25]
	s_waitcnt lgkmcnt(8)
	s_barrier
	s_setprio 1
	s_waitcnt lgkmcnt(7)
	v_mfma_f32_16x16x32_bf16 v[124:127], v[150:153], v[166:169], v[124:127]
	v_mfma_f32_16x16x32_bf16 v[120:123], v[158:161], v[166:169], v[120:123]
	s_waitcnt lgkmcnt(5)
	v_mfma_f32_16x16x32_bf16 v[116:119], v[150:153], v[174:177], v[116:119]
	v_mfma_f32_16x16x32_bf16 v[112:115], v[158:161], v[174:177], v[112:115]
	s_waitcnt lgkmcnt(3)
	v_mfma_f32_16x16x32_bf16 v[100:103], v[150:153], v[182:185], v[100:103]
	v_mfma_f32_16x16x32_bf16 v[96:99], v[158:161], v[182:185], v[96:99]
	s_waitcnt lgkmcnt(1)
	v_mfma_f32_16x16x32_bf16 v[84:87], v[150:153], v[190:193], v[84:87]
	v_mfma_f32_16x16x32_bf16 v[80:83], v[158:161], v[190:193], v[80:83]
	v_mfma_f32_16x16x32_bf16 v[124:127], v[154:157], v[170:173], v[124:127]
	v_mfma_f32_16x16x32_bf16 v[120:123], v[162:165], v[170:173], v[120:123]
	v_mfma_f32_16x16x32_bf16 v[116:119], v[154:157], v[178:181], v[116:119]
	v_mfma_f32_16x16x32_bf16 v[112:115], v[162:165], v[178:181], v[112:115]
	v_mfma_f32_16x16x32_bf16 v[100:103], v[154:157], v[186:189], v[100:103]
	v_mfma_f32_16x16x32_bf16 v[96:99], v[162:165], v[186:189], v[96:99]
	s_waitcnt lgkmcnt(0)
	v_mfma_f32_16x16x32_bf16 v[84:87], v[154:157], v[198:201], v[84:87]
	v_mfma_f32_16x16x32_bf16 v[80:83], v[162:165], v[198:201], v[80:83]
	s_setprio 0
	s_barrier
	s_add_i32 s24, 0, 0x1c000
	v_add_u32_e32 v196, s24, v146
	ds_read_b128 v[202:205], v196
	ds_read_b128 v[206:209], v196 offset:1024
	ds_read_b128 v[210:213], v196 offset:2048
	ds_read_b128 v[214:217], v196 offset:3072
	s_add_i32 s3, s3, s29
	v_lshl_add_u64 v[194:195], v[194:195], 0, s[8:9]
	s_mov_b32 m0, s3
	s_nop 0
	global_load_lds_dwordx4 v[194:195], off
	v_lshl_add_u64 v[194:195], v[218:219], 0, s[8:9]
	s_add_i32 m0, s3, 0x2000
	s_nop 0
	global_load_lds_dwordx4 v[194:195], off
	s_barrier
	s_setprio 1
	s_waitcnt lgkmcnt(3)
	v_mfma_f32_16x16x32_bf16 v[108:111], v[202:205], v[166:169], v[108:111]
	s_waitcnt lgkmcnt(1)
	v_mfma_f32_16x16x32_bf16 v[104:107], v[210:213], v[166:169], v[104:107]
	v_mfma_f32_16x16x32_bf16 v[92:95], v[202:205], v[174:177], v[92:95]
	v_mfma_f32_16x16x32_bf16 v[88:91], v[210:213], v[174:177], v[88:91]
	v_mfma_f32_16x16x32_bf16 v[76:79], v[202:205], v[182:185], v[76:79]
	v_mfma_f32_16x16x32_bf16 v[72:75], v[210:213], v[182:185], v[72:75]
	v_mfma_f32_16x16x32_bf16 v[68:71], v[202:205], v[190:193], v[68:71]
	v_mfma_f32_16x16x32_bf16 v[64:67], v[210:213], v[190:193], v[64:67]
	v_mfma_f32_16x16x32_bf16 v[108:111], v[206:209], v[170:173], v[108:111]
	s_mov_b32 m0, s39
	s_waitcnt lgkmcnt(0)
	v_mfma_f32_16x16x32_bf16 v[104:107], v[214:217], v[170:173], v[104:107]
	v_lshl_add_u64 v[194:195], v[220:221], 0, s[8:9]
	v_mfma_f32_16x16x32_bf16 v[92:95], v[206:209], v[178:181], v[92:95]
	v_mfma_f32_16x16x32_bf16 v[88:91], v[214:217], v[178:181], v[88:91]
	v_mfma_f32_16x16x32_bf16 v[76:79], v[206:209], v[186:189], v[76:79]
	v_mfma_f32_16x16x32_bf16 v[72:75], v[214:217], v[186:189], v[72:75]
	v_mfma_f32_16x16x32_bf16 v[68:71], v[206:209], v[198:201], v[68:71]
	v_mfma_f32_16x16x32_bf16 v[64:67], v[214:217], v[198:201], v[64:67]
	s_setprio 0
	s_barrier
	ds_read_b128 v[166:169], v148 offset:49152
	ds_read_b128 v[170:173], v148 offset:50176
	ds_read_b128 v[174:177], v148 offset:51200
	ds_read_b128 v[178:181], v148 offset:52224
	ds_read_b128 v[182:185], v148 offset:53248
	ds_read_b128 v[186:189], v148 offset:54272
	ds_read_b128 v[190:193], v148 offset:55296
	ds_read_b128 v[198:201], v148 offset:56320
	global_load_lds_dwordx4 v[194:195], off
	v_lshl_add_u64 v[194:195], v[222:223], 0, s[8:9]
	s_mov_b32 m0, s42
	s_nop 0
	global_load_lds_dwordx4 v[194:195], off
	s_waitcnt vmcnt(10)
	s_barrier
; #define PG8_STAGE(bufoff, gbase, voff) do { _Pragma("unroll") for (int _i = 0; _i < 2; ++_i) \
;         __builtin_amdgcn_global_load_lds((const unsigned*)((const char*)(gbase) + (voff)[_i]), (LAS unsigned*)(lds + (bufoff) + ldsw + _i * 8192), 16, 0, 0); } while (0)
; #define PG8_MMA(ai, bj, At, Bt) do { __builtin_amdgcn_s_setprio(1); _Pragma("unroll") for (int m = 0; m < 4; ++m) _Pragma("unroll") for (int n = 0; n < 2; ++n) _Pragma("unroll") for (int k = 0; k < 2; ++k) \
;         acc[ai][bj][m][n] = __builtin_amdgcn_mfma_f32_16x16x32_bf16(Bt[n][k], At[m][k], acc[ai][bj][m][n], 0, 0, 0); __builtin_amdgcn_s_setprio(0); } while (0)
; #define PG8_WAIT_V(n) asm volatile("s_waitcnt vmcnt(" #n ")" ::: "memory")
; #define PG8_WAIT_L(n) asm volatile("s_waitcnt lgkmcnt(" #n ")" ::: "memory")
; #define PG8_BAR __builtin_amdgcn_s_barrier()
; #define PG8_SCHED __builtin_amdgcn_sched_barrier(0)
; template <class Map, class Epi>
; DI void gemm_phase(LAS unsigned char* lds, const Map& MP, const Epi& E, const int nM, const int nN, const int K, const int lda, const int ldb) {
;     ...
;             PG8_BAR; PG8_WAIT_L(0); PG8_MMA(1, 0, At, B0); PG8_BAR; PG8_SCHED;
;             PG8_STAGE(PG8_SB(1, 1), b3 + hstepB, voffB);
;             PG8_WAIT_V(6); PG8_BAR; PG8_MMA(1, 1, At, B1); PG8_BAR;
	s_setprio 1
	s_waitcnt lgkmcnt(7)
	v_mfma_f32_16x16x32_bf16 v[60:63], v[150:153], v[166:169], v[60:63]
	v_mfma_f32_16x16x32_bf16 v[56:59], v[158:161], v[166:169], v[56:59]
	s_waitcnt lgkmcnt(5)
	v_mfma_f32_16x16x32_bf16 v[52:55], v[150:153], v[174:177], v[52:55]
	v_mfma_f32_16x16x32_bf16 v[48:51], v[158:161], v[174:177], v[48:51]
	s_waitcnt lgkmcnt(3)
	v_mfma_f32_16x16x32_bf16 v[36:39], v[150:153], v[182:185], v[36:39]
	v_mfma_f32_16x16x32_bf16 v[32:35], v[158:161], v[182:185], v[32:35]
	s_waitcnt lgkmcnt(1)
	v_mfma_f32_16x16x32_bf16 v[20:23], v[150:153], v[190:193], v[20:23]
	v_mfma_f32_16x16x32_bf16 v[16:19], v[158:161], v[190:193], v[16:19]
	v_mfma_f32_16x16x32_bf16 v[60:63], v[154:157], v[170:173], v[60:63]
	v_mfma_f32_16x16x32_bf16 v[56:59], v[162:165], v[170:173], v[56:59]
	v_mfma_f32_16x16x32_bf16 v[52:55], v[154:157], v[178:181], v[52:55]
	v_mfma_f32_16x16x32_bf16 v[48:51], v[162:165], v[178:181], v[48:51]
	v_mfma_f32_16x16x32_bf16 v[36:39], v[154:157], v[186:189], v[36:39]
	v_mfma_f32_16x16x32_bf16 v[32:35], v[162:165], v[186:189], v[32:35]
	s_waitcnt lgkmcnt(0)
	v_mfma_f32_16x16x32_bf16 v[20:23], v[154:157], v[198:201], v[20:23]
	v_mfma_f32_16x16x32_bf16 v[16:19], v[162:165], v[198:201], v[16:19]
	s_setprio 0
	s_barrier
	s_add_u32 s22, s22, 0x80080
	s_addc_u32 s23, s23, 0
	s_add_i32 s3, s24, s29
	s_mov_b32 m0, s3
	s_nop 0
	global_load_lds_dwordx4 v132, s[22:23]
	s_add_i32 m0, s3, 0x2000
	s_nop 0
	global_load_lds_dwordx4 v128, s[22:23]
	s_waitcnt vmcnt(6)
	s_barrier
	s_setprio 1
	v_mfma_f32_16x16x32_bf16 v[44:47], v[202:205], v[166:169], v[44:47]
	v_mfma_f32_16x16x32_bf16 v[40:43], v[210:213], v[166:169], v[40:43]
	ds_read_b128 v[150:153], v147
	v_mfma_f32_16x16x32_bf16 v[28:31], v[202:205], v[174:177], v[28:31]
	v_mfma_f32_16x16x32_bf16 v[24:27], v[210:213], v[174:177], v[24:27]
	ds_read_b128 v[154:157], v147 offset:1024
	v_mfma_f32_16x16x32_bf16 v[12:15], v[202:205], v[182:185], v[12:15]
	v_mfma_f32_16x16x32_bf16 v[8:11], v[210:213], v[182:185], v[8:11]
	ds_read_b128 v[158:161], v147 offset:2048
	v_mfma_f32_16x16x32_bf16 v[4:7], v[202:205], v[190:193], v[4:7]
	v_mfma_f32_16x16x32_bf16 v[0:3], v[210:213], v[190:193], v[0:3]
	ds_read_b128 v[162:165], v147 offset:3072
	v_mfma_f32_16x16x32_bf16 v[44:47], v[206:209], v[170:173], v[44:47]
	s_add_i32 s54, s54, 2
	v_mfma_f32_16x16x32_bf16 v[40:43], v[214:217], v[170:173], v[40:43]
	s_add_u32 s52, s52, 0x100
	s_addc_u32 s53, s53, 0
	v_mfma_f32_16x16x32_bf16 v[28:31], v[206:209], v[178:181], v[28:31]
	s_add_u32 s20, s20, 0x100
	s_addc_u32 s21, s21, 0
	v_mfma_f32_16x16x32_bf16 v[24:27], v[214:217], v[178:181], v[24:27]
	s_cmp_gt_u32 s54, 29
	v_mfma_f32_16x16x32_bf16 v[12:15], v[206:209], v[186:189], v[12:15]
	v_mfma_f32_16x16x32_bf16 v[8:11], v[214:217], v[186:189], v[8:11]
	v_mfma_f32_16x16x32_bf16 v[4:7], v[206:209], v[198:201], v[4:7]
	v_mfma_f32_16x16x32_bf16 v[0:3], v[214:217], v[198:201], v[0:3]
	s_setprio 0
	s_barrier
	s_cbranch_scc0 .LBB1_693
; DI unsigned pack2(float a, float b) { f32x2 v = {a, b}; hwbf16x2 r = __builtin_convertvector(v, hwbf16x2); return __builtin_bit_cast(unsigned, r); }
;     DI void operator()(const f32x4 (&acc)[2][2][4][2], const Unit& u, int wr, int wc, int fr, int fq) const {
;         bf16_t* O = O1; int ldc = ldc1, pn = u.pn; if (pn >= split) { O = O2; ldc = ldc2; pn -= split; }
;         const int row0 = u.pm * BM + wr * 64 + fr, col0 = pn * BM + wc * 32 + 8 * fq;
; #pragma unroll
;         for (int ai = 0; ai < 2; ++ai)
; #pragma unroll
;             for (int m = 0; m < 4; ++m) { bf16_t* rowp = O + (size_t)(row0 + ai * HALF + m * 16) * ldc + col0;
; #pragma unroll
;                 for (int bj = 0; bj < 2; ++bj) { const f32x4 v0 = acc[ai][bj][m][0], v1 = acc[ai][bj][m][1];
;                     u32x4 o; o[0] = pack2(v0[0], v0[1]); o[1] = pack2(v0[2], v0[3]); o[2] = pack2(v1[0], v1[1]); o[3] = pack2(v1[2], v1[3]);
;                     *(u32x4*)(rowp + bj * HALF) = o; } }
	s_waitcnt lgkmcnt(0)
	s_lshl_b32 s3, s10, 8
	v_mov_b32_e32 v150, v144
	v_mov_b32_e32 v151, v145
	s_add_i32 s3, s3, s37
	v_cvt_pk_bf16_f32 v68, v68, v69
	v_add_u32_e32 v154, s3, v150
	s_lshl_b32 s3, s47, 8
	s_or_b32 s3, s3, s38
	v_lshl_add_u32 v150, v151, 3, s3
	v_ashrrev_i32_e32 v151, 31, v150
	v_lshl_add_u64 v[150:151], v[150:151], 1, s[6:7]
	v_cvt_pk_bf16_f32 v69, v70, v71
	v_cvt_pk_bf16_f32 v70, v64, v65
	v_add_u32_e32 v64, 0x80, v154
	v_mad_i64_i32 v[152:153], s[20:21], v154, s46, v[150:151]
	v_cvt_pk_bf16_f32 v108, v108, v109
	v_cvt_pk_bf16_f32 v109, v110, v111
	v_cvt_pk_bf16_f32 v110, v104, v105
	v_cvt_pk_bf16_f32 v111, v106, v107
	v_add_u32_e32 v104, 16, v154
	v_mad_i64_i32 v[64:65], s[20:21], v64, s46, v[150:151]
	v_cvt_pk_bf16_f32 v44, v44, v45
	v_cvt_pk_bf16_f32 v45, v46, v47
	v_cvt_pk_bf16_f32 v46, v40, v41
	v_cvt_pk_bf16_f32 v47, v42, v43
	v_add_u32_e32 v40, 0x90, v154
	global_store_dwordx4 v[152:153], v[108:111], off offset:256
	v_cvt_pk_bf16_f32 v92, v92, v93
	v_cvt_pk_bf16_f32 v93, v94, v95
	v_mad_i64_i32 v[108:109], s[20:21], v104, s46, v[150:151]
	v_cvt_pk_bf16_f32 v94, v88, v89
	v_cvt_pk_bf16_f32 v95, v90, v91
	v_add_u32_e32 v88, 32, v154
	global_store_dwordx4 v[64:65], v[44:47], off offset:256
	v_cvt_pk_bf16_f32 v28, v28, v29
	v_cvt_pk_bf16_f32 v29, v30, v31
	v_mad_i64_i32 v[44:45], s[20:21], v40, s46, v[150:151]
	v_cvt_pk_bf16_f32 v30, v24, v25
	v_cvt_pk_bf16_f32 v31, v26, v27
	v_add_u32_e32 v24, 0xa0, v154
	global_store_dwordx4 v[108:109], v[92:95], off offset:256
	v_cvt_pk_bf16_f32 v76, v76, v77
	v_cvt_pk_bf16_f32 v77, v78, v79
	v_mad_i64_i32 v[92:93], s[20:21], v88, s46, v[150:151]
	v_cvt_pk_bf16_f32 v78, v72, v73
	v_cvt_pk_bf16_f32 v79, v74, v75
	v_add_u32_e32 v72, 48, v154
	global_store_dwordx4 v[44:45], v[28:31], off offset:256
	v_cvt_pk_bf16_f32 v12, v12, v13
	v_cvt_pk_bf16_f32 v13, v14, v15
	v_mad_i64_i32 v[28:29], s[20:21], v24, s46, v[150:151]
	v_cvt_pk_bf16_f32 v14, v8, v9
	v_cvt_pk_bf16_f32 v15, v10, v11
	v_add_u32_e32 v8, 0xb0, v154
	global_store_dwordx4 v[92:93], v[76:79], off offset:256
	global_store_dwordx4 v[28:29], v[12:15], off offset:256
	v_cvt_pk_bf16_f32 v124, v124, v125
	v_mad_i64_i32 v[76:77], s[20:21], v72, s46, v[150:151]
	v_mad_i64_i32 v[12:13], s[20:21], v8, s46, v[150:151]
	v_cvt_pk_bf16_f32 v125, v126, v127
	v_cvt_pk_bf16_f32 v126, v120, v121
	v_cvt_pk_bf16_f32 v127, v122, v123
	v_cvt_pk_bf16_f32 v104, v116, v117
	v_cvt_pk_bf16_f32 v105, v118, v119
	v_cvt_pk_bf16_f32 v106, v112, v113
	v_cvt_pk_bf16_f32 v107, v114, v115
	v_cvt_pk_bf16_f32 v88, v100, v101
	v_cvt_pk_bf16_f32 v89, v102, v103
	v_cvt_pk_bf16_f32 v90, v96, v97
	v_cvt_pk_bf16_f32 v91, v98, v99
	v_cvt_pk_bf16_f32 v72, v84, v85
	v_cvt_pk_bf16_f32 v73, v86, v87
	v_cvt_pk_bf16_f32 v74, v80, v81
	v_cvt_pk_bf16_f32 v75, v82, v83
	v_cvt_pk_bf16_f32 v71, v66, v67
	v_cvt_pk_bf16_f32 v60, v60, v61
	v_cvt_pk_bf16_f32 v61, v62, v63
	v_cvt_pk_bf16_f32 v62, v56, v57
	v_cvt_pk_bf16_f32 v63, v58, v59
	v_cvt_pk_bf16_f32 v40, v52, v53
	v_cvt_pk_bf16_f32 v41, v54, v55
	v_cvt_pk_bf16_f32 v42, v48, v49
	v_cvt_pk_bf16_f32 v43, v50, v51
	v_cvt_pk_bf16_f32 v24, v36, v37
	v_cvt_pk_bf16_f32 v25, v38, v39
	v_cvt_pk_bf16_f32 v26, v32, v33
	v_cvt_pk_bf16_f32 v27, v34, v35
	v_cvt_pk_bf16_f32 v8, v20, v21
	v_cvt_pk_bf16_f32 v9, v22, v23
	v_cvt_pk_bf16_f32 v10, v16, v17
	v_cvt_pk_bf16_f32 v11, v18, v19
	v_cvt_pk_bf16_f32 v4, v4, v5
	v_cvt_pk_bf16_f32 v5, v6, v7
	v_cvt_pk_bf16_f32 v6, v0, v1
	v_cvt_pk_bf16_f32 v7, v2, v3
	s_and_b64 vcc, exec, s[40:41]
	s_mov_b32 s47, s12
	s_mov_b32 s10, s14
	s_mov_b64 s[20:21], s[18:19]
	s_mov_b64 s[22:23], s[16:17]
	global_store_dwordx4 v[152:153], v[124:127], off
	global_store_dwordx4 v[108:109], v[104:107], off
	global_store_dwordx4 v[92:93], v[88:91], off
	global_store_dwordx4 v[76:77], v[72:75], off
	global_store_dwordx4 v[76:77], v[68:71], off offset:256
	global_store_dwordx4 v[64:65], v[60:63], off
	global_store_dwordx4 v[44:45], v[40:43], off
	global_store_dwordx4 v[28:29], v[24:27], off
	global_store_dwordx4 v[12:13], v[8:11], off
	global_store_dwordx4 v[12:13], v[4:7], off offset:256
	s_cbranch_vccz .LBB1_690
	s_waitcnt vmcnt(0)
	s_cmpk_gt_u32 s4, 0xff
	s_cbranch_scc1 .LBB1_697
	s_barrier

; #define PG8_STAGE(bufoff, gbase, voff) do { _Pragma("unroll") for (int _i = 0; _i < 2; ++_i) \
;         __builtin_amdgcn_global_load_lds((const unsigned*)((const char*)(gbase) + (voff)[_i]), (LAS unsigned*)(lds + (bufoff) + ldsw + _i * 8192), 16, 0, 0); } while (0)
; #define PG8_LDA(dst, b, h) do { _Pragma("unroll") for (int m = 0; m < 4; ++m) _Pragma("unroll") for (int k = 0; k < 2; ++k) dst[m][k] = *(const LAS bf16x8*)(lds + PG8_SA(b, h) + aoff + m * 2048 + k * 1024); } while (0)
; #define PG8_LDB(dst, b, h) do { _Pragma("unroll") for (int n = 0; n < 2; ++n) _Pragma("unroll") for (int k = 0; k < 2; ++k) dst[n][k] = *(const LAS bf16x8*)(lds + PG8_SB(b, h) + boff + n * 2048 + k * 1024); } while (0)
; #define PG8_MMA(ai, bj, At, Bt) do { __builtin_amdgcn_s_setprio(1); _Pragma("unroll") for (int m = 0; m < 4; ++m) _Pragma("unroll") for (int n = 0; n < 2; ++n) _Pragma("unroll") for (int k = 0; k < 2; ++k) \
;         acc[ai][bj][m][n] = __builtin_amdgcn_mfma_f32_16x16x32_bf16(Bt[n][k], At[m][k], acc[ai][bj][m][n], 0, 0, 0); __builtin_amdgcn_s_setprio(0); } while (0)
; #define PG8_WAIT_L(n) asm volatile("s_waitcnt lgkmcnt(" #n ")" ::: "memory")
; #define PG8_BAR __builtin_amdgcn_s_barrier()
; #define PG8_SCHED __builtin_amdgcn_sched_barrier(0)
; template <class Map, class Epi>
; DI void gemm_phase(LAS unsigned char* lds, const Map& MP, const Epi& E, const int nM, const int nN, const int K, const int lda, const int ldb) {
;     ...
;             PG8_LDB(B0, 0, 0); PG8_SCHED; PG8_LDA(At, 0, 0); PG8_STAGE(PG8_SA(1, 1), a1 + hstepA, voffA);
;             PG8_WAIT_L(8); PG8_BAR; PG8_WAIT_L(0); PG8_MMA(0, 0, At, B0); PG8_BAR; PG8_SCHED;
;             PG8_LDB(B1, 0, 1); PG8_STAGE(PG8_SB(0, 0), b2, voffB);
;             PG8_BAR; PG8_WAIT_L(0); PG8_MMA(0, 1, At, B1); PG8_BAR;
;             PG8_LDA(At, 0, 1); PG8_STAGE(PG8_SA(0, 0), a2, voffA);
;             PG8_BAR; PG8_WAIT_L(0); PG8_MMA(1, 0, At, B0); PG8_BAR; PG8_SCHED;
.LBB1_925:
	ds_read_b128 v[168:171], v150
	ds_read_b128 v[172:175], v150 offset:1024
	ds_read_b128 v[176:179], v150 offset:2048
	ds_read_b128 v[180:183], v150 offset:3072
	ds_read_b128 v[184:187], v150 offset:4096
	ds_read_b128 v[188:191], v150 offset:5120
	ds_read_b128 v[192:195], v150 offset:6144
	ds_read_b128 v[198:201], v150 offset:7168
	s_add_u32 s3, s10, 0xfff80080
	s_addc_u32 s12, s11, -1
	s_cmp_eq_u32 s48, 28
	s_cselect_b32 s15, s4, s12
	s_cselect_b32 s14, s5, s3
	s_cselect_b32 s13, s37, s47
	s_cselect_b32 s12, s38, s39
	s_add_i32 m0, s24, 0xc000
	s_nop 0
	global_load_lds_dwordx4 v138, s[10:11]
	s_add_i32 m0, s24, 0xe000
	s_nop 0
	global_load_lds_dwordx4 v136, s[10:11]
	s_waitcnt lgkmcnt(8)
	s_barrier
	s_setprio 1
	s_waitcnt lgkmcnt(7)
	v_mfma_f32_16x16x32_bf16 v[124:127], v[152:155], v[168:171], v[124:127]
	v_mfma_f32_16x16x32_bf16 v[120:123], v[160:163], v[168:171], v[120:123]
	s_waitcnt lgkmcnt(5)
	v_mfma_f32_16x16x32_bf16 v[108:111], v[152:155], v[176:179], v[108:111]
	v_mfma_f32_16x16x32_bf16 v[104:107], v[160:163], v[176:179], v[104:107]
	s_waitcnt lgkmcnt(3)
	v_mfma_f32_16x16x32_bf16 v[92:95], v[152:155], v[184:187], v[92:95]
	v_mfma_f32_16x16x32_bf16 v[88:91], v[160:163], v[184:187], v[88:91]
	s_waitcnt lgkmcnt(1)
	v_mfma_f32_16x16x32_bf16 v[76:79], v[152:155], v[192:195], v[76:79]
	v_mfma_f32_16x16x32_bf16 v[72:75], v[160:163], v[192:195], v[72:75]
	v_mfma_f32_16x16x32_bf16 v[124:127], v[156:159], v[172:175], v[124:127]
	v_mfma_f32_16x16x32_bf16 v[120:123], v[164:167], v[172:175], v[120:123]
	v_mfma_f32_16x16x32_bf16 v[108:111], v[156:159], v[180:183], v[108:111]
	v_mfma_f32_16x16x32_bf16 v[104:107], v[164:167], v[180:183], v[104:107]
	v_mfma_f32_16x16x32_bf16 v[92:95], v[156:159], v[188:191], v[92:95]
	v_mfma_f32_16x16x32_bf16 v[88:91], v[164:167], v[188:191], v[88:91]
	s_waitcnt lgkmcnt(0)
	v_mfma_f32_16x16x32_bf16 v[76:79], v[156:159], v[198:201], v[76:79]
	v_mfma_f32_16x16x32_bf16 v[72:75], v[164:167], v[198:201], v[72:75]
	s_setprio 0
	s_barrier
	ds_read_b128 v[202:205], v151
	ds_read_b128 v[206:209], v151 offset:1024
	ds_read_b128 v[210:213], v151 offset:2048
	ds_read_b128 v[214:217], v151 offset:3072
	s_add_i32 s3, s35, s22
	v_lshl_add_u64 v[144:145], s[12:13], 0, v[132:133]
	s_mov_b32 m0, s3
	s_nop 0
	global_load_lds_dwordx4 v[144:145], off
	v_lshl_add_u64 v[218:219], s[12:13], 0, v[128:129]
	s_add_i32 m0, s3, 0x2000
	s_nop 0
	global_load_lds_dwordx4 v[218:219], off
	s_barrier
	s_setprio 1
	s_waitcnt lgkmcnt(3)
	v_mfma_f32_16x16x32_bf16 v[116:119], v[202:205], v[168:171], v[116:119]
	s_waitcnt lgkmcnt(1)
	v_mfma_f32_16x16x32_bf16 v[112:115], v[210:213], v[168:171], v[112:115]
	v_mfma_f32_16x16x32_bf16 v[100:103], v[202:205], v[176:179], v[100:103]
	v_mfma_f32_16x16x32_bf16 v[96:99], v[210:213], v[176:179], v[96:99]
	v_mfma_f32_16x16x32_bf16 v[84:87], v[202:205], v[184:187], v[84:87]
	v_mfma_f32_16x16x32_bf16 v[80:83], v[210:213], v[184:187], v[80:83]
	v_mfma_f32_16x16x32_bf16 v[68:71], v[202:205], v[192:195], v[68:71]
	v_mfma_f32_16x16x32_bf16 v[64:67], v[210:213], v[192:195], v[64:67]
	v_mfma_f32_16x16x32_bf16 v[116:119], v[206:209], v[172:175], v[116:119]
	s_mov_b32 m0, s24
	s_waitcnt lgkmcnt(0)
	v_mfma_f32_16x16x32_bf16 v[112:115], v[214:217], v[172:175], v[112:115]
	v_lshl_add_u64 v[220:221], s[14:15], 0, v[134:135]
	v_mfma_f32_16x16x32_bf16 v[100:103], v[206:209], v[180:183], v[100:103]
	v_mfma_f32_16x16x32_bf16 v[96:99], v[214:217], v[180:183], v[96:99]
	v_mfma_f32_16x16x32_bf16 v[84:87], v[206:209], v[188:191], v[84:87]
	v_mfma_f32_16x16x32_bf16 v[80:83], v[214:217], v[188:191], v[80:83]
	v_mfma_f32_16x16x32_bf16 v[68:71], v[206:209], v[198:201], v[68:71]
	v_mfma_f32_16x16x32_bf16 v[64:67], v[214:217], v[198:201], v[64:67]
	s_setprio 0
	s_barrier
	ds_read_b128 v[168:171], v150 offset:16384
	ds_read_b128 v[172:175], v150 offset:17408
	ds_read_b128 v[176:179], v150 offset:18432
	ds_read_b128 v[180:183], v150 offset:19456
	ds_read_b128 v[184:187], v150 offset:20480
	ds_read_b128 v[188:191], v150 offset:21504
	ds_read_b128 v[192:195], v150 offset:22528
	ds_read_b128 v[198:201], v150 offset:23552
	global_load_lds_dwordx4 v[220:221], off
	v_lshl_add_u64 v[222:223], s[14:15], 0, v[130:131]
	s_mov_b32 m0, s9
	s_nop 0
	global_load_lds_dwordx4 v[222:223], off
	s_waitcnt vmcnt(10)
	s_barrier
	s_setprio 1
	s_waitcnt lgkmcnt(7)
	v_mfma_f32_16x16x32_bf16 v[60:63], v[152:155], v[168:171], v[60:63]
	v_mfma_f32_16x16x32_bf16 v[56:59], v[160:163], v[168:171], v[56:59]
	s_waitcnt lgkmcnt(5)
	v_mfma_f32_16x16x32_bf16 v[44:47], v[152:155], v[176:179], v[44:47]
	v_mfma_f32_16x16x32_bf16 v[40:43], v[160:163], v[176:179], v[40:43]
	s_waitcnt lgkmcnt(3)
	v_mfma_f32_16x16x32_bf16 v[28:31], v[152:155], v[184:187], v[28:31]
	v_mfma_f32_16x16x32_bf16 v[24:27], v[160:163], v[184:187], v[24:27]
	s_waitcnt lgkmcnt(1)
	v_mfma_f32_16x16x32_bf16 v[12:15], v[152:155], v[192:195], v[12:15]
	v_mfma_f32_16x16x32_bf16 v[8:11], v[160:163], v[192:195], v[8:11]
	v_mfma_f32_16x16x32_bf16 v[60:63], v[156:159], v[172:175], v[60:63]
	v_mfma_f32_16x16x32_bf16 v[56:59], v[164:167], v[172:175], v[56:59]
	v_mfma_f32_16x16x32_bf16 v[44:47], v[156:159], v[180:183], v[44:47]
	v_mfma_f32_16x16x32_bf16 v[40:43], v[164:167], v[180:183], v[40:43]
	v_mfma_f32_16x16x32_bf16 v[28:31], v[156:159], v[188:191], v[28:31]
	v_mfma_f32_16x16x32_bf16 v[24:27], v[164:167], v[188:191], v[24:27]
	s_waitcnt lgkmcnt(0)
	v_mfma_f32_16x16x32_bf16 v[12:15], v[156:159], v[198:201], v[12:15]
	v_mfma_f32_16x16x32_bf16 v[8:11], v[164:167], v[198:201], v[8:11]
	s_setprio 0
	s_barrier
; #define PG8_STAGE(bufoff, gbase, voff) do { _Pragma("unroll") for (int _i = 0; _i < 2; ++_i) \
;         __builtin_amdgcn_global_load_lds((const unsigned*)((const char*)(gbase) + (voff)[_i]), (LAS unsigned*)(lds + (bufoff) + ldsw + _i * 8192), 16, 0, 0); } while (0)
; #define PG8_LDA(dst, b, h) do { _Pragma("unroll") for (int m = 0; m < 4; ++m) _Pragma("unroll") for (int k = 0; k < 2; ++k) dst[m][k] = *(const LAS bf16x8*)(lds + PG8_SA(b, h) + aoff + m * 2048 + k * 1024); } while (0)
; #define PG8_LDB(dst, b, h) do { _Pragma("unroll") for (int n = 0; n < 2; ++n) _Pragma("unroll") for (int k = 0; k < 2; ++k) dst[n][k] = *(const LAS bf16x8*)(lds + PG8_SB(b, h) + boff + n * 2048 + k * 1024); } while (0)
; #define PG8_MMA(ai, bj, At, Bt) do { __builtin_amdgcn_s_setprio(1); _Pragma("unroll") for (int m = 0; m < 4; ++m) _Pragma("unroll") for (int n = 0; n < 2; ++n) _Pragma("unroll") for (int k = 0; k < 2; ++k) \
;         acc[ai][bj][m][n] = __builtin_amdgcn_mfma_f32_16x16x32_bf16(Bt[n][k], At[m][k], acc[ai][bj][m][n], 0, 0, 0); __builtin_amdgcn_s_setprio(0); } while (0)
; #define PG8_WAIT_V(n) asm volatile("s_waitcnt vmcnt(" #n ")" ::: "memory")
; #define PG8_WAIT_L(n) asm volatile("s_waitcnt lgkmcnt(" #n ")" ::: "memory")
; #define PG8_BAR __builtin_amdgcn_s_barrier()
; #define PG8_SCHED __builtin_amdgcn_sched_barrier(0)
; template <class Map, class Epi>
; DI void gemm_phase(LAS unsigned char* lds, const Map& MP, const Epi& E, const int nM, const int nN, const int K, const int lda, const int ldb) {
;     ...
;             PG8_STAGE(PG8_SB(0, 1), b2 + hstepB, voffB);
;             PG8_WAIT_V(6); PG8_BAR; PG8_MMA(1, 1, At, B1); PG8_BAR;
;             PG8_LDB(B0, 1, 0); PG8_SCHED; PG8_LDA(At, 1, 0); PG8_STAGE(PG8_SA(0, 1), a2 + hstepA, voffA);
;             PG8_WAIT_L(8); PG8_BAR; PG8_WAIT_L(0); PG8_MMA(0, 0, At, B0); PG8_BAR; PG8_SCHED;
;             PG8_LDB(B1, 1, 1); PG8_STAGE(PG8_SB(1, 0), b3, voffB);
;             PG8_BAR; PG8_WAIT_L(0); PG8_MMA(0, 1, At, B1); PG8_BAR;
;             PG8_LDA(At, 1, 1); PG8_STAGE(PG8_SA(1, 0), a3, voffA);
;             PG8_BAR; PG8_WAIT_L(0); PG8_MMA(1, 0, At, B0); PG8_BAR; PG8_SCHED;
	s_add_u32 s56, s12, 0x80000
	s_addc_u32 s57, s13, 0
	s_add_i32 s3, s36, s22
	s_mov_b32 m0, s3
	s_nop 0
	global_load_lds_dwordx4 v132, s[56:57]
	s_add_i32 m0, s3, 0x2000
	s_nop 0
	global_load_lds_dwordx4 v128, s[56:57]
	s_waitcnt vmcnt(6)
	s_barrier
	s_setprio 1
	v_mfma_f32_16x16x32_bf16 v[52:55], v[202:205], v[168:171], v[52:55]
	v_mfma_f32_16x16x32_bf16 v[48:51], v[210:213], v[168:171], v[48:51]
	s_add_i32 s3, 0, 0x18000
	v_add_u32_e32 v164, s3, v148
	ds_read_b128 v[152:155], v164
	v_mfma_f32_16x16x32_bf16 v[36:39], v[202:205], v[176:179], v[36:39]
	v_mfma_f32_16x16x32_bf16 v[32:35], v[210:213], v[176:179], v[32:35]
	ds_read_b128 v[156:159], v164 offset:1024
	v_mfma_f32_16x16x32_bf16 v[20:23], v[202:205], v[184:187], v[20:23]
	v_mfma_f32_16x16x32_bf16 v[16:19], v[210:213], v[184:187], v[16:19]
	ds_read_b128 v[160:163], v164 offset:2048
	v_mfma_f32_16x16x32_bf16 v[4:7], v[202:205], v[192:195], v[4:7]
	v_mfma_f32_16x16x32_bf16 v[0:3], v[210:213], v[192:195], v[0:3]
	ds_read_b128 v[164:167], v164 offset:3072
	v_mfma_f32_16x16x32_bf16 v[52:55], v[206:209], v[172:175], v[52:55]
	v_mfma_f32_16x16x32_bf16 v[48:51], v[214:217], v[172:175], v[48:51]
	v_mfma_f32_16x16x32_bf16 v[36:39], v[206:209], v[180:183], v[36:39]
	v_mfma_f32_16x16x32_bf16 v[32:35], v[214:217], v[180:183], v[32:35]
	v_mfma_f32_16x16x32_bf16 v[20:23], v[206:209], v[188:191], v[20:23]
	v_mfma_f32_16x16x32_bf16 v[16:19], v[214:217], v[188:191], v[16:19]
	v_mfma_f32_16x16x32_bf16 v[4:7], v[206:209], v[198:201], v[4:7]
	v_mfma_f32_16x16x32_bf16 v[0:3], v[214:217], v[198:201], v[0:3]
	s_setprio 0
	s_barrier
	ds_read_b128 v[168:171], v150 offset:32768
	ds_read_b128 v[172:175], v150 offset:33792
	ds_read_b128 v[176:179], v150 offset:34816
	ds_read_b128 v[180:183], v150 offset:35840
	ds_read_b128 v[184:187], v150 offset:36864
	ds_read_b128 v[188:191], v150 offset:37888
	ds_read_b128 v[192:195], v150 offset:38912
	ds_read_b128 v[198:201], v150 offset:39936
	s_add_u32 s14, s14, 0x80000
	s_addc_u32 s15, s15, 0
	s_mov_b32 m0, s25
	s_nop 0
	global_load_lds_dwordx4 v134, s[14:15]
	s_mov_b32 m0, s26
	s_nop 0
	global_load_lds_dwordx4 v130, s[14:15]
	s_waitcnt lgkmcnt(8)
	s_barrier
	s_setprio 1
	s_waitcnt lgkmcnt(7)
	v_mfma_f32_16x16x32_bf16 v[124:127], v[152:155], v[168:171], v[124:127]
	v_mfma_f32_16x16x32_bf16 v[120:123], v[160:163], v[168:171], v[120:123]
	s_waitcnt lgkmcnt(5)
	v_mfma_f32_16x16x32_bf16 v[108:111], v[152:155], v[176:179], v[108:111]
	v_mfma_f32_16x16x32_bf16 v[104:107], v[160:163], v[176:179], v[104:107]
	s_waitcnt lgkmcnt(3)
	v_mfma_f32_16x16x32_bf16 v[92:95], v[152:155], v[184:187], v[92:95]
	v_mfma_f32_16x16x32_bf16 v[88:91], v[160:163], v[184:187], v[88:91]
	s_waitcnt lgkmcnt(1)
	v_mfma_f32_16x16x32_bf16 v[76:79], v[152:155], v[192:195], v[76:79]
	v_mfma_f32_16x16x32_bf16 v[72:75], v[160:163], v[192:195], v[72:75]
	v_mfma_f32_16x16x32_bf16 v[124:127], v[156:159], v[172:175], v[124:127]
	v_mfma_f32_16x16x32_bf16 v[120:123], v[164:167], v[172:175], v[120:123]
	v_mfma_f32_16x16x32_bf16 v[108:111], v[156:159], v[180:183], v[108:111]
	v_mfma_f32_16x16x32_bf16 v[104:107], v[164:167], v[180:183], v[104:107]
	v_mfma_f32_16x16x32_bf16 v[92:95], v[156:159], v[188:191], v[92:95]
	v_mfma_f32_16x16x32_bf16 v[88:91], v[164:167], v[188:191], v[88:91]
	s_waitcnt lgkmcnt(0)
	v_mfma_f32_16x16x32_bf16 v[76:79], v[156:159], v[198:201], v[76:79]
	v_mfma_f32_16x16x32_bf16 v[72:75], v[164:167], v[198:201], v[72:75]
	s_setprio 0
	s_barrier
	s_add_i32 s14, 0, 0x1c000
	v_add_u32_e32 v196, s14, v148
	ds_read_b128 v[202:205], v196
	ds_read_b128 v[206:209], v196 offset:1024
	ds_read_b128 v[210:213], v196 offset:2048
	ds_read_b128 v[214:217], v196 offset:3072
	s_add_i32 s3, s3, s22
	v_lshl_add_u64 v[144:145], v[144:145], 0, s[44:45]
	s_mov_b32 m0, s3
	s_nop 0
	global_load_lds_dwordx4 v[144:145], off
	v_lshl_add_u64 v[144:145], v[218:219], 0, s[44:45]
	s_add_i32 m0, s3, 0x2000
	s_nop 0
	global_load_lds_dwordx4 v[144:145], off
	s_barrier
	s_setprio 1
	s_waitcnt lgkmcnt(3)
	v_mfma_f32_16x16x32_bf16 v[116:119], v[202:205], v[168:171], v[116:119]
	s_waitcnt lgkmcnt(1)
	v_mfma_f32_16x16x32_bf16 v[112:115], v[210:213], v[168:171], v[112:115]
	v_mfma_f32_16x16x32_bf16 v[100:103], v[202:205], v[176:179], v[100:103]
	v_mfma_f32_16x16x32_bf16 v[96:99], v[210:213], v[176:179], v[96:99]
	v_mfma_f32_16x16x32_bf16 v[84:87], v[202:205], v[184:187], v[84:87]
	v_mfma_f32_16x16x32_bf16 v[80:83], v[210:213], v[184:187], v[80:83]
	v_mfma_f32_16x16x32_bf16 v[68:71], v[202:205], v[192:195], v[68:71]
	v_mfma_f32_16x16x32_bf16 v[64:67], v[210:213], v[192:195], v[64:67]
	v_mfma_f32_16x16x32_bf16 v[116:119], v[206:209], v[172:175], v[116:119]
	s_mov_b32 m0, s30
	s_waitcnt lgkmcnt(0)
	v_mfma_f32_16x16x32_bf16 v[112:115], v[214:217], v[172:175], v[112:115]
	v_lshl_add_u64 v[144:145], v[220:221], 0, s[44:45]
	v_mfma_f32_16x16x32_bf16 v[100:103], v[206:209], v[180:183], v[100:103]
	v_mfma_f32_16x16x32_bf16 v[96:99], v[214:217], v[180:183], v[96:99]
	v_mfma_f32_16x16x32_bf16 v[84:87], v[206:209], v[188:191], v[84:87]
	v_mfma_f32_16x16x32_bf16 v[80:83], v[214:217], v[188:191], v[80:83]
	v_mfma_f32_16x16x32_bf16 v[68:71], v[206:209], v[198:201], v[68:71]
	v_mfma_f32_16x16x32_bf16 v[64:67], v[214:217], v[198:201], v[64:67]
	s_setprio 0
	s_barrier
	ds_read_b128 v[168:171], v150 offset:49152
	ds_read_b128 v[172:175], v150 offset:50176
	ds_read_b128 v[176:179], v150 offset:51200
	ds_read_b128 v[180:183], v150 offset:52224
	ds_read_b128 v[184:187], v150 offset:53248
	ds_read_b128 v[188:191], v150 offset:54272
	ds_read_b128 v[192:195], v150 offset:55296
	ds_read_b128 v[198:201], v150 offset:56320
	global_load_lds_dwordx4 v[144:145], off
	v_lshl_add_u64 v[144:145], v[222:223], 0, s[44:45]
	s_mov_b32 m0, s31
	s_nop 0
	global_load_lds_dwordx4 v[144:145], off
	s_waitcnt vmcnt(10)
	s_barrier
; DI unsigned pack2(float a, float b) { f32x2 v = {a, b}; hwbf16x2 r = __builtin_convertvector(v, hwbf16x2); return __builtin_bit_cast(unsigned, r); }
; DI float bflo(unsigned w) { return __uint_as_float(w << 16); }
; DI float bfhi(unsigned w) { return __uint_as_float(w & 0xffff0000u); }
; #define PG8_STAGE(bufoff, gbase, voff) do { _Pragma("unroll") for (int _i = 0; _i < 2; ++_i) \
;         __builtin_amdgcn_global_load_lds((const unsigned*)((const char*)(gbase) + (voff)[_i]), (LAS unsigned*)(lds + (bufoff) + ldsw + _i * 8192), 16, 0, 0); } while (0)
; #define PG8_WAIT_V(n) asm volatile("s_waitcnt vmcnt(" #n ")" ::: "memory")
; #define PG8_WAIT_L(n) asm volatile("s_waitcnt lgkmcnt(" #n ")" ::: "memory")
;     DI void operator()(const f32x4 (&acc)[2][2][4][2], const Unit& u, int wr, int wc, int fr, int fq) const {
;     ...
;         for (int ai = 0; ai < 2; ++ai)
; #pragma unroll
;             for (int m = 0; m < 4; ++m) { const size_t ro = (size_t)(row0 + ai * HALF + m * 16) * D + col0;
; #pragma unroll
;                 for (int bj = 0; bj < 2; ++bj) {
;                     f32x4 x0, x1;
;                     if constexpr (IB) { const u32x4 w = *(const u32x4*)((const bf16_t*)Xin + ro + bj * HALF);
;                         x0 = (f32x4){bflo(w[0]), bfhi(w[0]), bflo(w[1]), bfhi(w[1])}; x1 = (f32x4){bflo(w[2]), bfhi(w[2]), bflo(w[3]), bfhi(w[3])}; }
;                     else { x0 = *(const f32x4*)((const float*)Xin + ro + bj * HALF); x1 = *(const f32x4*)((const float*)Xin + ro + bj * HALF + 4); }
;                     x0 += acc[ai][bj][m][0] * sc[bj][0]; x1 += acc[ai][bj][m][1] * sc[bj][1];
;                     if constexpr (OB) { u32x4 o; o[0] = pack2(x0[0], x0[1]); o[1] = pack2(x0[2], x0[3]); o[2] = pack2(x1[0], x1[1]); o[3] = pack2(x1[2], x1[3]);
;                         *(u32x4*)((bf16_t*)Xout + ro + bj * HALF) = o; }
;                     else { *(f32x4*)((float*)Xout + ro + bj * HALF) = x0; *(f32x4*)((float*)Xout + ro + bj * HALF + 4) = x1; } } }
; template <class Map, class Epi>
; DI void gemm_phase(LAS unsigned char* lds, const Map& MP, const Epi& E, const int nM, const int nN, const int K, const int lda, const int ldb) {
;     ...
;             PG8_BAR; PG8_WAIT_L(0); PG8_MMA(1, 0, At, B0); PG8_BAR; PG8_SCHED;
;             PG8_STAGE(PG8_SB(1, 1), b3 + hstepB, voffB);
;             PG8_WAIT_V(6); PG8_BAR; PG8_MMA(1, 1, At, B1); PG8_BAR;
	s_setprio 1
	s_waitcnt lgkmcnt(7)
	v_mfma_f32_16x16x32_bf16 v[60:63], v[152:155], v[168:171], v[60:63]
	v_mfma_f32_16x16x32_bf16 v[56:59], v[160:163], v[168:171], v[56:59]
	s_waitcnt lgkmcnt(5)
	v_mfma_f32_16x16x32_bf16 v[44:47], v[152:155], v[176:179], v[44:47]
	v_mfma_f32_16x16x32_bf16 v[40:43], v[160:163], v[176:179], v[40:43]
	s_waitcnt lgkmcnt(3)
	v_mfma_f32_16x16x32_bf16 v[28:31], v[152:155], v[184:187], v[28:31]
	v_mfma_f32_16x16x32_bf16 v[24:27], v[160:163], v[184:187], v[24:27]
	s_waitcnt lgkmcnt(1)
	v_mfma_f32_16x16x32_bf16 v[12:15], v[152:155], v[192:195], v[12:15]
	v_mfma_f32_16x16x32_bf16 v[8:11], v[160:163], v[192:195], v[8:11]
	v_mfma_f32_16x16x32_bf16 v[60:63], v[156:159], v[172:175], v[60:63]
	v_mfma_f32_16x16x32_bf16 v[56:59], v[164:167], v[172:175], v[56:59]
	v_mfma_f32_16x16x32_bf16 v[44:47], v[156:159], v[180:183], v[44:47]
	v_mfma_f32_16x16x32_bf16 v[40:43], v[164:167], v[180:183], v[40:43]
	v_mfma_f32_16x16x32_bf16 v[28:31], v[156:159], v[188:191], v[28:31]
	v_mfma_f32_16x16x32_bf16 v[24:27], v[164:167], v[188:191], v[24:27]
	s_waitcnt lgkmcnt(0)
	v_mfma_f32_16x16x32_bf16 v[12:15], v[156:159], v[198:201], v[12:15]
	v_mfma_f32_16x16x32_bf16 v[8:11], v[164:167], v[198:201], v[8:11]
	s_setprio 0
	s_barrier
	s_add_u32 s12, s12, 0x80080
	s_addc_u32 s13, s13, 0
	s_add_i32 s3, s14, s22
	s_mov_b32 m0, s3
	s_nop 0
	global_load_lds_dwordx4 v132, s[12:13]
	s_add_i32 m0, s3, 0x2000
	s_nop 0
	global_load_lds_dwordx4 v128, s[12:13]
	s_waitcnt vmcnt(6)
	s_barrier
	s_setprio 1
	v_mfma_f32_16x16x32_bf16 v[52:55], v[202:205], v[168:171], v[52:55]
	v_mfma_f32_16x16x32_bf16 v[48:51], v[210:213], v[168:171], v[48:51]
	ds_read_b128 v[152:155], v149
	v_mfma_f32_16x16x32_bf16 v[36:39], v[202:205], v[176:179], v[36:39]
	v_mfma_f32_16x16x32_bf16 v[32:35], v[210:213], v[176:179], v[32:35]
	ds_read_b128 v[156:159], v149 offset:1024
	v_mfma_f32_16x16x32_bf16 v[20:23], v[202:205], v[184:187], v[20:23]
	v_mfma_f32_16x16x32_bf16 v[16:19], v[210:213], v[184:187], v[16:19]
	ds_read_b128 v[160:163], v149 offset:2048
	v_mfma_f32_16x16x32_bf16 v[4:7], v[202:205], v[192:195], v[4:7]
	v_mfma_f32_16x16x32_bf16 v[0:3], v[210:213], v[192:195], v[0:3]
	ds_read_b128 v[164:167], v149 offset:3072
	v_mfma_f32_16x16x32_bf16 v[52:55], v[206:209], v[172:175], v[52:55]
	s_add_i32 s48, s48, 2
	v_mfma_f32_16x16x32_bf16 v[48:51], v[214:217], v[172:175], v[48:51]
	s_add_u32 s39, s39, 0x100
	s_addc_u32 s47, s47, 0
	v_mfma_f32_16x16x32_bf16 v[36:39], v[206:209], v[180:183], v[36:39]
	s_add_u32 s10, s10, 0x100
	s_addc_u32 s11, s11, 0
	v_mfma_f32_16x16x32_bf16 v[32:35], v[214:217], v[180:183], v[32:35]
	s_cmp_gt_u32 s48, 29
	v_mfma_f32_16x16x32_bf16 v[20:23], v[206:209], v[188:191], v[20:23]
	v_mfma_f32_16x16x32_bf16 v[16:19], v[214:217], v[188:191], v[16:19]
	v_mfma_f32_16x16x32_bf16 v[4:7], v[206:209], v[198:201], v[4:7]
	v_mfma_f32_16x16x32_bf16 v[0:3], v[214:217], v[198:201], v[0:3]
	s_setprio 0
	s_barrier
	s_cbranch_scc0 .LBB1_925
	s_waitcnt lgkmcnt(0)
	v_mov_b32_e32 v152, v147
	v_mov_b32_e32 v144, v146
	s_lshl_b32 s2, s2, 8
	s_or_b32 s2, s2, s29
	v_lshl_add_u32 v144, v144, 3, s2
	s_lshl_b32 s2, s8, 8
	s_add_i32 s2, s2, s28
	v_add_u32_e32 v152, s2, v152
	v_ashrrev_i32_e32 v153, 31, v152
	v_lshlrev_b64 v[152:153], 12, v[152:153]
	v_ashrrev_i32_e32 v145, 31, v144
	v_lshl_add_u64 v[152:153], s[42:43], 0, v[152:153]
	v_lshl_add_u64 v[144:145], v[144:145], 1, v[152:153]
	global_load_dwordx4 v[160:163], v[144:145], off
	global_load_dwordx4 v[164:167], v[144:145], off offset:256
	s_mov_b64 s[98:99], 0x10000
	v_lshl_add_u64 v[154:155], v[144:145], 0, s[98:99]
	global_load_dwordx4 v[168:171], v[154:155], off
	global_load_dwordx4 v[172:175], v[154:155], off offset:256
	s_mov_b64 s[98:99], 0x20000
	v_lshl_add_u64 v[154:155], v[144:145], 0, s[98:99]
	global_load_dwordx4 v[176:179], v[154:155], off
	global_load_dwordx4 v[180:183], v[154:155], off offset:256
	s_mov_b64 s[98:99], 0x30000
	v_lshl_add_u64 v[154:155], v[144:145], 0, s[98:99]
	global_load_dwordx4 v[184:187], v[154:155], off
	global_load_dwordx4 v[188:191], v[154:155], off offset:256
	s_mov_b64 s[98:99], 0x80000
	v_lshl_add_u64 v[154:155], v[144:145], 0, s[98:99]
	global_load_dwordx4 v[192:195], v[154:155], off
	global_load_dwordx4 v[198:201], v[154:155], off offset:256
	s_mov_b64 s[98:99], 0x90000
	v_lshl_add_u64 v[154:155], v[144:145], 0, s[98:99]
	global_load_dwordx4 v[202:205], v[154:155], off
	global_load_dwordx4 v[206:209], v[154:155], off offset:256
	s_mov_b64 s[98:99], 0xa0000
	v_lshl_add_u64 v[154:155], v[144:145], 0, s[98:99]
	global_load_dwordx4 v[210:213], v[154:155], off
	global_load_dwordx4 v[214:217], v[154:155], off offset:256
	s_mov_b64 s[98:99], 0xb0000
	v_lshl_add_u64 v[154:155], v[144:145], 0, s[98:99]
	global_load_dwordx4 v[248:251], v[154:155], off
	global_load_dwordx4 v[252:255], v[154:155], off offset:256
	s_waitcnt vmcnt(15)
	s_nop 1
	v_mov_b32_e32 v152, v160
	v_mov_b32_e32 v153, v161
	v_mov_b32_e32 v154, v162
	v_mov_b32_e32 v155, v163
	s_mov_b64 s[2:3], 0x10000
	s_mov_b32 s8, s52
	s_mov_b64 s[10:11], s[6:7]
	s_mov_b64 s[12:13], s[54:55]
	s_waitcnt lgkmcnt(0)
	v_lshlrev_b32_e32 v156, 16, v152
	v_and_b32_e32 v157, 0xffff0000, v152
	v_lshlrev_b32_e32 v152, 16, v153
	v_and_b32_e32 v153, 0xffff0000, v153
	v_lshlrev_b32_e32 v158, 16, v154
	v_and_b32_e32 v159, 0xffff0000, v154
	v_lshlrev_b32_e32 v154, 16, v155
	v_and_b32_e32 v155, 0xffff0000, v155
	v_pk_add_f32 v[126:127], v[126:127], v[152:153]
	v_pk_add_f32 v[124:125], v[124:125], v[156:157]
	v_pk_add_f32 v[152:153], v[122:123], v[154:155]
	v_pk_add_f32 v[122:123], v[120:121], v[158:159]
	v_cvt_pk_bf16_f32 v120, v124, v125
	v_cvt_pk_bf16_f32 v121, v126, v127
	v_cvt_pk_bf16_f32 v122, v122, v123
	v_cvt_pk_bf16_f32 v123, v152, v153
	global_store_dwordx4 v[144:145], v[120:123], off
	s_waitcnt vmcnt(15)
; DI unsigned pack2(float a, float b) { f32x2 v = {a, b}; hwbf16x2 r = __builtin_convertvector(v, hwbf16x2); return __builtin_bit_cast(unsigned, r); }
; DI float bflo(unsigned w) { return __uint_as_float(w << 16); }
; DI float bfhi(unsigned w) { return __uint_as_float(w & 0xffff0000u); }
;     DI void operator()(const f32x4 (&acc)[2][2][4][2], const Unit& u, int wr, int wc, int fr, int fq) const {
;     ...
;         for (int ai = 0; ai < 2; ++ai)
; #pragma unroll
;             for (int m = 0; m < 4; ++m) { const size_t ro = (size_t)(row0 + ai * HALF + m * 16) * D + col0;
; #pragma unroll
;                 for (int bj = 0; bj < 2; ++bj) {
;                     f32x4 x0, x1;
;                     if constexpr (IB) { const u32x4 w = *(const u32x4*)((const bf16_t*)Xin + ro + bj * HALF);
;                         x0 = (f32x4){bflo(w[0]), bfhi(w[0]), bflo(w[1]), bfhi(w[1])}; x1 = (f32x4){bflo(w[2]), bfhi(w[2]), bflo(w[3]), bfhi(w[3])}; }
;                     else { x0 = *(const f32x4*)((const float*)Xin + ro + bj * HALF); x1 = *(const f32x4*)((const float*)Xin + ro + bj * HALF + 4); }
;                     x0 += acc[ai][bj][m][0] * sc[bj][0]; x1 += acc[ai][bj][m][1] * sc[bj][1];
;                     if constexpr (OB) { u32x4 o; o[0] = pack2(x0[0], x0[1]); o[1] = pack2(x0[2], x0[3]); o[2] = pack2(x1[0], x1[1]); o[3] = pack2(x1[2], x1[3]);
;                         *(u32x4*)((bf16_t*)Xout + ro + bj * HALF) = o; }
;                     else { *(f32x4*)((float*)Xout + ro + bj * HALF) = x0; *(f32x4*)((float*)Xout + ro + bj * HALF + 4) = x1; } } }
	s_nop 1
	v_mov_b32_e32 v120, v164
	v_mov_b32_e32 v121, v165
	v_mov_b32_e32 v122, v166
	v_mov_b32_e32 v123, v167
	s_waitcnt lgkmcnt(0)
	v_lshlrev_b32_e32 v124, 16, v120
	v_and_b32_e32 v125, 0xffff0000, v120
	v_lshlrev_b32_e32 v120, 16, v121
	v_and_b32_e32 v121, 0xffff0000, v121
	v_lshlrev_b32_e32 v126, 16, v122
	v_and_b32_e32 v127, 0xffff0000, v122
	v_lshlrev_b32_e32 v122, 16, v123
	v_and_b32_e32 v123, 0xffff0000, v123
	v_pk_add_f32 v[116:117], v[116:117], v[124:125]
	v_pk_add_f32 v[118:119], v[118:119], v[120:121]
	v_pk_add_f32 v[120:121], v[114:115], v[122:123]
	v_pk_add_f32 v[114:115], v[112:113], v[126:127]
	v_cvt_pk_bf16_f32 v112, v116, v117
	v_lshl_add_u64 v[116:117], v[144:145], 0, s[2:3]
	s_mov_b32 s2, 0x10000
	v_cvt_pk_bf16_f32 v113, v118, v119
	v_add_co_u32_e32 v118, vcc, s2, v144
	v_cvt_pk_bf16_f32 v114, v114, v115
	v_cvt_pk_bf16_f32 v115, v120, v121
	v_addc_co_u32_e32 v119, vcc, 0, v145, vcc
	global_store_dwordx4 v[144:145], v[112:115], off offset:256
	s_waitcnt vmcnt(15)
	s_nop 1
	v_mov_b32_e32 v112, v168
	v_mov_b32_e32 v113, v169
	v_mov_b32_e32 v114, v170
	v_mov_b32_e32 v115, v171
	s_mov_b64 s[2:3], 0x20000
	s_waitcnt lgkmcnt(0)
	v_lshlrev_b32_e32 v120, 16, v112
	v_and_b32_e32 v121, 0xffff0000, v112
	v_lshlrev_b32_e32 v112, 16, v113
	v_and_b32_e32 v113, 0xffff0000, v113
	v_lshlrev_b32_e32 v122, 16, v114
	v_and_b32_e32 v123, 0xffff0000, v114
	v_lshlrev_b32_e32 v114, 16, v115
	v_and_b32_e32 v115, 0xffff0000, v115
	v_pk_add_f32 v[110:111], v[110:111], v[112:113]
	v_pk_add_f32 v[108:109], v[108:109], v[120:121]
	v_pk_add_f32 v[112:113], v[106:107], v[114:115]
	v_pk_add_f32 v[106:107], v[104:105], v[122:123]
	v_cvt_pk_bf16_f32 v104, v108, v109
	v_cvt_pk_bf16_f32 v105, v110, v111
	v_cvt_pk_bf16_f32 v106, v106, v107
	v_cvt_pk_bf16_f32 v107, v112, v113
	global_store_dwordx4 v[118:119], v[104:107], off
	s_waitcnt vmcnt(15)
	s_nop 1
	v_mov_b32_e32 v104, v172
	v_mov_b32_e32 v105, v173
	v_mov_b32_e32 v106, v174
	v_mov_b32_e32 v107, v175
	s_waitcnt lgkmcnt(0)
	v_lshlrev_b32_e32 v108, 16, v104
	v_and_b32_e32 v109, 0xffff0000, v104
	v_lshlrev_b32_e32 v104, 16, v105
	v_and_b32_e32 v105, 0xffff0000, v105
	v_lshlrev_b32_e32 v110, 16, v106
	v_and_b32_e32 v111, 0xffff0000, v106
	v_lshlrev_b32_e32 v106, 16, v107
	v_and_b32_e32 v107, 0xffff0000, v107
	v_pk_add_f32 v[100:101], v[100:101], v[108:109]
	v_pk_add_f32 v[102:103], v[102:103], v[104:105]
	v_pk_add_f32 v[104:105], v[98:99], v[106:107]
	v_pk_add_f32 v[98:99], v[96:97], v[110:111]
	v_cvt_pk_bf16_f32 v96, v100, v101
	v_lshl_add_u64 v[100:101], v[144:145], 0, s[2:3]
	s_mov_b32 s2, 0x20000
	v_cvt_pk_bf16_f32 v97, v102, v103
	v_add_co_u32_e32 v102, vcc, s2, v144
	v_cvt_pk_bf16_f32 v98, v98, v99
	v_cvt_pk_bf16_f32 v99, v104, v105
	v_addc_co_u32_e32 v103, vcc, 0, v145, vcc
	global_store_dwordx4 v[116:117], v[96:99], off offset:256
	s_waitcnt vmcnt(15)
	s_nop 1
	v_mov_b32_e32 v96, v176
	v_mov_b32_e32 v97, v177
	v_mov_b32_e32 v98, v178
	v_mov_b32_e32 v99, v179
	s_mov_b64 s[2:3], 0x30000
	s_waitcnt lgkmcnt(0)
	v_lshlrev_b32_e32 v104, 16, v96
	v_and_b32_e32 v105, 0xffff0000, v96
	v_lshlrev_b32_e32 v96, 16, v97
	v_and_b32_e32 v97, 0xffff0000, v97
	v_lshlrev_b32_e32 v106, 16, v98
	v_and_b32_e32 v107, 0xffff0000, v98
	v_lshlrev_b32_e32 v98, 16, v99
	v_and_b32_e32 v99, 0xffff0000, v99
	v_pk_add_f32 v[94:95], v[94:95], v[96:97]
	v_pk_add_f32 v[92:93], v[92:93], v[104:105]
	v_pk_add_f32 v[96:97], v[90:91], v[98:99]
	v_pk_add_f32 v[90:91], v[88:89], v[106:107]
	v_cvt_pk_bf16_f32 v88, v92, v93
	v_cvt_pk_bf16_f32 v89, v94, v95
	v_cvt_pk_bf16_f32 v90, v90, v91
	v_cvt_pk_bf16_f32 v91, v96, v97
	global_store_dwordx4 v[102:103], v[88:91], off
	s_waitcnt vmcnt(15)
	s_nop 1
	v_mov_b32_e32 v88, v180
	v_mov_b32_e32 v89, v181
	v_mov_b32_e32 v90, v182
	v_mov_b32_e32 v91, v183
	s_waitcnt lgkmcnt(0)
	v_lshlrev_b32_e32 v92, 16, v88
	v_and_b32_e32 v93, 0xffff0000, v88
	v_lshlrev_b32_e32 v88, 16, v89
	v_and_b32_e32 v89, 0xffff0000, v89
	v_lshlrev_b32_e32 v94, 16, v90
	v_and_b32_e32 v95, 0xffff0000, v90
	v_lshlrev_b32_e32 v90, 16, v91
	v_and_b32_e32 v91, 0xffff0000, v91
	v_pk_add_f32 v[86:87], v[86:87], v[88:89]
	v_pk_add_f32 v[84:85], v[84:85], v[92:93]
	v_pk_add_f32 v[88:89], v[82:83], v[90:91]
	v_pk_add_f32 v[82:83], v[80:81], v[94:95]
	v_cvt_pk_bf16_f32 v80, v84, v85
	v_cvt_pk_bf16_f32 v81, v86, v87
	v_cvt_pk_bf16_f32 v82, v82, v83
	v_cvt_pk_bf16_f32 v83, v88, v89
	global_store_dwordx4 v[100:101], v[80:83], off offset:256
	s_nop 1
	v_lshl_add_u64 v[80:81], v[144:145], 0, s[2:3]
	s_mov_b32 s2, 0x30000
	v_add_co_u32_e32 v86, vcc, s2, v144
	s_mov_b64 s[2:3], 0x80000
	s_nop 0
	v_addc_co_u32_e32 v87, vcc, 0, v145, vcc
	s_waitcnt vmcnt(15)
	s_nop 1
	v_mov_b32_e32 v82, v184
	v_mov_b32_e32 v83, v185
	v_mov_b32_e32 v84, v186
	v_mov_b32_e32 v85, v187
	s_waitcnt lgkmcnt(0)
	v_lshlrev_b32_e32 v88, 16, v82
	v_and_b32_e32 v89, 0xffff0000, v82
	v_lshlrev_b32_e32 v82, 16, v83
	v_and_b32_e32 v83, 0xffff0000, v83
	v_lshlrev_b32_e32 v90, 16, v84
	v_and_b32_e32 v91, 0xffff0000, v84
	v_lshlrev_b32_e32 v84, 16, v85
	v_and_b32_e32 v85, 0xffff0000, v85
	v_pk_add_f32 v[78:79], v[78:79], v[82:83]
	v_pk_add_f32 v[76:77], v[76:77], v[88:89]
	v_pk_add_f32 v[82:83], v[74:75], v[84:85]
	v_pk_add_f32 v[74:75], v[72:73], v[90:91]
	v_cvt_pk_bf16_f32 v72, v76, v77
	v_cvt_pk_bf16_f32 v73, v78, v79
	v_cvt_pk_bf16_f32 v74, v74, v75
	v_cvt_pk_bf16_f32 v75, v82, v83
	global_store_dwordx4 v[86:87], v[72:75], off
	s_waitcnt vmcnt(15)
	s_nop 1
	v_mov_b32_e32 v72, v188
	v_mov_b32_e32 v73, v189
	v_mov_b32_e32 v74, v190
	v_mov_b32_e32 v75, v191
	s_waitcnt lgkmcnt(0)
; DI unsigned pack2(float a, float b) { f32x2 v = {a, b}; hwbf16x2 r = __builtin_convertvector(v, hwbf16x2); return __builtin_bit_cast(unsigned, r); }
; DI float bflo(unsigned w) { return __uint_as_float(w << 16); }
; DI float bfhi(unsigned w) { return __uint_as_float(w & 0xffff0000u); }
;     DI void operator()(const f32x4 (&acc)[2][2][4][2], const Unit& u, int wr, int wc, int fr, int fq) const {
;     ...
;         for (int ai = 0; ai < 2; ++ai)
; #pragma unroll
;             for (int m = 0; m < 4; ++m) { const size_t ro = (size_t)(row0 + ai * HALF + m * 16) * D + col0;
; #pragma unroll
;                 for (int bj = 0; bj < 2; ++bj) {
;                     f32x4 x0, x1;
;                     if constexpr (IB) { const u32x4 w = *(const u32x4*)((const bf16_t*)Xin + ro + bj * HALF);
;                         x0 = (f32x4){bflo(w[0]), bfhi(w[0]), bflo(w[1]), bfhi(w[1])}; x1 = (f32x4){bflo(w[2]), bfhi(w[2]), bflo(w[3]), bfhi(w[3])}; }
;                     else { x0 = *(const f32x4*)((const float*)Xin + ro + bj * HALF); x1 = *(const f32x4*)((const float*)Xin + ro + bj * HALF + 4); }
;                     x0 += acc[ai][bj][m][0] * sc[bj][0]; x1 += acc[ai][bj][m][1] * sc[bj][1];
;                     if constexpr (OB) { u32x4 o; o[0] = pack2(x0[0], x0[1]); o[1] = pack2(x0[2], x0[3]); o[2] = pack2(x1[0], x1[1]); o[3] = pack2(x1[2], x1[3]);
;                         *(u32x4*)((bf16_t*)Xout + ro + bj * HALF) = o; }
;                     else { *(f32x4*)((float*)Xout + ro + bj * HALF) = x0; *(f32x4*)((float*)Xout + ro + bj * HALF + 4) = x1; } } }
	v_lshlrev_b32_e32 v76, 16, v72
	v_and_b32_e32 v77, 0xffff0000, v72
	v_lshlrev_b32_e32 v72, 16, v73
	v_and_b32_e32 v73, 0xffff0000, v73
	v_lshlrev_b32_e32 v78, 16, v74
	v_and_b32_e32 v79, 0xffff0000, v74
	v_lshlrev_b32_e32 v74, 16, v75
	v_and_b32_e32 v75, 0xffff0000, v75
	v_pk_add_f32 v[70:71], v[70:71], v[72:73]
	v_pk_add_f32 v[68:69], v[68:69], v[76:77]
	v_pk_add_f32 v[72:73], v[66:67], v[74:75]
	v_pk_add_f32 v[66:67], v[64:65], v[78:79]
	v_cvt_pk_bf16_f32 v64, v68, v69
	v_cvt_pk_bf16_f32 v65, v70, v71
	v_cvt_pk_bf16_f32 v66, v66, v67
	v_cvt_pk_bf16_f32 v67, v72, v73
	global_store_dwordx4 v[80:81], v[64:67], off offset:256
	s_nop 1
	v_lshl_add_u64 v[64:65], v[144:145], 0, s[2:3]
	s_mov_b32 s2, 0x80000
	v_add_co_u32_e32 v70, vcc, s2, v144
	s_mov_b64 s[2:3], 0x90000
	s_nop 0
	v_addc_co_u32_e32 v71, vcc, 0, v145, vcc
	s_waitcnt vmcnt(15)
	s_nop 1
	v_mov_b32_e32 v66, v192
	v_mov_b32_e32 v67, v193
	v_mov_b32_e32 v68, v194
	v_mov_b32_e32 v69, v195
	s_waitcnt lgkmcnt(0)
	v_lshlrev_b32_e32 v72, 16, v66
	v_and_b32_e32 v73, 0xffff0000, v66
	v_lshlrev_b32_e32 v66, 16, v67
	v_and_b32_e32 v67, 0xffff0000, v67
	v_lshlrev_b32_e32 v74, 16, v68
	v_and_b32_e32 v75, 0xffff0000, v68
	v_lshlrev_b32_e32 v68, 16, v69
	v_and_b32_e32 v69, 0xffff0000, v69
	v_pk_add_f32 v[62:63], v[62:63], v[66:67]
	v_pk_add_f32 v[60:61], v[60:61], v[72:73]
	v_pk_add_f32 v[66:67], v[58:59], v[68:69]
	v_pk_add_f32 v[58:59], v[56:57], v[74:75]
	v_cvt_pk_bf16_f32 v56, v60, v61
	v_cvt_pk_bf16_f32 v57, v62, v63
	v_cvt_pk_bf16_f32 v58, v58, v59
	v_cvt_pk_bf16_f32 v59, v66, v67
	global_store_dwordx4 v[70:71], v[56:59], off
	s_waitcnt vmcnt(15)
	s_nop 1
	v_mov_b32_e32 v56, v198
	v_mov_b32_e32 v57, v199
	v_mov_b32_e32 v58, v200
	v_mov_b32_e32 v59, v201
	s_waitcnt lgkmcnt(0)
	v_lshlrev_b32_e32 v60, 16, v56
	v_and_b32_e32 v61, 0xffff0000, v56
	v_lshlrev_b32_e32 v56, 16, v57
	v_and_b32_e32 v57, 0xffff0000, v57
	v_lshlrev_b32_e32 v62, 16, v58
	v_and_b32_e32 v63, 0xffff0000, v58
	v_lshlrev_b32_e32 v58, 16, v59
	v_and_b32_e32 v59, 0xffff0000, v59
	v_pk_add_f32 v[54:55], v[54:55], v[56:57]
	v_pk_add_f32 v[52:53], v[52:53], v[60:61]
	v_pk_add_f32 v[56:57], v[50:51], v[58:59]
	v_pk_add_f32 v[50:51], v[48:49], v[62:63]
	v_cvt_pk_bf16_f32 v48, v52, v53
	v_cvt_pk_bf16_f32 v49, v54, v55
	v_cvt_pk_bf16_f32 v50, v50, v51
	v_cvt_pk_bf16_f32 v51, v56, v57
	global_store_dwordx4 v[64:65], v[48:51], off offset:256
	s_nop 1
	v_lshl_add_u64 v[48:49], v[144:145], 0, s[2:3]
	s_mov_b32 s2, 0x90000
	v_add_co_u32_e32 v54, vcc, s2, v144
	s_mov_b64 s[2:3], 0xa0000
	s_nop 0
	v_addc_co_u32_e32 v55, vcc, 0, v145, vcc
	s_waitcnt vmcnt(15)
	s_nop 1
	v_mov_b32_e32 v50, v202
	v_mov_b32_e32 v51, v203
	v_mov_b32_e32 v52, v204
	v_mov_b32_e32 v53, v205
	s_waitcnt lgkmcnt(0)
	v_lshlrev_b32_e32 v56, 16, v50
	v_and_b32_e32 v57, 0xffff0000, v50
	v_lshlrev_b32_e32 v50, 16, v51
	v_and_b32_e32 v51, 0xffff0000, v51
	v_lshlrev_b32_e32 v58, 16, v52
	v_and_b32_e32 v59, 0xffff0000, v52
	v_lshlrev_b32_e32 v52, 16, v53
	v_and_b32_e32 v53, 0xffff0000, v53
	v_pk_add_f32 v[46:47], v[46:47], v[50:51]
	v_pk_add_f32 v[44:45], v[44:45], v[56:57]
	v_pk_add_f32 v[50:51], v[42:43], v[52:53]
	v_pk_add_f32 v[42:43], v[40:41], v[58:59]
	v_cvt_pk_bf16_f32 v40, v44, v45
	v_cvt_pk_bf16_f32 v41, v46, v47
	v_cvt_pk_bf16_f32 v42, v42, v43
	v_cvt_pk_bf16_f32 v43, v50, v51
	global_store_dwordx4 v[54:55], v[40:43], off
	s_waitcnt vmcnt(15)
	s_nop 1
	v_mov_b32_e32 v40, v206
	v_mov_b32_e32 v41, v207
	v_mov_b32_e32 v42, v208
	v_mov_b32_e32 v43, v209
	s_waitcnt lgkmcnt(0)
; DI unsigned pack2(float a, float b) { f32x2 v = {a, b}; hwbf16x2 r = __builtin_convertvector(v, hwbf16x2); return __builtin_bit_cast(unsigned, r); }
; DI float bflo(unsigned w) { return __uint_as_float(w << 16); }
; DI float bfhi(unsigned w) { return __uint_as_float(w & 0xffff0000u); }
; #define PG8_WAIT_V(n) asm volatile("s_waitcnt vmcnt(" #n ")" ::: "memory")
; #define PG8_BAR __builtin_amdgcn_s_barrier()
;     DI void operator()(const f32x4 (&acc)[2][2][4][2], const Unit& u, int wr, int wc, int fr, int fq) const {
;     ...
;         for (int ai = 0; ai < 2; ++ai)
; #pragma unroll
;             for (int m = 0; m < 4; ++m) { const size_t ro = (size_t)(row0 + ai * HALF + m * 16) * D + col0;
; #pragma unroll
;                 for (int bj = 0; bj < 2; ++bj) {
;                     f32x4 x0, x1;
;                     if constexpr (IB) { const u32x4 w = *(const u32x4*)((const bf16_t*)Xin + ro + bj * HALF);
;                         x0 = (f32x4){bflo(w[0]), bfhi(w[0]), bflo(w[1]), bfhi(w[1])}; x1 = (f32x4){bflo(w[2]), bfhi(w[2]), bflo(w[3]), bfhi(w[3])}; }
;                     else { x0 = *(const f32x4*)((const float*)Xin + ro + bj * HALF); x1 = *(const f32x4*)((const float*)Xin + ro + bj * HALF + 4); }
;                     x0 += acc[ai][bj][m][0] * sc[bj][0]; x1 += acc[ai][bj][m][1] * sc[bj][1];
;                     if constexpr (OB) { u32x4 o; o[0] = pack2(x0[0], x0[1]); o[1] = pack2(x0[2], x0[3]); o[2] = pack2(x1[0], x1[1]); o[3] = pack2(x1[2], x1[3]);
;                         *(u32x4*)((bf16_t*)Xout + ro + bj * HALF) = o; }
;                     else { *(f32x4*)((float*)Xout + ro + bj * HALF) = x0; *(f32x4*)((float*)Xout + ro + bj * HALF + 4) = x1; } } }
; template <class Map, class Epi>
; DI void gemm_phase(LAS unsigned char* lds, const Map& MP, const Epi& E, const int nM, const int nN, const int K, const int lda, const int ldb) {
;     ...
;         cur = nxt; cA = nA; cB = nB; ++ui;
;     }
;     PG8_WAIT_V(0);
;     if (wr == 0) PG8_BAR;
;     PG8_BAR;
	v_lshlrev_b32_e32 v44, 16, v40
	v_and_b32_e32 v45, 0xffff0000, v40
	v_lshlrev_b32_e32 v40, 16, v41
	v_and_b32_e32 v41, 0xffff0000, v41
	v_lshlrev_b32_e32 v46, 16, v42
	v_and_b32_e32 v47, 0xffff0000, v42
	v_lshlrev_b32_e32 v42, 16, v43
	v_and_b32_e32 v43, 0xffff0000, v43
	v_pk_add_f32 v[38:39], v[38:39], v[40:41]
	v_pk_add_f32 v[36:37], v[36:37], v[44:45]
	v_pk_add_f32 v[40:41], v[34:35], v[42:43]
	v_pk_add_f32 v[34:35], v[32:33], v[46:47]
	v_cvt_pk_bf16_f32 v32, v36, v37
	v_cvt_pk_bf16_f32 v33, v38, v39
	v_cvt_pk_bf16_f32 v34, v34, v35
	v_cvt_pk_bf16_f32 v35, v40, v41
	global_store_dwordx4 v[48:49], v[32:35], off offset:256
	s_nop 1
	v_lshl_add_u64 v[32:33], v[144:145], 0, s[2:3]
	s_mov_b32 s2, 0xa0000
	v_add_co_u32_e32 v38, vcc, s2, v144
	s_mov_b64 s[2:3], 0xb0000
	s_nop 0
	v_addc_co_u32_e32 v39, vcc, 0, v145, vcc
	s_waitcnt vmcnt(15)
	s_nop 1
	v_mov_b32_e32 v34, v210
	v_mov_b32_e32 v35, v211
	v_mov_b32_e32 v36, v212
	v_mov_b32_e32 v37, v213
	s_waitcnt lgkmcnt(0)
	v_lshlrev_b32_e32 v40, 16, v34
	v_and_b32_e32 v41, 0xffff0000, v34
	v_lshlrev_b32_e32 v34, 16, v35
	v_and_b32_e32 v35, 0xffff0000, v35
	v_lshlrev_b32_e32 v42, 16, v36
	v_and_b32_e32 v43, 0xffff0000, v36
	v_lshlrev_b32_e32 v36, 16, v37
	v_and_b32_e32 v37, 0xffff0000, v37
	v_pk_add_f32 v[30:31], v[30:31], v[34:35]
	v_pk_add_f32 v[28:29], v[28:29], v[40:41]
	v_pk_add_f32 v[34:35], v[26:27], v[36:37]
	v_pk_add_f32 v[26:27], v[24:25], v[42:43]
	v_cvt_pk_bf16_f32 v24, v28, v29
	v_cvt_pk_bf16_f32 v25, v30, v31
	v_cvt_pk_bf16_f32 v26, v26, v27
	v_cvt_pk_bf16_f32 v27, v34, v35
	global_store_dwordx4 v[38:39], v[24:27], off
	s_waitcnt vmcnt(15)
	s_nop 1
	v_mov_b32_e32 v24, v214
	v_mov_b32_e32 v25, v215
	v_mov_b32_e32 v26, v216
	v_mov_b32_e32 v27, v217
	s_waitcnt lgkmcnt(0)
	v_lshlrev_b32_e32 v28, 16, v24
	v_and_b32_e32 v29, 0xffff0000, v24
	v_lshlrev_b32_e32 v24, 16, v25
	v_and_b32_e32 v25, 0xffff0000, v25
	v_lshlrev_b32_e32 v30, 16, v26
	v_and_b32_e32 v31, 0xffff0000, v26
	v_lshlrev_b32_e32 v26, 16, v27
	v_and_b32_e32 v27, 0xffff0000, v27
	v_pk_add_f32 v[22:23], v[22:23], v[24:25]
	v_pk_add_f32 v[20:21], v[20:21], v[28:29]
	v_pk_add_f32 v[24:25], v[18:19], v[26:27]
	v_pk_add_f32 v[18:19], v[16:17], v[30:31]
	v_cvt_pk_bf16_f32 v16, v20, v21
	v_cvt_pk_bf16_f32 v17, v22, v23
	v_cvt_pk_bf16_f32 v18, v18, v19
	v_cvt_pk_bf16_f32 v19, v24, v25
	global_store_dwordx4 v[32:33], v[16:19], off offset:256
	s_nop 1
	v_lshl_add_u64 v[16:17], v[144:145], 0, s[2:3]
	s_mov_b32 s2, 0xb0000
	v_add_co_u32_e32 v22, vcc, s2, v144
	s_mov_b32 s2, s46
	s_nop 0
	v_addc_co_u32_e32 v23, vcc, 0, v145, vcc
	s_waitcnt vmcnt(15)
	s_nop 1
	v_mov_b32_e32 v18, v248
	v_mov_b32_e32 v19, v249
	v_mov_b32_e32 v20, v250
	v_mov_b32_e32 v21, v251
	s_and_b64 vcc, exec, s[40:41]
	s_waitcnt lgkmcnt(0)
	v_lshlrev_b32_e32 v24, 16, v18
	v_and_b32_e32 v25, 0xffff0000, v18
	v_lshlrev_b32_e32 v18, 16, v19
	v_and_b32_e32 v19, 0xffff0000, v19
	v_lshlrev_b32_e32 v26, 16, v20
	v_and_b32_e32 v27, 0xffff0000, v20
	v_lshlrev_b32_e32 v20, 16, v21
	v_and_b32_e32 v21, 0xffff0000, v21
	v_pk_add_f32 v[14:15], v[14:15], v[18:19]
	v_pk_add_f32 v[12:13], v[12:13], v[24:25]
	v_pk_add_f32 v[18:19], v[10:11], v[20:21]
	v_pk_add_f32 v[10:11], v[8:9], v[26:27]
	v_cvt_pk_bf16_f32 v8, v12, v13
	v_cvt_pk_bf16_f32 v9, v14, v15
	v_cvt_pk_bf16_f32 v10, v10, v11
	v_cvt_pk_bf16_f32 v11, v18, v19
	global_store_dwordx4 v[22:23], v[8:11], off
	s_waitcnt vmcnt(15)
	s_nop 1
	v_mov_b32_e32 v8, v252
	v_mov_b32_e32 v9, v253
	v_mov_b32_e32 v10, v254
	v_mov_b32_e32 v11, v255
	s_waitcnt lgkmcnt(0)
	v_lshlrev_b32_e32 v12, 16, v8
	v_and_b32_e32 v13, 0xffff0000, v8
	v_lshlrev_b32_e32 v8, 16, v9
	v_and_b32_e32 v9, 0xffff0000, v9
	v_lshlrev_b32_e32 v14, 16, v10
	v_and_b32_e32 v15, 0xffff0000, v10
	v_lshlrev_b32_e32 v10, 16, v11
	v_and_b32_e32 v11, 0xffff0000, v11
	v_pk_add_f32 v[6:7], v[6:7], v[8:9]
	v_pk_add_f32 v[4:5], v[4:5], v[12:13]
	v_pk_add_f32 v[8:9], v[2:3], v[10:11]
	v_pk_add_f32 v[2:3], v[0:1], v[14:15]
	v_cvt_pk_bf16_f32 v0, v4, v5
	v_cvt_pk_bf16_f32 v1, v6, v7
	v_cvt_pk_bf16_f32 v2, v2, v3
	v_cvt_pk_bf16_f32 v3, v8, v9
	global_store_dwordx4 v[16:17], v[0:3], off offset:256
	s_cbranch_vccz .LBB1_922
	s_waitcnt vmcnt(0)
	s_cmpk_gt_u32 s17, 0xff
	s_cbranch_scc1 .LBB1_929
	s_barrier

; #define PG8_STAGE(bufoff, gbase, voff) do { _Pragma("unroll") for (int _i = 0; _i < 2; ++_i) \
;         __builtin_amdgcn_global_load_lds((const unsigned*)((const char*)(gbase) + (voff)[_i]), (LAS unsigned*)(lds + (bufoff) + ldsw + _i * 8192), 16, 0, 0); } while (0)
; #define PG8_LDA(dst, b, h) do { _Pragma("unroll") for (int m = 0; m < 4; ++m) _Pragma("unroll") for (int k = 0; k < 2; ++k) dst[m][k] = *(const LAS bf16x8*)(lds + PG8_SA(b, h) + aoff + m * 2048 + k * 1024); } while (0)
; #define PG8_LDB(dst, b, h) do { _Pragma("unroll") for (int n = 0; n < 2; ++n) _Pragma("unroll") for (int k = 0; k < 2; ++k) dst[n][k] = *(const LAS bf16x8*)(lds + PG8_SB(b, h) + boff + n * 2048 + k * 1024); } while (0)
; #define PG8_MMA(ai, bj, At, Bt) do { __builtin_amdgcn_s_setprio(1); _Pragma("unroll") for (int m = 0; m < 4; ++m) _Pragma("unroll") for (int n = 0; n < 2; ++n) _Pragma("unroll") for (int k = 0; k < 2; ++k) \
;         acc[ai][bj][m][n] = __builtin_amdgcn_mfma_f32_16x16x32_bf16(Bt[n][k], At[m][k], acc[ai][bj][m][n], 0, 0, 0); __builtin_amdgcn_s_setprio(0); } while (0)
; #define PG8_WAIT_V(n) asm volatile("s_waitcnt vmcnt(" #n ")" ::: "memory")
; #define PG8_WAIT_L(n) asm volatile("s_waitcnt lgkmcnt(" #n ")" ::: "memory")
; #define PG8_BAR __builtin_amdgcn_s_barrier()
; #define PG8_SCHED __builtin_amdgcn_sched_barrier(0)
; template <class Map, class Epi>
; DI void gemm_phase(LAS unsigned char* lds, const Map& MP, const Epi& E, const int nM, const int nN, const int K, const int lda, const int ldb) {
;     ...
;             PG8_LDB(B0, 0, 0); PG8_SCHED; PG8_LDA(At, 0, 0); PG8_STAGE(PG8_SA(1, 1), a1 + hstepA, voffA);
;             PG8_WAIT_L(8); PG8_BAR; PG8_WAIT_L(0); PG8_MMA(0, 0, At, B0); PG8_BAR; PG8_SCHED;
;             PG8_LDB(B1, 0, 1); PG8_STAGE(PG8_SB(0, 0), b2, voffB);
;             PG8_BAR; PG8_WAIT_L(0); PG8_MMA(0, 1, At, B1); PG8_BAR;
;             PG8_LDA(At, 0, 1); PG8_STAGE(PG8_SA(0, 0), a2, voffA);
;             PG8_BAR; PG8_WAIT_L(0); PG8_MMA(1, 0, At, B0); PG8_BAR; PG8_SCHED;
;             PG8_STAGE(PG8_SB(0, 1), b2 + hstepB, voffB);
;             PG8_WAIT_V(6); PG8_BAR; PG8_MMA(1, 1, At, B1); PG8_BAR;
.LBB1_1069:
	ds_read_b128 v[96:99], v190
	ds_read_b128 v[100:103], v190 offset:1024
	ds_read_b128 v[108:111], v190 offset:2048
	ds_read_b128 v[112:115], v190 offset:3072
	ds_read_b128 v[160:163], v190 offset:4096
	ds_read_b128 v[164:167], v190 offset:5120
	ds_read_b128 v[198:201], v190 offset:6144
	ds_read_b128 v[202:205], v190 offset:7168
	s_add_u32 s24, s42, 0xfff80080
	s_addc_u32 s25, s43, -1
	s_cmp_eq_u32 s3, 28
	s_cselect_b32 s47, s23, s25
	s_cselect_b32 s46, s58, s24
	s_cselect_b32 s25, s21, vcc_hi
	s_cselect_b32 s24, s59, vcc_lo
	s_add_i32 m0, s38, 0xc000
	s_nop 0
	global_load_lds_dwordx4 v178, s[42:43]
	s_add_i32 m0, s38, 0xe000
	s_nop 0
	global_load_lds_dwordx4 v176, s[42:43]
	s_waitcnt lgkmcnt(8)
	s_barrier
	s_setprio 1
	s_waitcnt lgkmcnt(7)
	v_mfma_f32_16x16x32_bf16 v[148:151], v[80:83], v[96:99], v[148:151]
	v_mfma_f32_16x16x32_bf16 v[144:147], v[88:91], v[96:99], v[144:147]
	s_waitcnt lgkmcnt(5)
	v_mfma_f32_16x16x32_bf16 v[136:139], v[80:83], v[108:111], v[136:139]
	v_mfma_f32_16x16x32_bf16 v[128:131], v[88:91], v[108:111], v[128:131]
	s_waitcnt lgkmcnt(3)
	v_mfma_f32_16x16x32_bf16 v[120:123], v[80:83], v[160:163], v[120:123]
	v_mfma_f32_16x16x32_bf16 v[104:107], v[88:91], v[160:163], v[104:107]
	s_waitcnt lgkmcnt(1)
	v_mfma_f32_16x16x32_bf16 v[76:79], v[80:83], v[198:201], v[76:79]
	v_mfma_f32_16x16x32_bf16 v[72:75], v[88:91], v[198:201], v[72:75]
	v_mfma_f32_16x16x32_bf16 v[148:151], v[84:87], v[100:103], v[148:151]
	v_mfma_f32_16x16x32_bf16 v[144:147], v[92:95], v[100:103], v[144:147]
	v_mfma_f32_16x16x32_bf16 v[136:139], v[84:87], v[112:115], v[136:139]
	v_mfma_f32_16x16x32_bf16 v[128:131], v[92:95], v[112:115], v[128:131]
	v_mfma_f32_16x16x32_bf16 v[120:123], v[84:87], v[164:167], v[120:123]
	v_mfma_f32_16x16x32_bf16 v[104:107], v[92:95], v[164:167], v[104:107]
	s_waitcnt lgkmcnt(0)
	v_mfma_f32_16x16x32_bf16 v[76:79], v[84:87], v[202:205], v[76:79]
	v_mfma_f32_16x16x32_bf16 v[72:75], v[92:95], v[202:205], v[72:75]
	s_setprio 0
	s_barrier
	ds_read_b128 v[206:209], v191
	ds_read_b128 v[210:213], v191 offset:1024
	ds_read_b128 v[214:217], v191 offset:2048
	ds_read_b128 v[218:221], v191 offset:3072
	s_add_i32 s68, s31, s66
	v_lshl_add_u64 v[184:185], s[24:25], 0, v[172:173]
	s_mov_b32 m0, s68
	s_nop 0
	global_load_lds_dwordx4 v[184:185], off
	v_lshl_add_u64 v[194:195], s[24:25], 0, v[168:169]
	s_add_i32 m0, s68, 0x2000
	s_nop 0
	global_load_lds_dwordx4 v[194:195], off
	s_barrier
	s_setprio 1
	s_waitcnt lgkmcnt(3)
	v_mfma_f32_16x16x32_bf16 v[156:159], v[206:209], v[96:99], v[156:159]
	s_waitcnt lgkmcnt(1)
	v_mfma_f32_16x16x32_bf16 v[96:99], v[214:217], v[96:99], v[152:155]
	v_mfma_f32_16x16x32_bf16 v[156:159], v[210:213], v[100:103], v[156:159]
	s_waitcnt lgkmcnt(0)
	v_mfma_f32_16x16x32_bf16 v[96:99], v[218:221], v[100:103], v[96:99]
	v_mfma_f32_16x16x32_bf16 v[100:103], v[206:209], v[108:111], v[140:143]
	v_mfma_f32_16x16x32_bf16 v[108:111], v[214:217], v[108:111], v[132:135]
	v_mfma_f32_16x16x32_bf16 v[116:119], v[214:217], v[160:163], v[116:119]
	v_mfma_f32_16x16x32_bf16 v[68:71], v[206:209], v[198:201], v[68:71]
	v_mfma_f32_16x16x32_bf16 v[64:67], v[214:217], v[198:201], v[64:67]
	s_mov_b32 m0, s38
	v_mfma_f32_16x16x32_bf16 v[100:103], v[210:213], v[112:115], v[100:103]
	v_lshl_add_u64 v[226:227], s[46:47], 0, v[174:175]
	v_mfma_f32_16x16x32_bf16 v[108:111], v[218:221], v[112:115], v[108:111]
	v_mfma_f32_16x16x32_bf16 v[112:115], v[206:209], v[160:163], v[124:127]
	v_mfma_f32_16x16x32_bf16 v[116:119], v[218:221], v[164:167], v[116:119]
	v_mfma_f32_16x16x32_bf16 v[68:71], v[210:213], v[202:205], v[68:71]
	v_mfma_f32_16x16x32_bf16 v[64:67], v[218:221], v[202:205], v[64:67]
	v_mfma_f32_16x16x32_bf16 v[112:115], v[210:213], v[164:167], v[112:115]
	s_setprio 0
	s_barrier
	ds_read_b128 v[124:127], v190 offset:16384
	ds_read_b128 v[132:135], v190 offset:17408
	ds_read_b128 v[140:143], v190 offset:18432
	ds_read_b128 v[152:155], v190 offset:19456
	ds_read_b128 v[160:163], v190 offset:20480
	ds_read_b128 v[164:167], v190 offset:21504
	ds_read_b128 v[198:201], v190 offset:22528
	ds_read_b128 v[202:205], v190 offset:23552
	global_load_lds_dwordx4 v[226:227], off
	v_lshl_add_u64 v[234:235], s[46:47], 0, v[170:171]
	s_mov_b32 m0, s39
	s_nop 0
	global_load_lds_dwordx4 v[234:235], off
	s_waitcnt vmcnt(10)
	s_barrier
	s_setprio 1
	s_waitcnt lgkmcnt(7)
	v_mfma_f32_16x16x32_bf16 v[60:63], v[80:83], v[124:127], v[60:63]
	v_mfma_f32_16x16x32_bf16 v[48:51], v[88:91], v[124:127], v[48:51]
	s_waitcnt lgkmcnt(5)
	v_mfma_f32_16x16x32_bf16 v[40:43], v[80:83], v[140:143], v[40:43]
	v_mfma_f32_16x16x32_bf16 v[32:35], v[88:91], v[140:143], v[32:35]
	s_waitcnt lgkmcnt(3)
	v_mfma_f32_16x16x32_bf16 v[24:27], v[80:83], v[160:163], v[24:27]
	v_mfma_f32_16x16x32_bf16 v[16:19], v[88:91], v[160:163], v[16:19]
	s_waitcnt lgkmcnt(1)
	v_mfma_f32_16x16x32_bf16 v[12:15], v[80:83], v[198:201], v[12:15]
	v_mfma_f32_16x16x32_bf16 v[8:11], v[88:91], v[198:201], v[8:11]
	v_mfma_f32_16x16x32_bf16 v[60:63], v[84:87], v[132:135], v[60:63]
	v_mfma_f32_16x16x32_bf16 v[48:51], v[92:95], v[132:135], v[48:51]
	v_mfma_f32_16x16x32_bf16 v[40:43], v[84:87], v[152:155], v[40:43]
	v_mfma_f32_16x16x32_bf16 v[32:35], v[92:95], v[152:155], v[32:35]
	v_mfma_f32_16x16x32_bf16 v[24:27], v[84:87], v[164:167], v[24:27]
	v_mfma_f32_16x16x32_bf16 v[16:19], v[92:95], v[164:167], v[16:19]
	s_waitcnt lgkmcnt(0)
	v_mfma_f32_16x16x32_bf16 v[12:15], v[84:87], v[202:205], v[12:15]
	v_mfma_f32_16x16x32_bf16 v[8:11], v[92:95], v[202:205], v[8:11]
	s_setprio 0
	s_barrier
	s_add_u32 s68, s24, 0x80000
	s_addc_u32 s69, s25, 0
	s_add_i32 s70, s2, s66
	s_mov_b32 m0, s70
	s_nop 0
	global_load_lds_dwordx4 v172, s[68:69]
	s_add_i32 m0, s70, 0x2000
	s_nop 0
	global_load_lds_dwordx4 v168, s[68:69]
	s_waitcnt vmcnt(6)
	s_barrier
; #define PG8_STAGE(bufoff, gbase, voff) do { _Pragma("unroll") for (int _i = 0; _i < 2; ++_i) \
;         __builtin_amdgcn_global_load_lds((const unsigned*)((const char*)(gbase) + (voff)[_i]), (LAS unsigned*)(lds + (bufoff) + ldsw + _i * 8192), 16, 0, 0); } while (0)
; #define PG8_LDA(dst, b, h) do { _Pragma("unroll") for (int m = 0; m < 4; ++m) _Pragma("unroll") for (int k = 0; k < 2; ++k) dst[m][k] = *(const LAS bf16x8*)(lds + PG8_SA(b, h) + aoff + m * 2048 + k * 1024); } while (0)
; #define PG8_LDB(dst, b, h) do { _Pragma("unroll") for (int n = 0; n < 2; ++n) _Pragma("unroll") for (int k = 0; k < 2; ++k) dst[n][k] = *(const LAS bf16x8*)(lds + PG8_SB(b, h) + boff + n * 2048 + k * 1024); } while (0)
; #define PG8_MMA(ai, bj, At, Bt) do { __builtin_amdgcn_s_setprio(1); _Pragma("unroll") for (int m = 0; m < 4; ++m) _Pragma("unroll") for (int n = 0; n < 2; ++n) _Pragma("unroll") for (int k = 0; k < 2; ++k) \
;         acc[ai][bj][m][n] = __builtin_amdgcn_mfma_f32_16x16x32_bf16(Bt[n][k], At[m][k], acc[ai][bj][m][n], 0, 0, 0); __builtin_amdgcn_s_setprio(0); } while (0)
; #define PG8_WAIT_V(n) asm volatile("s_waitcnt vmcnt(" #n ")" ::: "memory")
; #define PG8_WAIT_L(n) asm volatile("s_waitcnt lgkmcnt(" #n ")" ::: "memory")
; #define PG8_BAR __builtin_amdgcn_s_barrier()
; #define PG8_SCHED __builtin_amdgcn_sched_barrier(0)
; template <class Map, class Epi>
; DI void gemm_phase(LAS unsigned char* lds, const Map& MP, const Epi& E, const int nM, const int nN, const int K, const int lda, const int ldb) {
;     ...
;             PG8_WAIT_V(6); PG8_BAR; PG8_MMA(1, 1, At, B1); PG8_BAR;
;             PG8_LDB(B0, 1, 0); PG8_SCHED; PG8_LDA(At, 1, 0); PG8_STAGE(PG8_SA(0, 1), a2 + hstepA, voffA);
;             PG8_WAIT_L(8); PG8_BAR; PG8_WAIT_L(0); PG8_MMA(0, 0, At, B0); PG8_BAR; PG8_SCHED;
;             PG8_LDB(B1, 1, 1); PG8_STAGE(PG8_SB(1, 0), b3, voffB);
;             PG8_BAR; PG8_WAIT_L(0); PG8_MMA(0, 1, At, B1); PG8_BAR;
;             PG8_LDA(At, 1, 1); PG8_STAGE(PG8_SA(1, 0), a3, voffA);
;             PG8_BAR; PG8_WAIT_L(0); PG8_MMA(1, 0, At, B0); PG8_BAR; PG8_SCHED;
	s_setprio 1
	v_mfma_f32_16x16x32_bf16 v[56:59], v[206:209], v[124:127], v[56:59]
	v_mfma_f32_16x16x32_bf16 v[52:55], v[214:217], v[124:127], v[52:55]
	s_add_i32 s68, 0, 0x18000
	v_add_u32_e32 v92, s68, v188
	ds_read_b128 v[80:83], v92
	v_mfma_f32_16x16x32_bf16 v[44:47], v[206:209], v[140:143], v[44:47]
	v_mfma_f32_16x16x32_bf16 v[36:39], v[214:217], v[140:143], v[36:39]
	ds_read_b128 v[84:87], v92 offset:1024
	v_mfma_f32_16x16x32_bf16 v[28:31], v[206:209], v[160:163], v[28:31]
	v_mfma_f32_16x16x32_bf16 v[20:23], v[214:217], v[160:163], v[20:23]
	ds_read_b128 v[88:91], v92 offset:2048
	v_mfma_f32_16x16x32_bf16 v[4:7], v[206:209], v[198:201], v[4:7]
	v_mfma_f32_16x16x32_bf16 v[0:3], v[214:217], v[198:201], v[0:3]
	ds_read_b128 v[92:95], v92 offset:3072
	v_mfma_f32_16x16x32_bf16 v[56:59], v[210:213], v[132:135], v[56:59]
	v_mfma_f32_16x16x32_bf16 v[52:55], v[218:221], v[132:135], v[52:55]
	v_mfma_f32_16x16x32_bf16 v[44:47], v[210:213], v[152:155], v[44:47]
	v_mfma_f32_16x16x32_bf16 v[36:39], v[218:221], v[152:155], v[36:39]
	v_mfma_f32_16x16x32_bf16 v[28:31], v[210:213], v[164:167], v[28:31]
	v_mfma_f32_16x16x32_bf16 v[20:23], v[218:221], v[164:167], v[20:23]
	v_mfma_f32_16x16x32_bf16 v[4:7], v[210:213], v[202:205], v[4:7]
	v_mfma_f32_16x16x32_bf16 v[0:3], v[218:221], v[202:205], v[0:3]
	s_setprio 0
	s_barrier
	ds_read_b128 v[124:127], v190 offset:32768
	ds_read_b128 v[132:135], v190 offset:33792
	ds_read_b128 v[160:163], v190 offset:34816
	ds_read_b128 v[164:167], v190 offset:35840
	ds_read_b128 v[198:201], v190 offset:36864
	ds_read_b128 v[202:205], v190 offset:37888
	ds_read_b128 v[206:209], v190 offset:38912
	ds_read_b128 v[210:213], v190 offset:39936
	s_add_u32 s46, s46, 0x80000
	s_addc_u32 s47, s47, 0
	s_mov_b32 m0, s56
	s_nop 0
	global_load_lds_dwordx4 v174, s[46:47]
	s_mov_b32 m0, s57
	s_nop 0
	global_load_lds_dwordx4 v170, s[46:47]
	s_waitcnt lgkmcnt(8)
	s_barrier
	s_setprio 1
	s_waitcnt lgkmcnt(7)
	v_mfma_f32_16x16x32_bf16 v[140:143], v[80:83], v[124:127], v[148:151]
	s_waitcnt lgkmcnt(6)
	v_mfma_f32_16x16x32_bf16 v[148:151], v[84:87], v[132:135], v[140:143]
	v_mfma_f32_16x16x32_bf16 v[140:143], v[88:91], v[124:127], v[144:147]
	s_waitcnt lgkmcnt(5)
	v_mfma_f32_16x16x32_bf16 v[136:139], v[80:83], v[160:163], v[136:139]
	v_mfma_f32_16x16x32_bf16 v[128:131], v[88:91], v[160:163], v[128:131]
	s_waitcnt lgkmcnt(3)
	v_mfma_f32_16x16x32_bf16 v[120:123], v[80:83], v[198:201], v[120:123]
	v_mfma_f32_16x16x32_bf16 v[104:107], v[88:91], v[198:201], v[104:107]
	s_waitcnt lgkmcnt(1)
	v_mfma_f32_16x16x32_bf16 v[76:79], v[80:83], v[206:209], v[76:79]
	v_mfma_f32_16x16x32_bf16 v[72:75], v[88:91], v[206:209], v[72:75]
	v_mfma_f32_16x16x32_bf16 v[144:147], v[92:95], v[132:135], v[140:143]
	v_mfma_f32_16x16x32_bf16 v[136:139], v[84:87], v[164:167], v[136:139]
	v_mfma_f32_16x16x32_bf16 v[128:131], v[92:95], v[164:167], v[128:131]
	v_mfma_f32_16x16x32_bf16 v[120:123], v[84:87], v[202:205], v[120:123]
	v_mfma_f32_16x16x32_bf16 v[104:107], v[92:95], v[202:205], v[104:107]
	s_waitcnt lgkmcnt(0)
	v_mfma_f32_16x16x32_bf16 v[76:79], v[84:87], v[210:213], v[76:79]
	v_mfma_f32_16x16x32_bf16 v[72:75], v[92:95], v[210:213], v[72:75]
	s_setprio 0
	s_barrier
	s_add_i32 s46, 0, 0x1c000
	v_add_u32_e32 v140, s46, v188
	ds_read_b128 v[214:217], v140
	ds_read_b128 v[218:221], v140 offset:1024
	ds_read_b128 v[222:225], v140 offset:2048
	ds_read_b128 v[230:233], v140 offset:3072
	s_add_i32 s47, s68, s66
	v_lshl_add_u64 v[140:141], v[184:185], 0, s[14:15]
	s_mov_b32 m0, s47
	s_nop 0
	global_load_lds_dwordx4 v[140:141], off
	v_lshl_add_u64 v[140:141], v[194:195], 0, s[14:15]
	s_add_i32 m0, s47, 0x2000
	s_nop 0
	global_load_lds_dwordx4 v[140:141], off
	s_barrier
	s_setprio 1
	s_waitcnt lgkmcnt(1)
	v_mfma_f32_16x16x32_bf16 v[96:99], v[222:225], v[124:127], v[96:99]
	v_mfma_f32_16x16x32_bf16 v[140:143], v[214:217], v[124:127], v[156:159]
	s_waitcnt lgkmcnt(0)
	v_mfma_f32_16x16x32_bf16 v[152:155], v[230:233], v[132:135], v[96:99]
	v_mfma_f32_16x16x32_bf16 v[96:99], v[214:217], v[160:163], v[100:103]
	v_mfma_f32_16x16x32_bf16 v[156:159], v[218:221], v[132:135], v[140:143]
	v_mfma_f32_16x16x32_bf16 v[140:143], v[218:221], v[164:167], v[96:99]
	v_mfma_f32_16x16x32_bf16 v[96:99], v[222:225], v[160:163], v[108:111]
	v_mfma_f32_16x16x32_bf16 v[132:135], v[230:233], v[164:167], v[96:99]
	v_mfma_f32_16x16x32_bf16 v[96:99], v[214:217], v[198:201], v[112:115]
	s_mov_b32 m0, s63
	v_mfma_f32_16x16x32_bf16 v[124:127], v[218:221], v[202:205], v[96:99]
	v_lshl_add_u64 v[184:185], v[226:227], 0, s[14:15]
	v_mfma_f32_16x16x32_bf16 v[96:99], v[222:225], v[198:201], v[116:119]
	v_mfma_f32_16x16x32_bf16 v[68:71], v[214:217], v[206:209], v[68:71]
	v_mfma_f32_16x16x32_bf16 v[64:67], v[222:225], v[206:209], v[64:67]
	v_mfma_f32_16x16x32_bf16 v[116:119], v[230:233], v[202:205], v[96:99]
	v_mfma_f32_16x16x32_bf16 v[68:71], v[218:221], v[210:213], v[68:71]
	v_mfma_f32_16x16x32_bf16 v[64:67], v[230:233], v[210:213], v[64:67]
	s_setprio 0
	s_barrier
	ds_read_b128 v[96:99], v190 offset:49152
	ds_read_b128 v[100:103], v190 offset:50176
	ds_read_b128 v[108:111], v190 offset:51200
	ds_read_b128 v[112:115], v190 offset:52224
	ds_read_b128 v[160:163], v190 offset:53248
	ds_read_b128 v[164:167], v190 offset:54272
	ds_read_b128 v[198:201], v190 offset:55296
	ds_read_b128 v[202:205], v190 offset:56320
	global_load_lds_dwordx4 v[184:185], off
	v_lshl_add_u64 v[184:185], v[234:235], 0, s[14:15]
	s_mov_b32 m0, s4
	s_nop 0
	global_load_lds_dwordx4 v[184:185], off
	s_waitcnt vmcnt(10)
	s_barrier
; #define PG8_STAGE(bufoff, gbase, voff) do { _Pragma("unroll") for (int _i = 0; _i < 2; ++_i) \
;         __builtin_amdgcn_global_load_lds((const unsigned*)((const char*)(gbase) + (voff)[_i]), (LAS unsigned*)(lds + (bufoff) + ldsw + _i * 8192), 16, 0, 0); } while (0)
; #define PG8_MMA(ai, bj, At, Bt) do { __builtin_amdgcn_s_setprio(1); _Pragma("unroll") for (int m = 0; m < 4; ++m) _Pragma("unroll") for (int n = 0; n < 2; ++n) _Pragma("unroll") for (int k = 0; k < 2; ++k) \
;         acc[ai][bj][m][n] = __builtin_amdgcn_mfma_f32_16x16x32_bf16(Bt[n][k], At[m][k], acc[ai][bj][m][n], 0, 0, 0); __builtin_amdgcn_s_setprio(0); } while (0)
; #define PG8_WAIT_V(n) asm volatile("s_waitcnt vmcnt(" #n ")" ::: "memory")
; #define PG8_WAIT_L(n) asm volatile("s_waitcnt lgkmcnt(" #n ")" ::: "memory")
; #define PG8_BAR __builtin_amdgcn_s_barrier()
; #define PG8_SCHED __builtin_amdgcn_sched_barrier(0)
; template <class Map, class Epi>
; DI void gemm_phase(LAS unsigned char* lds, const Map& MP, const Epi& E, const int nM, const int nN, const int K, const int lda, const int ldb) {
;     ...
;             PG8_BAR; PG8_WAIT_L(0); PG8_MMA(1, 0, At, B0); PG8_BAR; PG8_SCHED;
;             PG8_STAGE(PG8_SB(1, 1), b3 + hstepB, voffB);
;             PG8_WAIT_V(6); PG8_BAR; PG8_MMA(1, 1, At, B1); PG8_BAR;
	s_setprio 1
	s_waitcnt lgkmcnt(7)
	v_mfma_f32_16x16x32_bf16 v[60:63], v[80:83], v[96:99], v[60:63]
	v_mfma_f32_16x16x32_bf16 v[48:51], v[88:91], v[96:99], v[48:51]
	s_waitcnt lgkmcnt(5)
	v_mfma_f32_16x16x32_bf16 v[40:43], v[80:83], v[108:111], v[40:43]
	v_mfma_f32_16x16x32_bf16 v[32:35], v[88:91], v[108:111], v[32:35]
	s_waitcnt lgkmcnt(3)
	v_mfma_f32_16x16x32_bf16 v[24:27], v[80:83], v[160:163], v[24:27]
	v_mfma_f32_16x16x32_bf16 v[16:19], v[88:91], v[160:163], v[16:19]
	s_waitcnt lgkmcnt(1)
	v_mfma_f32_16x16x32_bf16 v[12:15], v[80:83], v[198:201], v[12:15]
	v_mfma_f32_16x16x32_bf16 v[8:11], v[88:91], v[198:201], v[8:11]
	v_mfma_f32_16x16x32_bf16 v[60:63], v[84:87], v[100:103], v[60:63]
	v_mfma_f32_16x16x32_bf16 v[48:51], v[92:95], v[100:103], v[48:51]
	v_mfma_f32_16x16x32_bf16 v[40:43], v[84:87], v[112:115], v[40:43]
	v_mfma_f32_16x16x32_bf16 v[32:35], v[92:95], v[112:115], v[32:35]
	v_mfma_f32_16x16x32_bf16 v[24:27], v[84:87], v[164:167], v[24:27]
	v_mfma_f32_16x16x32_bf16 v[16:19], v[92:95], v[164:167], v[16:19]
	s_waitcnt lgkmcnt(0)
	v_mfma_f32_16x16x32_bf16 v[12:15], v[84:87], v[202:205], v[12:15]
	v_mfma_f32_16x16x32_bf16 v[8:11], v[92:95], v[202:205], v[8:11]
	s_setprio 0
	s_barrier
	s_add_u32 s24, s24, 0x80080
	s_addc_u32 s25, s25, 0
	s_add_i32 s46, s46, s66
	s_mov_b32 m0, s46
	s_nop 0
	global_load_lds_dwordx4 v172, s[24:25]
	s_add_i32 m0, s46, 0x2000
	s_nop 0
	global_load_lds_dwordx4 v168, s[24:25]
	s_waitcnt vmcnt(6)
	s_barrier
	s_setprio 1
	v_mfma_f32_16x16x32_bf16 v[56:59], v[214:217], v[96:99], v[56:59]
	v_mfma_f32_16x16x32_bf16 v[52:55], v[222:225], v[96:99], v[52:55]
	ds_read_b128 v[80:83], v189
	v_mfma_f32_16x16x32_bf16 v[44:47], v[214:217], v[108:111], v[44:47]
	v_mfma_f32_16x16x32_bf16 v[36:39], v[222:225], v[108:111], v[36:39]
	ds_read_b128 v[84:87], v189 offset:1024
	v_mfma_f32_16x16x32_bf16 v[28:31], v[214:217], v[160:163], v[28:31]
	v_mfma_f32_16x16x32_bf16 v[20:23], v[222:225], v[160:163], v[20:23]
	ds_read_b128 v[88:91], v189 offset:2048
	v_mfma_f32_16x16x32_bf16 v[4:7], v[214:217], v[198:201], v[4:7]
	v_mfma_f32_16x16x32_bf16 v[0:3], v[222:225], v[198:201], v[0:3]
	ds_read_b128 v[92:95], v189 offset:3072
	v_mfma_f32_16x16x32_bf16 v[56:59], v[218:221], v[100:103], v[56:59]
	s_add_i32 s3, s3, 2
	v_mfma_f32_16x16x32_bf16 v[52:55], v[230:233], v[100:103], v[52:55]
	s_add_u32 vcc_lo, vcc_lo, 0x100
	s_addc_u32 vcc_hi, vcc_hi, 0
	v_mfma_f32_16x16x32_bf16 v[44:47], v[218:221], v[112:115], v[44:47]
	s_add_u32 s42, s42, 0x100
	s_addc_u32 s43, s43, 0
	v_mfma_f32_16x16x32_bf16 v[36:39], v[230:233], v[112:115], v[36:39]
	s_cmp_gt_u32 s3, 29
	v_mfma_f32_16x16x32_bf16 v[28:31], v[218:221], v[164:167], v[28:31]
	v_mfma_f32_16x16x32_bf16 v[20:23], v[230:233], v[164:167], v[20:23]
	v_mfma_f32_16x16x32_bf16 v[4:7], v[218:221], v[202:205], v[4:7]
	v_mfma_f32_16x16x32_bf16 v[0:3], v[230:233], v[202:205], v[0:3]
	s_setprio 0
	s_barrier
	s_cbranch_scc0 .LBB1_1069
; DI float silu_mul(float g, float v) { return g * v * __builtin_amdgcn_rcpf(1.0f + __builtin_amdgcn_exp2f(-LOG2E * g)); }
;     DI void operator()(const f32x4 (&acc)[2][2][4][2], const Unit& u, int wr, int wc, int fr, int fq) const {
;         const int row0 = u.pm * BM + wr * 64 + fr, ch0 = u.pn * 128 + wc * 32 + 8 * fq;
;         f32x4 w0[2], w1[2], w2[2], bb[2];
; #pragma unroll
;         for (int n = 0; n < 2; ++n) { w0[n] = *(const f32x4*)(cw + ch0 + 4 * n); w1[n] = *(const f32x4*)(cw + DFF + ch0 + 4 * n); w2[n] = *(const f32x4*)(cw + 2 * DFF + ch0 + 4 * n); bb[n] = *(const f32x4*)(cb + ch0 + 4 * n); }
; #pragma unroll
;         for (int ai = 0; ai < 2; ++ai)
; #pragma unroll
;             for (int m = 0; m < 4; ++m) {
;                 const bool efirst = (m == 0) && (fr == 0), elast = (m == 3) && (fr == 15);
;                 const int row = row0 + ai * HALF + m * 16;
;                 f32x4 gc[2];
; #pragma unroll
;                 for (int n = 0; n < 2; ++n) {
;                     const f32x4 g = acc[ai][0][m][n];
;                     const f32x4 gprev = acc[ai][0][m > 0 ? m - 1 : 0][n], gnext = acc[ai][0][m < 3 ? m + 1 : 3][n];
;                     f32x4 up, dn;
; #pragma unroll
;                     for (int e = 0; e < 4; ++e) {
;                         const float pu = (m > 0 && fr == 15) ? gprev[e] : g[e];
;                         const float pd = (m < 3 && fr == 0) ? gnext[e] : g[e];
;                         up[e] = dpp_ror1(pu); dn[e] = dpp_ror15(pd);
;                     }
;                     if (efirst) up = (f32x4){0.f, 0.f, 0.f, 0.f};
;                     if (elast) dn = (f32x4){0.f, 0.f, 0.f, 0.f};
;                     gc[n] = w0[n] * up + w1[n] * g + w2[n] * dn + bb[n];
;                 }
;                 if (efirst || elast) {
;                     const size_t eo = (size_t)((row >> 6) * 2 + (elast ? 1 : 0)) * DFF + ch0;
; #pragma unroll
;                     for (int n = 0; n < 2; ++n) { *(f32x4*)(EP + eo + 4 * n) = gc[n]; *(f32x4*)(ER + eo + 4 * n) = acc[ai][0][m][n]; *(f32x4*)(EV + eo + 4 * n) = acc[ai][1][m][n]; }
;                 } else {
;                     const f32x4 v0 = acc[ai][1][m][0], v1 = acc[ai][1][m][1];
;                     u32x4 o;
;                     o[0] = pack2(silu_mul(gc[0][0], v0[0]), silu_mul(gc[0][1], v0[1])); o[1] = pack2(silu_mul(gc[0][2], v0[2]), silu_mul(gc[0][3], v0[3]));
	s_waitcnt lgkmcnt(0)
	s_lshl_b32 s21, s45, 7
	v_mov_b32_e32 v194, v186
	v_mov_b32_e32 v80, v187
	s_or_b32 s21, s21, s62
	v_mov_b32_e32 v160, 0
	v_lshl_add_u32 v184, v80, 3, s21
	v_ashrrev_i32_e32 v185, 31, v184
	v_lshlrev_b64 v[80:81], 2, v[184:185]
	v_lshl_add_u64 v[84:85], s[6:7], 0, v[80:81]
	v_lshl_add_u64 v[88:89], s[16:17], 0, v[80:81]
	v_lshl_add_u64 v[92:93], s[18:19], 0, v[80:81]
	v_lshl_add_u64 v[112:113], s[52:53], 0, v[80:81]
	global_load_dwordx4 v[80:83], v[84:85], off offset:16
	global_load_dwordx4 v[96:99], v[84:85], off
	s_nop 0
	global_load_dwordx4 v[84:87], v[88:89], off offset:16
	global_load_dwordx4 v[100:103], v[88:89], off
	s_nop 0
	global_load_dwordx4 v[88:91], v[92:93], off offset:16
	global_load_dwordx4 v[108:111], v[92:93], off
	s_nop 0
	global_load_dwordx4 v[92:95], v[112:113], off offset:16
	s_nop 0
	global_load_dwordx4 v[112:115], v[112:113], off
	v_cmp_eq_u32_e32 vcc, 0, v194
	v_mov_b32_e32 v164, 0
	v_mov_b32_e32 v195, 0
	v_cndmask_b32_e32 v161, v148, v136, vcc
	v_cndmask_b32_e32 v162, v149, v137, vcc
	v_cndmask_b32_e32 v163, v150, v138, vcc
	v_mov_b32_dpp v160, v161 row_ror:15 row_mask:0xf bank_mask:0xf
	v_mov_b32_e32 v161, 0
	v_mov_b32_e32 v166, 0
	v_mov_b32_e32 v167, 0
	v_mov_b32_dpp v161, v162 row_ror:15 row_mask:0xf bank_mask:0xf
	v_mov_b32_e32 v162, 0
	v_mov_b32_dpp v164, v150 row_ror:1 row_mask:0xf bank_mask:0xf
	v_cndmask_b32_e32 v165, v151, v139, vcc
	v_mov_b32_dpp v162, v163 row_ror:15 row_mask:0xf bank_mask:0xf
	v_mov_b32_dpp v195, v151 row_ror:1 row_mask:0xf bank_mask:0xf
	v_mov_b32_e32 v163, 0
	v_mov_b32_dpp v166, v148 row_ror:1 row_mask:0xf bank_mask:0xf
	v_mov_b32_dpp v167, v149 row_ror:1 row_mask:0xf bank_mask:0xf
	v_mov_b32_dpp v163, v165 row_ror:15 row_mask:0xf bank_mask:0xf
	v_cndmask_b32_e64 v165, v195, 0, vcc
	v_cndmask_b32_e64 v164, v164, 0, vcc
	v_cndmask_b32_e64 v167, v167, 0, vcc
	v_cndmask_b32_e64 v166, v166, 0, vcc
	v_mov_b32_e32 v195, 0
	v_mov_b32_e32 v196, 0
	v_mov_b32_e32 v198, 0
	v_mov_b32_e32 v200, 0
	v_mov_b32_dpp v195, v144 row_ror:1 row_mask:0xf bank_mask:0xf
	v_mov_b32_dpp v196, v145 row_ror:1 row_mask:0xf bank_mask:0xf
	v_mov_b32_dpp v198, v146 row_ror:1 row_mask:0xf bank_mask:0xf
	v_cndmask_b32_e32 v199, v147, v131, vcc
	v_mov_b32_dpp v200, v147 row_ror:1 row_mask:0xf bank_mask:0xf
	v_cndmask_b32_e64 v198, v198, 0, vcc
	v_cndmask_b32_e64 v201, v196, 0, vcc
	s_lshl_b32 s3, s44, 8
	s_add_i32 s3, s3, s49
	v_add_u32_e32 v193, s3, v194
	v_cmp_ne_u32_e64 s[46:47], 0, v194
	s_waitcnt vmcnt(0)
	v_pk_mul_f32 v[164:165], v[98:99], v[164:165]
	v_pk_mul_f32 v[166:167], v[96:97], v[166:167]
	v_pk_fma_f32 v[164:165], v[150:151], v[102:103], v[164:165]
	v_pk_fma_f32 v[166:167], v[148:149], v[100:101], v[166:167]
	v_pk_fma_f32 v[162:163], v[110:111], v[162:163], v[164:165]
	v_cndmask_b32_e32 v165, v144, v128, vcc
	v_mov_b32_e32 v164, 0
	v_pk_fma_f32 v[160:161], v[108:109], v[160:161], v[166:167]
	v_cndmask_b32_e32 v166, v145, v129, vcc
	v_mov_b32_dpp v164, v165 row_ror:15 row_mask:0xf bank_mask:0xf
	v_mov_b32_e32 v165, 0
	v_cndmask_b32_e32 v167, v146, v130, vcc
	v_pk_add_f32 v[162:163], v[114:115], v[162:163]
	v_mov_b32_dpp v165, v166 row_ror:15 row_mask:0xf bank_mask:0xf
	v_mov_b32_e32 v166, 0
	v_pk_add_f32 v[160:161], v[112:113], v[160:161]
	s_nop 0
	v_mov_b32_dpp v166, v167 row_ror:15 row_mask:0xf bank_mask:0xf
	v_mov_b32_e32 v167, 0
	s_nop 1
	v_mov_b32_dpp v167, v199 row_ror:15 row_mask:0xf bank_mask:0xf
	v_cndmask_b32_e64 v199, v200, 0, vcc
	v_cndmask_b32_e64 v200, v195, 0, vcc
	v_pk_mul_f32 v[200:201], v[80:81], v[200:201]
	v_pk_mul_f32 v[198:199], v[82:83], v[198:199]
	v_pk_fma_f32 v[200:201], v[144:145], v[84:85], v[200:201]
	v_pk_fma_f32 v[198:199], v[146:147], v[86:87], v[198:199]
	v_pk_fma_f32 v[164:165], v[88:89], v[164:165], v[200:201]
	v_pk_fma_f32 v[166:167], v[90:91], v[166:167], v[198:199]
	v_pk_add_f32 v[164:165], v[92:93], v[164:165]
	v_pk_add_f32 v[166:167], v[94:95], v[166:167]
	s_and_saveexec_b64 s[24:25], s[46:47]
	s_xor_b64 s[24:25], exec, s[24:25]
	s_cbranch_execz .LBB1_1072
	v_mul_f32_e32 v195, 0xbfb8aa3b, v160
	v_exp_f32_e32 v195, v195
	v_mul_f32_e32 v196, 0xbfb8aa3b, v161
	v_exp_f32_e32 v196, v196
	v_pk_mul_f32 v[160:161], v[156:157], v[160:161]
	v_add_f32_e32 v195, 1.0, v195
	v_rcp_f32_e32 v198, v195
	v_add_f32_e32 v196, 1.0, v196
	v_mul_f32_e32 v195, 0xbfb8aa3b, v162
	v_rcp_f32_e32 v199, v196
	v_exp_f32_e32 v195, v195
	v_mul_f32_e32 v196, 0xbfb8aa3b, v163
	v_exp_f32_e32 v196, v196
	v_pk_mul_f32 v[160:161], v[160:161], v[198:199]
	v_add_f32_e32 v195, 1.0, v195
	v_rcp_f32_e32 v200, v195
	v_add_f32_e32 v195, 1.0, v196
	v_rcp_f32_e32 v201, v195
	v_cvt_pk_bf16_f32 v160, v160, v161
	v_mul_f32_e32 v161, 0xbfb8aa3b, v164
	v_exp_f32_e32 v195, v161
	v_mul_f32_e32 v161, 0xbfb8aa3b, v165
	v_exp_f32_e32 v196, v161
	v_pk_mul_f32 v[162:163], v[158:159], v[162:163]
	v_pk_mul_f32 v[164:165], v[152:153], v[164:165]
	v_pk_mul_f32 v[162:163], v[162:163], v[200:201]
	s_nop 0
	v_cvt_pk_bf16_f32 v161, v162, v163
	v_add_f32_e32 v162, 1.0, v195
	v_mul_f32_e32 v195, 0xbfb8aa3b, v166
	v_add_f32_e32 v163, 1.0, v196
	v_exp_f32_e32 v195, v195
	v_mul_f32_e32 v196, 0xbfb8aa3b, v167
	v_exp_f32_e32 v196, v196
	v_rcp_f32_e32 v162, v162
	v_add_f32_e32 v195, 1.0, v195
	v_rcp_f32_e32 v198, v195
	v_add_f32_e32 v195, 1.0, v196
	v_rcp_f32_e32 v163, v163
	v_rcp_f32_e32 v199, v195
	v_pk_mul_f32 v[166:167], v[154:155], v[166:167]
	v_pk_mul_f32 v[162:163], v[164:165], v[162:163]
	v_pk_mul_f32 v[164:165], v[166:167], v[198:199]
	v_cvt_pk_bf16_f32 v162, v162, v163
	v_cvt_pk_bf16_f32 v163, v164, v165
	v_mov_b64_e32 v[164:165], s[54:55]
	v_mad_i64_i32 v[164:165], s[42:43], v193, s60, v[164:165]
	v_lshl_add_u64 v[164:165], v[184:185], 1, v[164:165]
	global_store_dwordx4 v[164:165], v[160:163], off

; #define PG8_STAGE(bufoff, gbase, voff) do { _Pragma("unroll") for (int _i = 0; _i < 2; ++_i) \
;         __builtin_amdgcn_global_load_lds((const unsigned*)((const char*)(gbase) + (voff)[_i]), (LAS unsigned*)(lds + (bufoff) + ldsw + _i * 8192), 16, 0, 0); } while (0)
; #define PG8_LDA(dst, b, h) do { _Pragma("unroll") for (int m = 0; m < 4; ++m) _Pragma("unroll") for (int k = 0; k < 2; ++k) dst[m][k] = *(const LAS bf16x8*)(lds + PG8_SA(b, h) + aoff + m * 2048 + k * 1024); } while (0)
; #define PG8_LDB(dst, b, h) do { _Pragma("unroll") for (int n = 0; n < 2; ++n) _Pragma("unroll") for (int k = 0; k < 2; ++k) dst[n][k] = *(const LAS bf16x8*)(lds + PG8_SB(b, h) + boff + n * 2048 + k * 1024); } while (0)
; #define PG8_MMA(ai, bj, At, Bt) do { __builtin_amdgcn_s_setprio(1); _Pragma("unroll") for (int m = 0; m < 4; ++m) _Pragma("unroll") for (int n = 0; n < 2; ++n) _Pragma("unroll") for (int k = 0; k < 2; ++k) \
;         acc[ai][bj][m][n] = __builtin_amdgcn_mfma_f32_16x16x32_bf16(Bt[n][k], At[m][k], acc[ai][bj][m][n], 0, 0, 0); __builtin_amdgcn_s_setprio(0); } while (0)
; #define PG8_WAIT_L(n) asm volatile("s_waitcnt lgkmcnt(" #n ")" ::: "memory")
; #define PG8_BAR __builtin_amdgcn_s_barrier()
; #define PG8_SCHED __builtin_amdgcn_sched_barrier(0)
; template <class Map, class Epi>
; DI void gemm_phase(LAS unsigned char* lds, const Map& MP, const Epi& E, const int nM, const int nN, const int K, const int lda, const int ldb) {
;     ...
;             PG8_LDB(B0, 0, 0); PG8_SCHED; PG8_LDA(At, 0, 0); PG8_STAGE(PG8_SA(1, 1), a1 + hstepA, voffA);
;             PG8_WAIT_L(8); PG8_BAR; PG8_WAIT_L(0); PG8_MMA(0, 0, At, B0); PG8_BAR; PG8_SCHED;
;             PG8_LDB(B1, 0, 1); PG8_STAGE(PG8_SB(0, 0), b2, voffB);
;             PG8_BAR; PG8_WAIT_L(0); PG8_MMA(0, 1, At, B1); PG8_BAR;
;             PG8_LDA(At, 0, 1); PG8_STAGE(PG8_SA(0, 0), a2, voffA);
;             PG8_BAR; PG8_WAIT_L(0); PG8_MMA(1, 0, At, B0); PG8_BAR; PG8_SCHED;
.LBB1_1239:
	ds_read_b128 v[168:171], v150
	ds_read_b128 v[172:175], v150 offset:1024
	ds_read_b128 v[176:179], v150 offset:2048
	ds_read_b128 v[180:183], v150 offset:3072
	ds_read_b128 v[184:187], v150 offset:4096
	ds_read_b128 v[188:191], v150 offset:5120
	ds_read_b128 v[192:195], v150 offset:6144
	ds_read_b128 v[198:201], v150 offset:7168
	s_add_u32 s10, s8, 0x100
	s_addc_u32 s11, s9, 0
	s_cmpk_eq_i32 s3, 0x54
	s_cselect_b32 s15, s43, s11
	s_cselect_b32 s14, s42, s10
	s_cselect_b32 s13, s7, s38
	s_cselect_b32 s12, s6, s5
	s_add_i32 m0, s24, 0xc000
	s_nop 0
	global_load_lds_dwordx4 v138, s[8:9]
	s_add_i32 m0, s24, 0xe000
	s_nop 0
	global_load_lds_dwordx4 v136, s[8:9]
	s_waitcnt lgkmcnt(8)
	s_barrier
	s_setprio 1
	s_waitcnt lgkmcnt(7)
	v_mfma_f32_16x16x32_bf16 v[124:127], v[152:155], v[168:171], v[124:127]
	v_mfma_f32_16x16x32_bf16 v[120:123], v[160:163], v[168:171], v[120:123]
	s_waitcnt lgkmcnt(5)
	v_mfma_f32_16x16x32_bf16 v[108:111], v[152:155], v[176:179], v[108:111]
	v_mfma_f32_16x16x32_bf16 v[104:107], v[160:163], v[176:179], v[104:107]
	s_waitcnt lgkmcnt(3)
	v_mfma_f32_16x16x32_bf16 v[92:95], v[152:155], v[184:187], v[92:95]
	v_mfma_f32_16x16x32_bf16 v[88:91], v[160:163], v[184:187], v[88:91]
	s_waitcnt lgkmcnt(1)
	v_mfma_f32_16x16x32_bf16 v[76:79], v[152:155], v[192:195], v[76:79]
	v_mfma_f32_16x16x32_bf16 v[72:75], v[160:163], v[192:195], v[72:75]
	v_mfma_f32_16x16x32_bf16 v[124:127], v[156:159], v[172:175], v[124:127]
	v_mfma_f32_16x16x32_bf16 v[120:123], v[164:167], v[172:175], v[120:123]
	v_mfma_f32_16x16x32_bf16 v[108:111], v[156:159], v[180:183], v[108:111]
	v_mfma_f32_16x16x32_bf16 v[104:107], v[164:167], v[180:183], v[104:107]
	v_mfma_f32_16x16x32_bf16 v[92:95], v[156:159], v[188:191], v[92:95]
	v_mfma_f32_16x16x32_bf16 v[88:91], v[164:167], v[188:191], v[88:91]
	s_waitcnt lgkmcnt(0)
	v_mfma_f32_16x16x32_bf16 v[76:79], v[156:159], v[198:201], v[76:79]
	v_mfma_f32_16x16x32_bf16 v[72:75], v[164:167], v[198:201], v[72:75]
	s_setprio 0
	s_barrier
	ds_read_b128 v[202:205], v151
	ds_read_b128 v[206:209], v151 offset:1024
	ds_read_b128 v[210:213], v151 offset:2048
	ds_read_b128 v[214:217], v151 offset:3072
	s_add_i32 s8, s35, s22
	v_lshl_add_u64 v[144:145], s[12:13], 0, v[132:133]
	s_mov_b32 m0, s8
	s_nop 0
	global_load_lds_dwordx4 v[144:145], off
	v_lshl_add_u64 v[218:219], s[12:13], 0, v[128:129]
	s_add_i32 m0, s8, 0x2000
	s_nop 0
	global_load_lds_dwordx4 v[218:219], off
	s_barrier
	s_setprio 1
	s_waitcnt lgkmcnt(3)
	v_mfma_f32_16x16x32_bf16 v[116:119], v[202:205], v[168:171], v[116:119]
	s_waitcnt lgkmcnt(1)
	v_mfma_f32_16x16x32_bf16 v[112:115], v[210:213], v[168:171], v[112:115]
	v_mfma_f32_16x16x32_bf16 v[100:103], v[202:205], v[176:179], v[100:103]
	v_mfma_f32_16x16x32_bf16 v[96:99], v[210:213], v[176:179], v[96:99]
	v_mfma_f32_16x16x32_bf16 v[84:87], v[202:205], v[184:187], v[84:87]
	v_mfma_f32_16x16x32_bf16 v[80:83], v[210:213], v[184:187], v[80:83]
	v_mfma_f32_16x16x32_bf16 v[68:71], v[202:205], v[192:195], v[68:71]
	v_mfma_f32_16x16x32_bf16 v[64:67], v[210:213], v[192:195], v[64:67]
	v_mfma_f32_16x16x32_bf16 v[116:119], v[206:209], v[172:175], v[116:119]
	s_mov_b32 m0, s24
	s_waitcnt lgkmcnt(0)
	v_mfma_f32_16x16x32_bf16 v[112:115], v[214:217], v[172:175], v[112:115]
	v_lshl_add_u64 v[220:221], s[14:15], 0, v[134:135]
	v_mfma_f32_16x16x32_bf16 v[100:103], v[206:209], v[180:183], v[100:103]
	v_mfma_f32_16x16x32_bf16 v[96:99], v[214:217], v[180:183], v[96:99]
	v_mfma_f32_16x16x32_bf16 v[84:87], v[206:209], v[188:191], v[84:87]
	v_mfma_f32_16x16x32_bf16 v[80:83], v[214:217], v[188:191], v[80:83]
	v_mfma_f32_16x16x32_bf16 v[68:71], v[206:209], v[198:201], v[68:71]
	v_mfma_f32_16x16x32_bf16 v[64:67], v[214:217], v[198:201], v[64:67]
	s_setprio 0
	s_barrier
	ds_read_b128 v[168:171], v150 offset:16384
	ds_read_b128 v[172:175], v150 offset:17408
	ds_read_b128 v[176:179], v150 offset:18432
	ds_read_b128 v[180:183], v150 offset:19456
	ds_read_b128 v[184:187], v150 offset:20480
	ds_read_b128 v[188:191], v150 offset:21504
	ds_read_b128 v[192:195], v150 offset:22528
	ds_read_b128 v[198:201], v150 offset:23552
	global_load_lds_dwordx4 v[220:221], off
	v_lshl_add_u64 v[222:223], s[14:15], 0, v[130:131]
	s_mov_b32 m0, s25
	s_nop 0
	global_load_lds_dwordx4 v[222:223], off
	s_waitcnt vmcnt(10)
	s_barrier
	s_setprio 1
	s_waitcnt lgkmcnt(7)
	v_mfma_f32_16x16x32_bf16 v[60:63], v[152:155], v[168:171], v[60:63]
	v_mfma_f32_16x16x32_bf16 v[56:59], v[160:163], v[168:171], v[56:59]
	s_waitcnt lgkmcnt(5)
	v_mfma_f32_16x16x32_bf16 v[44:47], v[152:155], v[176:179], v[44:47]
	v_mfma_f32_16x16x32_bf16 v[40:43], v[160:163], v[176:179], v[40:43]
	s_waitcnt lgkmcnt(3)
	v_mfma_f32_16x16x32_bf16 v[28:31], v[152:155], v[184:187], v[28:31]
	v_mfma_f32_16x16x32_bf16 v[24:27], v[160:163], v[184:187], v[24:27]
	s_waitcnt lgkmcnt(1)
	v_mfma_f32_16x16x32_bf16 v[12:15], v[152:155], v[192:195], v[12:15]
	v_mfma_f32_16x16x32_bf16 v[8:11], v[160:163], v[192:195], v[8:11]
	v_mfma_f32_16x16x32_bf16 v[60:63], v[156:159], v[172:175], v[60:63]
	v_mfma_f32_16x16x32_bf16 v[56:59], v[164:167], v[172:175], v[56:59]
	v_mfma_f32_16x16x32_bf16 v[44:47], v[156:159], v[180:183], v[44:47]
	v_mfma_f32_16x16x32_bf16 v[40:43], v[164:167], v[180:183], v[40:43]
	v_mfma_f32_16x16x32_bf16 v[28:31], v[156:159], v[188:191], v[28:31]
	v_mfma_f32_16x16x32_bf16 v[24:27], v[164:167], v[188:191], v[24:27]
	s_waitcnt lgkmcnt(0)
	v_mfma_f32_16x16x32_bf16 v[12:15], v[156:159], v[198:201], v[12:15]
	v_mfma_f32_16x16x32_bf16 v[8:11], v[164:167], v[198:201], v[8:11]
	s_setprio 0
	s_barrier
; #define PG8_STAGE(bufoff, gbase, voff) do { _Pragma("unroll") for (int _i = 0; _i < 2; ++_i) \
;         __builtin_amdgcn_global_load_lds((const unsigned*)((const char*)(gbase) + (voff)[_i]), (LAS unsigned*)(lds + (bufoff) + ldsw + _i * 8192), 16, 0, 0); } while (0)
; #define PG8_LDA(dst, b, h) do { _Pragma("unroll") for (int m = 0; m < 4; ++m) _Pragma("unroll") for (int k = 0; k < 2; ++k) dst[m][k] = *(const LAS bf16x8*)(lds + PG8_SA(b, h) + aoff + m * 2048 + k * 1024); } while (0)
; #define PG8_LDB(dst, b, h) do { _Pragma("unroll") for (int n = 0; n < 2; ++n) _Pragma("unroll") for (int k = 0; k < 2; ++k) dst[n][k] = *(const LAS bf16x8*)(lds + PG8_SB(b, h) + boff + n * 2048 + k * 1024); } while (0)
; #define PG8_MMA(ai, bj, At, Bt) do { __builtin_amdgcn_s_setprio(1); _Pragma("unroll") for (int m = 0; m < 4; ++m) _Pragma("unroll") for (int n = 0; n < 2; ++n) _Pragma("unroll") for (int k = 0; k < 2; ++k) \
;         acc[ai][bj][m][n] = __builtin_amdgcn_mfma_f32_16x16x32_bf16(Bt[n][k], At[m][k], acc[ai][bj][m][n], 0, 0, 0); __builtin_amdgcn_s_setprio(0); } while (0)
; #define PG8_WAIT_V(n) asm volatile("s_waitcnt vmcnt(" #n ")" ::: "memory")
; #define PG8_WAIT_L(n) asm volatile("s_waitcnt lgkmcnt(" #n ")" ::: "memory")
; #define PG8_BAR __builtin_amdgcn_s_barrier()
; #define PG8_SCHED __builtin_amdgcn_sched_barrier(0)
; template <class Map, class Epi>
; DI void gemm_phase(LAS unsigned char* lds, const Map& MP, const Epi& E, const int nM, const int nN, const int K, const int lda, const int ldb) {
;     ...
;             PG8_STAGE(PG8_SB(0, 1), b2 + hstepB, voffB);
;             PG8_WAIT_V(6); PG8_BAR; PG8_MMA(1, 1, At, B1); PG8_BAR;
;             PG8_LDB(B0, 1, 0); PG8_SCHED; PG8_LDA(At, 1, 0); PG8_STAGE(PG8_SA(0, 1), a2 + hstepA, voffA);
;             PG8_WAIT_L(8); PG8_BAR; PG8_WAIT_L(0); PG8_MMA(0, 0, At, B0); PG8_BAR; PG8_SCHED;
;             PG8_LDB(B1, 1, 1); PG8_STAGE(PG8_SB(1, 0), b3, voffB);
;             PG8_BAR; PG8_WAIT_L(0); PG8_MMA(0, 1, At, B1); PG8_BAR;
;             PG8_LDA(At, 1, 1); PG8_STAGE(PG8_SA(1, 0), a3, voffA);
;             PG8_BAR; PG8_WAIT_L(0); PG8_MMA(1, 0, At, B0); PG8_BAR; PG8_SCHED;
	s_add_u32 s8, s12, 0x160000
	s_addc_u32 s9, s13, 0
	s_add_i32 s39, s36, s22
	s_mov_b32 m0, s39
	s_nop 0
	global_load_lds_dwordx4 v132, s[8:9]
	s_add_i32 m0, s39, 0x2000
	s_nop 0
	global_load_lds_dwordx4 v128, s[8:9]
	s_waitcnt vmcnt(6)
	s_barrier
	s_setprio 1
	v_mfma_f32_16x16x32_bf16 v[52:55], v[202:205], v[168:171], v[52:55]
	v_mfma_f32_16x16x32_bf16 v[48:51], v[210:213], v[168:171], v[48:51]
	s_add_i32 s39, 0, 0x18000
	v_add_u32_e32 v164, s39, v148
	ds_read_b128 v[152:155], v164
	v_mfma_f32_16x16x32_bf16 v[36:39], v[202:205], v[176:179], v[36:39]
	v_mfma_f32_16x16x32_bf16 v[32:35], v[210:213], v[176:179], v[32:35]
	ds_read_b128 v[156:159], v164 offset:1024
	v_mfma_f32_16x16x32_bf16 v[20:23], v[202:205], v[184:187], v[20:23]
	v_mfma_f32_16x16x32_bf16 v[16:19], v[210:213], v[184:187], v[16:19]
	ds_read_b128 v[160:163], v164 offset:2048
	v_mfma_f32_16x16x32_bf16 v[4:7], v[202:205], v[192:195], v[4:7]
	v_mfma_f32_16x16x32_bf16 v[0:3], v[210:213], v[192:195], v[0:3]
	ds_read_b128 v[164:167], v164 offset:3072
	v_mfma_f32_16x16x32_bf16 v[52:55], v[206:209], v[172:175], v[52:55]
	v_mfma_f32_16x16x32_bf16 v[48:51], v[214:217], v[172:175], v[48:51]
	v_mfma_f32_16x16x32_bf16 v[36:39], v[206:209], v[180:183], v[36:39]
	v_mfma_f32_16x16x32_bf16 v[32:35], v[214:217], v[180:183], v[32:35]
	v_mfma_f32_16x16x32_bf16 v[20:23], v[206:209], v[188:191], v[20:23]
	v_mfma_f32_16x16x32_bf16 v[16:19], v[214:217], v[188:191], v[16:19]
	v_mfma_f32_16x16x32_bf16 v[4:7], v[206:209], v[198:201], v[4:7]
	v_mfma_f32_16x16x32_bf16 v[0:3], v[214:217], v[198:201], v[0:3]
	s_setprio 0
	s_barrier
	ds_read_b128 v[168:171], v150 offset:32768
	ds_read_b128 v[172:175], v150 offset:33792
	ds_read_b128 v[176:179], v150 offset:34816
	ds_read_b128 v[180:183], v150 offset:35840
	ds_read_b128 v[184:187], v150 offset:36864
	ds_read_b128 v[188:191], v150 offset:37888
	ds_read_b128 v[192:195], v150 offset:38912
	ds_read_b128 v[198:201], v150 offset:39936
	s_add_u32 s8, s14, 0x160000
	s_addc_u32 s9, s15, 0
	s_mov_b32 m0, s26
	s_nop 0
	global_load_lds_dwordx4 v134, s[8:9]
	s_mov_b32 m0, s27
	s_nop 0
	global_load_lds_dwordx4 v130, s[8:9]
	s_waitcnt lgkmcnt(8)
	s_barrier
	s_setprio 1
	s_waitcnt lgkmcnt(7)
	v_mfma_f32_16x16x32_bf16 v[124:127], v[152:155], v[168:171], v[124:127]
	v_mfma_f32_16x16x32_bf16 v[120:123], v[160:163], v[168:171], v[120:123]
	s_waitcnt lgkmcnt(5)
	v_mfma_f32_16x16x32_bf16 v[108:111], v[152:155], v[176:179], v[108:111]
	v_mfma_f32_16x16x32_bf16 v[104:107], v[160:163], v[176:179], v[104:107]
	s_waitcnt lgkmcnt(3)
	v_mfma_f32_16x16x32_bf16 v[92:95], v[152:155], v[184:187], v[92:95]
	v_mfma_f32_16x16x32_bf16 v[88:91], v[160:163], v[184:187], v[88:91]
	s_waitcnt lgkmcnt(1)
	v_mfma_f32_16x16x32_bf16 v[76:79], v[152:155], v[192:195], v[76:79]
	v_mfma_f32_16x16x32_bf16 v[72:75], v[160:163], v[192:195], v[72:75]
	v_mfma_f32_16x16x32_bf16 v[124:127], v[156:159], v[172:175], v[124:127]
	v_mfma_f32_16x16x32_bf16 v[120:123], v[164:167], v[172:175], v[120:123]
	v_mfma_f32_16x16x32_bf16 v[108:111], v[156:159], v[180:183], v[108:111]
	v_mfma_f32_16x16x32_bf16 v[104:107], v[164:167], v[180:183], v[104:107]
	v_mfma_f32_16x16x32_bf16 v[92:95], v[156:159], v[188:191], v[92:95]
	v_mfma_f32_16x16x32_bf16 v[88:91], v[164:167], v[188:191], v[88:91]
	s_waitcnt lgkmcnt(0)
	v_mfma_f32_16x16x32_bf16 v[76:79], v[156:159], v[198:201], v[76:79]
	v_mfma_f32_16x16x32_bf16 v[72:75], v[164:167], v[198:201], v[72:75]
	s_setprio 0
	s_barrier
	s_add_i32 s14, 0, 0x1c000
	v_add_u32_e32 v196, s14, v148
	ds_read_b128 v[202:205], v196
	ds_read_b128 v[206:209], v196 offset:1024
	ds_read_b128 v[210:213], v196 offset:2048
	ds_read_b128 v[214:217], v196 offset:3072
	s_add_i32 s8, s39, s22
	v_lshl_add_u64 v[144:145], v[144:145], 0, s[52:53]
	s_mov_b32 m0, s8
	s_nop 0
	global_load_lds_dwordx4 v[144:145], off
	v_lshl_add_u64 v[144:145], v[218:219], 0, s[52:53]
	s_add_i32 m0, s8, 0x2000
	s_nop 0
	global_load_lds_dwordx4 v[144:145], off
	s_barrier
	s_setprio 1
	s_waitcnt lgkmcnt(3)
	v_mfma_f32_16x16x32_bf16 v[116:119], v[202:205], v[168:171], v[116:119]
	s_waitcnt lgkmcnt(1)
	v_mfma_f32_16x16x32_bf16 v[112:115], v[210:213], v[168:171], v[112:115]
	v_mfma_f32_16x16x32_bf16 v[100:103], v[202:205], v[176:179], v[100:103]
	v_mfma_f32_16x16x32_bf16 v[96:99], v[210:213], v[176:179], v[96:99]
	v_mfma_f32_16x16x32_bf16 v[84:87], v[202:205], v[184:187], v[84:87]
	v_mfma_f32_16x16x32_bf16 v[80:83], v[210:213], v[184:187], v[80:83]
	v_mfma_f32_16x16x32_bf16 v[68:71], v[202:205], v[192:195], v[68:71]
	v_mfma_f32_16x16x32_bf16 v[64:67], v[210:213], v[192:195], v[64:67]
	v_mfma_f32_16x16x32_bf16 v[116:119], v[206:209], v[172:175], v[116:119]
	s_mov_b32 m0, s30
	s_waitcnt lgkmcnt(0)
	v_mfma_f32_16x16x32_bf16 v[112:115], v[214:217], v[172:175], v[112:115]
	v_lshl_add_u64 v[144:145], v[220:221], 0, s[52:53]
	v_mfma_f32_16x16x32_bf16 v[100:103], v[206:209], v[180:183], v[100:103]
	v_mfma_f32_16x16x32_bf16 v[96:99], v[214:217], v[180:183], v[96:99]
	v_mfma_f32_16x16x32_bf16 v[84:87], v[206:209], v[188:191], v[84:87]
	v_mfma_f32_16x16x32_bf16 v[80:83], v[214:217], v[188:191], v[80:83]
	v_mfma_f32_16x16x32_bf16 v[68:71], v[206:209], v[198:201], v[68:71]
	v_mfma_f32_16x16x32_bf16 v[64:67], v[214:217], v[198:201], v[64:67]
	s_setprio 0
	s_barrier
	ds_read_b128 v[168:171], v150 offset:49152
	ds_read_b128 v[172:175], v150 offset:50176
	ds_read_b128 v[176:179], v150 offset:51200
	ds_read_b128 v[180:183], v150 offset:52224
	ds_read_b128 v[184:187], v150 offset:53248
	ds_read_b128 v[188:191], v150 offset:54272
	ds_read_b128 v[192:195], v150 offset:55296
	ds_read_b128 v[198:201], v150 offset:56320
	global_load_lds_dwordx4 v[144:145], off
	v_lshl_add_u64 v[144:145], v[222:223], 0, s[52:53]
	s_mov_b32 m0, s31
	s_nop 0
	global_load_lds_dwordx4 v[144:145], off
	s_waitcnt vmcnt(10)
	s_barrier
; DI unsigned pack2(float a, float b) { f32x2 v = {a, b}; hwbf16x2 r = __builtin_convertvector(v, hwbf16x2); return __builtin_bit_cast(unsigned, r); }
; DI float bflo(unsigned w) { return __uint_as_float(w << 16); }
; DI float bfhi(unsigned w) { return __uint_as_float(w & 0xffff0000u); }
; #define PG8_STAGE(bufoff, gbase, voff) do { _Pragma("unroll") for (int _i = 0; _i < 2; ++_i) \
;         __builtin_amdgcn_global_load_lds((const unsigned*)((const char*)(gbase) + (voff)[_i]), (LAS unsigned*)(lds + (bufoff) + ldsw + _i * 8192), 16, 0, 0); } while (0)
; #define PG8_WAIT_V(n) asm volatile("s_waitcnt vmcnt(" #n ")" ::: "memory")
; #define PG8_WAIT_L(n) asm volatile("s_waitcnt lgkmcnt(" #n ")" ::: "memory")
;     DI void operator()(const f32x4 (&acc)[2][2][4][2], const Unit& u, int wr, int wc, int fr, int fq) const {
;     ...
;         for (int ai = 0; ai < 2; ++ai)
; #pragma unroll
;             for (int m = 0; m < 4; ++m) { const size_t ro = (size_t)(row0 + ai * HALF + m * 16) * D + col0;
; #pragma unroll
;                 for (int bj = 0; bj < 2; ++bj) {
;                     f32x4 x0, x1;
;                     if constexpr (IB) { const u32x4 w = *(const u32x4*)((const bf16_t*)Xin + ro + bj * HALF);
;                         x0 = (f32x4){bflo(w[0]), bfhi(w[0]), bflo(w[1]), bfhi(w[1])}; x1 = (f32x4){bflo(w[2]), bfhi(w[2]), bflo(w[3]), bfhi(w[3])}; }
;                     else { x0 = *(const f32x4*)((const float*)Xin + ro + bj * HALF); x1 = *(const f32x4*)((const float*)Xin + ro + bj * HALF + 4); }
;                     x0 += acc[ai][bj][m][0] * sc[bj][0]; x1 += acc[ai][bj][m][1] * sc[bj][1];
;                     if constexpr (OB) { u32x4 o; o[0] = pack2(x0[0], x0[1]); o[1] = pack2(x0[2], x0[3]); o[2] = pack2(x1[0], x1[1]); o[3] = pack2(x1[2], x1[3]);
;                         *(u32x4*)((bf16_t*)Xout + ro + bj * HALF) = o; }
;                     else { *(f32x4*)((float*)Xout + ro + bj * HALF) = x0; *(f32x4*)((float*)Xout + ro + bj * HALF + 4) = x1; } } }
; template <class Map, class Epi>
; DI void gemm_phase(LAS unsigned char* lds, const Map& MP, const Epi& E, const int nM, const int nN, const int K, const int lda, const int ldb) {
;     ...
;             PG8_BAR; PG8_WAIT_L(0); PG8_MMA(1, 0, At, B0); PG8_BAR; PG8_SCHED;
;             PG8_STAGE(PG8_SB(1, 1), b3 + hstepB, voffB);
;             PG8_WAIT_V(6); PG8_BAR; PG8_MMA(1, 1, At, B1); PG8_BAR;
	s_setprio 1
	s_waitcnt lgkmcnt(7)
	v_mfma_f32_16x16x32_bf16 v[60:63], v[152:155], v[168:171], v[60:63]
	v_mfma_f32_16x16x32_bf16 v[56:59], v[160:163], v[168:171], v[56:59]
	s_waitcnt lgkmcnt(5)
	v_mfma_f32_16x16x32_bf16 v[44:47], v[152:155], v[176:179], v[44:47]
	v_mfma_f32_16x16x32_bf16 v[40:43], v[160:163], v[176:179], v[40:43]
	s_waitcnt lgkmcnt(3)
	v_mfma_f32_16x16x32_bf16 v[28:31], v[152:155], v[184:187], v[28:31]
	v_mfma_f32_16x16x32_bf16 v[24:27], v[160:163], v[184:187], v[24:27]
	s_waitcnt lgkmcnt(1)
	v_mfma_f32_16x16x32_bf16 v[12:15], v[152:155], v[192:195], v[12:15]
	v_mfma_f32_16x16x32_bf16 v[8:11], v[160:163], v[192:195], v[8:11]
	v_mfma_f32_16x16x32_bf16 v[60:63], v[156:159], v[172:175], v[60:63]
	v_mfma_f32_16x16x32_bf16 v[56:59], v[164:167], v[172:175], v[56:59]
	v_mfma_f32_16x16x32_bf16 v[44:47], v[156:159], v[180:183], v[44:47]
	v_mfma_f32_16x16x32_bf16 v[40:43], v[164:167], v[180:183], v[40:43]
	v_mfma_f32_16x16x32_bf16 v[28:31], v[156:159], v[188:191], v[28:31]
	v_mfma_f32_16x16x32_bf16 v[24:27], v[164:167], v[188:191], v[24:27]
	s_waitcnt lgkmcnt(0)
	v_mfma_f32_16x16x32_bf16 v[12:15], v[156:159], v[198:201], v[12:15]
	v_mfma_f32_16x16x32_bf16 v[8:11], v[164:167], v[198:201], v[8:11]
	s_setprio 0
	s_barrier
	s_add_u32 s8, s12, 0x160080
	s_addc_u32 s9, s13, 0
	s_add_i32 s12, s14, s22
	s_mov_b32 m0, s12
	s_nop 0
	global_load_lds_dwordx4 v132, s[8:9]
	s_add_i32 m0, s12, 0x2000
	s_nop 0
	global_load_lds_dwordx4 v128, s[8:9]
	s_waitcnt vmcnt(6)
	s_barrier
	s_setprio 1
	v_mfma_f32_16x16x32_bf16 v[52:55], v[202:205], v[168:171], v[52:55]
	v_mfma_f32_16x16x32_bf16 v[48:51], v[210:213], v[168:171], v[48:51]
	ds_read_b128 v[152:155], v149
	v_mfma_f32_16x16x32_bf16 v[36:39], v[202:205], v[176:179], v[36:39]
	v_mfma_f32_16x16x32_bf16 v[32:35], v[210:213], v[176:179], v[32:35]
	ds_read_b128 v[156:159], v149 offset:1024
	v_mfma_f32_16x16x32_bf16 v[20:23], v[202:205], v[184:187], v[20:23]
	v_mfma_f32_16x16x32_bf16 v[16:19], v[210:213], v[184:187], v[16:19]
	ds_read_b128 v[160:163], v149 offset:2048
	v_mfma_f32_16x16x32_bf16 v[4:7], v[202:205], v[192:195], v[4:7]
	v_mfma_f32_16x16x32_bf16 v[0:3], v[210:213], v[192:195], v[0:3]
	ds_read_b128 v[164:167], v149 offset:3072
	v_mfma_f32_16x16x32_bf16 v[52:55], v[206:209], v[172:175], v[52:55]
	s_add_i32 s3, s3, 2
	v_mfma_f32_16x16x32_bf16 v[48:51], v[214:217], v[172:175], v[48:51]
	s_add_u32 s5, s5, 0x100
	s_addc_u32 s38, s38, 0
	v_mfma_f32_16x16x32_bf16 v[36:39], v[206:209], v[180:183], v[36:39]
	s_cmpk_gt_u32 s3, 0x55
	v_mfma_f32_16x16x32_bf16 v[32:35], v[214:217], v[180:183], v[32:35]
	s_mov_b64 s[8:9], s[10:11]
	v_mfma_f32_16x16x32_bf16 v[20:23], v[206:209], v[188:191], v[20:23]
	v_mfma_f32_16x16x32_bf16 v[16:19], v[214:217], v[188:191], v[16:19]
	v_mfma_f32_16x16x32_bf16 v[4:7], v[206:209], v[198:201], v[4:7]
	v_mfma_f32_16x16x32_bf16 v[0:3], v[214:217], v[198:201], v[0:3]
	s_setprio 0
	s_barrier
	s_cbranch_scc0 .LBB1_1239
	s_waitcnt lgkmcnt(0)
	v_mov_b32_e32 v152, v147
	v_mov_b32_e32 v144, v146
	s_lshl_b32 s2, s2, 8
	s_add_i32 s2, s2, s29
	s_lshl_b32 s3, s4, 8
	v_add_u32_e32 v152, s2, v152
	s_or_b32 s3, s3, s54
	v_ashrrev_i32_e32 v153, 31, v152
	v_lshl_add_u32 v144, v144, 3, s3
	v_lshlrev_b64 v[152:153], 12, v[152:153]
	v_ashrrev_i32_e32 v145, 31, v144
	v_lshl_add_u64 v[152:153], s[46:47], 0, v[152:153]
	v_lshl_add_u64 v[144:145], v[144:145], 1, v[152:153]
	global_load_dwordx4 v[160:163], v[144:145], off
	global_load_dwordx4 v[164:167], v[144:145], off offset:256
	s_mov_b64 s[98:99], 0x10000
	v_lshl_add_u64 v[154:155], v[144:145], 0, s[98:99]
	global_load_dwordx4 v[168:171], v[154:155], off
	global_load_dwordx4 v[172:175], v[154:155], off offset:256
	s_mov_b64 s[98:99], 0x20000
	v_lshl_add_u64 v[154:155], v[144:145], 0, s[98:99]
	global_load_dwordx4 v[176:179], v[154:155], off
	global_load_dwordx4 v[180:183], v[154:155], off offset:256
	s_mov_b64 s[98:99], 0x30000
	v_lshl_add_u64 v[154:155], v[144:145], 0, s[98:99]
	global_load_dwordx4 v[184:187], v[154:155], off
	global_load_dwordx4 v[188:191], v[154:155], off offset:256
	s_mov_b64 s[98:99], 0x80000
	v_lshl_add_u64 v[154:155], v[144:145], 0, s[98:99]
	global_load_dwordx4 v[192:195], v[154:155], off
	global_load_dwordx4 v[198:201], v[154:155], off offset:256
	s_mov_b64 s[98:99], 0x90000
	v_lshl_add_u64 v[154:155], v[144:145], 0, s[98:99]
	global_load_dwordx4 v[202:205], v[154:155], off
	global_load_dwordx4 v[206:209], v[154:155], off offset:256
	s_mov_b64 s[98:99], 0xa0000
	v_lshl_add_u64 v[154:155], v[144:145], 0, s[98:99]
	global_load_dwordx4 v[210:213], v[154:155], off
	global_load_dwordx4 v[214:217], v[154:155], off offset:256
	s_mov_b64 s[98:99], 0xb0000
	v_lshl_add_u64 v[154:155], v[144:145], 0, s[98:99]
	global_load_dwordx4 v[248:251], v[154:155], off
	global_load_dwordx4 v[252:255], v[154:155], off offset:256
	s_waitcnt vmcnt(15)
	s_nop 1
	v_mov_b32_e32 v152, v160
	v_mov_b32_e32 v153, v161
	v_mov_b32_e32 v154, v162
	v_mov_b32_e32 v155, v163
	s_mov_b64 s[2:3], 0x10000
	s_mov_b32 s4, s37
	s_mov_b64 s[10:11], s[6:7]
	s_mov_b64 s[8:9], s[42:43]
	s_waitcnt lgkmcnt(0)
	v_lshlrev_b32_e32 v156, 16, v152
	v_and_b32_e32 v157, 0xffff0000, v152
	v_lshlrev_b32_e32 v152, 16, v153
	v_and_b32_e32 v153, 0xffff0000, v153
	v_lshlrev_b32_e32 v158, 16, v154
	v_and_b32_e32 v159, 0xffff0000, v154
	v_lshlrev_b32_e32 v154, 16, v155
	v_and_b32_e32 v155, 0xffff0000, v155
	v_pk_add_f32 v[126:127], v[126:127], v[152:153]
	v_pk_add_f32 v[124:125], v[124:125], v[156:157]
	v_pk_add_f32 v[152:153], v[122:123], v[154:155]
	v_pk_add_f32 v[122:123], v[120:121], v[158:159]
	v_cvt_pk_bf16_f32 v120, v124, v125
	v_cvt_pk_bf16_f32 v121, v126, v127
	v_cvt_pk_bf16_f32 v122, v122, v123
	v_cvt_pk_bf16_f32 v123, v152, v153
	global_store_dwordx4 v[144:145], v[120:123], off
	s_waitcnt vmcnt(15)
; DI unsigned pack2(float a, float b) { f32x2 v = {a, b}; hwbf16x2 r = __builtin_convertvector(v, hwbf16x2); return __builtin_bit_cast(unsigned, r); }
; DI float bflo(unsigned w) { return __uint_as_float(w << 16); }
; DI float bfhi(unsigned w) { return __uint_as_float(w & 0xffff0000u); }
;     DI void operator()(const f32x4 (&acc)[2][2][4][2], const Unit& u, int wr, int wc, int fr, int fq) const {
;     ...
;         for (int ai = 0; ai < 2; ++ai)
; #pragma unroll
;             for (int m = 0; m < 4; ++m) { const size_t ro = (size_t)(row0 + ai * HALF + m * 16) * D + col0;
; #pragma unroll
;                 for (int bj = 0; bj < 2; ++bj) {
;                     f32x4 x0, x1;
;                     if constexpr (IB) { const u32x4 w = *(const u32x4*)((const bf16_t*)Xin + ro + bj * HALF);
;                         x0 = (f32x4){bflo(w[0]), bfhi(w[0]), bflo(w[1]), bfhi(w[1])}; x1 = (f32x4){bflo(w[2]), bfhi(w[2]), bflo(w[3]), bfhi(w[3])}; }
;                     else { x0 = *(const f32x4*)((const float*)Xin + ro + bj * HALF); x1 = *(const f32x4*)((const float*)Xin + ro + bj * HALF + 4); }
;                     x0 += acc[ai][bj][m][0] * sc[bj][0]; x1 += acc[ai][bj][m][1] * sc[bj][1];
;                     if constexpr (OB) { u32x4 o; o[0] = pack2(x0[0], x0[1]); o[1] = pack2(x0[2], x0[3]); o[2] = pack2(x1[0], x1[1]); o[3] = pack2(x1[2], x1[3]);
;                         *(u32x4*)((bf16_t*)Xout + ro + bj * HALF) = o; }
;                     else { *(f32x4*)((float*)Xout + ro + bj * HALF) = x0; *(f32x4*)((float*)Xout + ro + bj * HALF + 4) = x1; } } }
	s_nop 1
	v_mov_b32_e32 v120, v164
	v_mov_b32_e32 v121, v165
	v_mov_b32_e32 v122, v166
	v_mov_b32_e32 v123, v167
	s_waitcnt lgkmcnt(0)
	v_lshlrev_b32_e32 v124, 16, v120
	v_and_b32_e32 v125, 0xffff0000, v120
	v_lshlrev_b32_e32 v120, 16, v121
	v_and_b32_e32 v121, 0xffff0000, v121
	v_lshlrev_b32_e32 v126, 16, v122
	v_and_b32_e32 v127, 0xffff0000, v122
	v_lshlrev_b32_e32 v122, 16, v123
	v_and_b32_e32 v123, 0xffff0000, v123
	v_pk_add_f32 v[116:117], v[116:117], v[124:125]
	v_pk_add_f32 v[118:119], v[118:119], v[120:121]
	v_pk_add_f32 v[120:121], v[114:115], v[122:123]
	v_pk_add_f32 v[114:115], v[112:113], v[126:127]
	v_cvt_pk_bf16_f32 v112, v116, v117
	v_lshl_add_u64 v[116:117], v[144:145], 0, s[2:3]
	s_mov_b32 s2, 0x10000
	v_cvt_pk_bf16_f32 v113, v118, v119
	v_add_co_u32_e32 v118, vcc, s2, v144
	v_cvt_pk_bf16_f32 v114, v114, v115
	v_cvt_pk_bf16_f32 v115, v120, v121
	v_addc_co_u32_e32 v119, vcc, 0, v145, vcc
	global_store_dwordx4 v[144:145], v[112:115], off offset:256
	s_waitcnt vmcnt(15)
	s_nop 1
	v_mov_b32_e32 v112, v168
	v_mov_b32_e32 v113, v169
	v_mov_b32_e32 v114, v170
	v_mov_b32_e32 v115, v171
	s_mov_b64 s[2:3], 0x20000
	s_waitcnt lgkmcnt(0)
	v_lshlrev_b32_e32 v120, 16, v112
	v_and_b32_e32 v121, 0xffff0000, v112
	v_lshlrev_b32_e32 v112, 16, v113
	v_and_b32_e32 v113, 0xffff0000, v113
	v_lshlrev_b32_e32 v122, 16, v114
	v_and_b32_e32 v123, 0xffff0000, v114
	v_lshlrev_b32_e32 v114, 16, v115
	v_and_b32_e32 v115, 0xffff0000, v115
	v_pk_add_f32 v[110:111], v[110:111], v[112:113]
	v_pk_add_f32 v[108:109], v[108:109], v[120:121]
	v_pk_add_f32 v[112:113], v[106:107], v[114:115]
	v_pk_add_f32 v[106:107], v[104:105], v[122:123]
	v_cvt_pk_bf16_f32 v104, v108, v109
	v_cvt_pk_bf16_f32 v105, v110, v111
	v_cvt_pk_bf16_f32 v106, v106, v107
	v_cvt_pk_bf16_f32 v107, v112, v113
	global_store_dwordx4 v[118:119], v[104:107], off
	s_waitcnt vmcnt(15)
	s_nop 1
	v_mov_b32_e32 v104, v172
	v_mov_b32_e32 v105, v173
	v_mov_b32_e32 v106, v174
	v_mov_b32_e32 v107, v175
	s_waitcnt lgkmcnt(0)
	v_lshlrev_b32_e32 v108, 16, v104
	v_and_b32_e32 v109, 0xffff0000, v104
	v_lshlrev_b32_e32 v104, 16, v105
	v_and_b32_e32 v105, 0xffff0000, v105
	v_lshlrev_b32_e32 v110, 16, v106
	v_and_b32_e32 v111, 0xffff0000, v106
	v_lshlrev_b32_e32 v106, 16, v107
	v_and_b32_e32 v107, 0xffff0000, v107
	v_pk_add_f32 v[100:101], v[100:101], v[108:109]
	v_pk_add_f32 v[102:103], v[102:103], v[104:105]
	v_pk_add_f32 v[104:105], v[98:99], v[106:107]
	v_pk_add_f32 v[98:99], v[96:97], v[110:111]
	v_cvt_pk_bf16_f32 v96, v100, v101
	v_lshl_add_u64 v[100:101], v[144:145], 0, s[2:3]
	s_mov_b32 s2, 0x20000
	v_cvt_pk_bf16_f32 v97, v102, v103
	v_add_co_u32_e32 v102, vcc, s2, v144
	v_cvt_pk_bf16_f32 v98, v98, v99
	v_cvt_pk_bf16_f32 v99, v104, v105
	v_addc_co_u32_e32 v103, vcc, 0, v145, vcc
	global_store_dwordx4 v[116:117], v[96:99], off offset:256
	s_waitcnt vmcnt(15)
	s_nop 1
	v_mov_b32_e32 v96, v176
	v_mov_b32_e32 v97, v177
	v_mov_b32_e32 v98, v178
	v_mov_b32_e32 v99, v179
	s_mov_b64 s[2:3], 0x30000
	s_waitcnt lgkmcnt(0)
	v_lshlrev_b32_e32 v104, 16, v96
	v_and_b32_e32 v105, 0xffff0000, v96
	v_lshlrev_b32_e32 v96, 16, v97
	v_and_b32_e32 v97, 0xffff0000, v97
	v_lshlrev_b32_e32 v106, 16, v98
	v_and_b32_e32 v107, 0xffff0000, v98
	v_lshlrev_b32_e32 v98, 16, v99
	v_and_b32_e32 v99, 0xffff0000, v99
	v_pk_add_f32 v[94:95], v[94:95], v[96:97]
	v_pk_add_f32 v[92:93], v[92:93], v[104:105]
	v_pk_add_f32 v[96:97], v[90:91], v[98:99]
	v_pk_add_f32 v[90:91], v[88:89], v[106:107]
	v_cvt_pk_bf16_f32 v88, v92, v93
	v_cvt_pk_bf16_f32 v89, v94, v95
	v_cvt_pk_bf16_f32 v90, v90, v91
	v_cvt_pk_bf16_f32 v91, v96, v97
	global_store_dwordx4 v[102:103], v[88:91], off
	s_waitcnt vmcnt(15)
	s_nop 1
	v_mov_b32_e32 v88, v180
	v_mov_b32_e32 v89, v181
	v_mov_b32_e32 v90, v182
	v_mov_b32_e32 v91, v183
	s_waitcnt lgkmcnt(0)
	v_lshlrev_b32_e32 v92, 16, v88
	v_and_b32_e32 v93, 0xffff0000, v88
	v_lshlrev_b32_e32 v88, 16, v89
	v_and_b32_e32 v89, 0xffff0000, v89
	v_lshlrev_b32_e32 v94, 16, v90
	v_and_b32_e32 v95, 0xffff0000, v90
	v_lshlrev_b32_e32 v90, 16, v91
	v_and_b32_e32 v91, 0xffff0000, v91
	v_pk_add_f32 v[86:87], v[86:87], v[88:89]
	v_pk_add_f32 v[84:85], v[84:85], v[92:93]
	v_pk_add_f32 v[88:89], v[82:83], v[90:91]
	v_pk_add_f32 v[82:83], v[80:81], v[94:95]
	v_cvt_pk_bf16_f32 v80, v84, v85
	v_cvt_pk_bf16_f32 v81, v86, v87
	v_cvt_pk_bf16_f32 v82, v82, v83
	v_cvt_pk_bf16_f32 v83, v88, v89
	global_store_dwordx4 v[100:101], v[80:83], off offset:256
	s_nop 1
	v_lshl_add_u64 v[80:81], v[144:145], 0, s[2:3]
	s_mov_b32 s2, 0x30000
	v_add_co_u32_e32 v86, vcc, s2, v144
	s_mov_b64 s[2:3], 0x80000
	s_nop 0
	v_addc_co_u32_e32 v87, vcc, 0, v145, vcc
	s_waitcnt vmcnt(15)
	s_nop 1
	v_mov_b32_e32 v82, v184
	v_mov_b32_e32 v83, v185
	v_mov_b32_e32 v84, v186
	v_mov_b32_e32 v85, v187
	s_waitcnt lgkmcnt(0)
	v_lshlrev_b32_e32 v88, 16, v82
	v_and_b32_e32 v89, 0xffff0000, v82
	v_lshlrev_b32_e32 v82, 16, v83
	v_and_b32_e32 v83, 0xffff0000, v83
	v_lshlrev_b32_e32 v90, 16, v84
	v_and_b32_e32 v91, 0xffff0000, v84
	v_lshlrev_b32_e32 v84, 16, v85
	v_and_b32_e32 v85, 0xffff0000, v85
	v_pk_add_f32 v[78:79], v[78:79], v[82:83]
	v_pk_add_f32 v[76:77], v[76:77], v[88:89]
	v_pk_add_f32 v[82:83], v[74:75], v[84:85]
	v_pk_add_f32 v[74:75], v[72:73], v[90:91]
	v_cvt_pk_bf16_f32 v72, v76, v77
	v_cvt_pk_bf16_f32 v73, v78, v79
	v_cvt_pk_bf16_f32 v74, v74, v75
	v_cvt_pk_bf16_f32 v75, v82, v83
	global_store_dwordx4 v[86:87], v[72:75], off
	s_waitcnt vmcnt(15)
	s_nop 1
	v_mov_b32_e32 v72, v188
	v_mov_b32_e32 v73, v189
	v_mov_b32_e32 v74, v190
	v_mov_b32_e32 v75, v191
	s_waitcnt lgkmcnt(0)
; DI unsigned pack2(float a, float b) { f32x2 v = {a, b}; hwbf16x2 r = __builtin_convertvector(v, hwbf16x2); return __builtin_bit_cast(unsigned, r); }
; DI float bflo(unsigned w) { return __uint_as_float(w << 16); }
; DI float bfhi(unsigned w) { return __uint_as_float(w & 0xffff0000u); }
;     DI void operator()(const f32x4 (&acc)[2][2][4][2], const Unit& u, int wr, int wc, int fr, int fq) const {
;     ...
;         for (int ai = 0; ai < 2; ++ai)
; #pragma unroll
;             for (int m = 0; m < 4; ++m) { const size_t ro = (size_t)(row0 + ai * HALF + m * 16) * D + col0;
; #pragma unroll
;                 for (int bj = 0; bj < 2; ++bj) {
;                     f32x4 x0, x1;
;                     if constexpr (IB) { const u32x4 w = *(const u32x4*)((const bf16_t*)Xin + ro + bj * HALF);
;                         x0 = (f32x4){bflo(w[0]), bfhi(w[0]), bflo(w[1]), bfhi(w[1])}; x1 = (f32x4){bflo(w[2]), bfhi(w[2]), bflo(w[3]), bfhi(w[3])}; }
;                     else { x0 = *(const f32x4*)((const float*)Xin + ro + bj * HALF); x1 = *(const f32x4*)((const float*)Xin + ro + bj * HALF + 4); }
;                     x0 += acc[ai][bj][m][0] * sc[bj][0]; x1 += acc[ai][bj][m][1] * sc[bj][1];
;                     if constexpr (OB) { u32x4 o; o[0] = pack2(x0[0], x0[1]); o[1] = pack2(x0[2], x0[3]); o[2] = pack2(x1[0], x1[1]); o[3] = pack2(x1[2], x1[3]);
;                         *(u32x4*)((bf16_t*)Xout + ro + bj * HALF) = o; }
;                     else { *(f32x4*)((float*)Xout + ro + bj * HALF) = x0; *(f32x4*)((float*)Xout + ro + bj * HALF + 4) = x1; } } }
	v_lshlrev_b32_e32 v76, 16, v72
	v_and_b32_e32 v77, 0xffff0000, v72
	v_lshlrev_b32_e32 v72, 16, v73
	v_and_b32_e32 v73, 0xffff0000, v73
	v_lshlrev_b32_e32 v78, 16, v74
	v_and_b32_e32 v79, 0xffff0000, v74
	v_lshlrev_b32_e32 v74, 16, v75
	v_and_b32_e32 v75, 0xffff0000, v75
	v_pk_add_f32 v[70:71], v[70:71], v[72:73]
	v_pk_add_f32 v[68:69], v[68:69], v[76:77]
	v_pk_add_f32 v[72:73], v[66:67], v[74:75]
	v_pk_add_f32 v[66:67], v[64:65], v[78:79]
	v_cvt_pk_bf16_f32 v64, v68, v69
	v_cvt_pk_bf16_f32 v65, v70, v71
	v_cvt_pk_bf16_f32 v66, v66, v67
	v_cvt_pk_bf16_f32 v67, v72, v73
	global_store_dwordx4 v[80:81], v[64:67], off offset:256
	s_nop 1
	v_lshl_add_u64 v[64:65], v[144:145], 0, s[2:3]
	s_mov_b32 s2, 0x80000
	v_add_co_u32_e32 v70, vcc, s2, v144
	s_mov_b64 s[2:3], 0x90000
	s_nop 0
	v_addc_co_u32_e32 v71, vcc, 0, v145, vcc
	s_waitcnt vmcnt(15)
	s_nop 1
	v_mov_b32_e32 v66, v192
	v_mov_b32_e32 v67, v193
	v_mov_b32_e32 v68, v194
	v_mov_b32_e32 v69, v195
	s_waitcnt lgkmcnt(0)
	v_lshlrev_b32_e32 v72, 16, v66
	v_and_b32_e32 v73, 0xffff0000, v66
	v_lshlrev_b32_e32 v66, 16, v67
	v_and_b32_e32 v67, 0xffff0000, v67
	v_lshlrev_b32_e32 v74, 16, v68
	v_and_b32_e32 v75, 0xffff0000, v68
	v_lshlrev_b32_e32 v68, 16, v69
	v_and_b32_e32 v69, 0xffff0000, v69
	v_pk_add_f32 v[62:63], v[62:63], v[66:67]
	v_pk_add_f32 v[60:61], v[60:61], v[72:73]
	v_pk_add_f32 v[66:67], v[58:59], v[68:69]
	v_pk_add_f32 v[58:59], v[56:57], v[74:75]
	v_cvt_pk_bf16_f32 v56, v60, v61
	v_cvt_pk_bf16_f32 v57, v62, v63
	v_cvt_pk_bf16_f32 v58, v58, v59
	v_cvt_pk_bf16_f32 v59, v66, v67
	global_store_dwordx4 v[70:71], v[56:59], off
	s_waitcnt vmcnt(15)
	s_nop 1
	v_mov_b32_e32 v56, v198
	v_mov_b32_e32 v57, v199
	v_mov_b32_e32 v58, v200
	v_mov_b32_e32 v59, v201
	s_waitcnt lgkmcnt(0)
	v_lshlrev_b32_e32 v60, 16, v56
	v_and_b32_e32 v61, 0xffff0000, v56
	v_lshlrev_b32_e32 v56, 16, v57
	v_and_b32_e32 v57, 0xffff0000, v57
	v_lshlrev_b32_e32 v62, 16, v58
	v_and_b32_e32 v63, 0xffff0000, v58
	v_lshlrev_b32_e32 v58, 16, v59
	v_and_b32_e32 v59, 0xffff0000, v59
	v_pk_add_f32 v[54:55], v[54:55], v[56:57]
	v_pk_add_f32 v[52:53], v[52:53], v[60:61]
	v_pk_add_f32 v[56:57], v[50:51], v[58:59]
	v_pk_add_f32 v[50:51], v[48:49], v[62:63]
	v_cvt_pk_bf16_f32 v48, v52, v53
	v_cvt_pk_bf16_f32 v49, v54, v55
	v_cvt_pk_bf16_f32 v50, v50, v51
	v_cvt_pk_bf16_f32 v51, v56, v57
	global_store_dwordx4 v[64:65], v[48:51], off offset:256
	s_nop 1
	v_lshl_add_u64 v[48:49], v[144:145], 0, s[2:3]
	s_mov_b32 s2, 0x90000
	v_add_co_u32_e32 v54, vcc, s2, v144
	s_mov_b64 s[2:3], 0xa0000
	s_nop 0
	v_addc_co_u32_e32 v55, vcc, 0, v145, vcc
	s_waitcnt vmcnt(15)
	s_nop 1
	v_mov_b32_e32 v50, v202
	v_mov_b32_e32 v51, v203
	v_mov_b32_e32 v52, v204
	v_mov_b32_e32 v53, v205
	s_waitcnt lgkmcnt(0)
	v_lshlrev_b32_e32 v56, 16, v50
	v_and_b32_e32 v57, 0xffff0000, v50
	v_lshlrev_b32_e32 v50, 16, v51
	v_and_b32_e32 v51, 0xffff0000, v51
	v_lshlrev_b32_e32 v58, 16, v52
	v_and_b32_e32 v59, 0xffff0000, v52
	v_lshlrev_b32_e32 v52, 16, v53
	v_and_b32_e32 v53, 0xffff0000, v53
	v_pk_add_f32 v[46:47], v[46:47], v[50:51]
	v_pk_add_f32 v[44:45], v[44:45], v[56:57]
	v_pk_add_f32 v[50:51], v[42:43], v[52:53]
	v_pk_add_f32 v[42:43], v[40:41], v[58:59]
	v_cvt_pk_bf16_f32 v40, v44, v45
	v_cvt_pk_bf16_f32 v41, v46, v47
	v_cvt_pk_bf16_f32 v42, v42, v43
	v_cvt_pk_bf16_f32 v43, v50, v51
	global_store_dwordx4 v[54:55], v[40:43], off
	s_waitcnt vmcnt(15)
	s_nop 1
	v_mov_b32_e32 v40, v206
	v_mov_b32_e32 v41, v207
	v_mov_b32_e32 v42, v208
	v_mov_b32_e32 v43, v209
	s_waitcnt lgkmcnt(0)
; DI unsigned pack2(float a, float b) { f32x2 v = {a, b}; hwbf16x2 r = __builtin_convertvector(v, hwbf16x2); return __builtin_bit_cast(unsigned, r); }
; DI float bflo(unsigned w) { return __uint_as_float(w << 16); }
; DI float bfhi(unsigned w) { return __uint_as_float(w & 0xffff0000u); }
;     DI const char* a(const Unit& u) const { return (const char*)(A + (size_t)u.pm * BM * lda); }
;     DI const char* a(const Unit& u) const { return (const char*)(A + (size_t)u.pm * BM * 2048 + (u.pn >> 1) * 512); }
; #define PG8_BAR __builtin_amdgcn_s_barrier()
;     DI void operator()(const f32x4 (&acc)[2][2][4][2], const Unit& u, int wr, int wc, int fr, int fq) const {
;     ...
;             for (int m = 0; m < 4; ++m) { const size_t ro = (size_t)(row0 + ai * HALF + m * 16) * D + col0;
; #pragma unroll
;                 for (int bj = 0; bj < 2; ++bj) {
;                     f32x4 x0, x1;
;                     if constexpr (IB) { const u32x4 w = *(const u32x4*)((const bf16_t*)Xin + ro + bj * HALF);
;                         x0 = (f32x4){bflo(w[0]), bfhi(w[0]), bflo(w[1]), bfhi(w[1])}; x1 = (f32x4){bflo(w[2]), bfhi(w[2]), bflo(w[3]), bfhi(w[3])}; }
;                     else { x0 = *(const f32x4*)((const float*)Xin + ro + bj * HALF); x1 = *(const f32x4*)((const float*)Xin + ro + bj * HALF + 4); }
;                     x0 += acc[ai][bj][m][0] * sc[bj][0]; x1 += acc[ai][bj][m][1] * sc[bj][1];
;                     if constexpr (OB) { u32x4 o; o[0] = pack2(x0[0], x0[1]); o[1] = pack2(x0[2], x0[3]); o[2] = pack2(x1[0], x1[1]); o[3] = pack2(x1[2], x1[3]);
;                         *(u32x4*)((bf16_t*)Xout + ro + bj * HALF) = o; }
;                     else { *(f32x4*)((float*)Xout + ro + bj * HALF) = x0; *(f32x4*)((float*)Xout + ro + bj * HALF + 4) = x1; } } }
; template <class Map, class Epi>
; DI void gemm_phase(LAS unsigned char* lds, const Map& MP, const Epi& E, const int nM, const int nN, const int K, const int lda, const int ldb) {
;     ...
;         if (!has_next) break;
; #pragma unroll
;         for (int a = 0; a < 2; ++a)
; #pragma unroll
;             for (int b = 0; b < 2; ++b)
; #pragma unroll
;                 for (int m = 0; m < 4; ++m)
; #pragma unroll
;                     for (int n = 0; n < 2; ++n) acc[a][b][m][n] = (f32x4){0.f, 0.f, 0.f, 0.f};
;         cur = nxt; cA = nA; cB = nB; ++ui;
;     }
;     PG8_WAIT_V(0);
;     if (wr == 0) PG8_BAR;
;     PG8_BAR;
	v_lshlrev_b32_e32 v44, 16, v40
	v_and_b32_e32 v45, 0xffff0000, v40
	v_lshlrev_b32_e32 v40, 16, v41
	v_and_b32_e32 v41, 0xffff0000, v41
	v_lshlrev_b32_e32 v46, 16, v42
	v_and_b32_e32 v47, 0xffff0000, v42
	v_lshlrev_b32_e32 v42, 16, v43
	v_and_b32_e32 v43, 0xffff0000, v43
	v_pk_add_f32 v[38:39], v[38:39], v[40:41]
	v_pk_add_f32 v[36:37], v[36:37], v[44:45]
	v_pk_add_f32 v[40:41], v[34:35], v[42:43]
	v_pk_add_f32 v[34:35], v[32:33], v[46:47]
	v_cvt_pk_bf16_f32 v32, v36, v37
	v_cvt_pk_bf16_f32 v33, v38, v39
	v_cvt_pk_bf16_f32 v34, v34, v35
	v_cvt_pk_bf16_f32 v35, v40, v41
	global_store_dwordx4 v[48:49], v[32:35], off offset:256
	s_nop 1
	v_lshl_add_u64 v[32:33], v[144:145], 0, s[2:3]
	s_mov_b32 s2, 0xa0000
	v_add_co_u32_e32 v38, vcc, s2, v144
	s_mov_b64 s[2:3], 0xb0000
	s_nop 0
	v_addc_co_u32_e32 v39, vcc, 0, v145, vcc
	s_waitcnt vmcnt(15)
	s_nop 1
	v_mov_b32_e32 v34, v210
	v_mov_b32_e32 v35, v211
	v_mov_b32_e32 v36, v212
	v_mov_b32_e32 v37, v213
	s_waitcnt lgkmcnt(0)
	v_lshlrev_b32_e32 v40, 16, v34
	v_and_b32_e32 v41, 0xffff0000, v34
	v_lshlrev_b32_e32 v34, 16, v35
	v_and_b32_e32 v35, 0xffff0000, v35
	v_lshlrev_b32_e32 v42, 16, v36
	v_and_b32_e32 v43, 0xffff0000, v36
	v_lshlrev_b32_e32 v36, 16, v37
	v_and_b32_e32 v37, 0xffff0000, v37
	v_pk_add_f32 v[30:31], v[30:31], v[34:35]
	v_pk_add_f32 v[28:29], v[28:29], v[40:41]
	v_pk_add_f32 v[34:35], v[26:27], v[36:37]
	v_pk_add_f32 v[26:27], v[24:25], v[42:43]
	v_cvt_pk_bf16_f32 v24, v28, v29
	v_cvt_pk_bf16_f32 v25, v30, v31
	v_cvt_pk_bf16_f32 v26, v26, v27
	v_cvt_pk_bf16_f32 v27, v34, v35
	global_store_dwordx4 v[38:39], v[24:27], off
	s_waitcnt vmcnt(15)
	s_nop 1
	v_mov_b32_e32 v24, v214
	v_mov_b32_e32 v25, v215
	v_mov_b32_e32 v26, v216
	v_mov_b32_e32 v27, v217
	s_waitcnt lgkmcnt(0)
	v_lshlrev_b32_e32 v28, 16, v24
	v_and_b32_e32 v29, 0xffff0000, v24
	v_lshlrev_b32_e32 v24, 16, v25
	v_and_b32_e32 v25, 0xffff0000, v25
	v_lshlrev_b32_e32 v30, 16, v26
	v_and_b32_e32 v31, 0xffff0000, v26
	v_lshlrev_b32_e32 v26, 16, v27
	v_and_b32_e32 v27, 0xffff0000, v27
	v_pk_add_f32 v[22:23], v[22:23], v[24:25]
	v_pk_add_f32 v[20:21], v[20:21], v[28:29]
	v_pk_add_f32 v[24:25], v[18:19], v[26:27]
	v_pk_add_f32 v[18:19], v[16:17], v[30:31]
	v_cvt_pk_bf16_f32 v16, v20, v21
	v_cvt_pk_bf16_f32 v17, v22, v23
	v_cvt_pk_bf16_f32 v18, v18, v19
	v_cvt_pk_bf16_f32 v19, v24, v25
	global_store_dwordx4 v[32:33], v[16:19], off offset:256
	s_nop 1
	v_lshl_add_u64 v[16:17], v[144:145], 0, s[2:3]
	s_mov_b32 s2, 0xb0000
	v_add_co_u32_e32 v22, vcc, s2, v144
	s_mov_b32 s2, s55
	s_nop 0
	v_addc_co_u32_e32 v23, vcc, 0, v145, vcc
	s_waitcnt vmcnt(15)
	s_nop 1
	v_mov_b32_e32 v18, v248
	v_mov_b32_e32 v19, v249
	v_mov_b32_e32 v20, v250
	v_mov_b32_e32 v21, v251
	s_and_b64 vcc, exec, s[40:41]
	s_waitcnt lgkmcnt(0)
	v_lshlrev_b32_e32 v24, 16, v18
	v_and_b32_e32 v25, 0xffff0000, v18
	v_lshlrev_b32_e32 v18, 16, v19
	v_and_b32_e32 v19, 0xffff0000, v19
	v_lshlrev_b32_e32 v26, 16, v20
	v_and_b32_e32 v27, 0xffff0000, v20
	v_lshlrev_b32_e32 v20, 16, v21
	v_and_b32_e32 v21, 0xffff0000, v21
	v_pk_add_f32 v[14:15], v[14:15], v[18:19]
	v_pk_add_f32 v[12:13], v[12:13], v[24:25]
	v_pk_add_f32 v[18:19], v[10:11], v[20:21]
	v_pk_add_f32 v[10:11], v[8:9], v[26:27]
	v_cvt_pk_bf16_f32 v8, v12, v13
	v_cvt_pk_bf16_f32 v9, v14, v15
	v_cvt_pk_bf16_f32 v10, v10, v11
	v_cvt_pk_bf16_f32 v11, v18, v19
	global_store_dwordx4 v[22:23], v[8:11], off
	s_waitcnt vmcnt(15)
	s_nop 1
	v_mov_b32_e32 v8, v252
	v_mov_b32_e32 v9, v253
	v_mov_b32_e32 v10, v254
	v_mov_b32_e32 v11, v255
	s_waitcnt lgkmcnt(0)
	v_lshlrev_b32_e32 v12, 16, v8
	v_and_b32_e32 v13, 0xffff0000, v8
	v_lshlrev_b32_e32 v8, 16, v9
	v_and_b32_e32 v9, 0xffff0000, v9
	v_lshlrev_b32_e32 v14, 16, v10
	v_and_b32_e32 v15, 0xffff0000, v10
	v_lshlrev_b32_e32 v10, 16, v11
	v_and_b32_e32 v11, 0xffff0000, v11
	v_pk_add_f32 v[6:7], v[6:7], v[8:9]
	v_pk_add_f32 v[4:5], v[4:5], v[12:13]
	v_pk_add_f32 v[8:9], v[2:3], v[10:11]
	v_pk_add_f32 v[2:3], v[0:1], v[14:15]
	v_cvt_pk_bf16_f32 v0, v4, v5
	v_cvt_pk_bf16_f32 v1, v6, v7
	v_cvt_pk_bf16_f32 v2, v2, v3
	v_cvt_pk_bf16_f32 v3, v8, v9
	global_store_dwordx4 v[16:17], v[0:3], off offset:256
	s_cbranch_vccz .LBB1_1232
	s_waitcnt vmcnt(0)
	s_cmpk_gt_u32 s17, 0xff
	s_cbranch_scc1 .LBB1_1243
	s_barrier

; #define PG8_STAGE(bufoff, gbase, voff) do { _Pragma("unroll") for (int _i = 0; _i < 2; ++_i) \
;         __builtin_amdgcn_global_load_lds((const unsigned*)((const char*)(gbase) + (voff)[_i]), (LAS unsigned*)(lds + (bufoff) + ldsw + _i * 8192), 16, 0, 0); } while (0)
; #define PG8_LDA(dst, b, h) do { _Pragma("unroll") for (int m = 0; m < 4; ++m) _Pragma("unroll") for (int k = 0; k < 2; ++k) dst[m][k] = *(const LAS bf16x8*)(lds + PG8_SA(b, h) + aoff + m * 2048 + k * 1024); } while (0)
; #define PG8_LDB(dst, b, h) do { _Pragma("unroll") for (int n = 0; n < 2; ++n) _Pragma("unroll") for (int k = 0; k < 2; ++k) dst[n][k] = *(const LAS bf16x8*)(lds + PG8_SB(b, h) + boff + n * 2048 + k * 1024); } while (0)
; #define PG8_MMA(ai, bj, At, Bt) do { __builtin_amdgcn_s_setprio(1); _Pragma("unroll") for (int m = 0; m < 4; ++m) _Pragma("unroll") for (int n = 0; n < 2; ++n) _Pragma("unroll") for (int k = 0; k < 2; ++k) \
;         acc[ai][bj][m][n] = __builtin_amdgcn_mfma_f32_16x16x32_bf16(Bt[n][k], At[m][k], acc[ai][bj][m][n], 0, 0, 0); __builtin_amdgcn_s_setprio(0); } while (0)
; #define PG8_WAIT_L(n) asm volatile("s_waitcnt lgkmcnt(" #n ")" ::: "memory")
; #define PG8_BAR __builtin_amdgcn_s_barrier()
; #define PG8_SCHED __builtin_amdgcn_sched_barrier(0)
; template <class Map, class Epi>
; DI void gemm_phase(LAS unsigned char* lds, const Map& MP, const Epi& E, const int nM, const int nN, const int K, const int lda, const int ldb) {
;     ...
;             PG8_LDB(B0, 0, 0); PG8_SCHED; PG8_LDA(At, 0, 0); PG8_STAGE(PG8_SA(1, 1), a1 + hstepA, voffA);
;             PG8_WAIT_L(8); PG8_BAR; PG8_WAIT_L(0); PG8_MMA(0, 0, At, B0); PG8_BAR; PG8_SCHED;
;             PG8_LDB(B1, 0, 1); PG8_STAGE(PG8_SB(0, 0), b2, voffB);
;             PG8_BAR; PG8_WAIT_L(0); PG8_MMA(0, 1, At, B1); PG8_BAR;
;             PG8_LDA(At, 0, 1); PG8_STAGE(PG8_SA(0, 0), a2, voffA);
;             PG8_BAR; PG8_WAIT_L(0); PG8_MMA(1, 0, At, B0); PG8_BAR; PG8_SCHED;
.LBB1_1382:
	ds_read_b128 v[166:169], v148
	ds_read_b128 v[170:173], v148 offset:1024
	ds_read_b128 v[174:177], v148 offset:2048
	ds_read_b128 v[178:181], v148 offset:3072
	ds_read_b128 v[182:185], v148 offset:4096
	ds_read_b128 v[186:189], v148 offset:5120
	ds_read_b128 v[190:193], v148 offset:6144
	ds_read_b128 v[198:201], v148 offset:7168
	s_add_u32 s22, s20, 0xfff80080
	s_addc_u32 s23, s21, -1
	s_cmp_eq_u32 s3, 28
	s_cselect_b32 s25, s15, s23
	s_cselect_b32 s24, s48, s22
	s_cselect_b32 s23, s13, s53
	s_cselect_b32 s22, s49, s52
	s_add_i32 m0, s31, 0xc000
	s_nop 0
	global_load_lds_dwordx4 v138, s[20:21]
	s_add_i32 m0, s31, 0xe000
	s_nop 0
	global_load_lds_dwordx4 v136, s[20:21]
	s_waitcnt lgkmcnt(8)
	s_barrier
	s_setprio 1
	s_waitcnt lgkmcnt(7)
	v_mfma_f32_16x16x32_bf16 v[124:127], v[150:153], v[166:169], v[124:127]
	v_mfma_f32_16x16x32_bf16 v[120:123], v[158:161], v[166:169], v[120:123]
	s_waitcnt lgkmcnt(5)
	v_mfma_f32_16x16x32_bf16 v[116:119], v[150:153], v[174:177], v[116:119]
	v_mfma_f32_16x16x32_bf16 v[112:115], v[158:161], v[174:177], v[112:115]
	s_waitcnt lgkmcnt(3)
	v_mfma_f32_16x16x32_bf16 v[100:103], v[150:153], v[182:185], v[100:103]
	v_mfma_f32_16x16x32_bf16 v[96:99], v[158:161], v[182:185], v[96:99]
	s_waitcnt lgkmcnt(1)
	v_mfma_f32_16x16x32_bf16 v[84:87], v[150:153], v[190:193], v[84:87]
	v_mfma_f32_16x16x32_bf16 v[80:83], v[158:161], v[190:193], v[80:83]
	v_mfma_f32_16x16x32_bf16 v[124:127], v[154:157], v[170:173], v[124:127]
	v_mfma_f32_16x16x32_bf16 v[120:123], v[162:165], v[170:173], v[120:123]
	v_mfma_f32_16x16x32_bf16 v[116:119], v[154:157], v[178:181], v[116:119]
	v_mfma_f32_16x16x32_bf16 v[112:115], v[162:165], v[178:181], v[112:115]
	v_mfma_f32_16x16x32_bf16 v[100:103], v[154:157], v[186:189], v[100:103]
	v_mfma_f32_16x16x32_bf16 v[96:99], v[162:165], v[186:189], v[96:99]
	s_waitcnt lgkmcnt(0)
	v_mfma_f32_16x16x32_bf16 v[84:87], v[154:157], v[198:201], v[84:87]
	v_mfma_f32_16x16x32_bf16 v[80:83], v[162:165], v[198:201], v[80:83]
	s_setprio 0
	s_barrier
	ds_read_b128 v[202:205], v149
	ds_read_b128 v[206:209], v149 offset:1024
	ds_read_b128 v[210:213], v149 offset:2048
	ds_read_b128 v[214:217], v149 offset:3072
	s_add_i32 s54, s44, s29
	v_lshl_add_u64 v[194:195], s[22:23], 0, v[132:133]
	s_mov_b32 m0, s54
	s_nop 0
	global_load_lds_dwordx4 v[194:195], off
	v_lshl_add_u64 v[218:219], s[22:23], 0, v[128:129]
	s_add_i32 m0, s54, 0x2000
	s_nop 0
	global_load_lds_dwordx4 v[218:219], off
	s_barrier
	s_setprio 1
	s_waitcnt lgkmcnt(3)
	v_mfma_f32_16x16x32_bf16 v[108:111], v[202:205], v[166:169], v[108:111]
	s_waitcnt lgkmcnt(1)
	v_mfma_f32_16x16x32_bf16 v[104:107], v[210:213], v[166:169], v[104:107]
	v_mfma_f32_16x16x32_bf16 v[92:95], v[202:205], v[174:177], v[92:95]
	v_mfma_f32_16x16x32_bf16 v[88:91], v[210:213], v[174:177], v[88:91]
	v_mfma_f32_16x16x32_bf16 v[76:79], v[202:205], v[182:185], v[76:79]
	v_mfma_f32_16x16x32_bf16 v[72:75], v[210:213], v[182:185], v[72:75]
	v_mfma_f32_16x16x32_bf16 v[68:71], v[202:205], v[190:193], v[68:71]
	v_mfma_f32_16x16x32_bf16 v[64:67], v[210:213], v[190:193], v[64:67]
	v_mfma_f32_16x16x32_bf16 v[108:111], v[206:209], v[170:173], v[108:111]
	s_mov_b32 m0, s31
	s_waitcnt lgkmcnt(0)
	v_mfma_f32_16x16x32_bf16 v[104:107], v[214:217], v[170:173], v[104:107]
	v_lshl_add_u64 v[220:221], s[24:25], 0, v[134:135]
	v_mfma_f32_16x16x32_bf16 v[92:95], v[206:209], v[178:181], v[92:95]
	v_mfma_f32_16x16x32_bf16 v[88:91], v[214:217], v[178:181], v[88:91]
	v_mfma_f32_16x16x32_bf16 v[76:79], v[206:209], v[186:189], v[76:79]
	v_mfma_f32_16x16x32_bf16 v[72:75], v[214:217], v[186:189], v[72:75]
	v_mfma_f32_16x16x32_bf16 v[68:71], v[206:209], v[198:201], v[68:71]
	v_mfma_f32_16x16x32_bf16 v[64:67], v[214:217], v[198:201], v[64:67]
	s_setprio 0
	s_barrier
	ds_read_b128 v[166:169], v148 offset:16384
	ds_read_b128 v[170:173], v148 offset:17408
	ds_read_b128 v[174:177], v148 offset:18432
	ds_read_b128 v[178:181], v148 offset:19456
	ds_read_b128 v[182:185], v148 offset:20480
	ds_read_b128 v[186:189], v148 offset:21504
	ds_read_b128 v[190:193], v148 offset:22528
	ds_read_b128 v[198:201], v148 offset:23552
	global_load_lds_dwordx4 v[220:221], off
	v_lshl_add_u64 v[222:223], s[24:25], 0, v[130:131]
	s_mov_b32 m0, s11
	s_nop 0
	global_load_lds_dwordx4 v[222:223], off
	s_waitcnt vmcnt(10)
	s_barrier
	s_setprio 1
	s_waitcnt lgkmcnt(7)
	v_mfma_f32_16x16x32_bf16 v[60:63], v[150:153], v[166:169], v[60:63]
	v_mfma_f32_16x16x32_bf16 v[56:59], v[158:161], v[166:169], v[56:59]
	s_waitcnt lgkmcnt(5)
	v_mfma_f32_16x16x32_bf16 v[52:55], v[150:153], v[174:177], v[52:55]
	v_mfma_f32_16x16x32_bf16 v[48:51], v[158:161], v[174:177], v[48:51]
	s_waitcnt lgkmcnt(3)
	v_mfma_f32_16x16x32_bf16 v[36:39], v[150:153], v[182:185], v[36:39]
	v_mfma_f32_16x16x32_bf16 v[32:35], v[158:161], v[182:185], v[32:35]
	s_waitcnt lgkmcnt(1)
	v_mfma_f32_16x16x32_bf16 v[20:23], v[150:153], v[190:193], v[20:23]
	v_mfma_f32_16x16x32_bf16 v[16:19], v[158:161], v[190:193], v[16:19]
	v_mfma_f32_16x16x32_bf16 v[60:63], v[154:157], v[170:173], v[60:63]
	v_mfma_f32_16x16x32_bf16 v[56:59], v[162:165], v[170:173], v[56:59]
	v_mfma_f32_16x16x32_bf16 v[52:55], v[154:157], v[178:181], v[52:55]
	v_mfma_f32_16x16x32_bf16 v[48:51], v[162:165], v[178:181], v[48:51]
	v_mfma_f32_16x16x32_bf16 v[36:39], v[154:157], v[186:189], v[36:39]
	v_mfma_f32_16x16x32_bf16 v[32:35], v[162:165], v[186:189], v[32:35]
	s_waitcnt lgkmcnt(0)
	v_mfma_f32_16x16x32_bf16 v[20:23], v[154:157], v[198:201], v[20:23]
	v_mfma_f32_16x16x32_bf16 v[16:19], v[162:165], v[198:201], v[16:19]
	s_setprio 0
	s_barrier
; #define PG8_STAGE(bufoff, gbase, voff) do { _Pragma("unroll") for (int _i = 0; _i < 2; ++_i) \
;         __builtin_amdgcn_global_load_lds((const unsigned*)((const char*)(gbase) + (voff)[_i]), (LAS unsigned*)(lds + (bufoff) + ldsw + _i * 8192), 16, 0, 0); } while (0)
; #define PG8_LDA(dst, b, h) do { _Pragma("unroll") for (int m = 0; m < 4; ++m) _Pragma("unroll") for (int k = 0; k < 2; ++k) dst[m][k] = *(const LAS bf16x8*)(lds + PG8_SA(b, h) + aoff + m * 2048 + k * 1024); } while (0)
; #define PG8_LDB(dst, b, h) do { _Pragma("unroll") for (int n = 0; n < 2; ++n) _Pragma("unroll") for (int k = 0; k < 2; ++k) dst[n][k] = *(const LAS bf16x8*)(lds + PG8_SB(b, h) + boff + n * 2048 + k * 1024); } while (0)
; #define PG8_MMA(ai, bj, At, Bt) do { __builtin_amdgcn_s_setprio(1); _Pragma("unroll") for (int m = 0; m < 4; ++m) _Pragma("unroll") for (int n = 0; n < 2; ++n) _Pragma("unroll") for (int k = 0; k < 2; ++k) \
;         acc[ai][bj][m][n] = __builtin_amdgcn_mfma_f32_16x16x32_bf16(Bt[n][k], At[m][k], acc[ai][bj][m][n], 0, 0, 0); __builtin_amdgcn_s_setprio(0); } while (0)
; #define PG8_WAIT_V(n) asm volatile("s_waitcnt vmcnt(" #n ")" ::: "memory")
; #define PG8_WAIT_L(n) asm volatile("s_waitcnt lgkmcnt(" #n ")" ::: "memory")
; #define PG8_BAR __builtin_amdgcn_s_barrier()
; #define PG8_SCHED __builtin_amdgcn_sched_barrier(0)
; template <class Map, class Epi>
; DI void gemm_phase(LAS unsigned char* lds, const Map& MP, const Epi& E, const int nM, const int nN, const int K, const int lda, const int ldb) {
;     ...
;             PG8_STAGE(PG8_SB(0, 1), b2 + hstepB, voffB);
;             PG8_WAIT_V(6); PG8_BAR; PG8_MMA(1, 1, At, B1); PG8_BAR;
;             PG8_LDB(B0, 1, 0); PG8_SCHED; PG8_LDA(At, 1, 0); PG8_STAGE(PG8_SA(0, 1), a2 + hstepA, voffA);
;             PG8_WAIT_L(8); PG8_BAR; PG8_WAIT_L(0); PG8_MMA(0, 0, At, B0); PG8_BAR; PG8_SCHED;
;             PG8_LDB(B1, 1, 1); PG8_STAGE(PG8_SB(1, 0), b3, voffB);
;             PG8_BAR; PG8_WAIT_L(0); PG8_MMA(0, 1, At, B1); PG8_BAR;
;             PG8_LDA(At, 1, 1); PG8_STAGE(PG8_SA(1, 0), a3, voffA);
;             PG8_BAR; PG8_WAIT_L(0); PG8_MMA(1, 0, At, B0); PG8_BAR; PG8_SCHED;
	s_add_u32 s54, s22, 0x80000
	s_addc_u32 s55, s23, 0
	s_add_i32 s56, s45, s29
	s_mov_b32 m0, s56
	s_nop 0
	global_load_lds_dwordx4 v132, s[54:55]
	s_add_i32 m0, s56, 0x2000
	s_nop 0
	global_load_lds_dwordx4 v128, s[54:55]
	s_waitcnt vmcnt(6)
	s_barrier
	s_setprio 1
	v_mfma_f32_16x16x32_bf16 v[44:47], v[202:205], v[166:169], v[44:47]
	v_mfma_f32_16x16x32_bf16 v[40:43], v[210:213], v[166:169], v[40:43]
	s_add_i32 s54, 0, 0x18000
	v_add_u32_e32 v162, s54, v146
	ds_read_b128 v[150:153], v162
	v_mfma_f32_16x16x32_bf16 v[28:31], v[202:205], v[174:177], v[28:31]
	v_mfma_f32_16x16x32_bf16 v[24:27], v[210:213], v[174:177], v[24:27]
	ds_read_b128 v[154:157], v162 offset:1024
	v_mfma_f32_16x16x32_bf16 v[12:15], v[202:205], v[182:185], v[12:15]
	v_mfma_f32_16x16x32_bf16 v[8:11], v[210:213], v[182:185], v[8:11]
	ds_read_b128 v[158:161], v162 offset:2048
	v_mfma_f32_16x16x32_bf16 v[4:7], v[202:205], v[190:193], v[4:7]
	v_mfma_f32_16x16x32_bf16 v[0:3], v[210:213], v[190:193], v[0:3]
	ds_read_b128 v[162:165], v162 offset:3072
	v_mfma_f32_16x16x32_bf16 v[44:47], v[206:209], v[170:173], v[44:47]
	v_mfma_f32_16x16x32_bf16 v[40:43], v[214:217], v[170:173], v[40:43]
	v_mfma_f32_16x16x32_bf16 v[28:31], v[206:209], v[178:181], v[28:31]
	v_mfma_f32_16x16x32_bf16 v[24:27], v[214:217], v[178:181], v[24:27]
	v_mfma_f32_16x16x32_bf16 v[12:15], v[206:209], v[186:189], v[12:15]
	v_mfma_f32_16x16x32_bf16 v[8:11], v[214:217], v[186:189], v[8:11]
	v_mfma_f32_16x16x32_bf16 v[4:7], v[206:209], v[198:201], v[4:7]
	v_mfma_f32_16x16x32_bf16 v[0:3], v[214:217], v[198:201], v[0:3]
	s_setprio 0
	s_barrier
	ds_read_b128 v[166:169], v148 offset:32768
	ds_read_b128 v[170:173], v148 offset:33792
	ds_read_b128 v[174:177], v148 offset:34816
	ds_read_b128 v[178:181], v148 offset:35840
	ds_read_b128 v[182:185], v148 offset:36864
	ds_read_b128 v[186:189], v148 offset:37888
	ds_read_b128 v[190:193], v148 offset:38912
	ds_read_b128 v[198:201], v148 offset:39936
	s_add_u32 s24, s24, 0x80000
	s_addc_u32 s25, s25, 0
	s_mov_b32 m0, s34
	s_nop 0
	global_load_lds_dwordx4 v134, s[24:25]
	s_mov_b32 m0, s35
	s_nop 0
	global_load_lds_dwordx4 v130, s[24:25]
	s_waitcnt lgkmcnt(8)
	s_barrier
	s_setprio 1
	s_waitcnt lgkmcnt(7)
	v_mfma_f32_16x16x32_bf16 v[124:127], v[150:153], v[166:169], v[124:127]
	v_mfma_f32_16x16x32_bf16 v[120:123], v[158:161], v[166:169], v[120:123]
	s_waitcnt lgkmcnt(5)
	v_mfma_f32_16x16x32_bf16 v[116:119], v[150:153], v[174:177], v[116:119]
	v_mfma_f32_16x16x32_bf16 v[112:115], v[158:161], v[174:177], v[112:115]
	s_waitcnt lgkmcnt(3)
	v_mfma_f32_16x16x32_bf16 v[100:103], v[150:153], v[182:185], v[100:103]
	v_mfma_f32_16x16x32_bf16 v[96:99], v[158:161], v[182:185], v[96:99]
	s_waitcnt lgkmcnt(1)
	v_mfma_f32_16x16x32_bf16 v[84:87], v[150:153], v[190:193], v[84:87]
	v_mfma_f32_16x16x32_bf16 v[80:83], v[158:161], v[190:193], v[80:83]
	v_mfma_f32_16x16x32_bf16 v[124:127], v[154:157], v[170:173], v[124:127]
	v_mfma_f32_16x16x32_bf16 v[120:123], v[162:165], v[170:173], v[120:123]
	v_mfma_f32_16x16x32_bf16 v[116:119], v[154:157], v[178:181], v[116:119]
	v_mfma_f32_16x16x32_bf16 v[112:115], v[162:165], v[178:181], v[112:115]
	v_mfma_f32_16x16x32_bf16 v[100:103], v[154:157], v[186:189], v[100:103]
	v_mfma_f32_16x16x32_bf16 v[96:99], v[162:165], v[186:189], v[96:99]
	s_waitcnt lgkmcnt(0)
	v_mfma_f32_16x16x32_bf16 v[84:87], v[154:157], v[198:201], v[84:87]
	v_mfma_f32_16x16x32_bf16 v[80:83], v[162:165], v[198:201], v[80:83]
	s_setprio 0
	s_barrier
	s_add_i32 s24, 0, 0x1c000
	v_add_u32_e32 v196, s24, v146
	ds_read_b128 v[202:205], v196
	ds_read_b128 v[206:209], v196 offset:1024
	ds_read_b128 v[210:213], v196 offset:2048
	ds_read_b128 v[214:217], v196 offset:3072
	s_add_i32 s25, s54, s29
	v_lshl_add_u64 v[194:195], v[194:195], 0, s[8:9]
	s_mov_b32 m0, s25
	s_nop 0
	global_load_lds_dwordx4 v[194:195], off
	v_lshl_add_u64 v[194:195], v[218:219], 0, s[8:9]
	s_add_i32 m0, s25, 0x2000
	s_nop 0
	global_load_lds_dwordx4 v[194:195], off
	s_barrier
	s_setprio 1
	s_waitcnt lgkmcnt(3)
	v_mfma_f32_16x16x32_bf16 v[108:111], v[202:205], v[166:169], v[108:111]
	s_waitcnt lgkmcnt(1)
	v_mfma_f32_16x16x32_bf16 v[104:107], v[210:213], v[166:169], v[104:107]
	v_mfma_f32_16x16x32_bf16 v[92:95], v[202:205], v[174:177], v[92:95]
	v_mfma_f32_16x16x32_bf16 v[88:91], v[210:213], v[174:177], v[88:91]
	v_mfma_f32_16x16x32_bf16 v[76:79], v[202:205], v[182:185], v[76:79]
	v_mfma_f32_16x16x32_bf16 v[72:75], v[210:213], v[182:185], v[72:75]
	v_mfma_f32_16x16x32_bf16 v[68:71], v[202:205], v[190:193], v[68:71]
	v_mfma_f32_16x16x32_bf16 v[64:67], v[210:213], v[190:193], v[64:67]
	v_mfma_f32_16x16x32_bf16 v[108:111], v[206:209], v[170:173], v[108:111]
	s_mov_b32 m0, s39
	s_waitcnt lgkmcnt(0)
	v_mfma_f32_16x16x32_bf16 v[104:107], v[214:217], v[170:173], v[104:107]
	v_lshl_add_u64 v[194:195], v[220:221], 0, s[8:9]
	v_mfma_f32_16x16x32_bf16 v[92:95], v[206:209], v[178:181], v[92:95]
	v_mfma_f32_16x16x32_bf16 v[88:91], v[214:217], v[178:181], v[88:91]
	v_mfma_f32_16x16x32_bf16 v[76:79], v[206:209], v[186:189], v[76:79]
	v_mfma_f32_16x16x32_bf16 v[72:75], v[214:217], v[186:189], v[72:75]
	v_mfma_f32_16x16x32_bf16 v[68:71], v[206:209], v[198:201], v[68:71]
	v_mfma_f32_16x16x32_bf16 v[64:67], v[214:217], v[198:201], v[64:67]
	s_setprio 0
	s_barrier
	ds_read_b128 v[166:169], v148 offset:49152
	ds_read_b128 v[170:173], v148 offset:50176
	ds_read_b128 v[174:177], v148 offset:51200
	ds_read_b128 v[178:181], v148 offset:52224
	ds_read_b128 v[182:185], v148 offset:53248
	ds_read_b128 v[186:189], v148 offset:54272
	ds_read_b128 v[190:193], v148 offset:55296
	ds_read_b128 v[198:201], v148 offset:56320
	global_load_lds_dwordx4 v[194:195], off
	v_lshl_add_u64 v[194:195], v[222:223], 0, s[8:9]
	s_mov_b32 m0, s42
	s_nop 0
	global_load_lds_dwordx4 v[194:195], off
	s_waitcnt vmcnt(10)
	s_barrier
; #define PG8_STAGE(bufoff, gbase, voff) do { _Pragma("unroll") for (int _i = 0; _i < 2; ++_i) \
;         __builtin_amdgcn_global_load_lds((const unsigned*)((const char*)(gbase) + (voff)[_i]), (LAS unsigned*)(lds + (bufoff) + ldsw + _i * 8192), 16, 0, 0); } while (0)
; #define PG8_MMA(ai, bj, At, Bt) do { __builtin_amdgcn_s_setprio(1); _Pragma("unroll") for (int m = 0; m < 4; ++m) _Pragma("unroll") for (int n = 0; n < 2; ++n) _Pragma("unroll") for (int k = 0; k < 2; ++k) \
;         acc[ai][bj][m][n] = __builtin_amdgcn_mfma_f32_16x16x32_bf16(Bt[n][k], At[m][k], acc[ai][bj][m][n], 0, 0, 0); __builtin_amdgcn_s_setprio(0); } while (0)
; #define PG8_WAIT_V(n) asm volatile("s_waitcnt vmcnt(" #n ")" ::: "memory")
; #define PG8_WAIT_L(n) asm volatile("s_waitcnt lgkmcnt(" #n ")" ::: "memory")
; #define PG8_BAR __builtin_amdgcn_s_barrier()
; #define PG8_SCHED __builtin_amdgcn_sched_barrier(0)
; template <class Map, class Epi>
; DI void gemm_phase(LAS unsigned char* lds, const Map& MP, const Epi& E, const int nM, const int nN, const int K, const int lda, const int ldb) {
;     ...
;             PG8_BAR; PG8_WAIT_L(0); PG8_MMA(1, 0, At, B0); PG8_BAR; PG8_SCHED;
;             PG8_STAGE(PG8_SB(1, 1), b3 + hstepB, voffB);
;             PG8_WAIT_V(6); PG8_BAR; PG8_MMA(1, 1, At, B1); PG8_BAR;
	s_setprio 1
	s_waitcnt lgkmcnt(7)
	v_mfma_f32_16x16x32_bf16 v[60:63], v[150:153], v[166:169], v[60:63]
	v_mfma_f32_16x16x32_bf16 v[56:59], v[158:161], v[166:169], v[56:59]
	s_waitcnt lgkmcnt(5)
	v_mfma_f32_16x16x32_bf16 v[52:55], v[150:153], v[174:177], v[52:55]
	v_mfma_f32_16x16x32_bf16 v[48:51], v[158:161], v[174:177], v[48:51]
	s_waitcnt lgkmcnt(3)
	v_mfma_f32_16x16x32_bf16 v[36:39], v[150:153], v[182:185], v[36:39]
	v_mfma_f32_16x16x32_bf16 v[32:35], v[158:161], v[182:185], v[32:35]
	s_waitcnt lgkmcnt(1)
	v_mfma_f32_16x16x32_bf16 v[20:23], v[150:153], v[190:193], v[20:23]
	v_mfma_f32_16x16x32_bf16 v[16:19], v[158:161], v[190:193], v[16:19]
	v_mfma_f32_16x16x32_bf16 v[60:63], v[154:157], v[170:173], v[60:63]
	v_mfma_f32_16x16x32_bf16 v[56:59], v[162:165], v[170:173], v[56:59]
	v_mfma_f32_16x16x32_bf16 v[52:55], v[154:157], v[178:181], v[52:55]
	v_mfma_f32_16x16x32_bf16 v[48:51], v[162:165], v[178:181], v[48:51]
	v_mfma_f32_16x16x32_bf16 v[36:39], v[154:157], v[186:189], v[36:39]
	v_mfma_f32_16x16x32_bf16 v[32:35], v[162:165], v[186:189], v[32:35]
	s_waitcnt lgkmcnt(0)
	v_mfma_f32_16x16x32_bf16 v[20:23], v[154:157], v[198:201], v[20:23]
	v_mfma_f32_16x16x32_bf16 v[16:19], v[162:165], v[198:201], v[16:19]
	s_setprio 0
	s_barrier
	s_add_u32 s22, s22, 0x80080
	s_addc_u32 s23, s23, 0
	s_add_i32 s24, s24, s29
	s_mov_b32 m0, s24
	s_nop 0
	global_load_lds_dwordx4 v132, s[22:23]
	s_add_i32 m0, s24, 0x2000
	s_nop 0
	global_load_lds_dwordx4 v128, s[22:23]
	s_waitcnt vmcnt(6)
	s_barrier
	s_setprio 1
	v_mfma_f32_16x16x32_bf16 v[44:47], v[202:205], v[166:169], v[44:47]
	v_mfma_f32_16x16x32_bf16 v[40:43], v[210:213], v[166:169], v[40:43]
	ds_read_b128 v[150:153], v147
	v_mfma_f32_16x16x32_bf16 v[28:31], v[202:205], v[174:177], v[28:31]
	v_mfma_f32_16x16x32_bf16 v[24:27], v[210:213], v[174:177], v[24:27]
	ds_read_b128 v[154:157], v147 offset:1024
	v_mfma_f32_16x16x32_bf16 v[12:15], v[202:205], v[182:185], v[12:15]
	v_mfma_f32_16x16x32_bf16 v[8:11], v[210:213], v[182:185], v[8:11]
	ds_read_b128 v[158:161], v147 offset:2048
	v_mfma_f32_16x16x32_bf16 v[4:7], v[202:205], v[190:193], v[4:7]
	v_mfma_f32_16x16x32_bf16 v[0:3], v[210:213], v[190:193], v[0:3]
	ds_read_b128 v[162:165], v147 offset:3072
	v_mfma_f32_16x16x32_bf16 v[44:47], v[206:209], v[170:173], v[44:47]
	s_add_i32 s3, s3, 2
	v_mfma_f32_16x16x32_bf16 v[40:43], v[214:217], v[170:173], v[40:43]
	s_add_u32 s52, s52, 0x100
	s_addc_u32 s53, s53, 0
	v_mfma_f32_16x16x32_bf16 v[28:31], v[206:209], v[178:181], v[28:31]
	s_add_u32 s20, s20, 0x100
	s_addc_u32 s21, s21, 0
	v_mfma_f32_16x16x32_bf16 v[24:27], v[214:217], v[178:181], v[24:27]
	s_cmp_gt_u32 s3, 29
	v_mfma_f32_16x16x32_bf16 v[12:15], v[206:209], v[186:189], v[12:15]
	v_mfma_f32_16x16x32_bf16 v[8:11], v[214:217], v[186:189], v[8:11]
	v_mfma_f32_16x16x32_bf16 v[4:7], v[206:209], v[198:201], v[4:7]
	v_mfma_f32_16x16x32_bf16 v[0:3], v[214:217], v[198:201], v[0:3]
	s_setprio 0
	s_barrier
	s_cbranch_scc0 .LBB1_1382
; DI unsigned pack2(float a, float b) { f32x2 v = {a, b}; hwbf16x2 r = __builtin_convertvector(v, hwbf16x2); return __builtin_bit_cast(unsigned, r); }
;     DI const char* a(const Unit& u) const { return (const char*)(A + (size_t)u.pm * BM * lda); }
;     DI const char* a(const Unit& u) const { return (const char*)(A + (size_t)u.pm * BM * 2048 + (u.pn >> 1) * 512); }
;     DI const char* a(const Unit& u) const { return (const char*)((u.pn < 12 ? A1 : A2) + (size_t)u.pm * BM * 512); }
; #define PG8_WAIT_V(n) asm volatile("s_waitcnt vmcnt(" #n ")" ::: "memory")
; #define PG8_BAR __builtin_amdgcn_s_barrier()
;     DI void operator()(const f32x4 (&acc)[2][2][4][2], const Unit& u, int wr, int wc, int fr, int fq) const {
;         bf16_t* O = O1; int ldc = ldc1, pn = u.pn; if (pn >= split) { O = O2; ldc = ldc2; pn -= split; }
;         const int row0 = u.pm * BM + wr * 64 + fr, col0 = pn * BM + wc * 32 + 8 * fq;
; #pragma unroll
;         for (int ai = 0; ai < 2; ++ai)
; #pragma unroll
;             for (int m = 0; m < 4; ++m) { bf16_t* rowp = O + (size_t)(row0 + ai * HALF + m * 16) * ldc + col0;
; #pragma unroll
;                 for (int bj = 0; bj < 2; ++bj) { const f32x4 v0 = acc[ai][bj][m][0], v1 = acc[ai][bj][m][1];
;                     u32x4 o; o[0] = pack2(v0[0], v0[1]); o[1] = pack2(v0[2], v0[3]); o[2] = pack2(v1[0], v1[1]); o[3] = pack2(v1[2], v1[3]);
;                     *(u32x4*)(rowp + bj * HALF) = o; } }
; template <class Map, class Epi>
; DI void gemm_phase(LAS unsigned char* lds, const Map& MP, const Epi& E, const int nM, const int nN, const int K, const int lda, const int ldb) {
;     ...
;         { int frr = fr, fqq = fq; asm volatile("" : "+v"(frr), "+v"(fqq)); E(acc, cur, wr, wc, frr, fqq); }
;         if (!has_next) break;
; #pragma unroll
;         for (int a = 0; a < 2; ++a)
; #pragma unroll
;             for (int b = 0; b < 2; ++b)
; #pragma unroll
;                 for (int m = 0; m < 4; ++m)
; #pragma unroll
;                     for (int n = 0; n < 2; ++n) acc[a][b][m][n] = (f32x4){0.f, 0.f, 0.f, 0.f};
;         cur = nxt; cA = nA; cB = nB; ++ui;
;     }
;     PG8_WAIT_V(0);
;     if (wr == 0) PG8_BAR;
;     PG8_BAR;
	s_waitcnt lgkmcnt(0)
	s_lshl_b32 s3, s10, 8
	v_mov_b32_e32 v150, v144
	v_mov_b32_e32 v151, v145
	s_add_i32 s3, s3, s37
	v_cvt_pk_bf16_f32 v68, v68, v69
	v_add_u32_e32 v154, s3, v150
	s_lshl_b32 s3, s47, 8
	s_or_b32 s3, s3, s38
	v_lshl_add_u32 v150, v151, 3, s3
	v_ashrrev_i32_e32 v151, 31, v150
	v_lshl_add_u64 v[150:151], v[150:151], 1, s[6:7]
	v_cvt_pk_bf16_f32 v69, v70, v71
	v_cvt_pk_bf16_f32 v70, v64, v65
	v_add_u32_e32 v64, 0x80, v154
	v_mad_i64_i32 v[152:153], s[20:21], v154, s46, v[150:151]
	v_cvt_pk_bf16_f32 v108, v108, v109
	v_cvt_pk_bf16_f32 v109, v110, v111
	v_cvt_pk_bf16_f32 v110, v104, v105
	v_cvt_pk_bf16_f32 v111, v106, v107
	v_add_u32_e32 v104, 16, v154
	v_mad_i64_i32 v[64:65], s[20:21], v64, s46, v[150:151]
	v_cvt_pk_bf16_f32 v44, v44, v45
	v_cvt_pk_bf16_f32 v45, v46, v47
	v_cvt_pk_bf16_f32 v46, v40, v41
	v_cvt_pk_bf16_f32 v47, v42, v43
	v_add_u32_e32 v40, 0x90, v154
	global_store_dwordx4 v[152:153], v[108:111], off offset:256
	v_cvt_pk_bf16_f32 v92, v92, v93
	v_cvt_pk_bf16_f32 v93, v94, v95
	v_mad_i64_i32 v[108:109], s[20:21], v104, s46, v[150:151]
	v_cvt_pk_bf16_f32 v94, v88, v89
	v_cvt_pk_bf16_f32 v95, v90, v91
	v_add_u32_e32 v88, 32, v154
	global_store_dwordx4 v[64:65], v[44:47], off offset:256
	v_cvt_pk_bf16_f32 v28, v28, v29
	v_cvt_pk_bf16_f32 v29, v30, v31
	v_mad_i64_i32 v[44:45], s[20:21], v40, s46, v[150:151]
	v_cvt_pk_bf16_f32 v30, v24, v25
	v_cvt_pk_bf16_f32 v31, v26, v27
	v_add_u32_e32 v24, 0xa0, v154
	global_store_dwordx4 v[108:109], v[92:95], off offset:256
	v_cvt_pk_bf16_f32 v76, v76, v77
	v_cvt_pk_bf16_f32 v77, v78, v79
	v_mad_i64_i32 v[92:93], s[20:21], v88, s46, v[150:151]
	v_cvt_pk_bf16_f32 v78, v72, v73
	v_cvt_pk_bf16_f32 v79, v74, v75
	v_add_u32_e32 v72, 48, v154
	global_store_dwordx4 v[44:45], v[28:31], off offset:256
	v_cvt_pk_bf16_f32 v12, v12, v13
	v_cvt_pk_bf16_f32 v13, v14, v15
	v_mad_i64_i32 v[28:29], s[20:21], v24, s46, v[150:151]
	v_cvt_pk_bf16_f32 v14, v8, v9
	v_cvt_pk_bf16_f32 v15, v10, v11
	v_add_u32_e32 v8, 0xb0, v154
	global_store_dwordx4 v[92:93], v[76:79], off offset:256
	global_store_dwordx4 v[28:29], v[12:15], off offset:256
	v_cvt_pk_bf16_f32 v124, v124, v125
	v_mad_i64_i32 v[76:77], s[20:21], v72, s46, v[150:151]
	v_mad_i64_i32 v[12:13], s[20:21], v8, s46, v[150:151]
	v_cvt_pk_bf16_f32 v125, v126, v127
	v_cvt_pk_bf16_f32 v126, v120, v121
	v_cvt_pk_bf16_f32 v127, v122, v123
	v_cvt_pk_bf16_f32 v104, v116, v117
	v_cvt_pk_bf16_f32 v105, v118, v119
	v_cvt_pk_bf16_f32 v106, v112, v113
	v_cvt_pk_bf16_f32 v107, v114, v115
	v_cvt_pk_bf16_f32 v88, v100, v101
	v_cvt_pk_bf16_f32 v89, v102, v103
	v_cvt_pk_bf16_f32 v90, v96, v97
	v_cvt_pk_bf16_f32 v91, v98, v99
	v_cvt_pk_bf16_f32 v72, v84, v85
	v_cvt_pk_bf16_f32 v73, v86, v87
	v_cvt_pk_bf16_f32 v74, v80, v81
	v_cvt_pk_bf16_f32 v75, v82, v83
	v_cvt_pk_bf16_f32 v71, v66, v67
	v_cvt_pk_bf16_f32 v60, v60, v61
	v_cvt_pk_bf16_f32 v61, v62, v63
	v_cvt_pk_bf16_f32 v62, v56, v57
	v_cvt_pk_bf16_f32 v63, v58, v59
	v_cvt_pk_bf16_f32 v40, v52, v53
	v_cvt_pk_bf16_f32 v41, v54, v55
	v_cvt_pk_bf16_f32 v42, v48, v49
	v_cvt_pk_bf16_f32 v43, v50, v51
	v_cvt_pk_bf16_f32 v24, v36, v37
	v_cvt_pk_bf16_f32 v25, v38, v39
	v_cvt_pk_bf16_f32 v26, v32, v33
	v_cvt_pk_bf16_f32 v27, v34, v35
	v_cvt_pk_bf16_f32 v8, v20, v21
	v_cvt_pk_bf16_f32 v9, v22, v23
	v_cvt_pk_bf16_f32 v10, v16, v17
	v_cvt_pk_bf16_f32 v11, v18, v19
	v_cvt_pk_bf16_f32 v4, v4, v5
	v_cvt_pk_bf16_f32 v5, v6, v7
	v_cvt_pk_bf16_f32 v6, v0, v1
	v_cvt_pk_bf16_f32 v7, v2, v3
	s_and_b64 vcc, exec, s[40:41]
	s_mov_b32 s47, s12
	s_mov_b32 s10, s14
	s_mov_b64 s[20:21], s[18:19]
	s_mov_b64 s[22:23], s[16:17]
	global_store_dwordx4 v[152:153], v[124:127], off
	global_store_dwordx4 v[108:109], v[104:107], off
	global_store_dwordx4 v[92:93], v[88:91], off
	global_store_dwordx4 v[76:77], v[72:75], off
	global_store_dwordx4 v[76:77], v[68:71], off offset:256
	global_store_dwordx4 v[64:65], v[60:63], off
	global_store_dwordx4 v[44:45], v[40:43], off
	global_store_dwordx4 v[28:29], v[24:27], off
	global_store_dwordx4 v[12:13], v[8:11], off
	global_store_dwordx4 v[12:13], v[4:7], off offset:256
	s_cbranch_vccz .LBB1_1379
	s_waitcnt vmcnt(0)
	s_cmpk_gt_u32 s4, 0xff
	s_cbranch_scc1 .LBB1_1386
	s_barrier

; #define PG8_STAGE(bufoff, gbase, voff) do { _Pragma("unroll") for (int _i = 0; _i < 2; ++_i) \
;         __builtin_amdgcn_global_load_lds((const unsigned*)((const char*)(gbase) + (voff)[_i]), (LAS unsigned*)(lds + (bufoff) + ldsw + _i * 8192), 16, 0, 0); } while (0)
; #define PG8_LDA(dst, b, h) do { _Pragma("unroll") for (int m = 0; m < 4; ++m) _Pragma("unroll") for (int k = 0; k < 2; ++k) dst[m][k] = *(const LAS bf16x8*)(lds + PG8_SA(b, h) + aoff + m * 2048 + k * 1024); } while (0)
; #define PG8_LDB(dst, b, h) do { _Pragma("unroll") for (int n = 0; n < 2; ++n) _Pragma("unroll") for (int k = 0; k < 2; ++k) dst[n][k] = *(const LAS bf16x8*)(lds + PG8_SB(b, h) + boff + n * 2048 + k * 1024); } while (0)
; #define PG8_MMA(ai, bj, At, Bt) do { __builtin_amdgcn_s_setprio(1); _Pragma("unroll") for (int m = 0; m < 4; ++m) _Pragma("unroll") for (int n = 0; n < 2; ++n) _Pragma("unroll") for (int k = 0; k < 2; ++k) \
;         acc[ai][bj][m][n] = __builtin_amdgcn_mfma_f32_16x16x32_bf16(Bt[n][k], At[m][k], acc[ai][bj][m][n], 0, 0, 0); __builtin_amdgcn_s_setprio(0); } while (0)
; #define PG8_WAIT_L(n) asm volatile("s_waitcnt lgkmcnt(" #n ")" ::: "memory")
; #define PG8_BAR __builtin_amdgcn_s_barrier()
; #define PG8_SCHED __builtin_amdgcn_sched_barrier(0)
; template <class Map, class Epi>
; DI void gemm_phase(LAS unsigned char* lds, const Map& MP, const Epi& E, const int nM, const int nN, const int K, const int lda, const int ldb) {
;     ...
;             PG8_LDB(B0, 0, 0); PG8_SCHED; PG8_LDA(At, 0, 0); PG8_STAGE(PG8_SA(1, 1), a1 + hstepA, voffA);
;             PG8_WAIT_L(8); PG8_BAR; PG8_WAIT_L(0); PG8_MMA(0, 0, At, B0); PG8_BAR; PG8_SCHED;
;             PG8_LDB(B1, 0, 1); PG8_STAGE(PG8_SB(0, 0), b2, voffB);
;             PG8_BAR; PG8_WAIT_L(0); PG8_MMA(0, 1, At, B1); PG8_BAR;
;             PG8_LDA(At, 0, 1); PG8_STAGE(PG8_SA(0, 0), a2, voffA);
;             PG8_BAR; PG8_WAIT_L(0); PG8_MMA(1, 0, At, B0); PG8_BAR; PG8_SCHED;
.LBB1_1529:
	ds_read_b128 v[166:169], v148
	ds_read_b128 v[170:173], v148 offset:1024
	ds_read_b128 v[174:177], v148 offset:2048
	ds_read_b128 v[178:181], v148 offset:3072
	ds_read_b128 v[182:185], v148 offset:4096
	ds_read_b128 v[186:189], v148 offset:5120
	ds_read_b128 v[190:193], v148 offset:6144
	ds_read_b128 v[198:201], v148 offset:7168
	s_add_u32 s20, s18, 0xfffe0080
	s_addc_u32 s21, s19, -1
	s_cmp_eq_u32 s3, 4
	s_cselect_b32 s23, s13, s21
	s_cselect_b32 s22, s52, s20
	s_cselect_b32 s21, s53, s56
	s_cselect_b32 s20, s54, s55
	s_add_i32 m0, s11, 0xc000
	s_nop 0
	global_load_lds_dwordx4 v138, s[18:19]
	s_add_i32 m0, s11, 0xe000
	s_nop 0
	global_load_lds_dwordx4 v136, s[18:19]
	s_waitcnt lgkmcnt(8)
	s_barrier
	s_setprio 1
	s_waitcnt lgkmcnt(7)
	v_mfma_f32_16x16x32_bf16 v[124:127], v[150:153], v[166:169], v[124:127]
	v_mfma_f32_16x16x32_bf16 v[120:123], v[158:161], v[166:169], v[120:123]
	s_waitcnt lgkmcnt(5)
	v_mfma_f32_16x16x32_bf16 v[116:119], v[150:153], v[174:177], v[116:119]
	v_mfma_f32_16x16x32_bf16 v[112:115], v[158:161], v[174:177], v[112:115]
	s_waitcnt lgkmcnt(3)
	v_mfma_f32_16x16x32_bf16 v[100:103], v[150:153], v[182:185], v[100:103]
	v_mfma_f32_16x16x32_bf16 v[96:99], v[158:161], v[182:185], v[96:99]
	s_waitcnt lgkmcnt(1)
	v_mfma_f32_16x16x32_bf16 v[84:87], v[150:153], v[190:193], v[84:87]
	v_mfma_f32_16x16x32_bf16 v[80:83], v[158:161], v[190:193], v[80:83]
	v_mfma_f32_16x16x32_bf16 v[124:127], v[154:157], v[170:173], v[124:127]
	v_mfma_f32_16x16x32_bf16 v[120:123], v[162:165], v[170:173], v[120:123]
	v_mfma_f32_16x16x32_bf16 v[116:119], v[154:157], v[178:181], v[116:119]
	v_mfma_f32_16x16x32_bf16 v[112:115], v[162:165], v[178:181], v[112:115]
	v_mfma_f32_16x16x32_bf16 v[100:103], v[154:157], v[186:189], v[100:103]
	v_mfma_f32_16x16x32_bf16 v[96:99], v[162:165], v[186:189], v[96:99]
	s_waitcnt lgkmcnt(0)
	v_mfma_f32_16x16x32_bf16 v[84:87], v[154:157], v[198:201], v[84:87]
	v_mfma_f32_16x16x32_bf16 v[80:83], v[162:165], v[198:201], v[80:83]
	s_setprio 0
	s_barrier
	ds_read_b128 v[202:205], v149
	ds_read_b128 v[206:209], v149 offset:1024
	ds_read_b128 v[210:213], v149 offset:2048
	ds_read_b128 v[214:217], v149 offset:3072
	s_add_i32 s57, s47, s31
	v_lshl_add_u64 v[194:195], s[20:21], 0, v[132:133]
	s_mov_b32 m0, s57
	s_nop 0
	global_load_lds_dwordx4 v[194:195], off
	v_lshl_add_u64 v[218:219], s[20:21], 0, v[128:129]
	s_add_i32 m0, s57, 0x2000
	s_nop 0
	global_load_lds_dwordx4 v[218:219], off
	s_barrier
	s_setprio 1
	s_waitcnt lgkmcnt(3)
	v_mfma_f32_16x16x32_bf16 v[108:111], v[202:205], v[166:169], v[108:111]
	s_waitcnt lgkmcnt(1)
	v_mfma_f32_16x16x32_bf16 v[104:107], v[210:213], v[166:169], v[104:107]
	v_mfma_f32_16x16x32_bf16 v[92:95], v[202:205], v[174:177], v[92:95]
	v_mfma_f32_16x16x32_bf16 v[88:91], v[210:213], v[174:177], v[88:91]
	v_mfma_f32_16x16x32_bf16 v[76:79], v[202:205], v[182:185], v[76:79]
	v_mfma_f32_16x16x32_bf16 v[72:75], v[210:213], v[182:185], v[72:75]
	v_mfma_f32_16x16x32_bf16 v[68:71], v[202:205], v[190:193], v[68:71]
	v_mfma_f32_16x16x32_bf16 v[64:67], v[210:213], v[190:193], v[64:67]
	v_mfma_f32_16x16x32_bf16 v[108:111], v[206:209], v[170:173], v[108:111]
	s_mov_b32 m0, s11
	s_waitcnt lgkmcnt(0)
	v_mfma_f32_16x16x32_bf16 v[104:107], v[214:217], v[170:173], v[104:107]
	v_lshl_add_u64 v[220:221], s[22:23], 0, v[134:135]
	v_mfma_f32_16x16x32_bf16 v[92:95], v[206:209], v[178:181], v[92:95]
	v_mfma_f32_16x16x32_bf16 v[88:91], v[214:217], v[178:181], v[88:91]
	v_mfma_f32_16x16x32_bf16 v[76:79], v[206:209], v[186:189], v[76:79]
	v_mfma_f32_16x16x32_bf16 v[72:75], v[214:217], v[186:189], v[72:75]
	v_mfma_f32_16x16x32_bf16 v[68:71], v[206:209], v[198:201], v[68:71]
	v_mfma_f32_16x16x32_bf16 v[64:67], v[214:217], v[198:201], v[64:67]
	s_setprio 0
	s_barrier
	ds_read_b128 v[166:169], v148 offset:16384
	ds_read_b128 v[170:173], v148 offset:17408
	ds_read_b128 v[174:177], v148 offset:18432
	ds_read_b128 v[178:181], v148 offset:19456
	ds_read_b128 v[182:185], v148 offset:20480
	ds_read_b128 v[186:189], v148 offset:21504
	ds_read_b128 v[190:193], v148 offset:22528
	ds_read_b128 v[198:201], v148 offset:23552
	global_load_lds_dwordx4 v[220:221], off
	v_lshl_add_u64 v[222:223], s[22:23], 0, v[130:131]
	s_mov_b32 m0, s35
	s_nop 0
	global_load_lds_dwordx4 v[222:223], off
	s_waitcnt vmcnt(10)
	s_barrier
	s_setprio 1
	s_waitcnt lgkmcnt(7)
	v_mfma_f32_16x16x32_bf16 v[60:63], v[150:153], v[166:169], v[60:63]
	v_mfma_f32_16x16x32_bf16 v[56:59], v[158:161], v[166:169], v[56:59]
	s_waitcnt lgkmcnt(5)
	v_mfma_f32_16x16x32_bf16 v[52:55], v[150:153], v[174:177], v[52:55]
	v_mfma_f32_16x16x32_bf16 v[48:51], v[158:161], v[174:177], v[48:51]
	s_waitcnt lgkmcnt(3)
	v_mfma_f32_16x16x32_bf16 v[36:39], v[150:153], v[182:185], v[36:39]
	v_mfma_f32_16x16x32_bf16 v[32:35], v[158:161], v[182:185], v[32:35]
	s_waitcnt lgkmcnt(1)
	v_mfma_f32_16x16x32_bf16 v[20:23], v[150:153], v[190:193], v[20:23]
	v_mfma_f32_16x16x32_bf16 v[16:19], v[158:161], v[190:193], v[16:19]
	v_mfma_f32_16x16x32_bf16 v[60:63], v[154:157], v[170:173], v[60:63]
	v_mfma_f32_16x16x32_bf16 v[56:59], v[162:165], v[170:173], v[56:59]
	v_mfma_f32_16x16x32_bf16 v[52:55], v[154:157], v[178:181], v[52:55]
	v_mfma_f32_16x16x32_bf16 v[48:51], v[162:165], v[178:181], v[48:51]
	v_mfma_f32_16x16x32_bf16 v[36:39], v[154:157], v[186:189], v[36:39]
	v_mfma_f32_16x16x32_bf16 v[32:35], v[162:165], v[186:189], v[32:35]
	s_waitcnt lgkmcnt(0)
	v_mfma_f32_16x16x32_bf16 v[20:23], v[154:157], v[198:201], v[20:23]
	v_mfma_f32_16x16x32_bf16 v[16:19], v[162:165], v[198:201], v[16:19]
	s_setprio 0
	s_barrier
; #define PG8_STAGE(bufoff, gbase, voff) do { _Pragma("unroll") for (int _i = 0; _i < 2; ++_i) \
;         __builtin_amdgcn_global_load_lds((const unsigned*)((const char*)(gbase) + (voff)[_i]), (LAS unsigned*)(lds + (bufoff) + ldsw + _i * 8192), 16, 0, 0); } while (0)
; #define PG8_LDA(dst, b, h) do { _Pragma("unroll") for (int m = 0; m < 4; ++m) _Pragma("unroll") for (int k = 0; k < 2; ++k) dst[m][k] = *(const LAS bf16x8*)(lds + PG8_SA(b, h) + aoff + m * 2048 + k * 1024); } while (0)
; #define PG8_LDB(dst, b, h) do { _Pragma("unroll") for (int n = 0; n < 2; ++n) _Pragma("unroll") for (int k = 0; k < 2; ++k) dst[n][k] = *(const LAS bf16x8*)(lds + PG8_SB(b, h) + boff + n * 2048 + k * 1024); } while (0)
; #define PG8_MMA(ai, bj, At, Bt) do { __builtin_amdgcn_s_setprio(1); _Pragma("unroll") for (int m = 0; m < 4; ++m) _Pragma("unroll") for (int n = 0; n < 2; ++n) _Pragma("unroll") for (int k = 0; k < 2; ++k) \
;         acc[ai][bj][m][n] = __builtin_amdgcn_mfma_f32_16x16x32_bf16(Bt[n][k], At[m][k], acc[ai][bj][m][n], 0, 0, 0); __builtin_amdgcn_s_setprio(0); } while (0)
; #define PG8_WAIT_V(n) asm volatile("s_waitcnt vmcnt(" #n ")" ::: "memory")
; #define PG8_WAIT_L(n) asm volatile("s_waitcnt lgkmcnt(" #n ")" ::: "memory")
; #define PG8_BAR __builtin_amdgcn_s_barrier()
; #define PG8_SCHED __builtin_amdgcn_sched_barrier(0)
; template <class Map, class Epi>
; DI void gemm_phase(LAS unsigned char* lds, const Map& MP, const Epi& E, const int nM, const int nN, const int K, const int lda, const int ldb) {
;     ...
;             PG8_BAR; PG8_WAIT_L(0); PG8_MMA(1, 0, At, B0); PG8_BAR; PG8_SCHED;
;             PG8_STAGE(PG8_SB(0, 1), b2 + hstepB, voffB);
;             PG8_WAIT_V(6); PG8_BAR; PG8_MMA(1, 1, At, B1); PG8_BAR;
;             PG8_LDB(B0, 1, 0); PG8_SCHED; PG8_LDA(At, 1, 0); PG8_STAGE(PG8_SA(0, 1), a2 + hstepA, voffA);
;             PG8_WAIT_L(8); PG8_BAR; PG8_WAIT_L(0); PG8_MMA(0, 0, At, B0); PG8_BAR; PG8_SCHED;
;             PG8_LDB(B1, 1, 1); PG8_STAGE(PG8_SB(1, 0), b3, voffB);
;             PG8_BAR; PG8_WAIT_L(0); PG8_MMA(0, 1, At, B1); PG8_BAR;
;             PG8_LDA(At, 1, 1); PG8_STAGE(PG8_SA(1, 0), a3, voffA);
;             PG8_BAR; PG8_WAIT_L(0); PG8_MMA(1, 0, At, B0); PG8_BAR; PG8_SCHED;
	s_add_u32 s58, s20, 0x20000
	s_addc_u32 s59, s21, 0
	s_add_i32 s57, s48, s31
	s_mov_b32 m0, s57
	s_nop 0
	global_load_lds_dwordx4 v132, s[58:59]
	s_add_i32 m0, s57, 0x2000
	s_nop 0
	global_load_lds_dwordx4 v128, s[58:59]
	s_waitcnt vmcnt(6)
	s_barrier
	s_setprio 1
	v_mfma_f32_16x16x32_bf16 v[44:47], v[202:205], v[166:169], v[44:47]
	v_mfma_f32_16x16x32_bf16 v[40:43], v[210:213], v[166:169], v[40:43]
	s_add_i32 s57, 0, 0x18000
	v_add_u32_e32 v162, s57, v146
	ds_read_b128 v[150:153], v162
	v_mfma_f32_16x16x32_bf16 v[28:31], v[202:205], v[174:177], v[28:31]
	v_mfma_f32_16x16x32_bf16 v[24:27], v[210:213], v[174:177], v[24:27]
	ds_read_b128 v[154:157], v162 offset:1024
	v_mfma_f32_16x16x32_bf16 v[12:15], v[202:205], v[182:185], v[12:15]
	v_mfma_f32_16x16x32_bf16 v[8:11], v[210:213], v[182:185], v[8:11]
	ds_read_b128 v[158:161], v162 offset:2048
	v_mfma_f32_16x16x32_bf16 v[4:7], v[202:205], v[190:193], v[4:7]
	v_mfma_f32_16x16x32_bf16 v[0:3], v[210:213], v[190:193], v[0:3]
	ds_read_b128 v[162:165], v162 offset:3072
	v_mfma_f32_16x16x32_bf16 v[44:47], v[206:209], v[170:173], v[44:47]
	v_mfma_f32_16x16x32_bf16 v[40:43], v[214:217], v[170:173], v[40:43]
	v_mfma_f32_16x16x32_bf16 v[28:31], v[206:209], v[178:181], v[28:31]
	v_mfma_f32_16x16x32_bf16 v[24:27], v[214:217], v[178:181], v[24:27]
	v_mfma_f32_16x16x32_bf16 v[12:15], v[206:209], v[186:189], v[12:15]
	v_mfma_f32_16x16x32_bf16 v[8:11], v[214:217], v[186:189], v[8:11]
	v_mfma_f32_16x16x32_bf16 v[4:7], v[206:209], v[198:201], v[4:7]
	v_mfma_f32_16x16x32_bf16 v[0:3], v[214:217], v[198:201], v[0:3]
	s_setprio 0
	s_barrier
	ds_read_b128 v[166:169], v148 offset:32768
	ds_read_b128 v[170:173], v148 offset:33792
	ds_read_b128 v[174:177], v148 offset:34816
	ds_read_b128 v[178:181], v148 offset:35840
	ds_read_b128 v[182:185], v148 offset:36864
	ds_read_b128 v[186:189], v148 offset:37888
	ds_read_b128 v[190:193], v148 offset:38912
	ds_read_b128 v[198:201], v148 offset:39936
	s_add_u32 s22, s22, 0x20000
	s_addc_u32 s23, s23, 0
	s_mov_b32 m0, s36
	s_nop 0
	global_load_lds_dwordx4 v134, s[22:23]
	s_mov_b32 m0, s37
	s_nop 0
	global_load_lds_dwordx4 v130, s[22:23]
	s_waitcnt lgkmcnt(8)
	s_barrier
	s_setprio 1
	s_waitcnt lgkmcnt(7)
	v_mfma_f32_16x16x32_bf16 v[124:127], v[150:153], v[166:169], v[124:127]
	v_mfma_f32_16x16x32_bf16 v[120:123], v[158:161], v[166:169], v[120:123]
	s_waitcnt lgkmcnt(5)
	v_mfma_f32_16x16x32_bf16 v[116:119], v[150:153], v[174:177], v[116:119]
	v_mfma_f32_16x16x32_bf16 v[112:115], v[158:161], v[174:177], v[112:115]
	s_waitcnt lgkmcnt(3)
	v_mfma_f32_16x16x32_bf16 v[100:103], v[150:153], v[182:185], v[100:103]
	v_mfma_f32_16x16x32_bf16 v[96:99], v[158:161], v[182:185], v[96:99]
	s_waitcnt lgkmcnt(1)
	v_mfma_f32_16x16x32_bf16 v[84:87], v[150:153], v[190:193], v[84:87]
	v_mfma_f32_16x16x32_bf16 v[80:83], v[158:161], v[190:193], v[80:83]
	v_mfma_f32_16x16x32_bf16 v[124:127], v[154:157], v[170:173], v[124:127]
	v_mfma_f32_16x16x32_bf16 v[120:123], v[162:165], v[170:173], v[120:123]
	v_mfma_f32_16x16x32_bf16 v[116:119], v[154:157], v[178:181], v[116:119]
	v_mfma_f32_16x16x32_bf16 v[112:115], v[162:165], v[178:181], v[112:115]
	v_mfma_f32_16x16x32_bf16 v[100:103], v[154:157], v[186:189], v[100:103]
	v_mfma_f32_16x16x32_bf16 v[96:99], v[162:165], v[186:189], v[96:99]
	s_waitcnt lgkmcnt(0)
	v_mfma_f32_16x16x32_bf16 v[84:87], v[154:157], v[198:201], v[84:87]
	v_mfma_f32_16x16x32_bf16 v[80:83], v[162:165], v[198:201], v[80:83]
	s_setprio 0
	s_barrier
	s_add_i32 s22, 0, 0x1c000
	v_add_u32_e32 v196, s22, v146
	ds_read_b128 v[202:205], v196
	ds_read_b128 v[206:209], v196 offset:1024
	ds_read_b128 v[210:213], v196 offset:2048
	ds_read_b128 v[214:217], v196 offset:3072
	s_add_i32 s23, s57, s31
	v_lshl_add_u64 v[194:195], v[194:195], 0, s[8:9]
	s_mov_b32 m0, s23
	s_nop 0
	global_load_lds_dwordx4 v[194:195], off
	v_lshl_add_u64 v[194:195], v[218:219], 0, s[8:9]
	s_add_i32 m0, s23, 0x2000
	s_nop 0
	global_load_lds_dwordx4 v[194:195], off
	s_barrier
	s_setprio 1
	s_waitcnt lgkmcnt(3)
	v_mfma_f32_16x16x32_bf16 v[108:111], v[202:205], v[166:169], v[108:111]
	s_waitcnt lgkmcnt(1)
	v_mfma_f32_16x16x32_bf16 v[104:107], v[210:213], v[166:169], v[104:107]
	v_mfma_f32_16x16x32_bf16 v[92:95], v[202:205], v[174:177], v[92:95]
	v_mfma_f32_16x16x32_bf16 v[88:91], v[210:213], v[174:177], v[88:91]
	v_mfma_f32_16x16x32_bf16 v[76:79], v[202:205], v[182:185], v[76:79]
	v_mfma_f32_16x16x32_bf16 v[72:75], v[210:213], v[182:185], v[72:75]
	v_mfma_f32_16x16x32_bf16 v[68:71], v[202:205], v[190:193], v[68:71]
	v_mfma_f32_16x16x32_bf16 v[64:67], v[210:213], v[190:193], v[64:67]
	v_mfma_f32_16x16x32_bf16 v[108:111], v[206:209], v[170:173], v[108:111]
	s_mov_b32 m0, s43
	s_waitcnt lgkmcnt(0)
	v_mfma_f32_16x16x32_bf16 v[104:107], v[214:217], v[170:173], v[104:107]
	v_lshl_add_u64 v[194:195], v[220:221], 0, s[8:9]
	v_mfma_f32_16x16x32_bf16 v[92:95], v[206:209], v[178:181], v[92:95]
	v_mfma_f32_16x16x32_bf16 v[88:91], v[214:217], v[178:181], v[88:91]
	v_mfma_f32_16x16x32_bf16 v[76:79], v[206:209], v[186:189], v[76:79]
	v_mfma_f32_16x16x32_bf16 v[72:75], v[214:217], v[186:189], v[72:75]
	v_mfma_f32_16x16x32_bf16 v[68:71], v[206:209], v[198:201], v[68:71]
	v_mfma_f32_16x16x32_bf16 v[64:67], v[214:217], v[198:201], v[64:67]
	s_setprio 0
	s_barrier
	ds_read_b128 v[166:169], v148 offset:49152
	ds_read_b128 v[170:173], v148 offset:50176
	ds_read_b128 v[174:177], v148 offset:51200
	ds_read_b128 v[178:181], v148 offset:52224
	ds_read_b128 v[182:185], v148 offset:53248
	ds_read_b128 v[186:189], v148 offset:54272
	ds_read_b128 v[190:193], v148 offset:55296
	ds_read_b128 v[198:201], v148 offset:56320
	global_load_lds_dwordx4 v[194:195], off
	v_lshl_add_u64 v[194:195], v[222:223], 0, s[8:9]
	s_mov_b32 m0, s44
	s_nop 0
	global_load_lds_dwordx4 v[194:195], off
	s_waitcnt vmcnt(10)
	s_barrier
; #define PG8_STAGE(bufoff, gbase, voff) do { _Pragma("unroll") for (int _i = 0; _i < 2; ++_i) \
;         __builtin_amdgcn_global_load_lds((const unsigned*)((const char*)(gbase) + (voff)[_i]), (LAS unsigned*)(lds + (bufoff) + ldsw + _i * 8192), 16, 0, 0); } while (0)
; #define PG8_MMA(ai, bj, At, Bt) do { __builtin_amdgcn_s_setprio(1); _Pragma("unroll") for (int m = 0; m < 4; ++m) _Pragma("unroll") for (int n = 0; n < 2; ++n) _Pragma("unroll") for (int k = 0; k < 2; ++k) \
;         acc[ai][bj][m][n] = __builtin_amdgcn_mfma_f32_16x16x32_bf16(Bt[n][k], At[m][k], acc[ai][bj][m][n], 0, 0, 0); __builtin_amdgcn_s_setprio(0); } while (0)
; #define PG8_WAIT_V(n) asm volatile("s_waitcnt vmcnt(" #n ")" ::: "memory")
; #define PG8_WAIT_L(n) asm volatile("s_waitcnt lgkmcnt(" #n ")" ::: "memory")
; #define PG8_BAR __builtin_amdgcn_s_barrier()
; #define PG8_SCHED __builtin_amdgcn_sched_barrier(0)
; template <class Map, class Epi>
; DI void gemm_phase(LAS unsigned char* lds, const Map& MP, const Epi& E, const int nM, const int nN, const int K, const int lda, const int ldb) {
;     ...
;             PG8_BAR; PG8_WAIT_L(0); PG8_MMA(1, 0, At, B0); PG8_BAR; PG8_SCHED;
;             PG8_STAGE(PG8_SB(1, 1), b3 + hstepB, voffB);
;             PG8_WAIT_V(6); PG8_BAR; PG8_MMA(1, 1, At, B1); PG8_BAR;
	s_setprio 1
	s_waitcnt lgkmcnt(7)
	v_mfma_f32_16x16x32_bf16 v[60:63], v[150:153], v[166:169], v[60:63]
	v_mfma_f32_16x16x32_bf16 v[56:59], v[158:161], v[166:169], v[56:59]
	s_waitcnt lgkmcnt(5)
	v_mfma_f32_16x16x32_bf16 v[52:55], v[150:153], v[174:177], v[52:55]
	v_mfma_f32_16x16x32_bf16 v[48:51], v[158:161], v[174:177], v[48:51]
	s_waitcnt lgkmcnt(3)
	v_mfma_f32_16x16x32_bf16 v[36:39], v[150:153], v[182:185], v[36:39]
	v_mfma_f32_16x16x32_bf16 v[32:35], v[158:161], v[182:185], v[32:35]
	s_waitcnt lgkmcnt(1)
	v_mfma_f32_16x16x32_bf16 v[20:23], v[150:153], v[190:193], v[20:23]
	v_mfma_f32_16x16x32_bf16 v[16:19], v[158:161], v[190:193], v[16:19]
	v_mfma_f32_16x16x32_bf16 v[60:63], v[154:157], v[170:173], v[60:63]
	v_mfma_f32_16x16x32_bf16 v[56:59], v[162:165], v[170:173], v[56:59]
	v_mfma_f32_16x16x32_bf16 v[52:55], v[154:157], v[178:181], v[52:55]
	v_mfma_f32_16x16x32_bf16 v[48:51], v[162:165], v[178:181], v[48:51]
	v_mfma_f32_16x16x32_bf16 v[36:39], v[154:157], v[186:189], v[36:39]
	v_mfma_f32_16x16x32_bf16 v[32:35], v[162:165], v[186:189], v[32:35]
	s_waitcnt lgkmcnt(0)
	v_mfma_f32_16x16x32_bf16 v[20:23], v[154:157], v[198:201], v[20:23]
	v_mfma_f32_16x16x32_bf16 v[16:19], v[162:165], v[198:201], v[16:19]
	s_setprio 0
	s_barrier
	s_add_u32 s20, s20, 0x20080
	s_addc_u32 s21, s21, 0
	s_add_i32 s22, s22, s31
	s_mov_b32 m0, s22
	s_nop 0
	global_load_lds_dwordx4 v132, s[20:21]
	s_add_i32 m0, s22, 0x2000
	s_nop 0
	global_load_lds_dwordx4 v128, s[20:21]
	s_waitcnt vmcnt(6)
	s_barrier
	s_setprio 1
	v_mfma_f32_16x16x32_bf16 v[44:47], v[202:205], v[166:169], v[44:47]
	v_mfma_f32_16x16x32_bf16 v[40:43], v[210:213], v[166:169], v[40:43]
	ds_read_b128 v[150:153], v147
	v_mfma_f32_16x16x32_bf16 v[28:31], v[202:205], v[174:177], v[28:31]
	v_mfma_f32_16x16x32_bf16 v[24:27], v[210:213], v[174:177], v[24:27]
	ds_read_b128 v[154:157], v147 offset:1024
	v_mfma_f32_16x16x32_bf16 v[12:15], v[202:205], v[182:185], v[12:15]
	v_mfma_f32_16x16x32_bf16 v[8:11], v[210:213], v[182:185], v[8:11]
	ds_read_b128 v[158:161], v147 offset:2048
	v_mfma_f32_16x16x32_bf16 v[4:7], v[202:205], v[190:193], v[4:7]
	v_mfma_f32_16x16x32_bf16 v[0:3], v[210:213], v[190:193], v[0:3]
	ds_read_b128 v[162:165], v147 offset:3072
	v_mfma_f32_16x16x32_bf16 v[44:47], v[206:209], v[170:173], v[44:47]
	s_add_i32 s3, s3, 2
	v_mfma_f32_16x16x32_bf16 v[40:43], v[214:217], v[170:173], v[40:43]
	s_add_u32 s55, s55, 0x100
	s_addc_u32 s56, s56, 0
	v_mfma_f32_16x16x32_bf16 v[28:31], v[206:209], v[178:181], v[28:31]
	s_add_u32 s18, s18, 0x100
	s_addc_u32 s19, s19, 0
	v_mfma_f32_16x16x32_bf16 v[24:27], v[214:217], v[178:181], v[24:27]
	s_cmp_gt_u32 s3, 5
	v_mfma_f32_16x16x32_bf16 v[12:15], v[206:209], v[186:189], v[12:15]
	v_mfma_f32_16x16x32_bf16 v[8:11], v[214:217], v[186:189], v[8:11]
	v_mfma_f32_16x16x32_bf16 v[4:7], v[206:209], v[198:201], v[4:7]
	v_mfma_f32_16x16x32_bf16 v[0:3], v[214:217], v[198:201], v[0:3]
	s_setprio 0
	s_barrier
	s_cbranch_scc0 .LBB1_1529
; DI unsigned pack2(float a, float b) { f32x2 v = {a, b}; hwbf16x2 r = __builtin_convertvector(v, hwbf16x2); return __builtin_bit_cast(unsigned, r); }
;     DI void operator()(const f32x4 (&acc)[2][2][4][2], const Unit& u, int wr, int wc, int fr, int fq) const {
;         bf16_t* O = O1; int ldc = ldc1, pn = u.pn; if (pn >= split) { O = O2; ldc = ldc2; pn -= split; }
;         const int row0 = u.pm * BM + wr * 64 + fr, col0 = pn * BM + wc * 32 + 8 * fq;
; #pragma unroll
;         for (int ai = 0; ai < 2; ++ai)
; #pragma unroll
;             for (int m = 0; m < 4; ++m) { bf16_t* rowp = O + (size_t)(row0 + ai * HALF + m * 16) * ldc + col0;
; #pragma unroll
;                 for (int bj = 0; bj < 2; ++bj) { const f32x4 v0 = acc[ai][bj][m][0], v1 = acc[ai][bj][m][1];
;                     u32x4 o; o[0] = pack2(v0[0], v0[1]); o[1] = pack2(v0[2], v0[3]); o[2] = pack2(v1[0], v1[1]); o[3] = pack2(v1[2], v1[3]);
;                     *(u32x4*)(rowp + bj * HALF) = o; } }
	s_waitcnt lgkmcnt(0)
	s_cmp_lt_i32 s45, 12
	s_cselect_b32 s3, 0, -12
	s_mov_b32 s13, 0x1e510000
	s_movk_i32 s18, 0xc00
	s_cselect_b32 s13, s13, 0x2a510000
	s_cselect_b32 s20, s18, 0x1000
	s_add_i32 s3, s3, s45
	s_add_u32 s18, s6, s13
	v_mov_b32_e32 v150, v144
	v_mov_b32_e32 v151, v145
	s_addc_u32 s19, s7, 0
	s_lshl_b32 s10, s10, 8
	s_lshl_b32 s3, s3, 8
	s_add_i32 s10, s10, s39
	s_or_b32 s3, s3, s42
	v_add_u32_e32 v154, s10, v150
	v_lshl_add_u32 v150, v151, 3, s3
	v_ashrrev_i32_e32 v151, 31, v150
	v_lshl_add_u64 v[150:151], v[150:151], 1, s[18:19]
	v_mad_i64_i32 v[152:153], s[18:19], s20, v154, 0
	v_cvt_pk_bf16_f32 v108, v108, v109
	v_cvt_pk_bf16_f32 v109, v110, v111
	v_cvt_pk_bf16_f32 v110, v104, v105
	v_add_u32_e32 v104, 16, v154
	v_lshl_add_u64 v[152:153], v[152:153], 1, v[150:151]
	v_cvt_pk_bf16_f32 v111, v106, v107
	v_mad_i64_i32 v[104:105], s[18:19], s20, v104, 0
	v_cvt_pk_bf16_f32 v92, v92, v93
	v_cvt_pk_bf16_f32 v93, v94, v95
	v_cvt_pk_bf16_f32 v94, v88, v89
	v_add_u32_e32 v88, 32, v154
	v_cvt_pk_bf16_f32 v124, v124, v125
	v_cvt_pk_bf16_f32 v125, v126, v127
	v_cvt_pk_bf16_f32 v126, v120, v121
	v_cvt_pk_bf16_f32 v127, v122, v123
	global_store_dwordx4 v[152:153], v[108:111], off offset:256
	v_cvt_pk_bf16_f32 v95, v90, v91
	v_mad_i64_i32 v[88:89], s[18:19], s20, v88, 0
	v_lshl_add_u64 v[108:109], v[104:105], 1, v[150:151]
	v_cvt_pk_bf16_f32 v76, v76, v77
	v_cvt_pk_bf16_f32 v77, v78, v79
	v_cvt_pk_bf16_f32 v78, v72, v73
	v_add_u32_e32 v72, 48, v154
	v_cvt_pk_bf16_f32 v68, v68, v69
	v_cvt_pk_bf16_f32 v69, v70, v71
	v_cvt_pk_bf16_f32 v70, v64, v65
	v_add_u32_e32 v64, 0x80, v154
	global_store_dwordx4 v[152:153], v[124:127], off
	v_cvt_pk_bf16_f32 v104, v116, v117
	v_cvt_pk_bf16_f32 v105, v118, v119
	v_cvt_pk_bf16_f32 v106, v112, v113
	v_cvt_pk_bf16_f32 v107, v114, v115
	global_store_dwordx4 v[108:109], v[92:95], off offset:256
	v_cvt_pk_bf16_f32 v79, v74, v75
	v_mad_i64_i32 v[72:73], s[18:19], s20, v72, 0
	v_lshl_add_u64 v[92:93], v[88:89], 1, v[150:151]
	v_mad_i64_i32 v[64:65], s[18:19], s20, v64, 0
	v_cvt_pk_bf16_f32 v44, v44, v45
	v_cvt_pk_bf16_f32 v45, v46, v47
	v_cvt_pk_bf16_f32 v46, v40, v41
	v_add_u32_e32 v40, 0x90, v154
	global_store_dwordx4 v[108:109], v[104:107], off
	v_cvt_pk_bf16_f32 v88, v100, v101
	v_cvt_pk_bf16_f32 v89, v102, v103
	v_cvt_pk_bf16_f32 v90, v96, v97
	v_cvt_pk_bf16_f32 v91, v98, v99
	global_store_dwordx4 v[92:93], v[76:79], off offset:256
	v_cvt_pk_bf16_f32 v74, v80, v81
	v_cvt_pk_bf16_f32 v75, v82, v83
	v_lshl_add_u64 v[76:77], v[72:73], 1, v[150:151]
	v_cvt_pk_bf16_f32 v72, v84, v85
	v_cvt_pk_bf16_f32 v73, v86, v87
	v_cvt_pk_bf16_f32 v71, v66, v67
	v_lshl_add_u64 v[64:65], v[64:65], 1, v[150:151]
	v_cvt_pk_bf16_f32 v47, v42, v43
	v_mad_i64_i32 v[40:41], s[18:19], s20, v40, 0
	v_cvt_pk_bf16_f32 v28, v28, v29
	v_cvt_pk_bf16_f32 v29, v30, v31
	v_cvt_pk_bf16_f32 v30, v24, v25
	v_add_u32_e32 v24, 0xa0, v154
	global_store_dwordx4 v[92:93], v[88:91], off
	global_store_dwordx4 v[76:77], v[72:75], off
	global_store_dwordx4 v[76:77], v[68:71], off offset:256
	v_cvt_pk_bf16_f32 v60, v60, v61
	v_cvt_pk_bf16_f32 v61, v62, v63
	v_cvt_pk_bf16_f32 v62, v56, v57
	v_cvt_pk_bf16_f32 v63, v58, v59
	global_store_dwordx4 v[64:65], v[44:47], off offset:256
	v_cvt_pk_bf16_f32 v31, v26, v27
	v_mad_i64_i32 v[24:25], s[18:19], s20, v24, 0
	v_lshl_add_u64 v[44:45], v[40:41], 1, v[150:151]
	v_cvt_pk_bf16_f32 v12, v12, v13
	v_cvt_pk_bf16_f32 v13, v14, v15
	v_cvt_pk_bf16_f32 v14, v8, v9
	v_add_u32_e32 v8, 0xb0, v154
	global_store_dwordx4 v[64:65], v[60:63], off
	v_cvt_pk_bf16_f32 v40, v52, v53
	v_cvt_pk_bf16_f32 v41, v54, v55
	v_cvt_pk_bf16_f32 v42, v48, v49
	v_cvt_pk_bf16_f32 v43, v50, v51
	global_store_dwordx4 v[44:45], v[28:31], off offset:256
	v_cvt_pk_bf16_f32 v15, v10, v11
	v_mad_i64_i32 v[8:9], s[18:19], s20, v8, 0
	v_lshl_add_u64 v[28:29], v[24:25], 1, v[150:151]
	global_store_dwordx4 v[44:45], v[40:43], off
	v_cvt_pk_bf16_f32 v24, v36, v37
	v_cvt_pk_bf16_f32 v25, v38, v39
	v_cvt_pk_bf16_f32 v26, v32, v33
	v_cvt_pk_bf16_f32 v27, v34, v35
	global_store_dwordx4 v[28:29], v[12:15], off offset:256
	v_cvt_pk_bf16_f32 v10, v16, v17
	v_cvt_pk_bf16_f32 v11, v18, v19
	v_lshl_add_u64 v[12:13], v[8:9], 1, v[150:151]
	v_cvt_pk_bf16_f32 v8, v20, v21
	v_cvt_pk_bf16_f32 v9, v22, v23
	v_cvt_pk_bf16_f32 v4, v4, v5
	v_cvt_pk_bf16_f32 v5, v6, v7
	v_cvt_pk_bf16_f32 v6, v0, v1
	v_cvt_pk_bf16_f32 v7, v2, v3
	s_and_b64 vcc, exec, s[40:41]
	s_mov_b32 s45, s49
	s_mov_b32 s10, s12
	s_mov_b64 s[18:19], s[16:17]
	s_mov_b64 s[20:21], s[14:15]
	global_store_dwordx4 v[28:29], v[24:27], off
	global_store_dwordx4 v[12:13], v[8:11], off
	global_store_dwordx4 v[12:13], v[4:7], off offset:256
	s_cbranch_vccz .LBB1_1526
	s_waitcnt vmcnt(0)
	s_cmpk_gt_u32 s4, 0xff
	s_cbranch_scc1 .LBB1_1533
	s_barrier

; #define PG8_STAGE(bufoff, gbase, voff) do { _Pragma("unroll") for (int _i = 0; _i < 2; ++_i) \
;         __builtin_amdgcn_global_load_lds((const unsigned*)((const char*)(gbase) + (voff)[_i]), (LAS unsigned*)(lds + (bufoff) + ldsw + _i * 8192), 16, 0, 0); } while (0)
; #define PG8_LDA(dst, b, h) do { _Pragma("unroll") for (int m = 0; m < 4; ++m) _Pragma("unroll") for (int k = 0; k < 2; ++k) dst[m][k] = *(const LAS bf16x8*)(lds + PG8_SA(b, h) + aoff + m * 2048 + k * 1024); } while (0)
; #define PG8_LDB(dst, b, h) do { _Pragma("unroll") for (int n = 0; n < 2; ++n) _Pragma("unroll") for (int k = 0; k < 2; ++k) dst[n][k] = *(const LAS bf16x8*)(lds + PG8_SB(b, h) + boff + n * 2048 + k * 1024); } while (0)
; #define PG8_MMA(ai, bj, At, Bt) do { __builtin_amdgcn_s_setprio(1); _Pragma("unroll") for (int m = 0; m < 4; ++m) _Pragma("unroll") for (int n = 0; n < 2; ++n) _Pragma("unroll") for (int k = 0; k < 2; ++k) \
;         acc[ai][bj][m][n] = __builtin_amdgcn_mfma_f32_16x16x32_bf16(Bt[n][k], At[m][k], acc[ai][bj][m][n], 0, 0, 0); __builtin_amdgcn_s_setprio(0); } while (0)
; #define PG8_WAIT_L(n) asm volatile("s_waitcnt lgkmcnt(" #n ")" ::: "memory")
; #define PG8_BAR __builtin_amdgcn_s_barrier()
; #define PG8_SCHED __builtin_amdgcn_sched_barrier(0)
; template <class Map, class Epi>
; DI void gemm_phase(LAS unsigned char* lds, const Map& MP, const Epi& E, const int nM, const int nN, const int K, const int lda, const int ldb) {
;     ...
;             PG8_LDB(B0, 0, 0); PG8_SCHED; PG8_LDA(At, 0, 0); PG8_STAGE(PG8_SA(1, 1), a1 + hstepA, voffA);
;             PG8_WAIT_L(8); PG8_BAR; PG8_WAIT_L(0); PG8_MMA(0, 0, At, B0); PG8_BAR; PG8_SCHED;
;             PG8_LDB(B1, 0, 1); PG8_STAGE(PG8_SB(0, 0), b2, voffB);
;             PG8_BAR; PG8_WAIT_L(0); PG8_MMA(0, 1, At, B1); PG8_BAR;
;             PG8_LDA(At, 0, 1); PG8_STAGE(PG8_SA(0, 0), a2, voffA);
;             PG8_BAR; PG8_WAIT_L(0); PG8_MMA(1, 0, At, B0); PG8_BAR; PG8_SCHED;
.LBB1_1764:
	ds_read_b128 v[168:171], v150
	ds_read_b128 v[172:175], v150 offset:1024
	ds_read_b128 v[176:179], v150 offset:2048
	ds_read_b128 v[180:183], v150 offset:3072
	ds_read_b128 v[184:187], v150 offset:4096
	ds_read_b128 v[188:191], v150 offset:5120
	ds_read_b128 v[192:195], v150 offset:6144
	ds_read_b128 v[198:201], v150 offset:7168
	s_add_u32 s12, s10, 0xfff80080
	s_addc_u32 s13, s11, -1
	s_cmp_eq_u32 s3, 28
	s_cselect_b32 s15, s37, s13
	s_cselect_b32 s14, s38, s12
	s_cselect_b32 s13, s39, s48
	s_cselect_b32 s12, s45, s47
	s_add_i32 m0, s24, 0xc000
	s_nop 0
	global_load_lds_dwordx4 v138, s[10:11]
	s_add_i32 m0, s24, 0xe000
	s_nop 0
	global_load_lds_dwordx4 v136, s[10:11]
	s_waitcnt lgkmcnt(8)
	s_barrier
	s_setprio 1
	s_waitcnt lgkmcnt(7)
	v_mfma_f32_16x16x32_bf16 v[124:127], v[152:155], v[168:171], v[124:127]
	v_mfma_f32_16x16x32_bf16 v[120:123], v[160:163], v[168:171], v[120:123]
	s_waitcnt lgkmcnt(5)
	v_mfma_f32_16x16x32_bf16 v[108:111], v[152:155], v[176:179], v[108:111]
	v_mfma_f32_16x16x32_bf16 v[104:107], v[160:163], v[176:179], v[104:107]
	s_waitcnt lgkmcnt(3)
	v_mfma_f32_16x16x32_bf16 v[92:95], v[152:155], v[184:187], v[92:95]
	v_mfma_f32_16x16x32_bf16 v[88:91], v[160:163], v[184:187], v[88:91]
	s_waitcnt lgkmcnt(1)
	v_mfma_f32_16x16x32_bf16 v[76:79], v[152:155], v[192:195], v[76:79]
	v_mfma_f32_16x16x32_bf16 v[72:75], v[160:163], v[192:195], v[72:75]
	v_mfma_f32_16x16x32_bf16 v[124:127], v[156:159], v[172:175], v[124:127]
	v_mfma_f32_16x16x32_bf16 v[120:123], v[164:167], v[172:175], v[120:123]
	v_mfma_f32_16x16x32_bf16 v[108:111], v[156:159], v[180:183], v[108:111]
	v_mfma_f32_16x16x32_bf16 v[104:107], v[164:167], v[180:183], v[104:107]
	v_mfma_f32_16x16x32_bf16 v[92:95], v[156:159], v[188:191], v[92:95]
	v_mfma_f32_16x16x32_bf16 v[88:91], v[164:167], v[188:191], v[88:91]
	s_waitcnt lgkmcnt(0)
	v_mfma_f32_16x16x32_bf16 v[76:79], v[156:159], v[198:201], v[76:79]
	v_mfma_f32_16x16x32_bf16 v[72:75], v[164:167], v[198:201], v[72:75]
	s_setprio 0
	s_barrier
	ds_read_b128 v[202:205], v151
	ds_read_b128 v[206:209], v151 offset:1024
	ds_read_b128 v[210:213], v151 offset:2048
	ds_read_b128 v[214:217], v151 offset:3072
	s_add_i32 s49, s35, s22
	v_lshl_add_u64 v[144:145], s[12:13], 0, v[132:133]
	s_mov_b32 m0, s49
	s_nop 0
	global_load_lds_dwordx4 v[144:145], off
	v_lshl_add_u64 v[218:219], s[12:13], 0, v[128:129]
	s_add_i32 m0, s49, 0x2000
	s_nop 0
	global_load_lds_dwordx4 v[218:219], off
	s_barrier
	s_setprio 1
	s_waitcnt lgkmcnt(3)
	v_mfma_f32_16x16x32_bf16 v[116:119], v[202:205], v[168:171], v[116:119]
	s_waitcnt lgkmcnt(1)
	v_mfma_f32_16x16x32_bf16 v[112:115], v[210:213], v[168:171], v[112:115]
	v_mfma_f32_16x16x32_bf16 v[100:103], v[202:205], v[176:179], v[100:103]
	v_mfma_f32_16x16x32_bf16 v[96:99], v[210:213], v[176:179], v[96:99]
	v_mfma_f32_16x16x32_bf16 v[84:87], v[202:205], v[184:187], v[84:87]
	v_mfma_f32_16x16x32_bf16 v[80:83], v[210:213], v[184:187], v[80:83]
	v_mfma_f32_16x16x32_bf16 v[68:71], v[202:205], v[192:195], v[68:71]
	v_mfma_f32_16x16x32_bf16 v[64:67], v[210:213], v[192:195], v[64:67]
	v_mfma_f32_16x16x32_bf16 v[116:119], v[206:209], v[172:175], v[116:119]
	s_mov_b32 m0, s24
	s_waitcnt lgkmcnt(0)
	v_mfma_f32_16x16x32_bf16 v[112:115], v[214:217], v[172:175], v[112:115]
	v_lshl_add_u64 v[220:221], s[14:15], 0, v[134:135]
	v_mfma_f32_16x16x32_bf16 v[100:103], v[206:209], v[180:183], v[100:103]
	v_mfma_f32_16x16x32_bf16 v[96:99], v[214:217], v[180:183], v[96:99]
	v_mfma_f32_16x16x32_bf16 v[84:87], v[206:209], v[188:191], v[84:87]
	v_mfma_f32_16x16x32_bf16 v[80:83], v[214:217], v[188:191], v[80:83]
	v_mfma_f32_16x16x32_bf16 v[68:71], v[206:209], v[198:201], v[68:71]
	v_mfma_f32_16x16x32_bf16 v[64:67], v[214:217], v[198:201], v[64:67]
	s_setprio 0
	s_barrier
	ds_read_b128 v[168:171], v150 offset:16384
	ds_read_b128 v[172:175], v150 offset:17408
	ds_read_b128 v[176:179], v150 offset:18432
	ds_read_b128 v[180:183], v150 offset:19456
	ds_read_b128 v[184:187], v150 offset:20480
	ds_read_b128 v[188:191], v150 offset:21504
	ds_read_b128 v[192:195], v150 offset:22528
	ds_read_b128 v[198:201], v150 offset:23552
	global_load_lds_dwordx4 v[220:221], off
	v_lshl_add_u64 v[222:223], s[14:15], 0, v[130:131]
	s_mov_b32 m0, s9
	s_nop 0
	global_load_lds_dwordx4 v[222:223], off
	s_waitcnt vmcnt(10)
	s_barrier
	s_setprio 1
	s_waitcnt lgkmcnt(7)
	v_mfma_f32_16x16x32_bf16 v[60:63], v[152:155], v[168:171], v[60:63]
	v_mfma_f32_16x16x32_bf16 v[56:59], v[160:163], v[168:171], v[56:59]
	s_waitcnt lgkmcnt(5)
	v_mfma_f32_16x16x32_bf16 v[44:47], v[152:155], v[176:179], v[44:47]
	v_mfma_f32_16x16x32_bf16 v[40:43], v[160:163], v[176:179], v[40:43]
	s_waitcnt lgkmcnt(3)
	v_mfma_f32_16x16x32_bf16 v[28:31], v[152:155], v[184:187], v[28:31]
	v_mfma_f32_16x16x32_bf16 v[24:27], v[160:163], v[184:187], v[24:27]
	s_waitcnt lgkmcnt(1)
	v_mfma_f32_16x16x32_bf16 v[12:15], v[152:155], v[192:195], v[12:15]
	v_mfma_f32_16x16x32_bf16 v[8:11], v[160:163], v[192:195], v[8:11]
	v_mfma_f32_16x16x32_bf16 v[60:63], v[156:159], v[172:175], v[60:63]
	v_mfma_f32_16x16x32_bf16 v[56:59], v[164:167], v[172:175], v[56:59]
	v_mfma_f32_16x16x32_bf16 v[44:47], v[156:159], v[180:183], v[44:47]
	v_mfma_f32_16x16x32_bf16 v[40:43], v[164:167], v[180:183], v[40:43]
	v_mfma_f32_16x16x32_bf16 v[28:31], v[156:159], v[188:191], v[28:31]
	v_mfma_f32_16x16x32_bf16 v[24:27], v[164:167], v[188:191], v[24:27]
	s_waitcnt lgkmcnt(0)
	v_mfma_f32_16x16x32_bf16 v[12:15], v[156:159], v[198:201], v[12:15]
	v_mfma_f32_16x16x32_bf16 v[8:11], v[164:167], v[198:201], v[8:11]
	s_setprio 0
	s_barrier
; #define PG8_STAGE(bufoff, gbase, voff) do { _Pragma("unroll") for (int _i = 0; _i < 2; ++_i) \
;         __builtin_amdgcn_global_load_lds((const unsigned*)((const char*)(gbase) + (voff)[_i]), (LAS unsigned*)(lds + (bufoff) + ldsw + _i * 8192), 16, 0, 0); } while (0)
; #define PG8_LDA(dst, b, h) do { _Pragma("unroll") for (int m = 0; m < 4; ++m) _Pragma("unroll") for (int k = 0; k < 2; ++k) dst[m][k] = *(const LAS bf16x8*)(lds + PG8_SA(b, h) + aoff + m * 2048 + k * 1024); } while (0)
; #define PG8_LDB(dst, b, h) do { _Pragma("unroll") for (int n = 0; n < 2; ++n) _Pragma("unroll") for (int k = 0; k < 2; ++k) dst[n][k] = *(const LAS bf16x8*)(lds + PG8_SB(b, h) + boff + n * 2048 + k * 1024); } while (0)
; #define PG8_MMA(ai, bj, At, Bt) do { __builtin_amdgcn_s_setprio(1); _Pragma("unroll") for (int m = 0; m < 4; ++m) _Pragma("unroll") for (int n = 0; n < 2; ++n) _Pragma("unroll") for (int k = 0; k < 2; ++k) \
;         acc[ai][bj][m][n] = __builtin_amdgcn_mfma_f32_16x16x32_bf16(Bt[n][k], At[m][k], acc[ai][bj][m][n], 0, 0, 0); __builtin_amdgcn_s_setprio(0); } while (0)
; #define PG8_WAIT_V(n) asm volatile("s_waitcnt vmcnt(" #n ")" ::: "memory")
; #define PG8_WAIT_L(n) asm volatile("s_waitcnt lgkmcnt(" #n ")" ::: "memory")
; #define PG8_BAR __builtin_amdgcn_s_barrier()
; #define PG8_SCHED __builtin_amdgcn_sched_barrier(0)
; template <class Map, class Epi>
; DI void gemm_phase(LAS unsigned char* lds, const Map& MP, const Epi& E, const int nM, const int nN, const int K, const int lda, const int ldb) {
;     ...
;             PG8_STAGE(PG8_SB(0, 1), b2 + hstepB, voffB);
;             PG8_WAIT_V(6); PG8_BAR; PG8_MMA(1, 1, At, B1); PG8_BAR;
;             PG8_LDB(B0, 1, 0); PG8_SCHED; PG8_LDA(At, 1, 0); PG8_STAGE(PG8_SA(0, 1), a2 + hstepA, voffA);
;             PG8_WAIT_L(8); PG8_BAR; PG8_WAIT_L(0); PG8_MMA(0, 0, At, B0); PG8_BAR; PG8_SCHED;
;             PG8_LDB(B1, 1, 1); PG8_STAGE(PG8_SB(1, 0), b3, voffB);
;             PG8_BAR; PG8_WAIT_L(0); PG8_MMA(0, 1, At, B1); PG8_BAR;
;             PG8_LDA(At, 1, 1); PG8_STAGE(PG8_SA(1, 0), a3, voffA);
;             PG8_BAR; PG8_WAIT_L(0); PG8_MMA(1, 0, At, B0); PG8_BAR; PG8_SCHED;
	s_add_u32 s54, s12, 0x80000
	s_addc_u32 s55, s13, 0
	s_add_i32 s49, s36, s22
	s_mov_b32 m0, s49
	s_nop 0
	global_load_lds_dwordx4 v132, s[54:55]
	s_add_i32 m0, s49, 0x2000
	s_nop 0
	global_load_lds_dwordx4 v128, s[54:55]
	s_waitcnt vmcnt(6)
	s_barrier
	s_setprio 1
	v_mfma_f32_16x16x32_bf16 v[52:55], v[202:205], v[168:171], v[52:55]
	v_mfma_f32_16x16x32_bf16 v[48:51], v[210:213], v[168:171], v[48:51]
	s_add_i32 s49, 0, 0x18000
	v_add_u32_e32 v164, s49, v148
	ds_read_b128 v[152:155], v164
	v_mfma_f32_16x16x32_bf16 v[36:39], v[202:205], v[176:179], v[36:39]
	v_mfma_f32_16x16x32_bf16 v[32:35], v[210:213], v[176:179], v[32:35]
	ds_read_b128 v[156:159], v164 offset:1024
	v_mfma_f32_16x16x32_bf16 v[20:23], v[202:205], v[184:187], v[20:23]
	v_mfma_f32_16x16x32_bf16 v[16:19], v[210:213], v[184:187], v[16:19]
	ds_read_b128 v[160:163], v164 offset:2048
	v_mfma_f32_16x16x32_bf16 v[4:7], v[202:205], v[192:195], v[4:7]
	v_mfma_f32_16x16x32_bf16 v[0:3], v[210:213], v[192:195], v[0:3]
	ds_read_b128 v[164:167], v164 offset:3072
	v_mfma_f32_16x16x32_bf16 v[52:55], v[206:209], v[172:175], v[52:55]
	v_mfma_f32_16x16x32_bf16 v[48:51], v[214:217], v[172:175], v[48:51]
	v_mfma_f32_16x16x32_bf16 v[36:39], v[206:209], v[180:183], v[36:39]
	v_mfma_f32_16x16x32_bf16 v[32:35], v[214:217], v[180:183], v[32:35]
	v_mfma_f32_16x16x32_bf16 v[20:23], v[206:209], v[188:191], v[20:23]
	v_mfma_f32_16x16x32_bf16 v[16:19], v[214:217], v[188:191], v[16:19]
	v_mfma_f32_16x16x32_bf16 v[4:7], v[206:209], v[198:201], v[4:7]
	v_mfma_f32_16x16x32_bf16 v[0:3], v[214:217], v[198:201], v[0:3]
	s_setprio 0
	s_barrier
	ds_read_b128 v[168:171], v150 offset:32768
	ds_read_b128 v[172:175], v150 offset:33792
	ds_read_b128 v[176:179], v150 offset:34816
	ds_read_b128 v[180:183], v150 offset:35840
	ds_read_b128 v[184:187], v150 offset:36864
	ds_read_b128 v[188:191], v150 offset:37888
	ds_read_b128 v[192:195], v150 offset:38912
	ds_read_b128 v[198:201], v150 offset:39936
	s_add_u32 s14, s14, 0x80000
	s_addc_u32 s15, s15, 0
	s_mov_b32 m0, s25
	s_nop 0
	global_load_lds_dwordx4 v134, s[14:15]
	s_mov_b32 m0, s26
	s_nop 0
	global_load_lds_dwordx4 v130, s[14:15]
	s_waitcnt lgkmcnt(8)
	s_barrier
	s_setprio 1
	s_waitcnt lgkmcnt(7)
	v_mfma_f32_16x16x32_bf16 v[124:127], v[152:155], v[168:171], v[124:127]
	v_mfma_f32_16x16x32_bf16 v[120:123], v[160:163], v[168:171], v[120:123]
	s_waitcnt lgkmcnt(5)
	v_mfma_f32_16x16x32_bf16 v[108:111], v[152:155], v[176:179], v[108:111]
	v_mfma_f32_16x16x32_bf16 v[104:107], v[160:163], v[176:179], v[104:107]
	s_waitcnt lgkmcnt(3)
	v_mfma_f32_16x16x32_bf16 v[92:95], v[152:155], v[184:187], v[92:95]
	v_mfma_f32_16x16x32_bf16 v[88:91], v[160:163], v[184:187], v[88:91]
	s_waitcnt lgkmcnt(1)
	v_mfma_f32_16x16x32_bf16 v[76:79], v[152:155], v[192:195], v[76:79]
	v_mfma_f32_16x16x32_bf16 v[72:75], v[160:163], v[192:195], v[72:75]
	v_mfma_f32_16x16x32_bf16 v[124:127], v[156:159], v[172:175], v[124:127]
	v_mfma_f32_16x16x32_bf16 v[120:123], v[164:167], v[172:175], v[120:123]
	v_mfma_f32_16x16x32_bf16 v[108:111], v[156:159], v[180:183], v[108:111]
	v_mfma_f32_16x16x32_bf16 v[104:107], v[164:167], v[180:183], v[104:107]
	v_mfma_f32_16x16x32_bf16 v[92:95], v[156:159], v[188:191], v[92:95]
	v_mfma_f32_16x16x32_bf16 v[88:91], v[164:167], v[188:191], v[88:91]
	s_waitcnt lgkmcnt(0)
	v_mfma_f32_16x16x32_bf16 v[76:79], v[156:159], v[198:201], v[76:79]
	v_mfma_f32_16x16x32_bf16 v[72:75], v[164:167], v[198:201], v[72:75]
	s_setprio 0
	s_barrier
	s_add_i32 s14, 0, 0x1c000
	v_add_u32_e32 v196, s14, v148
	ds_read_b128 v[202:205], v196
	ds_read_b128 v[206:209], v196 offset:1024
	ds_read_b128 v[210:213], v196 offset:2048
	ds_read_b128 v[214:217], v196 offset:3072
	s_add_i32 s15, s49, s22
	v_lshl_add_u64 v[144:145], v[144:145], 0, s[42:43]
	s_mov_b32 m0, s15
	s_nop 0
	global_load_lds_dwordx4 v[144:145], off
	v_lshl_add_u64 v[144:145], v[218:219], 0, s[42:43]
	s_add_i32 m0, s15, 0x2000
	s_nop 0
	global_load_lds_dwordx4 v[144:145], off
	s_barrier
	s_setprio 1
	s_waitcnt lgkmcnt(3)
	v_mfma_f32_16x16x32_bf16 v[116:119], v[202:205], v[168:171], v[116:119]
	s_waitcnt lgkmcnt(1)
	v_mfma_f32_16x16x32_bf16 v[112:115], v[210:213], v[168:171], v[112:115]
	v_mfma_f32_16x16x32_bf16 v[100:103], v[202:205], v[176:179], v[100:103]
	v_mfma_f32_16x16x32_bf16 v[96:99], v[210:213], v[176:179], v[96:99]
	v_mfma_f32_16x16x32_bf16 v[84:87], v[202:205], v[184:187], v[84:87]
	v_mfma_f32_16x16x32_bf16 v[80:83], v[210:213], v[184:187], v[80:83]
	v_mfma_f32_16x16x32_bf16 v[68:71], v[202:205], v[192:195], v[68:71]
	v_mfma_f32_16x16x32_bf16 v[64:67], v[210:213], v[192:195], v[64:67]
	v_mfma_f32_16x16x32_bf16 v[116:119], v[206:209], v[172:175], v[116:119]
	s_mov_b32 m0, s30
	s_waitcnt lgkmcnt(0)
	v_mfma_f32_16x16x32_bf16 v[112:115], v[214:217], v[172:175], v[112:115]
	v_lshl_add_u64 v[144:145], v[220:221], 0, s[42:43]
	v_mfma_f32_16x16x32_bf16 v[100:103], v[206:209], v[180:183], v[100:103]
	v_mfma_f32_16x16x32_bf16 v[96:99], v[214:217], v[180:183], v[96:99]
	v_mfma_f32_16x16x32_bf16 v[84:87], v[206:209], v[188:191], v[84:87]
	v_mfma_f32_16x16x32_bf16 v[80:83], v[214:217], v[188:191], v[80:83]
	v_mfma_f32_16x16x32_bf16 v[68:71], v[206:209], v[198:201], v[68:71]
	v_mfma_f32_16x16x32_bf16 v[64:67], v[214:217], v[198:201], v[64:67]
	s_setprio 0
	s_barrier
	ds_read_b128 v[168:171], v150 offset:49152
	ds_read_b128 v[172:175], v150 offset:50176
	ds_read_b128 v[176:179], v150 offset:51200
	ds_read_b128 v[180:183], v150 offset:52224
	ds_read_b128 v[184:187], v150 offset:53248
	ds_read_b128 v[188:191], v150 offset:54272
	ds_read_b128 v[192:195], v150 offset:55296
	ds_read_b128 v[198:201], v150 offset:56320
	global_load_lds_dwordx4 v[144:145], off
	v_lshl_add_u64 v[144:145], v[222:223], 0, s[42:43]
	s_mov_b32 m0, s31
	s_nop 0
	global_load_lds_dwordx4 v[144:145], off
	s_waitcnt vmcnt(10)
	s_barrier
; DI unsigned pack2(float a, float b) { f32x2 v = {a, b}; hwbf16x2 r = __builtin_convertvector(v, hwbf16x2); return __builtin_bit_cast(unsigned, r); }
; DI float bflo(unsigned w) { return __uint_as_float(w << 16); }
; DI float bfhi(unsigned w) { return __uint_as_float(w & 0xffff0000u); }
; #define PG8_WAIT_V(n) asm volatile("s_waitcnt vmcnt(" #n ")" ::: "memory")
;     DI void operator()(const f32x4 (&acc)[2][2][4][2], const Unit& u, int wr, int wc, int fr, int fq) const {
;         const int row0 = u.pm * BM + wr * 64 + fr, col0 = u.pn * BM + wc * 32 + 8 * fq;
;         f32x4 sc[2][2];
; #pragma unroll
;         for (int bj = 0; bj < 2; ++bj)
; #pragma unroll
;             for (int n = 0; n < 2; ++n) sc[bj][n] = scale ? *(const f32x4*)(scale + col0 + bj * HALF + 4 * n) : (f32x4){1.f, 1.f, 1.f, 1.f};
; #pragma unroll
;         for (int ai = 0; ai < 2; ++ai)
; #pragma unroll
;             for (int m = 0; m < 4; ++m) { const size_t ro = (size_t)(row0 + ai * HALF + m * 16) * D + col0;
; #pragma unroll
;                 for (int bj = 0; bj < 2; ++bj) {
;                     f32x4 x0, x1;
;                     if constexpr (IB) { const u32x4 w = *(const u32x4*)((const bf16_t*)Xin + ro + bj * HALF);
;                         x0 = (f32x4){bflo(w[0]), bfhi(w[0]), bflo(w[1]), bfhi(w[1])}; x1 = (f32x4){bflo(w[2]), bfhi(w[2]), bflo(w[3]), bfhi(w[3])}; }
;                     else { x0 = *(const f32x4*)((const float*)Xin + ro + bj * HALF); x1 = *(const f32x4*)((const float*)Xin + ro + bj * HALF + 4); }
;                     x0 += acc[ai][bj][m][0] * sc[bj][0]; x1 += acc[ai][bj][m][1] * sc[bj][1];
;                     if constexpr (OB) { u32x4 o; o[0] = pack2(x0[0], x0[1]); o[1] = pack2(x0[2], x0[3]); o[2] = pack2(x1[0], x1[1]); o[3] = pack2(x1[2], x1[3]);
;                         *(u32x4*)((bf16_t*)Xout + ro + bj * HALF) = o; }
;                     else { *(f32x4*)((float*)Xout + ro + bj * HALF) = x0; *(f32x4*)((float*)Xout + ro + bj * HALF + 4) = x1; } } }
; template <class Map, class Epi>
; DI void gemm_phase(LAS unsigned char* lds, const Map& MP, const Epi& E, const int nM, const int nN, const int K, const int lda, const int ldb) {
;     ...
;             PG8_BAR; PG8_WAIT_L(0); PG8_MMA(1, 0, At, B0); PG8_BAR; PG8_SCHED;
;             PG8_STAGE(PG8_SB(1, 1), b3 + hstepB, voffB);
;             PG8_WAIT_V(6); PG8_BAR; PG8_MMA(1, 1, At, B1); PG8_BAR;
	s_setprio 1
	s_waitcnt lgkmcnt(7)
	v_mfma_f32_16x16x32_bf16 v[60:63], v[152:155], v[168:171], v[60:63]
	v_mfma_f32_16x16x32_bf16 v[56:59], v[160:163], v[168:171], v[56:59]
	s_waitcnt lgkmcnt(5)
	v_mfma_f32_16x16x32_bf16 v[44:47], v[152:155], v[176:179], v[44:47]
	v_mfma_f32_16x16x32_bf16 v[40:43], v[160:163], v[176:179], v[40:43]
	s_waitcnt lgkmcnt(3)
	v_mfma_f32_16x16x32_bf16 v[28:31], v[152:155], v[184:187], v[28:31]
	v_mfma_f32_16x16x32_bf16 v[24:27], v[160:163], v[184:187], v[24:27]
	s_waitcnt lgkmcnt(1)
	v_mfma_f32_16x16x32_bf16 v[12:15], v[152:155], v[192:195], v[12:15]
	v_mfma_f32_16x16x32_bf16 v[8:11], v[160:163], v[192:195], v[8:11]
	v_mfma_f32_16x16x32_bf16 v[60:63], v[156:159], v[172:175], v[60:63]
	v_mfma_f32_16x16x32_bf16 v[56:59], v[164:167], v[172:175], v[56:59]
	v_mfma_f32_16x16x32_bf16 v[44:47], v[156:159], v[180:183], v[44:47]
	v_mfma_f32_16x16x32_bf16 v[40:43], v[164:167], v[180:183], v[40:43]
	v_mfma_f32_16x16x32_bf16 v[28:31], v[156:159], v[188:191], v[28:31]
	v_mfma_f32_16x16x32_bf16 v[24:27], v[164:167], v[188:191], v[24:27]
	s_waitcnt lgkmcnt(0)
	v_mfma_f32_16x16x32_bf16 v[12:15], v[156:159], v[198:201], v[12:15]
	v_mfma_f32_16x16x32_bf16 v[8:11], v[164:167], v[198:201], v[8:11]
	s_setprio 0
	s_barrier
	s_add_u32 s12, s12, 0x80080
	s_addc_u32 s13, s13, 0
	s_add_i32 s14, s14, s22
	s_mov_b32 m0, s14
	s_nop 0
	global_load_lds_dwordx4 v132, s[12:13]
	s_add_i32 m0, s14, 0x2000
	s_nop 0
	global_load_lds_dwordx4 v128, s[12:13]
	s_waitcnt vmcnt(6)
	s_barrier
	s_setprio 1
	v_mfma_f32_16x16x32_bf16 v[52:55], v[202:205], v[168:171], v[52:55]
	v_mfma_f32_16x16x32_bf16 v[48:51], v[210:213], v[168:171], v[48:51]
	ds_read_b128 v[152:155], v149
	v_mfma_f32_16x16x32_bf16 v[36:39], v[202:205], v[176:179], v[36:39]
	v_mfma_f32_16x16x32_bf16 v[32:35], v[210:213], v[176:179], v[32:35]
	ds_read_b128 v[156:159], v149 offset:1024
	v_mfma_f32_16x16x32_bf16 v[20:23], v[202:205], v[184:187], v[20:23]
	v_mfma_f32_16x16x32_bf16 v[16:19], v[210:213], v[184:187], v[16:19]
	ds_read_b128 v[160:163], v149 offset:2048
	v_mfma_f32_16x16x32_bf16 v[4:7], v[202:205], v[192:195], v[4:7]
	v_mfma_f32_16x16x32_bf16 v[0:3], v[210:213], v[192:195], v[0:3]
	ds_read_b128 v[164:167], v149 offset:3072
	v_mfma_f32_16x16x32_bf16 v[52:55], v[206:209], v[172:175], v[52:55]
	s_add_i32 s3, s3, 2
	v_mfma_f32_16x16x32_bf16 v[48:51], v[214:217], v[172:175], v[48:51]
	s_add_u32 s47, s47, 0x100
	s_addc_u32 s48, s48, 0
	v_mfma_f32_16x16x32_bf16 v[36:39], v[206:209], v[180:183], v[36:39]
	s_add_u32 s10, s10, 0x100
	s_addc_u32 s11, s11, 0
	v_mfma_f32_16x16x32_bf16 v[32:35], v[214:217], v[180:183], v[32:35]
	s_cmp_gt_u32 s3, 29
	v_mfma_f32_16x16x32_bf16 v[20:23], v[206:209], v[188:191], v[20:23]
	v_mfma_f32_16x16x32_bf16 v[16:19], v[214:217], v[188:191], v[16:19]
	v_mfma_f32_16x16x32_bf16 v[4:7], v[206:209], v[198:201], v[4:7]
	v_mfma_f32_16x16x32_bf16 v[0:3], v[214:217], v[198:201], v[0:3]
	s_setprio 0
	s_barrier
	s_cbranch_scc0 .LBB1_1764
	s_waitcnt lgkmcnt(0)
	v_mov_b32_e32 v152, v147
	v_mov_b32_e32 v144, v146
	s_lshl_b32 s2, s2, 8
	s_or_b32 s2, s2, s29
	v_lshl_add_u32 v144, v144, 3, s2
	s_lshl_b32 s2, s8, 8
	s_add_i32 s2, s2, s28
	v_add_u32_e32 v152, s2, v152
	v_ashrrev_i32_e32 v153, 31, v152
	v_lshlrev_b64 v[152:153], 12, v[152:153]
	v_ashrrev_i32_e32 v145, 31, v144
	v_lshl_add_u64 v[152:153], s[4:5], 0, v[152:153]
	v_lshl_add_u64 v[144:145], v[144:145], 1, v[152:153]
	global_load_dwordx4 v[160:163], v[144:145], off
	global_load_dwordx4 v[164:167], v[144:145], off offset:256
	s_mov_b64 s[98:99], 0x10000
	v_lshl_add_u64 v[154:155], v[144:145], 0, s[98:99]
	global_load_dwordx4 v[168:171], v[154:155], off
	global_load_dwordx4 v[172:175], v[154:155], off offset:256
	s_mov_b64 s[98:99], 0x20000
	v_lshl_add_u64 v[154:155], v[144:145], 0, s[98:99]
	global_load_dwordx4 v[176:179], v[154:155], off
	global_load_dwordx4 v[180:183], v[154:155], off offset:256
	s_mov_b64 s[98:99], 0x30000
	v_lshl_add_u64 v[154:155], v[144:145], 0, s[98:99]
	global_load_dwordx4 v[184:187], v[154:155], off
	global_load_dwordx4 v[188:191], v[154:155], off offset:256
	s_mov_b64 s[98:99], 0x80000
	v_lshl_add_u64 v[154:155], v[144:145], 0, s[98:99]
	global_load_dwordx4 v[192:195], v[154:155], off
	global_load_dwordx4 v[198:201], v[154:155], off offset:256
	s_mov_b64 s[98:99], 0x90000
	v_lshl_add_u64 v[154:155], v[144:145], 0, s[98:99]
	global_load_dwordx4 v[202:205], v[154:155], off
	global_load_dwordx4 v[206:209], v[154:155], off offset:256
	s_mov_b64 s[98:99], 0xa0000
	v_lshl_add_u64 v[154:155], v[144:145], 0, s[98:99]
	global_load_dwordx4 v[210:213], v[154:155], off
	global_load_dwordx4 v[214:217], v[154:155], off offset:256
	s_mov_b64 s[98:99], 0xb0000
	v_lshl_add_u64 v[154:155], v[144:145], 0, s[98:99]
	global_load_dwordx4 v[248:251], v[154:155], off
	global_load_dwordx4 v[252:255], v[154:155], off offset:256
	s_waitcnt vmcnt(15)
	s_nop 1
	v_mov_b32_e32 v152, v160
	v_mov_b32_e32 v153, v161
	v_mov_b32_e32 v154, v162
	v_mov_b32_e32 v155, v163
	s_mov_b64 s[2:3], 0x10000
	s_mov_b32 s8, s46
	s_mov_b64 s[10:11], s[6:7]
	s_mov_b64 s[12:13], s[52:53]
	s_waitcnt lgkmcnt(0)
	v_lshlrev_b32_e32 v156, 16, v152
	v_and_b32_e32 v157, 0xffff0000, v152
	v_lshlrev_b32_e32 v152, 16, v153
	v_and_b32_e32 v153, 0xffff0000, v153
	v_lshlrev_b32_e32 v158, 16, v154
	v_and_b32_e32 v159, 0xffff0000, v154
	v_lshlrev_b32_e32 v154, 16, v155
	v_and_b32_e32 v155, 0xffff0000, v155
	v_pk_add_f32 v[126:127], v[126:127], v[152:153]
	v_pk_add_f32 v[124:125], v[124:125], v[156:157]
	v_pk_add_f32 v[152:153], v[122:123], v[154:155]
	v_pk_add_f32 v[122:123], v[120:121], v[158:159]
	v_cvt_pk_bf16_f32 v120, v124, v125
	v_cvt_pk_bf16_f32 v121, v126, v127
	v_cvt_pk_bf16_f32 v122, v122, v123
	v_cvt_pk_bf16_f32 v123, v152, v153
	global_store_dwordx4 v[144:145], v[120:123], off
	s_waitcnt vmcnt(15)
; DI unsigned pack2(float a, float b) { f32x2 v = {a, b}; hwbf16x2 r = __builtin_convertvector(v, hwbf16x2); return __builtin_bit_cast(unsigned, r); }
; DI float bflo(unsigned w) { return __uint_as_float(w << 16); }
; DI float bfhi(unsigned w) { return __uint_as_float(w & 0xffff0000u); }
;     DI void operator()(const f32x4 (&acc)[2][2][4][2], const Unit& u, int wr, int wc, int fr, int fq) const {
;     ...
;             for (int m = 0; m < 4; ++m) { const size_t ro = (size_t)(row0 + ai * HALF + m * 16) * D + col0;
; #pragma unroll
;                 for (int bj = 0; bj < 2; ++bj) {
;                     f32x4 x0, x1;
;                     if constexpr (IB) { const u32x4 w = *(const u32x4*)((const bf16_t*)Xin + ro + bj * HALF);
;                         x0 = (f32x4){bflo(w[0]), bfhi(w[0]), bflo(w[1]), bfhi(w[1])}; x1 = (f32x4){bflo(w[2]), bfhi(w[2]), bflo(w[3]), bfhi(w[3])}; }
;                     else { x0 = *(const f32x4*)((const float*)Xin + ro + bj * HALF); x1 = *(const f32x4*)((const float*)Xin + ro + bj * HALF + 4); }
;                     x0 += acc[ai][bj][m][0] * sc[bj][0]; x1 += acc[ai][bj][m][1] * sc[bj][1];
;                     if constexpr (OB) { u32x4 o; o[0] = pack2(x0[0], x0[1]); o[1] = pack2(x0[2], x0[3]); o[2] = pack2(x1[0], x1[1]); o[3] = pack2(x1[2], x1[3]);
;                         *(u32x4*)((bf16_t*)Xout + ro + bj * HALF) = o; }
;                     else { *(f32x4*)((float*)Xout + ro + bj * HALF) = x0; *(f32x4*)((float*)Xout + ro + bj * HALF + 4) = x1; } } }
	s_nop 1
	v_mov_b32_e32 v120, v164
	v_mov_b32_e32 v121, v165
	v_mov_b32_e32 v122, v166
	v_mov_b32_e32 v123, v167
	s_waitcnt lgkmcnt(0)
	v_lshlrev_b32_e32 v124, 16, v120
	v_and_b32_e32 v125, 0xffff0000, v120
	v_lshlrev_b32_e32 v120, 16, v121
	v_and_b32_e32 v121, 0xffff0000, v121
	v_lshlrev_b32_e32 v126, 16, v122
	v_and_b32_e32 v127, 0xffff0000, v122
	v_lshlrev_b32_e32 v122, 16, v123
	v_and_b32_e32 v123, 0xffff0000, v123
	v_pk_add_f32 v[116:117], v[116:117], v[124:125]
	v_pk_add_f32 v[118:119], v[118:119], v[120:121]
	v_pk_add_f32 v[120:121], v[114:115], v[122:123]
	v_pk_add_f32 v[114:115], v[112:113], v[126:127]
	v_cvt_pk_bf16_f32 v112, v116, v117
	v_lshl_add_u64 v[116:117], v[144:145], 0, s[2:3]
	s_mov_b32 s2, 0x10000
	v_cvt_pk_bf16_f32 v113, v118, v119
	v_add_co_u32_e32 v118, vcc, s2, v144
	v_cvt_pk_bf16_f32 v114, v114, v115
	v_cvt_pk_bf16_f32 v115, v120, v121
	v_addc_co_u32_e32 v119, vcc, 0, v145, vcc
	global_store_dwordx4 v[144:145], v[112:115], off offset:256
	s_waitcnt vmcnt(15)
	s_nop 1
	v_mov_b32_e32 v112, v168
	v_mov_b32_e32 v113, v169
	v_mov_b32_e32 v114, v170
	v_mov_b32_e32 v115, v171
	s_mov_b64 s[2:3], 0x20000
	s_waitcnt lgkmcnt(0)
	v_lshlrev_b32_e32 v120, 16, v112
	v_and_b32_e32 v121, 0xffff0000, v112
	v_lshlrev_b32_e32 v112, 16, v113
	v_and_b32_e32 v113, 0xffff0000, v113
	v_lshlrev_b32_e32 v122, 16, v114
	v_and_b32_e32 v123, 0xffff0000, v114
	v_lshlrev_b32_e32 v114, 16, v115
	v_and_b32_e32 v115, 0xffff0000, v115
	v_pk_add_f32 v[110:111], v[110:111], v[112:113]
	v_pk_add_f32 v[108:109], v[108:109], v[120:121]
	v_pk_add_f32 v[112:113], v[106:107], v[114:115]
	v_pk_add_f32 v[106:107], v[104:105], v[122:123]
	v_cvt_pk_bf16_f32 v104, v108, v109
	v_cvt_pk_bf16_f32 v105, v110, v111
	v_cvt_pk_bf16_f32 v106, v106, v107
	v_cvt_pk_bf16_f32 v107, v112, v113
	global_store_dwordx4 v[118:119], v[104:107], off
	s_waitcnt vmcnt(15)
	s_nop 1
	v_mov_b32_e32 v104, v172
	v_mov_b32_e32 v105, v173
	v_mov_b32_e32 v106, v174
	v_mov_b32_e32 v107, v175
	s_waitcnt lgkmcnt(0)
	v_lshlrev_b32_e32 v108, 16, v104
	v_and_b32_e32 v109, 0xffff0000, v104
	v_lshlrev_b32_e32 v104, 16, v105
	v_and_b32_e32 v105, 0xffff0000, v105
	v_lshlrev_b32_e32 v110, 16, v106
	v_and_b32_e32 v111, 0xffff0000, v106
	v_lshlrev_b32_e32 v106, 16, v107
	v_and_b32_e32 v107, 0xffff0000, v107
	v_pk_add_f32 v[100:101], v[100:101], v[108:109]
	v_pk_add_f32 v[102:103], v[102:103], v[104:105]
	v_pk_add_f32 v[104:105], v[98:99], v[106:107]
	v_pk_add_f32 v[98:99], v[96:97], v[110:111]
	v_cvt_pk_bf16_f32 v96, v100, v101
	v_lshl_add_u64 v[100:101], v[144:145], 0, s[2:3]
	s_mov_b32 s2, 0x20000
	v_cvt_pk_bf16_f32 v97, v102, v103
	v_add_co_u32_e32 v102, vcc, s2, v144
	v_cvt_pk_bf16_f32 v98, v98, v99
	v_cvt_pk_bf16_f32 v99, v104, v105
	v_addc_co_u32_e32 v103, vcc, 0, v145, vcc
	global_store_dwordx4 v[116:117], v[96:99], off offset:256
	s_waitcnt vmcnt(15)
	s_nop 1
	v_mov_b32_e32 v96, v176
	v_mov_b32_e32 v97, v177
	v_mov_b32_e32 v98, v178
	v_mov_b32_e32 v99, v179
	s_mov_b64 s[2:3], 0x30000
	s_waitcnt lgkmcnt(0)
	v_lshlrev_b32_e32 v104, 16, v96
	v_and_b32_e32 v105, 0xffff0000, v96
	v_lshlrev_b32_e32 v96, 16, v97
	v_and_b32_e32 v97, 0xffff0000, v97
	v_lshlrev_b32_e32 v106, 16, v98
	v_and_b32_e32 v107, 0xffff0000, v98
	v_lshlrev_b32_e32 v98, 16, v99
	v_and_b32_e32 v99, 0xffff0000, v99
	v_pk_add_f32 v[94:95], v[94:95], v[96:97]
	v_pk_add_f32 v[92:93], v[92:93], v[104:105]
	v_pk_add_f32 v[96:97], v[90:91], v[98:99]
	v_pk_add_f32 v[90:91], v[88:89], v[106:107]
	v_cvt_pk_bf16_f32 v88, v92, v93
	v_cvt_pk_bf16_f32 v89, v94, v95
	v_cvt_pk_bf16_f32 v90, v90, v91
	v_cvt_pk_bf16_f32 v91, v96, v97
	global_store_dwordx4 v[102:103], v[88:91], off
	s_waitcnt vmcnt(15)
	s_nop 1
	v_mov_b32_e32 v88, v180
	v_mov_b32_e32 v89, v181
	v_mov_b32_e32 v90, v182
	v_mov_b32_e32 v91, v183
	s_waitcnt lgkmcnt(0)
	v_lshlrev_b32_e32 v92, 16, v88
	v_and_b32_e32 v93, 0xffff0000, v88
	v_lshlrev_b32_e32 v88, 16, v89
	v_and_b32_e32 v89, 0xffff0000, v89
	v_lshlrev_b32_e32 v94, 16, v90
	v_and_b32_e32 v95, 0xffff0000, v90
	v_lshlrev_b32_e32 v90, 16, v91
	v_and_b32_e32 v91, 0xffff0000, v91
	v_pk_add_f32 v[86:87], v[86:87], v[88:89]
	v_pk_add_f32 v[84:85], v[84:85], v[92:93]
	v_pk_add_f32 v[88:89], v[82:83], v[90:91]
	v_pk_add_f32 v[82:83], v[80:81], v[94:95]
	v_cvt_pk_bf16_f32 v80, v84, v85
	v_cvt_pk_bf16_f32 v81, v86, v87
	v_cvt_pk_bf16_f32 v82, v82, v83
	v_cvt_pk_bf16_f32 v83, v88, v89
	global_store_dwordx4 v[100:101], v[80:83], off offset:256
	s_nop 1
	v_lshl_add_u64 v[80:81], v[144:145], 0, s[2:3]
	s_mov_b32 s2, 0x30000
	v_add_co_u32_e32 v86, vcc, s2, v144
	s_mov_b64 s[2:3], 0x80000
	s_nop 0
	v_addc_co_u32_e32 v87, vcc, 0, v145, vcc
	s_waitcnt vmcnt(15)
	s_nop 1
	v_mov_b32_e32 v82, v184
	v_mov_b32_e32 v83, v185
	v_mov_b32_e32 v84, v186
	v_mov_b32_e32 v85, v187
	s_waitcnt lgkmcnt(0)
	v_lshlrev_b32_e32 v88, 16, v82
	v_and_b32_e32 v89, 0xffff0000, v82
	v_lshlrev_b32_e32 v82, 16, v83
	v_and_b32_e32 v83, 0xffff0000, v83
	v_lshlrev_b32_e32 v90, 16, v84
	v_and_b32_e32 v91, 0xffff0000, v84
	v_lshlrev_b32_e32 v84, 16, v85
	v_and_b32_e32 v85, 0xffff0000, v85
	v_pk_add_f32 v[78:79], v[78:79], v[82:83]
	v_pk_add_f32 v[76:77], v[76:77], v[88:89]
	v_pk_add_f32 v[82:83], v[74:75], v[84:85]
	v_pk_add_f32 v[74:75], v[72:73], v[90:91]
	v_cvt_pk_bf16_f32 v72, v76, v77
	v_cvt_pk_bf16_f32 v73, v78, v79
	v_cvt_pk_bf16_f32 v74, v74, v75
	v_cvt_pk_bf16_f32 v75, v82, v83
	global_store_dwordx4 v[86:87], v[72:75], off
	s_waitcnt vmcnt(15)
	s_nop 1
	v_mov_b32_e32 v72, v188
	v_mov_b32_e32 v73, v189
	v_mov_b32_e32 v74, v190
	v_mov_b32_e32 v75, v191
	s_waitcnt lgkmcnt(0)
; DI unsigned pack2(float a, float b) { f32x2 v = {a, b}; hwbf16x2 r = __builtin_convertvector(v, hwbf16x2); return __builtin_bit_cast(unsigned, r); }
; DI float bflo(unsigned w) { return __uint_as_float(w << 16); }
; DI float bfhi(unsigned w) { return __uint_as_float(w & 0xffff0000u); }
;     DI void operator()(const f32x4 (&acc)[2][2][4][2], const Unit& u, int wr, int wc, int fr, int fq) const {
;     ...
;             for (int m = 0; m < 4; ++m) { const size_t ro = (size_t)(row0 + ai * HALF + m * 16) * D + col0;
; #pragma unroll
;                 for (int bj = 0; bj < 2; ++bj) {
;                     f32x4 x0, x1;
;                     if constexpr (IB) { const u32x4 w = *(const u32x4*)((const bf16_t*)Xin + ro + bj * HALF);
;                         x0 = (f32x4){bflo(w[0]), bfhi(w[0]), bflo(w[1]), bfhi(w[1])}; x1 = (f32x4){bflo(w[2]), bfhi(w[2]), bflo(w[3]), bfhi(w[3])}; }
;                     else { x0 = *(const f32x4*)((const float*)Xin + ro + bj * HALF); x1 = *(const f32x4*)((const float*)Xin + ro + bj * HALF + 4); }
;                     x0 += acc[ai][bj][m][0] * sc[bj][0]; x1 += acc[ai][bj][m][1] * sc[bj][1];
;                     if constexpr (OB) { u32x4 o; o[0] = pack2(x0[0], x0[1]); o[1] = pack2(x0[2], x0[3]); o[2] = pack2(x1[0], x1[1]); o[3] = pack2(x1[2], x1[3]);
;                         *(u32x4*)((bf16_t*)Xout + ro + bj * HALF) = o; }
;                     else { *(f32x4*)((float*)Xout + ro + bj * HALF) = x0; *(f32x4*)((float*)Xout + ro + bj * HALF + 4) = x1; } } }
	v_lshlrev_b32_e32 v76, 16, v72
	v_and_b32_e32 v77, 0xffff0000, v72
	v_lshlrev_b32_e32 v72, 16, v73
	v_and_b32_e32 v73, 0xffff0000, v73
	v_lshlrev_b32_e32 v78, 16, v74
	v_and_b32_e32 v79, 0xffff0000, v74
	v_lshlrev_b32_e32 v74, 16, v75
	v_and_b32_e32 v75, 0xffff0000, v75
	v_pk_add_f32 v[70:71], v[70:71], v[72:73]
	v_pk_add_f32 v[68:69], v[68:69], v[76:77]
	v_pk_add_f32 v[72:73], v[66:67], v[74:75]
	v_pk_add_f32 v[66:67], v[64:65], v[78:79]
	v_cvt_pk_bf16_f32 v64, v68, v69
	v_cvt_pk_bf16_f32 v65, v70, v71
	v_cvt_pk_bf16_f32 v66, v66, v67
	v_cvt_pk_bf16_f32 v67, v72, v73
	global_store_dwordx4 v[80:81], v[64:67], off offset:256
	s_nop 1
	v_lshl_add_u64 v[64:65], v[144:145], 0, s[2:3]
	s_mov_b32 s2, 0x80000
	v_add_co_u32_e32 v70, vcc, s2, v144
	s_mov_b64 s[2:3], 0x90000
	s_nop 0
	v_addc_co_u32_e32 v71, vcc, 0, v145, vcc
	s_waitcnt vmcnt(15)
	s_nop 1
	v_mov_b32_e32 v66, v192
	v_mov_b32_e32 v67, v193
	v_mov_b32_e32 v68, v194
	v_mov_b32_e32 v69, v195
	s_waitcnt lgkmcnt(0)
	v_lshlrev_b32_e32 v72, 16, v66
	v_and_b32_e32 v73, 0xffff0000, v66
	v_lshlrev_b32_e32 v66, 16, v67
	v_and_b32_e32 v67, 0xffff0000, v67
	v_lshlrev_b32_e32 v74, 16, v68
	v_and_b32_e32 v75, 0xffff0000, v68
	v_lshlrev_b32_e32 v68, 16, v69
	v_and_b32_e32 v69, 0xffff0000, v69
	v_pk_add_f32 v[62:63], v[62:63], v[66:67]
	v_pk_add_f32 v[60:61], v[60:61], v[72:73]
	v_pk_add_f32 v[66:67], v[58:59], v[68:69]
	v_pk_add_f32 v[58:59], v[56:57], v[74:75]
	v_cvt_pk_bf16_f32 v56, v60, v61
	v_cvt_pk_bf16_f32 v57, v62, v63
	v_cvt_pk_bf16_f32 v58, v58, v59
	v_cvt_pk_bf16_f32 v59, v66, v67
	global_store_dwordx4 v[70:71], v[56:59], off
	s_waitcnt vmcnt(15)
	s_nop 1
	v_mov_b32_e32 v56, v198
	v_mov_b32_e32 v57, v199
	v_mov_b32_e32 v58, v200
	v_mov_b32_e32 v59, v201
	s_waitcnt lgkmcnt(0)
	v_lshlrev_b32_e32 v60, 16, v56
	v_and_b32_e32 v61, 0xffff0000, v56
	v_lshlrev_b32_e32 v56, 16, v57
	v_and_b32_e32 v57, 0xffff0000, v57
	v_lshlrev_b32_e32 v62, 16, v58
	v_and_b32_e32 v63, 0xffff0000, v58
	v_lshlrev_b32_e32 v58, 16, v59
	v_and_b32_e32 v59, 0xffff0000, v59
	v_pk_add_f32 v[54:55], v[54:55], v[56:57]
	v_pk_add_f32 v[52:53], v[52:53], v[60:61]
	v_pk_add_f32 v[56:57], v[50:51], v[58:59]
	v_pk_add_f32 v[50:51], v[48:49], v[62:63]
	v_cvt_pk_bf16_f32 v48, v52, v53
	v_cvt_pk_bf16_f32 v49, v54, v55
	v_cvt_pk_bf16_f32 v50, v50, v51
	v_cvt_pk_bf16_f32 v51, v56, v57
	global_store_dwordx4 v[64:65], v[48:51], off offset:256
	s_nop 1
	v_lshl_add_u64 v[48:49], v[144:145], 0, s[2:3]
	s_mov_b32 s2, 0x90000
	v_add_co_u32_e32 v54, vcc, s2, v144
	s_mov_b64 s[2:3], 0xa0000
	s_nop 0
	v_addc_co_u32_e32 v55, vcc, 0, v145, vcc
	s_waitcnt vmcnt(15)
	s_nop 1
	v_mov_b32_e32 v50, v202
	v_mov_b32_e32 v51, v203
	v_mov_b32_e32 v52, v204
	v_mov_b32_e32 v53, v205
	s_waitcnt lgkmcnt(0)
	v_lshlrev_b32_e32 v56, 16, v50
	v_and_b32_e32 v57, 0xffff0000, v50
	v_lshlrev_b32_e32 v50, 16, v51
	v_and_b32_e32 v51, 0xffff0000, v51
	v_lshlrev_b32_e32 v58, 16, v52
	v_and_b32_e32 v59, 0xffff0000, v52
	v_lshlrev_b32_e32 v52, 16, v53
	v_and_b32_e32 v53, 0xffff0000, v53
	v_pk_add_f32 v[46:47], v[46:47], v[50:51]
	v_pk_add_f32 v[44:45], v[44:45], v[56:57]
	v_pk_add_f32 v[50:51], v[42:43], v[52:53]
	v_pk_add_f32 v[42:43], v[40:41], v[58:59]
	v_cvt_pk_bf16_f32 v40, v44, v45
	v_cvt_pk_bf16_f32 v41, v46, v47
	v_cvt_pk_bf16_f32 v42, v42, v43
	v_cvt_pk_bf16_f32 v43, v50, v51
	global_store_dwordx4 v[54:55], v[40:43], off
	s_waitcnt vmcnt(15)
	s_nop 1
	v_mov_b32_e32 v40, v206
	v_mov_b32_e32 v41, v207
	v_mov_b32_e32 v42, v208
	v_mov_b32_e32 v43, v209
	s_waitcnt lgkmcnt(0)
; DI unsigned pack2(float a, float b) { f32x2 v = {a, b}; hwbf16x2 r = __builtin_convertvector(v, hwbf16x2); return __builtin_bit_cast(unsigned, r); }
; DI float bflo(unsigned w) { return __uint_as_float(w << 16); }
; DI float bfhi(unsigned w) { return __uint_as_float(w & 0xffff0000u); }
;     DI const char* a(const Unit& u) const { return (const char*)(A + (size_t)u.pm * BM * lda); }
;     DI const char* a(const Unit& u) const { return (const char*)(A + (size_t)u.pm * BM * 2048 + (u.pn >> 1) * 512); }
; #define PG8_BAR __builtin_amdgcn_s_barrier()
;     DI void operator()(const f32x4 (&acc)[2][2][4][2], const Unit& u, int wr, int wc, int fr, int fq) const {
;     ...
;             for (int m = 0; m < 4; ++m) { const size_t ro = (size_t)(row0 + ai * HALF + m * 16) * D + col0;
; #pragma unroll
;                 for (int bj = 0; bj < 2; ++bj) {
;                     f32x4 x0, x1;
;                     if constexpr (IB) { const u32x4 w = *(const u32x4*)((const bf16_t*)Xin + ro + bj * HALF);
;                         x0 = (f32x4){bflo(w[0]), bfhi(w[0]), bflo(w[1]), bfhi(w[1])}; x1 = (f32x4){bflo(w[2]), bfhi(w[2]), bflo(w[3]), bfhi(w[3])}; }
;                     else { x0 = *(const f32x4*)((const float*)Xin + ro + bj * HALF); x1 = *(const f32x4*)((const float*)Xin + ro + bj * HALF + 4); }
;                     x0 += acc[ai][bj][m][0] * sc[bj][0]; x1 += acc[ai][bj][m][1] * sc[bj][1];
;                     if constexpr (OB) { u32x4 o; o[0] = pack2(x0[0], x0[1]); o[1] = pack2(x0[2], x0[3]); o[2] = pack2(x1[0], x1[1]); o[3] = pack2(x1[2], x1[3]);
;                         *(u32x4*)((bf16_t*)Xout + ro + bj * HALF) = o; }
;                     else { *(f32x4*)((float*)Xout + ro + bj * HALF) = x0; *(f32x4*)((float*)Xout + ro + bj * HALF + 4) = x1; } } }
; template <class Map, class Epi>
; DI void gemm_phase(LAS unsigned char* lds, const Map& MP, const Epi& E, const int nM, const int nN, const int K, const int lda, const int ldb) {
;     ...
;         if (!has_next) break;
; #pragma unroll
;         for (int a = 0; a < 2; ++a)
; #pragma unroll
;             for (int b = 0; b < 2; ++b)
; #pragma unroll
;                 for (int m = 0; m < 4; ++m)
; #pragma unroll
;                     for (int n = 0; n < 2; ++n) acc[a][b][m][n] = (f32x4){0.f, 0.f, 0.f, 0.f};
;         cur = nxt; cA = nA; cB = nB; ++ui;
;     }
;     PG8_WAIT_V(0);
;     if (wr == 0) PG8_BAR;
;     PG8_BAR;
	v_lshlrev_b32_e32 v44, 16, v40
	v_and_b32_e32 v45, 0xffff0000, v40
	v_lshlrev_b32_e32 v40, 16, v41
	v_and_b32_e32 v41, 0xffff0000, v41
	v_lshlrev_b32_e32 v46, 16, v42
	v_and_b32_e32 v47, 0xffff0000, v42
	v_lshlrev_b32_e32 v42, 16, v43
	v_and_b32_e32 v43, 0xffff0000, v43
	v_pk_add_f32 v[38:39], v[38:39], v[40:41]
	v_pk_add_f32 v[36:37], v[36:37], v[44:45]
	v_pk_add_f32 v[40:41], v[34:35], v[42:43]
	v_pk_add_f32 v[34:35], v[32:33], v[46:47]
	v_cvt_pk_bf16_f32 v32, v36, v37
	v_cvt_pk_bf16_f32 v33, v38, v39
	v_cvt_pk_bf16_f32 v34, v34, v35
	v_cvt_pk_bf16_f32 v35, v40, v41
	global_store_dwordx4 v[48:49], v[32:35], off offset:256
	s_nop 1
	v_lshl_add_u64 v[32:33], v[144:145], 0, s[2:3]
	s_mov_b32 s2, 0xa0000
	v_add_co_u32_e32 v38, vcc, s2, v144
	s_mov_b64 s[2:3], 0xb0000
	s_nop 0
	v_addc_co_u32_e32 v39, vcc, 0, v145, vcc
	s_waitcnt vmcnt(15)
	s_nop 1
	v_mov_b32_e32 v34, v210
	v_mov_b32_e32 v35, v211
	v_mov_b32_e32 v36, v212
	v_mov_b32_e32 v37, v213
	s_waitcnt lgkmcnt(0)
	v_lshlrev_b32_e32 v40, 16, v34
	v_and_b32_e32 v41, 0xffff0000, v34
	v_lshlrev_b32_e32 v34, 16, v35
	v_and_b32_e32 v35, 0xffff0000, v35
	v_lshlrev_b32_e32 v42, 16, v36
	v_and_b32_e32 v43, 0xffff0000, v36
	v_lshlrev_b32_e32 v36, 16, v37
	v_and_b32_e32 v37, 0xffff0000, v37
	v_pk_add_f32 v[30:31], v[30:31], v[34:35]
	v_pk_add_f32 v[28:29], v[28:29], v[40:41]
	v_pk_add_f32 v[34:35], v[26:27], v[36:37]
	v_pk_add_f32 v[26:27], v[24:25], v[42:43]
	v_cvt_pk_bf16_f32 v24, v28, v29
	v_cvt_pk_bf16_f32 v25, v30, v31
	v_cvt_pk_bf16_f32 v26, v26, v27
	v_cvt_pk_bf16_f32 v27, v34, v35
	global_store_dwordx4 v[38:39], v[24:27], off
	s_waitcnt vmcnt(15)
	s_nop 1
	v_mov_b32_e32 v24, v214
	v_mov_b32_e32 v25, v215
	v_mov_b32_e32 v26, v216
	v_mov_b32_e32 v27, v217
	s_waitcnt lgkmcnt(0)
	v_lshlrev_b32_e32 v28, 16, v24
	v_and_b32_e32 v29, 0xffff0000, v24
	v_lshlrev_b32_e32 v24, 16, v25
	v_and_b32_e32 v25, 0xffff0000, v25
	v_lshlrev_b32_e32 v30, 16, v26
	v_and_b32_e32 v31, 0xffff0000, v26
	v_lshlrev_b32_e32 v26, 16, v27
	v_and_b32_e32 v27, 0xffff0000, v27
	v_pk_add_f32 v[22:23], v[22:23], v[24:25]
	v_pk_add_f32 v[20:21], v[20:21], v[28:29]
	v_pk_add_f32 v[24:25], v[18:19], v[26:27]
	v_pk_add_f32 v[18:19], v[16:17], v[30:31]
	v_cvt_pk_bf16_f32 v16, v20, v21
	v_cvt_pk_bf16_f32 v17, v22, v23
	v_cvt_pk_bf16_f32 v18, v18, v19
	v_cvt_pk_bf16_f32 v19, v24, v25
	global_store_dwordx4 v[32:33], v[16:19], off offset:256
	s_nop 1
	v_lshl_add_u64 v[16:17], v[144:145], 0, s[2:3]
	s_mov_b32 s2, 0xb0000
	v_add_co_u32_e32 v22, vcc, s2, v144
	s_mov_b32 s2, s44
	s_nop 0
	v_addc_co_u32_e32 v23, vcc, 0, v145, vcc
	s_waitcnt vmcnt(15)
	s_nop 1
	v_mov_b32_e32 v18, v248
	v_mov_b32_e32 v19, v249
	v_mov_b32_e32 v20, v250
	v_mov_b32_e32 v21, v251
	s_and_b64 vcc, exec, s[40:41]
	s_waitcnt lgkmcnt(0)
	v_lshlrev_b32_e32 v24, 16, v18
	v_and_b32_e32 v25, 0xffff0000, v18
	v_lshlrev_b32_e32 v18, 16, v19
	v_and_b32_e32 v19, 0xffff0000, v19
	v_lshlrev_b32_e32 v26, 16, v20
	v_and_b32_e32 v27, 0xffff0000, v20
	v_lshlrev_b32_e32 v20, 16, v21
	v_and_b32_e32 v21, 0xffff0000, v21
	v_pk_add_f32 v[14:15], v[14:15], v[18:19]
	v_pk_add_f32 v[12:13], v[12:13], v[24:25]
	v_pk_add_f32 v[18:19], v[10:11], v[20:21]
	v_pk_add_f32 v[10:11], v[8:9], v[26:27]
	v_cvt_pk_bf16_f32 v8, v12, v13
	v_cvt_pk_bf16_f32 v9, v14, v15
	v_cvt_pk_bf16_f32 v10, v10, v11
	v_cvt_pk_bf16_f32 v11, v18, v19
	global_store_dwordx4 v[22:23], v[8:11], off
	s_waitcnt vmcnt(15)
	s_nop 1
	v_mov_b32_e32 v8, v252
	v_mov_b32_e32 v9, v253
	v_mov_b32_e32 v10, v254
	v_mov_b32_e32 v11, v255
	s_waitcnt lgkmcnt(0)
	v_lshlrev_b32_e32 v12, 16, v8
	v_and_b32_e32 v13, 0xffff0000, v8
	v_lshlrev_b32_e32 v8, 16, v9
	v_and_b32_e32 v9, 0xffff0000, v9
	v_lshlrev_b32_e32 v14, 16, v10
	v_and_b32_e32 v15, 0xffff0000, v10
	v_lshlrev_b32_e32 v10, 16, v11
	v_and_b32_e32 v11, 0xffff0000, v11
	v_pk_add_f32 v[6:7], v[6:7], v[8:9]
	v_pk_add_f32 v[4:5], v[4:5], v[12:13]
	v_pk_add_f32 v[8:9], v[2:3], v[10:11]
	v_pk_add_f32 v[2:3], v[0:1], v[14:15]
	v_cvt_pk_bf16_f32 v0, v4, v5
	v_cvt_pk_bf16_f32 v1, v6, v7
	v_cvt_pk_bf16_f32 v2, v2, v3
	v_cvt_pk_bf16_f32 v3, v8, v9
	global_store_dwordx4 v[16:17], v[0:3], off offset:256
	s_cbranch_vccz .LBB1_1761
	s_waitcnt vmcnt(0)
	s_cmpk_gt_u32 s17, 0xff
	s_cbranch_scc1 .LBB1_1768
	s_barrier

; #define PG8_STAGE(bufoff, gbase, voff) do { _Pragma("unroll") for (int _i = 0; _i < 2; ++_i) \
;         __builtin_amdgcn_global_load_lds((const unsigned*)((const char*)(gbase) + (voff)[_i]), (LAS unsigned*)(lds + (bufoff) + ldsw + _i * 8192), 16, 0, 0); } while (0)
; #define PG8_LDA(dst, b, h) do { _Pragma("unroll") for (int m = 0; m < 4; ++m) _Pragma("unroll") for (int k = 0; k < 2; ++k) dst[m][k] = *(const LAS bf16x8*)(lds + PG8_SA(b, h) + aoff + m * 2048 + k * 1024); } while (0)
; #define PG8_LDB(dst, b, h) do { _Pragma("unroll") for (int n = 0; n < 2; ++n) _Pragma("unroll") for (int k = 0; k < 2; ++k) dst[n][k] = *(const LAS bf16x8*)(lds + PG8_SB(b, h) + boff + n * 2048 + k * 1024); } while (0)
; #define PG8_MMA(ai, bj, At, Bt) do { __builtin_amdgcn_s_setprio(1); _Pragma("unroll") for (int m = 0; m < 4; ++m) _Pragma("unroll") for (int n = 0; n < 2; ++n) _Pragma("unroll") for (int k = 0; k < 2; ++k) \
;         acc[ai][bj][m][n] = __builtin_amdgcn_mfma_f32_16x16x32_bf16(Bt[n][k], At[m][k], acc[ai][bj][m][n], 0, 0, 0); __builtin_amdgcn_s_setprio(0); } while (0)
; #define PG8_WAIT_V(n) asm volatile("s_waitcnt vmcnt(" #n ")" ::: "memory")
; #define PG8_WAIT_L(n) asm volatile("s_waitcnt lgkmcnt(" #n ")" ::: "memory")
; #define PG8_BAR __builtin_amdgcn_s_barrier()
; #define PG8_SCHED __builtin_amdgcn_sched_barrier(0)
; template <class Map, class Epi>
; DI void gemm_phase(LAS unsigned char* lds, const Map& MP, const Epi& E, const int nM, const int nN, const int K, const int lda, const int ldb) {
;     ...
;             PG8_LDB(B0, 0, 0); PG8_SCHED; PG8_LDA(At, 0, 0); PG8_STAGE(PG8_SA(1, 1), a1 + hstepA, voffA);
;             PG8_WAIT_L(8); PG8_BAR; PG8_WAIT_L(0); PG8_MMA(0, 0, At, B0); PG8_BAR; PG8_SCHED;
;             PG8_LDB(B1, 0, 1); PG8_STAGE(PG8_SB(0, 0), b2, voffB);
;             PG8_BAR; PG8_WAIT_L(0); PG8_MMA(0, 1, At, B1); PG8_BAR;
;             PG8_LDA(At, 0, 1); PG8_STAGE(PG8_SA(0, 0), a2, voffA);
;             PG8_BAR; PG8_WAIT_L(0); PG8_MMA(1, 0, At, B0); PG8_BAR; PG8_SCHED;
;             PG8_STAGE(PG8_SB(0, 1), b2 + hstepB, voffB);
;             PG8_WAIT_V(6); PG8_BAR; PG8_MMA(1, 1, At, B1); PG8_BAR;
;             PG8_LDB(B0, 1, 0); PG8_SCHED; PG8_LDA(At, 1, 0); PG8_STAGE(PG8_SA(0, 1), a2 + hstepA, voffA);
.LBB1_1908:
	ds_read_b128 v[96:99], v190
	ds_read_b128 v[100:103], v190 offset:1024
	ds_read_b128 v[108:111], v190 offset:2048
	ds_read_b128 v[112:115], v190 offset:3072
	ds_read_b128 v[160:163], v190 offset:4096
	ds_read_b128 v[164:167], v190 offset:5120
	ds_read_b128 v[198:201], v190 offset:6144
	ds_read_b128 v[202:205], v190 offset:7168
	s_add_u32 s28, s42, 0xfff80080
	s_addc_u32 s29, s43, -1
	s_cmp_eq_u32 s3, 28
	s_cselect_b32 s47, s23, s29
	s_cselect_b32 s46, s58, s28
	s_cselect_b32 s29, s21, vcc_hi
	s_cselect_b32 s28, s59, vcc_lo
	s_add_i32 m0, s38, 0xc000
	s_nop 0
	global_load_lds_dwordx4 v178, s[42:43]
	s_add_i32 m0, s38, 0xe000
	s_nop 0
	global_load_lds_dwordx4 v176, s[42:43]
	s_waitcnt lgkmcnt(8)
	s_barrier
	s_setprio 1
	s_waitcnt lgkmcnt(7)
	v_mfma_f32_16x16x32_bf16 v[148:151], v[80:83], v[96:99], v[148:151]
	v_mfma_f32_16x16x32_bf16 v[144:147], v[88:91], v[96:99], v[144:147]
	s_waitcnt lgkmcnt(5)
	v_mfma_f32_16x16x32_bf16 v[136:139], v[80:83], v[108:111], v[136:139]
	v_mfma_f32_16x16x32_bf16 v[128:131], v[88:91], v[108:111], v[128:131]
	s_waitcnt lgkmcnt(3)
	v_mfma_f32_16x16x32_bf16 v[120:123], v[80:83], v[160:163], v[120:123]
	v_mfma_f32_16x16x32_bf16 v[104:107], v[88:91], v[160:163], v[104:107]
	s_waitcnt lgkmcnt(1)
	v_mfma_f32_16x16x32_bf16 v[76:79], v[80:83], v[198:201], v[76:79]
	v_mfma_f32_16x16x32_bf16 v[72:75], v[88:91], v[198:201], v[72:75]
	v_mfma_f32_16x16x32_bf16 v[148:151], v[84:87], v[100:103], v[148:151]
	v_mfma_f32_16x16x32_bf16 v[144:147], v[92:95], v[100:103], v[144:147]
	v_mfma_f32_16x16x32_bf16 v[136:139], v[84:87], v[112:115], v[136:139]
	v_mfma_f32_16x16x32_bf16 v[128:131], v[92:95], v[112:115], v[128:131]
	v_mfma_f32_16x16x32_bf16 v[120:123], v[84:87], v[164:167], v[120:123]
	v_mfma_f32_16x16x32_bf16 v[104:107], v[92:95], v[164:167], v[104:107]
	s_waitcnt lgkmcnt(0)
	v_mfma_f32_16x16x32_bf16 v[76:79], v[84:87], v[202:205], v[76:79]
	v_mfma_f32_16x16x32_bf16 v[72:75], v[92:95], v[202:205], v[72:75]
	s_setprio 0
	s_barrier
	ds_read_b128 v[206:209], v191
	ds_read_b128 v[210:213], v191 offset:1024
	ds_read_b128 v[214:217], v191 offset:2048
	ds_read_b128 v[218:221], v191 offset:3072
	s_add_i32 s68, s2, s54
	v_lshl_add_u64 v[184:185], s[28:29], 0, v[172:173]
	s_mov_b32 m0, s68
	s_nop 0
	global_load_lds_dwordx4 v[184:185], off
	v_lshl_add_u64 v[194:195], s[28:29], 0, v[168:169]
	s_add_i32 m0, s68, 0x2000
	s_nop 0
	global_load_lds_dwordx4 v[194:195], off
	s_barrier
	s_setprio 1
	s_waitcnt lgkmcnt(3)
	v_mfma_f32_16x16x32_bf16 v[156:159], v[206:209], v[96:99], v[156:159]
	s_waitcnt lgkmcnt(1)
	v_mfma_f32_16x16x32_bf16 v[96:99], v[214:217], v[96:99], v[152:155]
	v_mfma_f32_16x16x32_bf16 v[156:159], v[210:213], v[100:103], v[156:159]
	s_waitcnt lgkmcnt(0)
	v_mfma_f32_16x16x32_bf16 v[96:99], v[218:221], v[100:103], v[96:99]
	v_mfma_f32_16x16x32_bf16 v[100:103], v[206:209], v[108:111], v[140:143]
	v_mfma_f32_16x16x32_bf16 v[108:111], v[214:217], v[108:111], v[132:135]
	v_mfma_f32_16x16x32_bf16 v[116:119], v[214:217], v[160:163], v[116:119]
	v_mfma_f32_16x16x32_bf16 v[68:71], v[206:209], v[198:201], v[68:71]
	v_mfma_f32_16x16x32_bf16 v[64:67], v[214:217], v[198:201], v[64:67]
	s_mov_b32 m0, s38
	v_mfma_f32_16x16x32_bf16 v[100:103], v[210:213], v[112:115], v[100:103]
	v_lshl_add_u64 v[226:227], s[46:47], 0, v[174:175]
	v_mfma_f32_16x16x32_bf16 v[108:111], v[218:221], v[112:115], v[108:111]
	v_mfma_f32_16x16x32_bf16 v[112:115], v[206:209], v[160:163], v[124:127]
	v_mfma_f32_16x16x32_bf16 v[116:119], v[218:221], v[164:167], v[116:119]
	v_mfma_f32_16x16x32_bf16 v[68:71], v[210:213], v[202:205], v[68:71]
	v_mfma_f32_16x16x32_bf16 v[64:67], v[218:221], v[202:205], v[64:67]
	v_mfma_f32_16x16x32_bf16 v[112:115], v[210:213], v[164:167], v[112:115]
	s_setprio 0
	s_barrier
	ds_read_b128 v[124:127], v190 offset:16384
	ds_read_b128 v[132:135], v190 offset:17408
	ds_read_b128 v[140:143], v190 offset:18432
	ds_read_b128 v[152:155], v190 offset:19456
	ds_read_b128 v[160:163], v190 offset:20480
	ds_read_b128 v[164:167], v190 offset:21504
	ds_read_b128 v[198:201], v190 offset:22528
	ds_read_b128 v[202:205], v190 offset:23552
	global_load_lds_dwordx4 v[226:227], off
	v_lshl_add_u64 v[234:235], s[46:47], 0, v[170:171]
	s_mov_b32 m0, s39
	s_nop 0
	global_load_lds_dwordx4 v[234:235], off
	s_waitcnt vmcnt(10)
	s_barrier
	s_setprio 1
	s_waitcnt lgkmcnt(7)
	v_mfma_f32_16x16x32_bf16 v[60:63], v[80:83], v[124:127], v[60:63]
	v_mfma_f32_16x16x32_bf16 v[48:51], v[88:91], v[124:127], v[48:51]
	s_waitcnt lgkmcnt(5)
	v_mfma_f32_16x16x32_bf16 v[40:43], v[80:83], v[140:143], v[40:43]
	v_mfma_f32_16x16x32_bf16 v[32:35], v[88:91], v[140:143], v[32:35]
	s_waitcnt lgkmcnt(3)
	v_mfma_f32_16x16x32_bf16 v[24:27], v[80:83], v[160:163], v[24:27]
	v_mfma_f32_16x16x32_bf16 v[16:19], v[88:91], v[160:163], v[16:19]
	s_waitcnt lgkmcnt(1)
	v_mfma_f32_16x16x32_bf16 v[12:15], v[80:83], v[198:201], v[12:15]
	v_mfma_f32_16x16x32_bf16 v[8:11], v[88:91], v[198:201], v[8:11]
	v_mfma_f32_16x16x32_bf16 v[60:63], v[84:87], v[132:135], v[60:63]
	v_mfma_f32_16x16x32_bf16 v[48:51], v[92:95], v[132:135], v[48:51]
	v_mfma_f32_16x16x32_bf16 v[40:43], v[84:87], v[152:155], v[40:43]
	v_mfma_f32_16x16x32_bf16 v[32:35], v[92:95], v[152:155], v[32:35]
	v_mfma_f32_16x16x32_bf16 v[24:27], v[84:87], v[164:167], v[24:27]
	v_mfma_f32_16x16x32_bf16 v[16:19], v[92:95], v[164:167], v[16:19]
	s_waitcnt lgkmcnt(0)
	v_mfma_f32_16x16x32_bf16 v[12:15], v[84:87], v[202:205], v[12:15]
	v_mfma_f32_16x16x32_bf16 v[8:11], v[92:95], v[202:205], v[8:11]
	s_setprio 0
	s_barrier
	s_add_u32 s68, s28, 0x80000
	s_addc_u32 s69, s29, 0
	s_add_i32 s70, s31, s54
	s_mov_b32 m0, s70
	s_nop 0
	global_load_lds_dwordx4 v172, s[68:69]
	s_add_i32 m0, s70, 0x2000
	s_nop 0
	global_load_lds_dwordx4 v168, s[68:69]
	s_waitcnt vmcnt(6)
	s_barrier
; #define PG8_STAGE(bufoff, gbase, voff) do { _Pragma("unroll") for (int _i = 0; _i < 2; ++_i) \
;         __builtin_amdgcn_global_load_lds((const unsigned*)((const char*)(gbase) + (voff)[_i]), (LAS unsigned*)(lds + (bufoff) + ldsw + _i * 8192), 16, 0, 0); } while (0)
; #define PG8_LDA(dst, b, h) do { _Pragma("unroll") for (int m = 0; m < 4; ++m) _Pragma("unroll") for (int k = 0; k < 2; ++k) dst[m][k] = *(const LAS bf16x8*)(lds + PG8_SA(b, h) + aoff + m * 2048 + k * 1024); } while (0)
; #define PG8_LDB(dst, b, h) do { _Pragma("unroll") for (int n = 0; n < 2; ++n) _Pragma("unroll") for (int k = 0; k < 2; ++k) dst[n][k] = *(const LAS bf16x8*)(lds + PG8_SB(b, h) + boff + n * 2048 + k * 1024); } while (0)
; #define PG8_MMA(ai, bj, At, Bt) do { __builtin_amdgcn_s_setprio(1); _Pragma("unroll") for (int m = 0; m < 4; ++m) _Pragma("unroll") for (int n = 0; n < 2; ++n) _Pragma("unroll") for (int k = 0; k < 2; ++k) \
;         acc[ai][bj][m][n] = __builtin_amdgcn_mfma_f32_16x16x32_bf16(Bt[n][k], At[m][k], acc[ai][bj][m][n], 0, 0, 0); __builtin_amdgcn_s_setprio(0); } while (0)
; #define PG8_WAIT_L(n) asm volatile("s_waitcnt lgkmcnt(" #n ")" ::: "memory")
; #define PG8_BAR __builtin_amdgcn_s_barrier()
; #define PG8_SCHED __builtin_amdgcn_sched_barrier(0)
; template <class Map, class Epi>
; DI void gemm_phase(LAS unsigned char* lds, const Map& MP, const Epi& E, const int nM, const int nN, const int K, const int lda, const int ldb) {
;     ...
;             PG8_LDB(B0, 1, 0); PG8_SCHED; PG8_LDA(At, 1, 0); PG8_STAGE(PG8_SA(0, 1), a2 + hstepA, voffA);
;             PG8_WAIT_L(8); PG8_BAR; PG8_WAIT_L(0); PG8_MMA(0, 0, At, B0); PG8_BAR; PG8_SCHED;
;             PG8_LDB(B1, 1, 1); PG8_STAGE(PG8_SB(1, 0), b3, voffB);
;             PG8_BAR; PG8_WAIT_L(0); PG8_MMA(0, 1, At, B1); PG8_BAR;
;             PG8_LDA(At, 1, 1); PG8_STAGE(PG8_SA(1, 0), a3, voffA);
;             PG8_BAR; PG8_WAIT_L(0); PG8_MMA(1, 0, At, B0); PG8_BAR; PG8_SCHED;
	s_setprio 1
	v_mfma_f32_16x16x32_bf16 v[56:59], v[206:209], v[124:127], v[56:59]
	v_mfma_f32_16x16x32_bf16 v[52:55], v[214:217], v[124:127], v[52:55]
	s_add_i32 s68, 0, 0x18000
	v_add_u32_e32 v92, s68, v188
	ds_read_b128 v[80:83], v92
	v_mfma_f32_16x16x32_bf16 v[44:47], v[206:209], v[140:143], v[44:47]
	v_mfma_f32_16x16x32_bf16 v[36:39], v[214:217], v[140:143], v[36:39]
	ds_read_b128 v[84:87], v92 offset:1024
	v_mfma_f32_16x16x32_bf16 v[28:31], v[206:209], v[160:163], v[28:31]
	v_mfma_f32_16x16x32_bf16 v[20:23], v[214:217], v[160:163], v[20:23]
	ds_read_b128 v[88:91], v92 offset:2048
	v_mfma_f32_16x16x32_bf16 v[4:7], v[206:209], v[198:201], v[4:7]
	v_mfma_f32_16x16x32_bf16 v[0:3], v[214:217], v[198:201], v[0:3]
	ds_read_b128 v[92:95], v92 offset:3072
	v_mfma_f32_16x16x32_bf16 v[56:59], v[210:213], v[132:135], v[56:59]
	v_mfma_f32_16x16x32_bf16 v[52:55], v[218:221], v[132:135], v[52:55]
	v_mfma_f32_16x16x32_bf16 v[44:47], v[210:213], v[152:155], v[44:47]
	v_mfma_f32_16x16x32_bf16 v[36:39], v[218:221], v[152:155], v[36:39]
	v_mfma_f32_16x16x32_bf16 v[28:31], v[210:213], v[164:167], v[28:31]
	v_mfma_f32_16x16x32_bf16 v[20:23], v[218:221], v[164:167], v[20:23]
	v_mfma_f32_16x16x32_bf16 v[4:7], v[210:213], v[202:205], v[4:7]
	v_mfma_f32_16x16x32_bf16 v[0:3], v[218:221], v[202:205], v[0:3]
	s_setprio 0
	s_barrier
	ds_read_b128 v[124:127], v190 offset:32768
	ds_read_b128 v[132:135], v190 offset:33792
	ds_read_b128 v[160:163], v190 offset:34816
	ds_read_b128 v[164:167], v190 offset:35840
	ds_read_b128 v[198:201], v190 offset:36864
	ds_read_b128 v[202:205], v190 offset:37888
	ds_read_b128 v[206:209], v190 offset:38912
	ds_read_b128 v[210:213], v190 offset:39936
	s_add_u32 s46, s46, 0x80000
	s_addc_u32 s47, s47, 0
	s_mov_b32 m0, s56
	s_nop 0
	global_load_lds_dwordx4 v174, s[46:47]
	s_mov_b32 m0, s57
	s_nop 0
	global_load_lds_dwordx4 v170, s[46:47]
	s_waitcnt lgkmcnt(8)
	s_barrier
	s_setprio 1
	s_waitcnt lgkmcnt(7)
	v_mfma_f32_16x16x32_bf16 v[140:143], v[80:83], v[124:127], v[148:151]
	s_waitcnt lgkmcnt(6)
	v_mfma_f32_16x16x32_bf16 v[148:151], v[84:87], v[132:135], v[140:143]
	v_mfma_f32_16x16x32_bf16 v[140:143], v[88:91], v[124:127], v[144:147]
	s_waitcnt lgkmcnt(5)
	v_mfma_f32_16x16x32_bf16 v[136:139], v[80:83], v[160:163], v[136:139]
	v_mfma_f32_16x16x32_bf16 v[128:131], v[88:91], v[160:163], v[128:131]
	s_waitcnt lgkmcnt(3)
	v_mfma_f32_16x16x32_bf16 v[120:123], v[80:83], v[198:201], v[120:123]
	v_mfma_f32_16x16x32_bf16 v[104:107], v[88:91], v[198:201], v[104:107]
	s_waitcnt lgkmcnt(1)
	v_mfma_f32_16x16x32_bf16 v[76:79], v[80:83], v[206:209], v[76:79]
	v_mfma_f32_16x16x32_bf16 v[72:75], v[88:91], v[206:209], v[72:75]
	v_mfma_f32_16x16x32_bf16 v[144:147], v[92:95], v[132:135], v[140:143]
	v_mfma_f32_16x16x32_bf16 v[136:139], v[84:87], v[164:167], v[136:139]
	v_mfma_f32_16x16x32_bf16 v[128:131], v[92:95], v[164:167], v[128:131]
	v_mfma_f32_16x16x32_bf16 v[120:123], v[84:87], v[202:205], v[120:123]
	v_mfma_f32_16x16x32_bf16 v[104:107], v[92:95], v[202:205], v[104:107]
	s_waitcnt lgkmcnt(0)
	v_mfma_f32_16x16x32_bf16 v[76:79], v[84:87], v[210:213], v[76:79]
	v_mfma_f32_16x16x32_bf16 v[72:75], v[92:95], v[210:213], v[72:75]
	s_setprio 0
	s_barrier
	s_add_i32 s46, 0, 0x1c000
	v_add_u32_e32 v140, s46, v188
	ds_read_b128 v[214:217], v140
	ds_read_b128 v[218:221], v140 offset:1024
	ds_read_b128 v[222:225], v140 offset:2048
	ds_read_b128 v[230:233], v140 offset:3072
	s_add_i32 s47, s68, s54
	v_lshl_add_u64 v[140:141], v[184:185], 0, s[14:15]
	s_mov_b32 m0, s47
	s_nop 0
	global_load_lds_dwordx4 v[140:141], off
	v_lshl_add_u64 v[140:141], v[194:195], 0, s[14:15]
	s_add_i32 m0, s47, 0x2000
	s_nop 0
	global_load_lds_dwordx4 v[140:141], off
	s_barrier
	s_setprio 1
	s_waitcnt lgkmcnt(1)
	v_mfma_f32_16x16x32_bf16 v[96:99], v[222:225], v[124:127], v[96:99]
	v_mfma_f32_16x16x32_bf16 v[140:143], v[214:217], v[124:127], v[156:159]
	s_waitcnt lgkmcnt(0)
	v_mfma_f32_16x16x32_bf16 v[152:155], v[230:233], v[132:135], v[96:99]
	v_mfma_f32_16x16x32_bf16 v[96:99], v[214:217], v[160:163], v[100:103]
	v_mfma_f32_16x16x32_bf16 v[156:159], v[218:221], v[132:135], v[140:143]
	v_mfma_f32_16x16x32_bf16 v[140:143], v[218:221], v[164:167], v[96:99]
	v_mfma_f32_16x16x32_bf16 v[96:99], v[222:225], v[160:163], v[108:111]
	v_mfma_f32_16x16x32_bf16 v[132:135], v[230:233], v[164:167], v[96:99]
	v_mfma_f32_16x16x32_bf16 v[96:99], v[214:217], v[198:201], v[112:115]
	s_mov_b32 m0, s63
	v_mfma_f32_16x16x32_bf16 v[124:127], v[218:221], v[202:205], v[96:99]
	v_lshl_add_u64 v[184:185], v[226:227], 0, s[14:15]
	v_mfma_f32_16x16x32_bf16 v[96:99], v[222:225], v[198:201], v[116:119]
	v_mfma_f32_16x16x32_bf16 v[68:71], v[214:217], v[206:209], v[68:71]
	v_mfma_f32_16x16x32_bf16 v[64:67], v[222:225], v[206:209], v[64:67]
	v_mfma_f32_16x16x32_bf16 v[116:119], v[230:233], v[202:205], v[96:99]
	v_mfma_f32_16x16x32_bf16 v[68:71], v[218:221], v[210:213], v[68:71]
	v_mfma_f32_16x16x32_bf16 v[64:67], v[230:233], v[210:213], v[64:67]
	s_setprio 0
	s_barrier
	ds_read_b128 v[96:99], v190 offset:49152
	ds_read_b128 v[100:103], v190 offset:50176
	ds_read_b128 v[108:111], v190 offset:51200
	ds_read_b128 v[112:115], v190 offset:52224
	ds_read_b128 v[160:163], v190 offset:53248
	ds_read_b128 v[164:167], v190 offset:54272
	ds_read_b128 v[198:201], v190 offset:55296
	ds_read_b128 v[202:205], v190 offset:56320
	global_load_lds_dwordx4 v[184:185], off
	v_lshl_add_u64 v[184:185], v[234:235], 0, s[14:15]
	s_mov_b32 m0, s66
	s_nop 0
	global_load_lds_dwordx4 v[184:185], off
	s_waitcnt vmcnt(10)
	s_barrier
; #define PG8_STAGE(bufoff, gbase, voff) do { _Pragma("unroll") for (int _i = 0; _i < 2; ++_i) \
;         __builtin_amdgcn_global_load_lds((const unsigned*)((const char*)(gbase) + (voff)[_i]), (LAS unsigned*)(lds + (bufoff) + ldsw + _i * 8192), 16, 0, 0); } while (0)
; #define PG8_MMA(ai, bj, At, Bt) do { __builtin_amdgcn_s_setprio(1); _Pragma("unroll") for (int m = 0; m < 4; ++m) _Pragma("unroll") for (int n = 0; n < 2; ++n) _Pragma("unroll") for (int k = 0; k < 2; ++k) \
;         acc[ai][bj][m][n] = __builtin_amdgcn_mfma_f32_16x16x32_bf16(Bt[n][k], At[m][k], acc[ai][bj][m][n], 0, 0, 0); __builtin_amdgcn_s_setprio(0); } while (0)
; #define PG8_WAIT_V(n) asm volatile("s_waitcnt vmcnt(" #n ")" ::: "memory")
; #define PG8_WAIT_L(n) asm volatile("s_waitcnt lgkmcnt(" #n ")" ::: "memory")
; #define PG8_BAR __builtin_amdgcn_s_barrier()
; #define PG8_SCHED __builtin_amdgcn_sched_barrier(0)
; template <class Map, class Epi>
; DI void gemm_phase(LAS unsigned char* lds, const Map& MP, const Epi& E, const int nM, const int nN, const int K, const int lda, const int ldb) {
;     ...
;             PG8_BAR; PG8_WAIT_L(0); PG8_MMA(1, 0, At, B0); PG8_BAR; PG8_SCHED;
;             PG8_STAGE(PG8_SB(1, 1), b3 + hstepB, voffB);
;             PG8_WAIT_V(6); PG8_BAR; PG8_MMA(1, 1, At, B1); PG8_BAR;
	s_setprio 1
	s_waitcnt lgkmcnt(7)
	v_mfma_f32_16x16x32_bf16 v[60:63], v[80:83], v[96:99], v[60:63]
	v_mfma_f32_16x16x32_bf16 v[48:51], v[88:91], v[96:99], v[48:51]
	s_waitcnt lgkmcnt(5)
	v_mfma_f32_16x16x32_bf16 v[40:43], v[80:83], v[108:111], v[40:43]
	v_mfma_f32_16x16x32_bf16 v[32:35], v[88:91], v[108:111], v[32:35]
	s_waitcnt lgkmcnt(3)
	v_mfma_f32_16x16x32_bf16 v[24:27], v[80:83], v[160:163], v[24:27]
	v_mfma_f32_16x16x32_bf16 v[16:19], v[88:91], v[160:163], v[16:19]
	s_waitcnt lgkmcnt(1)
	v_mfma_f32_16x16x32_bf16 v[12:15], v[80:83], v[198:201], v[12:15]
	v_mfma_f32_16x16x32_bf16 v[8:11], v[88:91], v[198:201], v[8:11]
	v_mfma_f32_16x16x32_bf16 v[60:63], v[84:87], v[100:103], v[60:63]
	v_mfma_f32_16x16x32_bf16 v[48:51], v[92:95], v[100:103], v[48:51]
	v_mfma_f32_16x16x32_bf16 v[40:43], v[84:87], v[112:115], v[40:43]
	v_mfma_f32_16x16x32_bf16 v[32:35], v[92:95], v[112:115], v[32:35]
	v_mfma_f32_16x16x32_bf16 v[24:27], v[84:87], v[164:167], v[24:27]
	v_mfma_f32_16x16x32_bf16 v[16:19], v[92:95], v[164:167], v[16:19]
	s_waitcnt lgkmcnt(0)
	v_mfma_f32_16x16x32_bf16 v[12:15], v[84:87], v[202:205], v[12:15]
	v_mfma_f32_16x16x32_bf16 v[8:11], v[92:95], v[202:205], v[8:11]
	s_setprio 0
	s_barrier
	s_add_u32 s28, s28, 0x80080
	s_addc_u32 s29, s29, 0
	s_add_i32 s46, s46, s54
	s_mov_b32 m0, s46
	s_nop 0
	global_load_lds_dwordx4 v172, s[28:29]
	s_add_i32 m0, s46, 0x2000
	s_nop 0
	global_load_lds_dwordx4 v168, s[28:29]
	s_waitcnt vmcnt(6)
	s_barrier
	s_setprio 1
	v_mfma_f32_16x16x32_bf16 v[56:59], v[214:217], v[96:99], v[56:59]
	v_mfma_f32_16x16x32_bf16 v[52:55], v[222:225], v[96:99], v[52:55]
	ds_read_b128 v[80:83], v189
	v_mfma_f32_16x16x32_bf16 v[44:47], v[214:217], v[108:111], v[44:47]
	v_mfma_f32_16x16x32_bf16 v[36:39], v[222:225], v[108:111], v[36:39]
	ds_read_b128 v[84:87], v189 offset:1024
	v_mfma_f32_16x16x32_bf16 v[28:31], v[214:217], v[160:163], v[28:31]
	v_mfma_f32_16x16x32_bf16 v[20:23], v[222:225], v[160:163], v[20:23]
	ds_read_b128 v[88:91], v189 offset:2048
	v_mfma_f32_16x16x32_bf16 v[4:7], v[214:217], v[198:201], v[4:7]
	v_mfma_f32_16x16x32_bf16 v[0:3], v[222:225], v[198:201], v[0:3]
	ds_read_b128 v[92:95], v189 offset:3072
	v_mfma_f32_16x16x32_bf16 v[56:59], v[218:221], v[100:103], v[56:59]
	s_add_i32 s3, s3, 2
	v_mfma_f32_16x16x32_bf16 v[52:55], v[230:233], v[100:103], v[52:55]
	s_add_u32 vcc_lo, vcc_lo, 0x100
	s_addc_u32 vcc_hi, vcc_hi, 0
	v_mfma_f32_16x16x32_bf16 v[44:47], v[218:221], v[112:115], v[44:47]
	s_add_u32 s42, s42, 0x100
	s_addc_u32 s43, s43, 0
	v_mfma_f32_16x16x32_bf16 v[36:39], v[230:233], v[112:115], v[36:39]
	s_cmp_gt_u32 s3, 29
	v_mfma_f32_16x16x32_bf16 v[28:31], v[218:221], v[164:167], v[28:31]
	v_mfma_f32_16x16x32_bf16 v[20:23], v[230:233], v[164:167], v[20:23]
	v_mfma_f32_16x16x32_bf16 v[4:7], v[218:221], v[202:205], v[4:7]
	v_mfma_f32_16x16x32_bf16 v[0:3], v[230:233], v[202:205], v[0:3]
	s_setprio 0
	s_barrier
	s_cbranch_scc0 .LBB1_1908
; DI float silu_mul(float g, float v) { return g * v * __builtin_amdgcn_rcpf(1.0f + __builtin_amdgcn_exp2f(-LOG2E * g)); }
;     DI void operator()(const f32x4 (&acc)[2][2][4][2], const Unit& u, int wr, int wc, int fr, int fq) const {
;         const int row0 = u.pm * BM + wr * 64 + fr, ch0 = u.pn * 128 + wc * 32 + 8 * fq;
;         f32x4 w0[2], w1[2], w2[2], bb[2];
; #pragma unroll
;         for (int n = 0; n < 2; ++n) { w0[n] = *(const f32x4*)(cw + ch0 + 4 * n); w1[n] = *(const f32x4*)(cw + DFF + ch0 + 4 * n); w2[n] = *(const f32x4*)(cw + 2 * DFF + ch0 + 4 * n); bb[n] = *(const f32x4*)(cb + ch0 + 4 * n); }
; #pragma unroll
;         for (int ai = 0; ai < 2; ++ai)
; #pragma unroll
;             for (int m = 0; m < 4; ++m) {
;                 const bool efirst = (m == 0) && (fr == 0), elast = (m == 3) && (fr == 15);
;                 const int row = row0 + ai * HALF + m * 16;
;                 f32x4 gc[2];
; #pragma unroll
;                 for (int n = 0; n < 2; ++n) {
;                     const f32x4 g = acc[ai][0][m][n];
;                     const f32x4 gprev = acc[ai][0][m > 0 ? m - 1 : 0][n], gnext = acc[ai][0][m < 3 ? m + 1 : 3][n];
;                     f32x4 up, dn;
; #pragma unroll
;                     for (int e = 0; e < 4; ++e) {
;                         const float pu = (m > 0 && fr == 15) ? gprev[e] : g[e];
;                         const float pd = (m < 3 && fr == 0) ? gnext[e] : g[e];
;                         up[e] = dpp_ror1(pu); dn[e] = dpp_ror15(pd);
;                     }
;                     if (efirst) up = (f32x4){0.f, 0.f, 0.f, 0.f};
;                     if (elast) dn = (f32x4){0.f, 0.f, 0.f, 0.f};
;                     gc[n] = w0[n] * up + w1[n] * g + w2[n] * dn + bb[n];
;                 }
;                 if (efirst || elast) {
;                     const size_t eo = (size_t)((row >> 6) * 2 + (elast ? 1 : 0)) * DFF + ch0;
; #pragma unroll
;                     for (int n = 0; n < 2; ++n) { *(f32x4*)(EP + eo + 4 * n) = gc[n]; *(f32x4*)(ER + eo + 4 * n) = acc[ai][0][m][n]; *(f32x4*)(EV + eo + 4 * n) = acc[ai][1][m][n]; }
;                 } else {
;                     const f32x4 v0 = acc[ai][1][m][0], v1 = acc[ai][1][m][1];
;                     u32x4 o;
;                     o[0] = pack2(silu_mul(gc[0][0], v0[0]), silu_mul(gc[0][1], v0[1])); o[1] = pack2(silu_mul(gc[0][2], v0[2]), silu_mul(gc[0][3], v0[3]));
	s_waitcnt lgkmcnt(0)
	s_lshl_b32 s21, s45, 7
	v_mov_b32_e32 v194, v186
	v_mov_b32_e32 v80, v187
	s_or_b32 s21, s21, s62
	v_mov_b32_e32 v160, 0
	v_lshl_add_u32 v184, v80, 3, s21
	v_ashrrev_i32_e32 v185, 31, v184
	v_lshlrev_b64 v[80:81], 2, v[184:185]
	v_lshl_add_u64 v[84:85], s[4:5], 0, v[80:81]
	v_lshl_add_u64 v[88:89], s[16:17], 0, v[80:81]
	v_lshl_add_u64 v[92:93], s[18:19], 0, v[80:81]
	v_lshl_add_u64 v[112:113], s[6:7], 0, v[80:81]
	global_load_dwordx4 v[80:83], v[84:85], off offset:16
	global_load_dwordx4 v[96:99], v[84:85], off
	s_nop 0
	global_load_dwordx4 v[84:87], v[88:89], off offset:16
	global_load_dwordx4 v[100:103], v[88:89], off
	s_nop 0
	global_load_dwordx4 v[88:91], v[92:93], off offset:16
	global_load_dwordx4 v[108:111], v[92:93], off
	s_nop 0
	global_load_dwordx4 v[92:95], v[112:113], off offset:16
	s_nop 0
	global_load_dwordx4 v[112:115], v[112:113], off
	v_cmp_eq_u32_e32 vcc, 0, v194
	v_mov_b32_e32 v164, 0
	v_mov_b32_e32 v195, 0
	v_cndmask_b32_e32 v161, v148, v136, vcc
	v_cndmask_b32_e32 v162, v149, v137, vcc
	v_cndmask_b32_e32 v163, v150, v138, vcc
	v_mov_b32_dpp v160, v161 row_ror:15 row_mask:0xf bank_mask:0xf
	v_mov_b32_e32 v161, 0
	v_mov_b32_e32 v166, 0
	v_mov_b32_e32 v167, 0
	v_mov_b32_dpp v161, v162 row_ror:15 row_mask:0xf bank_mask:0xf
	v_mov_b32_e32 v162, 0
	v_mov_b32_dpp v164, v150 row_ror:1 row_mask:0xf bank_mask:0xf
	v_cndmask_b32_e32 v165, v151, v139, vcc
	v_mov_b32_dpp v162, v163 row_ror:15 row_mask:0xf bank_mask:0xf
	v_mov_b32_dpp v195, v151 row_ror:1 row_mask:0xf bank_mask:0xf
	v_mov_b32_e32 v163, 0
	v_mov_b32_dpp v166, v148 row_ror:1 row_mask:0xf bank_mask:0xf
	v_mov_b32_dpp v167, v149 row_ror:1 row_mask:0xf bank_mask:0xf
	v_mov_b32_dpp v163, v165 row_ror:15 row_mask:0xf bank_mask:0xf
	v_cndmask_b32_e64 v165, v195, 0, vcc
	v_cndmask_b32_e64 v164, v164, 0, vcc
	v_cndmask_b32_e64 v167, v167, 0, vcc
	v_cndmask_b32_e64 v166, v166, 0, vcc
	v_mov_b32_e32 v195, 0
	v_mov_b32_e32 v196, 0
	v_mov_b32_e32 v198, 0
	v_mov_b32_e32 v200, 0
	v_mov_b32_dpp v195, v144 row_ror:1 row_mask:0xf bank_mask:0xf
	v_mov_b32_dpp v196, v145 row_ror:1 row_mask:0xf bank_mask:0xf
	v_mov_b32_dpp v198, v146 row_ror:1 row_mask:0xf bank_mask:0xf
	v_cndmask_b32_e32 v199, v147, v131, vcc
	v_mov_b32_dpp v200, v147 row_ror:1 row_mask:0xf bank_mask:0xf
	v_cndmask_b32_e64 v198, v198, 0, vcc
	v_cndmask_b32_e64 v201, v196, 0, vcc
	s_lshl_b32 s3, s44, 8
	s_add_i32 s3, s3, s49
	v_add_u32_e32 v193, s3, v194
	v_cmp_ne_u32_e64 s[46:47], 0, v194
	s_waitcnt vmcnt(0)
	v_pk_mul_f32 v[164:165], v[98:99], v[164:165]
	v_pk_mul_f32 v[166:167], v[96:97], v[166:167]
	v_pk_fma_f32 v[164:165], v[150:151], v[102:103], v[164:165]
	v_pk_fma_f32 v[166:167], v[148:149], v[100:101], v[166:167]
	v_pk_fma_f32 v[162:163], v[110:111], v[162:163], v[164:165]
	v_cndmask_b32_e32 v165, v144, v128, vcc
	v_mov_b32_e32 v164, 0
	v_pk_fma_f32 v[160:161], v[108:109], v[160:161], v[166:167]
	v_cndmask_b32_e32 v166, v145, v129, vcc
	v_mov_b32_dpp v164, v165 row_ror:15 row_mask:0xf bank_mask:0xf
	v_mov_b32_e32 v165, 0
	v_cndmask_b32_e32 v167, v146, v130, vcc
	v_pk_add_f32 v[162:163], v[114:115], v[162:163]
	v_mov_b32_dpp v165, v166 row_ror:15 row_mask:0xf bank_mask:0xf
	v_mov_b32_e32 v166, 0
	v_pk_add_f32 v[160:161], v[112:113], v[160:161]
	s_nop 0
	v_mov_b32_dpp v166, v167 row_ror:15 row_mask:0xf bank_mask:0xf
	v_mov_b32_e32 v167, 0
	s_nop 1
	v_mov_b32_dpp v167, v199 row_ror:15 row_mask:0xf bank_mask:0xf
	v_cndmask_b32_e64 v199, v200, 0, vcc
	v_cndmask_b32_e64 v200, v195, 0, vcc
	v_pk_mul_f32 v[200:201], v[80:81], v[200:201]
	v_pk_mul_f32 v[198:199], v[82:83], v[198:199]
	v_pk_fma_f32 v[200:201], v[144:145], v[84:85], v[200:201]
	v_pk_fma_f32 v[198:199], v[146:147], v[86:87], v[198:199]
	v_pk_fma_f32 v[164:165], v[88:89], v[164:165], v[200:201]
	v_pk_fma_f32 v[166:167], v[90:91], v[166:167], v[198:199]
	v_pk_add_f32 v[164:165], v[92:93], v[164:165]
	v_pk_add_f32 v[166:167], v[94:95], v[166:167]
	s_and_saveexec_b64 s[28:29], s[46:47]
	s_xor_b64 s[28:29], exec, s[28:29]
	s_cbranch_execz .LBB1_1911
	v_mul_f32_e32 v195, 0xbfb8aa3b, v160
	v_exp_f32_e32 v195, v195
	v_mul_f32_e32 v196, 0xbfb8aa3b, v161
	v_exp_f32_e32 v196, v196
	v_pk_mul_f32 v[160:161], v[156:157], v[160:161]
	v_add_f32_e32 v195, 1.0, v195
	v_rcp_f32_e32 v198, v195
	v_add_f32_e32 v196, 1.0, v196
	v_mul_f32_e32 v195, 0xbfb8aa3b, v162
	v_rcp_f32_e32 v199, v196
	v_exp_f32_e32 v195, v195
	v_mul_f32_e32 v196, 0xbfb8aa3b, v163
	v_exp_f32_e32 v196, v196
	v_pk_mul_f32 v[160:161], v[160:161], v[198:199]
	v_add_f32_e32 v195, 1.0, v195
	v_rcp_f32_e32 v200, v195
	v_add_f32_e32 v195, 1.0, v196
	v_rcp_f32_e32 v201, v195
	v_cvt_pk_bf16_f32 v160, v160, v161
	v_mul_f32_e32 v161, 0xbfb8aa3b, v164
	v_exp_f32_e32 v195, v161
	v_mul_f32_e32 v161, 0xbfb8aa3b, v165
	v_exp_f32_e32 v196, v161
	v_pk_mul_f32 v[162:163], v[158:159], v[162:163]
	v_pk_mul_f32 v[164:165], v[152:153], v[164:165]
	v_pk_mul_f32 v[162:163], v[162:163], v[200:201]
	s_nop 0
	v_cvt_pk_bf16_f32 v161, v162, v163
	v_add_f32_e32 v162, 1.0, v195
	v_mul_f32_e32 v195, 0xbfb8aa3b, v166
	v_add_f32_e32 v163, 1.0, v196
	v_exp_f32_e32 v195, v195
	v_mul_f32_e32 v196, 0xbfb8aa3b, v167
	v_exp_f32_e32 v196, v196
	v_rcp_f32_e32 v162, v162
	v_add_f32_e32 v195, 1.0, v195
	v_rcp_f32_e32 v198, v195
	v_add_f32_e32 v195, 1.0, v196
	v_rcp_f32_e32 v163, v163
	v_rcp_f32_e32 v199, v195
	v_pk_mul_f32 v[166:167], v[154:155], v[166:167]
	v_pk_mul_f32 v[162:163], v[164:165], v[162:163]
	v_pk_mul_f32 v[164:165], v[166:167], v[198:199]
	v_cvt_pk_bf16_f32 v162, v162, v163
	v_cvt_pk_bf16_f32 v163, v164, v165
	v_mov_b64_e32 v[164:165], s[52:53]
	v_mad_i64_i32 v[164:165], s[42:43], v193, s60, v[164:165]
	v_lshl_add_u64 v[164:165], v[184:185], 1, v[164:165]
	global_store_dwordx4 v[164:165], v[160:163], off

; #define PG8_STAGE(bufoff, gbase, voff) do { _Pragma("unroll") for (int _i = 0; _i < 2; ++_i) \
;         __builtin_amdgcn_global_load_lds((const unsigned*)((const char*)(gbase) + (voff)[_i]), (LAS unsigned*)(lds + (bufoff) + ldsw + _i * 8192), 16, 0, 0); } while (0)
; #define PG8_LDA(dst, b, h) do { _Pragma("unroll") for (int m = 0; m < 4; ++m) _Pragma("unroll") for (int k = 0; k < 2; ++k) dst[m][k] = *(const LAS bf16x8*)(lds + PG8_SA(b, h) + aoff + m * 2048 + k * 1024); } while (0)
; #define PG8_LDB(dst, b, h) do { _Pragma("unroll") for (int n = 0; n < 2; ++n) _Pragma("unroll") for (int k = 0; k < 2; ++k) dst[n][k] = *(const LAS bf16x8*)(lds + PG8_SB(b, h) + boff + n * 2048 + k * 1024); } while (0)
; #define PG8_MMA(ai, bj, At, Bt) do { __builtin_amdgcn_s_setprio(1); _Pragma("unroll") for (int m = 0; m < 4; ++m) _Pragma("unroll") for (int n = 0; n < 2; ++n) _Pragma("unroll") for (int k = 0; k < 2; ++k) \
;         acc[ai][bj][m][n] = __builtin_amdgcn_mfma_f32_16x16x32_bf16(Bt[n][k], At[m][k], acc[ai][bj][m][n], 0, 0, 0); __builtin_amdgcn_s_setprio(0); } while (0)
; #define PG8_WAIT_L(n) asm volatile("s_waitcnt lgkmcnt(" #n ")" ::: "memory")
; #define PG8_BAR __builtin_amdgcn_s_barrier()
; #define PG8_SCHED __builtin_amdgcn_sched_barrier(0)
; template <class Map, class Epi>
; DI void gemm_phase(LAS unsigned char* lds, const Map& MP, const Epi& E, const int nM, const int nN, const int K, const int lda, const int ldb) {
;     ...
;             PG8_LDB(B0, 0, 0); PG8_SCHED; PG8_LDA(At, 0, 0); PG8_STAGE(PG8_SA(1, 1), a1 + hstepA, voffA);
;             PG8_WAIT_L(8); PG8_BAR; PG8_WAIT_L(0); PG8_MMA(0, 0, At, B0); PG8_BAR; PG8_SCHED;
;             PG8_LDB(B1, 0, 1); PG8_STAGE(PG8_SB(0, 0), b2, voffB);
;             PG8_BAR; PG8_WAIT_L(0); PG8_MMA(0, 1, At, B1); PG8_BAR;
;             PG8_LDA(At, 0, 1); PG8_STAGE(PG8_SA(0, 0), a2, voffA);
;             PG8_BAR; PG8_WAIT_L(0); PG8_MMA(1, 0, At, B0); PG8_BAR; PG8_SCHED;
.LBB1_2078:
	ds_read_b128 v[168:171], v150
	ds_read_b128 v[172:175], v150 offset:1024
	ds_read_b128 v[176:179], v150 offset:2048
	ds_read_b128 v[180:183], v150 offset:3072
	ds_read_b128 v[184:187], v150 offset:4096
	ds_read_b128 v[188:191], v150 offset:5120
	ds_read_b128 v[192:195], v150 offset:6144
	ds_read_b128 v[198:201], v150 offset:7168
	s_add_u32 s10, s8, 0x100
	s_addc_u32 s11, s9, 0
	s_cmpk_eq_i32 s3, 0x54
	s_cselect_b32 s15, s43, s11
	s_cselect_b32 s14, s42, s10
	s_cselect_b32 s13, s7, s44
	s_cselect_b32 s12, s6, s39
	s_add_i32 m0, s24, 0xc000
	s_nop 0
	global_load_lds_dwordx4 v138, s[8:9]
	s_add_i32 m0, s24, 0xe000
	s_nop 0
	global_load_lds_dwordx4 v136, s[8:9]
	s_waitcnt lgkmcnt(8)
	s_barrier
	s_setprio 1
	s_waitcnt lgkmcnt(7)
	v_mfma_f32_16x16x32_bf16 v[124:127], v[152:155], v[168:171], v[124:127]
	v_mfma_f32_16x16x32_bf16 v[120:123], v[160:163], v[168:171], v[120:123]
	s_waitcnt lgkmcnt(5)
	v_mfma_f32_16x16x32_bf16 v[108:111], v[152:155], v[176:179], v[108:111]
	v_mfma_f32_16x16x32_bf16 v[104:107], v[160:163], v[176:179], v[104:107]
	s_waitcnt lgkmcnt(3)
	v_mfma_f32_16x16x32_bf16 v[92:95], v[152:155], v[184:187], v[92:95]
	v_mfma_f32_16x16x32_bf16 v[88:91], v[160:163], v[184:187], v[88:91]
	s_waitcnt lgkmcnt(1)
	v_mfma_f32_16x16x32_bf16 v[76:79], v[152:155], v[192:195], v[76:79]
	v_mfma_f32_16x16x32_bf16 v[72:75], v[160:163], v[192:195], v[72:75]
	v_mfma_f32_16x16x32_bf16 v[124:127], v[156:159], v[172:175], v[124:127]
	v_mfma_f32_16x16x32_bf16 v[120:123], v[164:167], v[172:175], v[120:123]
	v_mfma_f32_16x16x32_bf16 v[108:111], v[156:159], v[180:183], v[108:111]
	v_mfma_f32_16x16x32_bf16 v[104:107], v[164:167], v[180:183], v[104:107]
	v_mfma_f32_16x16x32_bf16 v[92:95], v[156:159], v[188:191], v[92:95]
	v_mfma_f32_16x16x32_bf16 v[88:91], v[164:167], v[188:191], v[88:91]
	s_waitcnt lgkmcnt(0)
	v_mfma_f32_16x16x32_bf16 v[76:79], v[156:159], v[198:201], v[76:79]
	v_mfma_f32_16x16x32_bf16 v[72:75], v[164:167], v[198:201], v[72:75]
	s_setprio 0
	s_barrier
	ds_read_b128 v[202:205], v151
	ds_read_b128 v[206:209], v151 offset:1024
	ds_read_b128 v[210:213], v151 offset:2048
	ds_read_b128 v[214:217], v151 offset:3072
	s_add_i32 s8, s35, s22
	v_lshl_add_u64 v[144:145], s[12:13], 0, v[132:133]
	s_mov_b32 m0, s8
	s_nop 0
	global_load_lds_dwordx4 v[144:145], off
	v_lshl_add_u64 v[218:219], s[12:13], 0, v[128:129]
	s_add_i32 m0, s8, 0x2000
	s_nop 0
	global_load_lds_dwordx4 v[218:219], off
	s_barrier
	s_setprio 1
	s_waitcnt lgkmcnt(3)
	v_mfma_f32_16x16x32_bf16 v[116:119], v[202:205], v[168:171], v[116:119]
	s_waitcnt lgkmcnt(1)
	v_mfma_f32_16x16x32_bf16 v[112:115], v[210:213], v[168:171], v[112:115]
	v_mfma_f32_16x16x32_bf16 v[100:103], v[202:205], v[176:179], v[100:103]
	v_mfma_f32_16x16x32_bf16 v[96:99], v[210:213], v[176:179], v[96:99]
	v_mfma_f32_16x16x32_bf16 v[84:87], v[202:205], v[184:187], v[84:87]
	v_mfma_f32_16x16x32_bf16 v[80:83], v[210:213], v[184:187], v[80:83]
	v_mfma_f32_16x16x32_bf16 v[68:71], v[202:205], v[192:195], v[68:71]
	v_mfma_f32_16x16x32_bf16 v[64:67], v[210:213], v[192:195], v[64:67]
	v_mfma_f32_16x16x32_bf16 v[116:119], v[206:209], v[172:175], v[116:119]
	s_mov_b32 m0, s24
	s_waitcnt lgkmcnt(0)
	v_mfma_f32_16x16x32_bf16 v[112:115], v[214:217], v[172:175], v[112:115]
	v_lshl_add_u64 v[220:221], s[14:15], 0, v[134:135]
	v_mfma_f32_16x16x32_bf16 v[100:103], v[206:209], v[180:183], v[100:103]
	v_mfma_f32_16x16x32_bf16 v[96:99], v[214:217], v[180:183], v[96:99]
	v_mfma_f32_16x16x32_bf16 v[84:87], v[206:209], v[188:191], v[84:87]
	v_mfma_f32_16x16x32_bf16 v[80:83], v[214:217], v[188:191], v[80:83]
	v_mfma_f32_16x16x32_bf16 v[68:71], v[206:209], v[198:201], v[68:71]
	v_mfma_f32_16x16x32_bf16 v[64:67], v[214:217], v[198:201], v[64:67]
	s_setprio 0
	s_barrier
	ds_read_b128 v[168:171], v150 offset:16384
	ds_read_b128 v[172:175], v150 offset:17408
	ds_read_b128 v[176:179], v150 offset:18432
	ds_read_b128 v[180:183], v150 offset:19456
	ds_read_b128 v[184:187], v150 offset:20480
	ds_read_b128 v[188:191], v150 offset:21504
	ds_read_b128 v[192:195], v150 offset:22528
	ds_read_b128 v[198:201], v150 offset:23552
	global_load_lds_dwordx4 v[220:221], off
	v_lshl_add_u64 v[222:223], s[14:15], 0, v[130:131]
	s_mov_b32 m0, s25
	s_nop 0
	global_load_lds_dwordx4 v[222:223], off
	s_waitcnt vmcnt(10)
	s_barrier
	s_setprio 1
	s_waitcnt lgkmcnt(7)
	v_mfma_f32_16x16x32_bf16 v[60:63], v[152:155], v[168:171], v[60:63]
	v_mfma_f32_16x16x32_bf16 v[56:59], v[160:163], v[168:171], v[56:59]
	s_waitcnt lgkmcnt(5)
	v_mfma_f32_16x16x32_bf16 v[44:47], v[152:155], v[176:179], v[44:47]
	v_mfma_f32_16x16x32_bf16 v[40:43], v[160:163], v[176:179], v[40:43]
	s_waitcnt lgkmcnt(3)
	v_mfma_f32_16x16x32_bf16 v[28:31], v[152:155], v[184:187], v[28:31]
	v_mfma_f32_16x16x32_bf16 v[24:27], v[160:163], v[184:187], v[24:27]
	s_waitcnt lgkmcnt(1)
	v_mfma_f32_16x16x32_bf16 v[12:15], v[152:155], v[192:195], v[12:15]
	v_mfma_f32_16x16x32_bf16 v[8:11], v[160:163], v[192:195], v[8:11]
	v_mfma_f32_16x16x32_bf16 v[60:63], v[156:159], v[172:175], v[60:63]
	v_mfma_f32_16x16x32_bf16 v[56:59], v[164:167], v[172:175], v[56:59]
	v_mfma_f32_16x16x32_bf16 v[44:47], v[156:159], v[180:183], v[44:47]
	v_mfma_f32_16x16x32_bf16 v[40:43], v[164:167], v[180:183], v[40:43]
	v_mfma_f32_16x16x32_bf16 v[28:31], v[156:159], v[188:191], v[28:31]
	v_mfma_f32_16x16x32_bf16 v[24:27], v[164:167], v[188:191], v[24:27]
	s_waitcnt lgkmcnt(0)
	v_mfma_f32_16x16x32_bf16 v[12:15], v[156:159], v[198:201], v[12:15]
	v_mfma_f32_16x16x32_bf16 v[8:11], v[164:167], v[198:201], v[8:11]
	s_setprio 0
	s_barrier
; #define PG8_STAGE(bufoff, gbase, voff) do { _Pragma("unroll") for (int _i = 0; _i < 2; ++_i) \
;         __builtin_amdgcn_global_load_lds((const unsigned*)((const char*)(gbase) + (voff)[_i]), (LAS unsigned*)(lds + (bufoff) + ldsw + _i * 8192), 16, 0, 0); } while (0)
; #define PG8_LDA(dst, b, h) do { _Pragma("unroll") for (int m = 0; m < 4; ++m) _Pragma("unroll") for (int k = 0; k < 2; ++k) dst[m][k] = *(const LAS bf16x8*)(lds + PG8_SA(b, h) + aoff + m * 2048 + k * 1024); } while (0)
; #define PG8_LDB(dst, b, h) do { _Pragma("unroll") for (int n = 0; n < 2; ++n) _Pragma("unroll") for (int k = 0; k < 2; ++k) dst[n][k] = *(const LAS bf16x8*)(lds + PG8_SB(b, h) + boff + n * 2048 + k * 1024); } while (0)
; #define PG8_MMA(ai, bj, At, Bt) do { __builtin_amdgcn_s_setprio(1); _Pragma("unroll") for (int m = 0; m < 4; ++m) _Pragma("unroll") for (int n = 0; n < 2; ++n) _Pragma("unroll") for (int k = 0; k < 2; ++k) \
;         acc[ai][bj][m][n] = __builtin_amdgcn_mfma_f32_16x16x32_bf16(Bt[n][k], At[m][k], acc[ai][bj][m][n], 0, 0, 0); __builtin_amdgcn_s_setprio(0); } while (0)
; #define PG8_WAIT_V(n) asm volatile("s_waitcnt vmcnt(" #n ")" ::: "memory")
; #define PG8_WAIT_L(n) asm volatile("s_waitcnt lgkmcnt(" #n ")" ::: "memory")
; #define PG8_BAR __builtin_amdgcn_s_barrier()
; #define PG8_SCHED __builtin_amdgcn_sched_barrier(0)
; template <class Map, class Epi>
; DI void gemm_phase(LAS unsigned char* lds, const Map& MP, const Epi& E, const int nM, const int nN, const int K, const int lda, const int ldb) {
;     ...
;             PG8_STAGE(PG8_SB(0, 1), b2 + hstepB, voffB);
;             PG8_WAIT_V(6); PG8_BAR; PG8_MMA(1, 1, At, B1); PG8_BAR;
;             PG8_LDB(B0, 1, 0); PG8_SCHED; PG8_LDA(At, 1, 0); PG8_STAGE(PG8_SA(0, 1), a2 + hstepA, voffA);
;             PG8_WAIT_L(8); PG8_BAR; PG8_WAIT_L(0); PG8_MMA(0, 0, At, B0); PG8_BAR; PG8_SCHED;
;             PG8_LDB(B1, 1, 1); PG8_STAGE(PG8_SB(1, 0), b3, voffB);
;             PG8_BAR; PG8_WAIT_L(0); PG8_MMA(0, 1, At, B1); PG8_BAR;
;             PG8_LDA(At, 1, 1); PG8_STAGE(PG8_SA(1, 0), a3, voffA);
;             PG8_BAR; PG8_WAIT_L(0); PG8_MMA(1, 0, At, B0); PG8_BAR; PG8_SCHED;
	s_add_u32 s8, s12, 0x160000
	s_addc_u32 s9, s13, 0
	s_add_i32 s45, s36, s22
	s_mov_b32 m0, s45
	s_nop 0
	global_load_lds_dwordx4 v132, s[8:9]
	s_add_i32 m0, s45, 0x2000
	s_nop 0
	global_load_lds_dwordx4 v128, s[8:9]
	s_waitcnt vmcnt(6)
	s_barrier
	s_setprio 1
	v_mfma_f32_16x16x32_bf16 v[52:55], v[202:205], v[168:171], v[52:55]
	v_mfma_f32_16x16x32_bf16 v[48:51], v[210:213], v[168:171], v[48:51]
	s_add_i32 s45, 0, 0x18000
	v_add_u32_e32 v164, s45, v148
	ds_read_b128 v[152:155], v164
	v_mfma_f32_16x16x32_bf16 v[36:39], v[202:205], v[176:179], v[36:39]
	v_mfma_f32_16x16x32_bf16 v[32:35], v[210:213], v[176:179], v[32:35]
	ds_read_b128 v[156:159], v164 offset:1024
	v_mfma_f32_16x16x32_bf16 v[20:23], v[202:205], v[184:187], v[20:23]
	v_mfma_f32_16x16x32_bf16 v[16:19], v[210:213], v[184:187], v[16:19]
	ds_read_b128 v[160:163], v164 offset:2048
	v_mfma_f32_16x16x32_bf16 v[4:7], v[202:205], v[192:195], v[4:7]
	v_mfma_f32_16x16x32_bf16 v[0:3], v[210:213], v[192:195], v[0:3]
	ds_read_b128 v[164:167], v164 offset:3072
	v_mfma_f32_16x16x32_bf16 v[52:55], v[206:209], v[172:175], v[52:55]
	v_mfma_f32_16x16x32_bf16 v[48:51], v[214:217], v[172:175], v[48:51]
	v_mfma_f32_16x16x32_bf16 v[36:39], v[206:209], v[180:183], v[36:39]
	v_mfma_f32_16x16x32_bf16 v[32:35], v[214:217], v[180:183], v[32:35]
	v_mfma_f32_16x16x32_bf16 v[20:23], v[206:209], v[188:191], v[20:23]
	v_mfma_f32_16x16x32_bf16 v[16:19], v[214:217], v[188:191], v[16:19]
	v_mfma_f32_16x16x32_bf16 v[4:7], v[206:209], v[198:201], v[4:7]
	v_mfma_f32_16x16x32_bf16 v[0:3], v[214:217], v[198:201], v[0:3]
	s_setprio 0
	s_barrier
	ds_read_b128 v[168:171], v150 offset:32768
	ds_read_b128 v[172:175], v150 offset:33792
	ds_read_b128 v[176:179], v150 offset:34816
	ds_read_b128 v[180:183], v150 offset:35840
	ds_read_b128 v[184:187], v150 offset:36864
	ds_read_b128 v[188:191], v150 offset:37888
	ds_read_b128 v[192:195], v150 offset:38912
	ds_read_b128 v[198:201], v150 offset:39936
	s_add_u32 s8, s14, 0x160000
	s_addc_u32 s9, s15, 0
	s_mov_b32 m0, s26
	s_nop 0
	global_load_lds_dwordx4 v134, s[8:9]
	s_mov_b32 m0, s27
	s_nop 0
	global_load_lds_dwordx4 v130, s[8:9]
	s_waitcnt lgkmcnt(8)
	s_barrier
	s_setprio 1
	s_waitcnt lgkmcnt(7)
	v_mfma_f32_16x16x32_bf16 v[124:127], v[152:155], v[168:171], v[124:127]
	v_mfma_f32_16x16x32_bf16 v[120:123], v[160:163], v[168:171], v[120:123]
	s_waitcnt lgkmcnt(5)
	v_mfma_f32_16x16x32_bf16 v[108:111], v[152:155], v[176:179], v[108:111]
	v_mfma_f32_16x16x32_bf16 v[104:107], v[160:163], v[176:179], v[104:107]
	s_waitcnt lgkmcnt(3)
	v_mfma_f32_16x16x32_bf16 v[92:95], v[152:155], v[184:187], v[92:95]
	v_mfma_f32_16x16x32_bf16 v[88:91], v[160:163], v[184:187], v[88:91]
	s_waitcnt lgkmcnt(1)
	v_mfma_f32_16x16x32_bf16 v[76:79], v[152:155], v[192:195], v[76:79]
	v_mfma_f32_16x16x32_bf16 v[72:75], v[160:163], v[192:195], v[72:75]
	v_mfma_f32_16x16x32_bf16 v[124:127], v[156:159], v[172:175], v[124:127]
	v_mfma_f32_16x16x32_bf16 v[120:123], v[164:167], v[172:175], v[120:123]
	v_mfma_f32_16x16x32_bf16 v[108:111], v[156:159], v[180:183], v[108:111]
	v_mfma_f32_16x16x32_bf16 v[104:107], v[164:167], v[180:183], v[104:107]
	v_mfma_f32_16x16x32_bf16 v[92:95], v[156:159], v[188:191], v[92:95]
	v_mfma_f32_16x16x32_bf16 v[88:91], v[164:167], v[188:191], v[88:91]
	s_waitcnt lgkmcnt(0)
	v_mfma_f32_16x16x32_bf16 v[76:79], v[156:159], v[198:201], v[76:79]
	v_mfma_f32_16x16x32_bf16 v[72:75], v[164:167], v[198:201], v[72:75]
	s_setprio 0
	s_barrier
	s_add_i32 s14, 0, 0x1c000
	v_add_u32_e32 v196, s14, v148
	ds_read_b128 v[202:205], v196
	ds_read_b128 v[206:209], v196 offset:1024
	ds_read_b128 v[210:213], v196 offset:2048
	ds_read_b128 v[214:217], v196 offset:3072
	s_add_i32 s8, s45, s22
	v_lshl_add_u64 v[144:145], v[144:145], 0, s[46:47]
	s_mov_b32 m0, s8
	s_nop 0
	global_load_lds_dwordx4 v[144:145], off
	v_lshl_add_u64 v[144:145], v[218:219], 0, s[46:47]
	s_add_i32 m0, s8, 0x2000
	s_nop 0
	global_load_lds_dwordx4 v[144:145], off
	s_barrier
	s_setprio 1
	s_waitcnt lgkmcnt(3)
	v_mfma_f32_16x16x32_bf16 v[116:119], v[202:205], v[168:171], v[116:119]
	s_waitcnt lgkmcnt(1)
	v_mfma_f32_16x16x32_bf16 v[112:115], v[210:213], v[168:171], v[112:115]
	v_mfma_f32_16x16x32_bf16 v[100:103], v[202:205], v[176:179], v[100:103]
	v_mfma_f32_16x16x32_bf16 v[96:99], v[210:213], v[176:179], v[96:99]
	v_mfma_f32_16x16x32_bf16 v[84:87], v[202:205], v[184:187], v[84:87]
	v_mfma_f32_16x16x32_bf16 v[80:83], v[210:213], v[184:187], v[80:83]
	v_mfma_f32_16x16x32_bf16 v[68:71], v[202:205], v[192:195], v[68:71]
	v_mfma_f32_16x16x32_bf16 v[64:67], v[210:213], v[192:195], v[64:67]
	v_mfma_f32_16x16x32_bf16 v[116:119], v[206:209], v[172:175], v[116:119]
	s_mov_b32 m0, s30
	s_waitcnt lgkmcnt(0)
	v_mfma_f32_16x16x32_bf16 v[112:115], v[214:217], v[172:175], v[112:115]
	v_lshl_add_u64 v[144:145], v[220:221], 0, s[46:47]
	v_mfma_f32_16x16x32_bf16 v[100:103], v[206:209], v[180:183], v[100:103]
	v_mfma_f32_16x16x32_bf16 v[96:99], v[214:217], v[180:183], v[96:99]
	v_mfma_f32_16x16x32_bf16 v[84:87], v[206:209], v[188:191], v[84:87]
	v_mfma_f32_16x16x32_bf16 v[80:83], v[214:217], v[188:191], v[80:83]
	v_mfma_f32_16x16x32_bf16 v[68:71], v[206:209], v[198:201], v[68:71]
	v_mfma_f32_16x16x32_bf16 v[64:67], v[214:217], v[198:201], v[64:67]
	s_setprio 0
	s_barrier
	ds_read_b128 v[168:171], v150 offset:49152
	ds_read_b128 v[172:175], v150 offset:50176
	ds_read_b128 v[176:179], v150 offset:51200
	ds_read_b128 v[180:183], v150 offset:52224
	ds_read_b128 v[184:187], v150 offset:53248
	ds_read_b128 v[188:191], v150 offset:54272
	ds_read_b128 v[192:195], v150 offset:55296
	ds_read_b128 v[198:201], v150 offset:56320
	global_load_lds_dwordx4 v[144:145], off
	v_lshl_add_u64 v[144:145], v[222:223], 0, s[46:47]
	s_mov_b32 m0, s31
	s_nop 0
	global_load_lds_dwordx4 v[144:145], off
	s_waitcnt vmcnt(10)
	s_barrier
; DI unsigned pack2(float a, float b) { f32x2 v = {a, b}; hwbf16x2 r = __builtin_convertvector(v, hwbf16x2); return __builtin_bit_cast(unsigned, r); }
; DI float bflo(unsigned w) { return __uint_as_float(w << 16); }
; DI float bfhi(unsigned w) { return __uint_as_float(w & 0xffff0000u); }
; #define PG8_WAIT_V(n) asm volatile("s_waitcnt vmcnt(" #n ")" ::: "memory")
;     DI void operator()(const f32x4 (&acc)[2][2][4][2], const Unit& u, int wr, int wc, int fr, int fq) const {
;         const int row0 = u.pm * BM + wr * 64 + fr, col0 = u.pn * BM + wc * 32 + 8 * fq;
;         f32x4 sc[2][2];
; #pragma unroll
;         for (int bj = 0; bj < 2; ++bj)
; #pragma unroll
;             for (int n = 0; n < 2; ++n) sc[bj][n] = scale ? *(const f32x4*)(scale + col0 + bj * HALF + 4 * n) : (f32x4){1.f, 1.f, 1.f, 1.f};
; #pragma unroll
;         for (int ai = 0; ai < 2; ++ai)
; #pragma unroll
;             for (int m = 0; m < 4; ++m) { const size_t ro = (size_t)(row0 + ai * HALF + m * 16) * D + col0;
; #pragma unroll
;                 for (int bj = 0; bj < 2; ++bj) {
;                     f32x4 x0, x1;
;                     if constexpr (IB) { const u32x4 w = *(const u32x4*)((const bf16_t*)Xin + ro + bj * HALF);
;                         x0 = (f32x4){bflo(w[0]), bfhi(w[0]), bflo(w[1]), bfhi(w[1])}; x1 = (f32x4){bflo(w[2]), bfhi(w[2]), bflo(w[3]), bfhi(w[3])}; }
;                     else { x0 = *(const f32x4*)((const float*)Xin + ro + bj * HALF); x1 = *(const f32x4*)((const float*)Xin + ro + bj * HALF + 4); }
;                     x0 += acc[ai][bj][m][0] * sc[bj][0]; x1 += acc[ai][bj][m][1] * sc[bj][1];
;                     if constexpr (OB) { u32x4 o; o[0] = pack2(x0[0], x0[1]); o[1] = pack2(x0[2], x0[3]); o[2] = pack2(x1[0], x1[1]); o[3] = pack2(x1[2], x1[3]);
;                         *(u32x4*)((bf16_t*)Xout + ro + bj * HALF) = o; }
;                     else { *(f32x4*)((float*)Xout + ro + bj * HALF) = x0; *(f32x4*)((float*)Xout + ro + bj * HALF + 4) = x1; } } }
; template <class Map, class Epi>
; DI void gemm_phase(LAS unsigned char* lds, const Map& MP, const Epi& E, const int nM, const int nN, const int K, const int lda, const int ldb) {
;     ...
;             PG8_BAR; PG8_WAIT_L(0); PG8_MMA(1, 0, At, B0); PG8_BAR; PG8_SCHED;
;             PG8_STAGE(PG8_SB(1, 1), b3 + hstepB, voffB);
;             PG8_WAIT_V(6); PG8_BAR; PG8_MMA(1, 1, At, B1); PG8_BAR;
	s_setprio 1
	s_waitcnt lgkmcnt(7)
	v_mfma_f32_16x16x32_bf16 v[60:63], v[152:155], v[168:171], v[60:63]
	v_mfma_f32_16x16x32_bf16 v[56:59], v[160:163], v[168:171], v[56:59]
	s_waitcnt lgkmcnt(5)
	v_mfma_f32_16x16x32_bf16 v[44:47], v[152:155], v[176:179], v[44:47]
	v_mfma_f32_16x16x32_bf16 v[40:43], v[160:163], v[176:179], v[40:43]
	s_waitcnt lgkmcnt(3)
	v_mfma_f32_16x16x32_bf16 v[28:31], v[152:155], v[184:187], v[28:31]
	v_mfma_f32_16x16x32_bf16 v[24:27], v[160:163], v[184:187], v[24:27]
	s_waitcnt lgkmcnt(1)
	v_mfma_f32_16x16x32_bf16 v[12:15], v[152:155], v[192:195], v[12:15]
	v_mfma_f32_16x16x32_bf16 v[8:11], v[160:163], v[192:195], v[8:11]
	v_mfma_f32_16x16x32_bf16 v[60:63], v[156:159], v[172:175], v[60:63]
	v_mfma_f32_16x16x32_bf16 v[56:59], v[164:167], v[172:175], v[56:59]
	v_mfma_f32_16x16x32_bf16 v[44:47], v[156:159], v[180:183], v[44:47]
	v_mfma_f32_16x16x32_bf16 v[40:43], v[164:167], v[180:183], v[40:43]
	v_mfma_f32_16x16x32_bf16 v[28:31], v[156:159], v[188:191], v[28:31]
	v_mfma_f32_16x16x32_bf16 v[24:27], v[164:167], v[188:191], v[24:27]
	s_waitcnt lgkmcnt(0)
	v_mfma_f32_16x16x32_bf16 v[12:15], v[156:159], v[198:201], v[12:15]
	v_mfma_f32_16x16x32_bf16 v[8:11], v[164:167], v[198:201], v[8:11]
	s_setprio 0
	s_barrier
	s_add_u32 s8, s12, 0x160080
	s_addc_u32 s9, s13, 0
	s_add_i32 s12, s14, s22
	s_mov_b32 m0, s12
	s_nop 0
	global_load_lds_dwordx4 v132, s[8:9]
	s_add_i32 m0, s12, 0x2000
	s_nop 0
	global_load_lds_dwordx4 v128, s[8:9]
	s_waitcnt vmcnt(6)
	s_barrier
	s_setprio 1
	v_mfma_f32_16x16x32_bf16 v[52:55], v[202:205], v[168:171], v[52:55]
	v_mfma_f32_16x16x32_bf16 v[48:51], v[210:213], v[168:171], v[48:51]
	ds_read_b128 v[152:155], v149
	v_mfma_f32_16x16x32_bf16 v[36:39], v[202:205], v[176:179], v[36:39]
	v_mfma_f32_16x16x32_bf16 v[32:35], v[210:213], v[176:179], v[32:35]
	ds_read_b128 v[156:159], v149 offset:1024
	v_mfma_f32_16x16x32_bf16 v[20:23], v[202:205], v[184:187], v[20:23]
	v_mfma_f32_16x16x32_bf16 v[16:19], v[210:213], v[184:187], v[16:19]
	ds_read_b128 v[160:163], v149 offset:2048
	v_mfma_f32_16x16x32_bf16 v[4:7], v[202:205], v[192:195], v[4:7]
	v_mfma_f32_16x16x32_bf16 v[0:3], v[210:213], v[192:195], v[0:3]
	ds_read_b128 v[164:167], v149 offset:3072
	v_mfma_f32_16x16x32_bf16 v[52:55], v[206:209], v[172:175], v[52:55]
	s_add_i32 s3, s3, 2
	v_mfma_f32_16x16x32_bf16 v[48:51], v[214:217], v[172:175], v[48:51]
	s_add_u32 s39, s39, 0x100
	s_addc_u32 s44, s44, 0
	v_mfma_f32_16x16x32_bf16 v[36:39], v[206:209], v[180:183], v[36:39]
	s_cmpk_gt_u32 s3, 0x55
	v_mfma_f32_16x16x32_bf16 v[32:35], v[214:217], v[180:183], v[32:35]
	s_mov_b64 s[8:9], s[10:11]
	v_mfma_f32_16x16x32_bf16 v[20:23], v[206:209], v[188:191], v[20:23]
	v_mfma_f32_16x16x32_bf16 v[16:19], v[214:217], v[188:191], v[16:19]
	v_mfma_f32_16x16x32_bf16 v[4:7], v[206:209], v[198:201], v[4:7]
	v_mfma_f32_16x16x32_bf16 v[0:3], v[214:217], v[198:201], v[0:3]
	s_setprio 0
	s_barrier
	s_cbranch_scc0 .LBB1_2078
	s_waitcnt lgkmcnt(0)
	v_mov_b32_e32 v152, v147
	v_mov_b32_e32 v144, v146
	s_lshl_b32 s2, s2, 8
	s_add_i32 s2, s2, s29
	s_lshl_b32 s3, s38, 8
	v_add_u32_e32 v152, s2, v152
	s_or_b32 s3, s3, s52
	v_ashrrev_i32_e32 v153, 31, v152
	v_lshl_add_u32 v144, v144, 3, s3
	v_lshlrev_b64 v[152:153], 12, v[152:153]
	v_ashrrev_i32_e32 v145, 31, v144
	v_lshl_add_u64 v[152:153], s[4:5], 0, v[152:153]
	v_lshl_add_u64 v[144:145], v[144:145], 1, v[152:153]
	global_load_dwordx4 v[160:163], v[144:145], off
	global_load_dwordx4 v[164:167], v[144:145], off offset:256
	s_mov_b64 s[98:99], 0x10000
	v_lshl_add_u64 v[154:155], v[144:145], 0, s[98:99]
	global_load_dwordx4 v[168:171], v[154:155], off
	global_load_dwordx4 v[172:175], v[154:155], off offset:256
	s_mov_b64 s[98:99], 0x20000
	v_lshl_add_u64 v[154:155], v[144:145], 0, s[98:99]
	global_load_dwordx4 v[176:179], v[154:155], off
	global_load_dwordx4 v[180:183], v[154:155], off offset:256
	s_mov_b64 s[98:99], 0x30000
	v_lshl_add_u64 v[154:155], v[144:145], 0, s[98:99]
	global_load_dwordx4 v[184:187], v[154:155], off
	global_load_dwordx4 v[188:191], v[154:155], off offset:256
	s_mov_b64 s[98:99], 0x80000
	v_lshl_add_u64 v[154:155], v[144:145], 0, s[98:99]
	global_load_dwordx4 v[192:195], v[154:155], off
	global_load_dwordx4 v[198:201], v[154:155], off offset:256
	s_mov_b64 s[98:99], 0x90000
	v_lshl_add_u64 v[154:155], v[144:145], 0, s[98:99]
	global_load_dwordx4 v[202:205], v[154:155], off
	global_load_dwordx4 v[206:209], v[154:155], off offset:256
	s_mov_b64 s[98:99], 0xa0000
	v_lshl_add_u64 v[154:155], v[144:145], 0, s[98:99]
	global_load_dwordx4 v[210:213], v[154:155], off
	global_load_dwordx4 v[214:217], v[154:155], off offset:256
	s_mov_b64 s[98:99], 0xb0000
	v_lshl_add_u64 v[154:155], v[144:145], 0, s[98:99]
	global_load_dwordx4 v[248:251], v[154:155], off
	global_load_dwordx4 v[252:255], v[154:155], off offset:256
	s_waitcnt vmcnt(15)
	s_nop 1
	v_mov_b32_e32 v152, v160
	v_mov_b32_e32 v153, v161
	v_mov_b32_e32 v154, v162
	v_mov_b32_e32 v155, v163
	s_mov_b64 s[2:3], 0x10000
	s_mov_b32 s38, s37
	s_mov_b64 s[10:11], s[6:7]
	s_mov_b64 s[8:9], s[42:43]
	s_waitcnt lgkmcnt(0)
	v_lshlrev_b32_e32 v156, 16, v152
	v_and_b32_e32 v157, 0xffff0000, v152
	v_lshlrev_b32_e32 v152, 16, v153
	v_and_b32_e32 v153, 0xffff0000, v153
	v_lshlrev_b32_e32 v158, 16, v154
	v_and_b32_e32 v159, 0xffff0000, v154
	v_lshlrev_b32_e32 v154, 16, v155
	v_and_b32_e32 v155, 0xffff0000, v155
	v_pk_add_f32 v[126:127], v[126:127], v[152:153]
	v_pk_add_f32 v[124:125], v[124:125], v[156:157]
	v_pk_add_f32 v[152:153], v[122:123], v[154:155]
	v_pk_add_f32 v[122:123], v[120:121], v[158:159]
	v_cvt_pk_bf16_f32 v120, v124, v125
	v_cvt_pk_bf16_f32 v121, v126, v127
	v_cvt_pk_bf16_f32 v122, v122, v123
	v_cvt_pk_bf16_f32 v123, v152, v153
	global_store_dwordx4 v[144:145], v[120:123], off
	s_waitcnt vmcnt(15)
; DI unsigned pack2(float a, float b) { f32x2 v = {a, b}; hwbf16x2 r = __builtin_convertvector(v, hwbf16x2); return __builtin_bit_cast(unsigned, r); }
; DI float bflo(unsigned w) { return __uint_as_float(w << 16); }
; DI float bfhi(unsigned w) { return __uint_as_float(w & 0xffff0000u); }
;     DI void operator()(const f32x4 (&acc)[2][2][4][2], const Unit& u, int wr, int wc, int fr, int fq) const {
;     ...
;             for (int m = 0; m < 4; ++m) { const size_t ro = (size_t)(row0 + ai * HALF + m * 16) * D + col0;
; #pragma unroll
;                 for (int bj = 0; bj < 2; ++bj) {
;                     f32x4 x0, x1;
;                     if constexpr (IB) { const u32x4 w = *(const u32x4*)((const bf16_t*)Xin + ro + bj * HALF);
;                         x0 = (f32x4){bflo(w[0]), bfhi(w[0]), bflo(w[1]), bfhi(w[1])}; x1 = (f32x4){bflo(w[2]), bfhi(w[2]), bflo(w[3]), bfhi(w[3])}; }
;                     else { x0 = *(const f32x4*)((const float*)Xin + ro + bj * HALF); x1 = *(const f32x4*)((const float*)Xin + ro + bj * HALF + 4); }
;                     x0 += acc[ai][bj][m][0] * sc[bj][0]; x1 += acc[ai][bj][m][1] * sc[bj][1];
;                     if constexpr (OB) { u32x4 o; o[0] = pack2(x0[0], x0[1]); o[1] = pack2(x0[2], x0[3]); o[2] = pack2(x1[0], x1[1]); o[3] = pack2(x1[2], x1[3]);
;                         *(u32x4*)((bf16_t*)Xout + ro + bj * HALF) = o; }
;                     else { *(f32x4*)((float*)Xout + ro + bj * HALF) = x0; *(f32x4*)((float*)Xout + ro + bj * HALF + 4) = x1; } } }
	s_nop 1
	v_mov_b32_e32 v120, v164
	v_mov_b32_e32 v121, v165
	v_mov_b32_e32 v122, v166
	v_mov_b32_e32 v123, v167
	s_waitcnt lgkmcnt(0)
	v_lshlrev_b32_e32 v124, 16, v120
	v_and_b32_e32 v125, 0xffff0000, v120
	v_lshlrev_b32_e32 v120, 16, v121
	v_and_b32_e32 v121, 0xffff0000, v121
	v_lshlrev_b32_e32 v126, 16, v122
	v_and_b32_e32 v127, 0xffff0000, v122
	v_lshlrev_b32_e32 v122, 16, v123
	v_and_b32_e32 v123, 0xffff0000, v123
	v_pk_add_f32 v[116:117], v[116:117], v[124:125]
	v_pk_add_f32 v[118:119], v[118:119], v[120:121]
	v_pk_add_f32 v[120:121], v[114:115], v[122:123]
	v_pk_add_f32 v[114:115], v[112:113], v[126:127]
	v_cvt_pk_bf16_f32 v112, v116, v117
	v_lshl_add_u64 v[116:117], v[144:145], 0, s[2:3]
	s_mov_b32 s2, 0x10000
	v_cvt_pk_bf16_f32 v113, v118, v119
	v_add_co_u32_e32 v118, vcc, s2, v144
	v_cvt_pk_bf16_f32 v114, v114, v115
	v_cvt_pk_bf16_f32 v115, v120, v121
	v_addc_co_u32_e32 v119, vcc, 0, v145, vcc
	global_store_dwordx4 v[144:145], v[112:115], off offset:256
	s_waitcnt vmcnt(15)
	s_nop 1
	v_mov_b32_e32 v112, v168
	v_mov_b32_e32 v113, v169
	v_mov_b32_e32 v114, v170
	v_mov_b32_e32 v115, v171
	s_mov_b64 s[2:3], 0x20000
	s_waitcnt lgkmcnt(0)
	v_lshlrev_b32_e32 v120, 16, v112
	v_and_b32_e32 v121, 0xffff0000, v112
	v_lshlrev_b32_e32 v112, 16, v113
	v_and_b32_e32 v113, 0xffff0000, v113
	v_lshlrev_b32_e32 v122, 16, v114
	v_and_b32_e32 v123, 0xffff0000, v114
	v_lshlrev_b32_e32 v114, 16, v115
	v_and_b32_e32 v115, 0xffff0000, v115
	v_pk_add_f32 v[110:111], v[110:111], v[112:113]
	v_pk_add_f32 v[108:109], v[108:109], v[120:121]
	v_pk_add_f32 v[112:113], v[106:107], v[114:115]
	v_pk_add_f32 v[106:107], v[104:105], v[122:123]
	v_cvt_pk_bf16_f32 v104, v108, v109
	v_cvt_pk_bf16_f32 v105, v110, v111
	v_cvt_pk_bf16_f32 v106, v106, v107
	v_cvt_pk_bf16_f32 v107, v112, v113
	global_store_dwordx4 v[118:119], v[104:107], off
	s_waitcnt vmcnt(15)
	s_nop 1
	v_mov_b32_e32 v104, v172
	v_mov_b32_e32 v105, v173
	v_mov_b32_e32 v106, v174
	v_mov_b32_e32 v107, v175
	s_waitcnt lgkmcnt(0)
	v_lshlrev_b32_e32 v108, 16, v104
	v_and_b32_e32 v109, 0xffff0000, v104
	v_lshlrev_b32_e32 v104, 16, v105
	v_and_b32_e32 v105, 0xffff0000, v105
	v_lshlrev_b32_e32 v110, 16, v106
	v_and_b32_e32 v111, 0xffff0000, v106
	v_lshlrev_b32_e32 v106, 16, v107
	v_and_b32_e32 v107, 0xffff0000, v107
	v_pk_add_f32 v[100:101], v[100:101], v[108:109]
	v_pk_add_f32 v[102:103], v[102:103], v[104:105]
	v_pk_add_f32 v[104:105], v[98:99], v[106:107]
	v_pk_add_f32 v[98:99], v[96:97], v[110:111]
	v_cvt_pk_bf16_f32 v96, v100, v101
	v_lshl_add_u64 v[100:101], v[144:145], 0, s[2:3]
	s_mov_b32 s2, 0x20000
	v_cvt_pk_bf16_f32 v97, v102, v103
	v_add_co_u32_e32 v102, vcc, s2, v144
	v_cvt_pk_bf16_f32 v98, v98, v99
	v_cvt_pk_bf16_f32 v99, v104, v105
	v_addc_co_u32_e32 v103, vcc, 0, v145, vcc
	global_store_dwordx4 v[116:117], v[96:99], off offset:256
	s_waitcnt vmcnt(15)
	s_nop 1
	v_mov_b32_e32 v96, v176
	v_mov_b32_e32 v97, v177
	v_mov_b32_e32 v98, v178
	v_mov_b32_e32 v99, v179
	s_mov_b64 s[2:3], 0x30000
	s_waitcnt lgkmcnt(0)
	v_lshlrev_b32_e32 v104, 16, v96
	v_and_b32_e32 v105, 0xffff0000, v96
	v_lshlrev_b32_e32 v96, 16, v97
	v_and_b32_e32 v97, 0xffff0000, v97
	v_lshlrev_b32_e32 v106, 16, v98
	v_and_b32_e32 v107, 0xffff0000, v98
	v_lshlrev_b32_e32 v98, 16, v99
	v_and_b32_e32 v99, 0xffff0000, v99
	v_pk_add_f32 v[94:95], v[94:95], v[96:97]
	v_pk_add_f32 v[92:93], v[92:93], v[104:105]
	v_pk_add_f32 v[96:97], v[90:91], v[98:99]
	v_pk_add_f32 v[90:91], v[88:89], v[106:107]
	v_cvt_pk_bf16_f32 v88, v92, v93
	v_cvt_pk_bf16_f32 v89, v94, v95
	v_cvt_pk_bf16_f32 v90, v90, v91
	v_cvt_pk_bf16_f32 v91, v96, v97
	global_store_dwordx4 v[102:103], v[88:91], off
	s_waitcnt vmcnt(15)
	s_nop 1
	v_mov_b32_e32 v88, v180
	v_mov_b32_e32 v89, v181
	v_mov_b32_e32 v90, v182
	v_mov_b32_e32 v91, v183
	s_waitcnt lgkmcnt(0)
	v_lshlrev_b32_e32 v92, 16, v88
	v_and_b32_e32 v93, 0xffff0000, v88
	v_lshlrev_b32_e32 v88, 16, v89
	v_and_b32_e32 v89, 0xffff0000, v89
	v_lshlrev_b32_e32 v94, 16, v90
	v_and_b32_e32 v95, 0xffff0000, v90
	v_lshlrev_b32_e32 v90, 16, v91
	v_and_b32_e32 v91, 0xffff0000, v91
	v_pk_add_f32 v[86:87], v[86:87], v[88:89]
	v_pk_add_f32 v[84:85], v[84:85], v[92:93]
	v_pk_add_f32 v[88:89], v[82:83], v[90:91]
	v_pk_add_f32 v[82:83], v[80:81], v[94:95]
	v_cvt_pk_bf16_f32 v80, v84, v85
	v_cvt_pk_bf16_f32 v81, v86, v87
	v_cvt_pk_bf16_f32 v82, v82, v83
	v_cvt_pk_bf16_f32 v83, v88, v89
	global_store_dwordx4 v[100:101], v[80:83], off offset:256
	s_nop 1
	v_lshl_add_u64 v[80:81], v[144:145], 0, s[2:3]
	s_mov_b32 s2, 0x30000
	v_add_co_u32_e32 v86, vcc, s2, v144
	s_mov_b64 s[2:3], 0x80000
	s_nop 0
	v_addc_co_u32_e32 v87, vcc, 0, v145, vcc
	s_waitcnt vmcnt(15)
	s_nop 1
	v_mov_b32_e32 v82, v184
	v_mov_b32_e32 v83, v185
	v_mov_b32_e32 v84, v186
	v_mov_b32_e32 v85, v187
	s_waitcnt lgkmcnt(0)
	v_lshlrev_b32_e32 v88, 16, v82
	v_and_b32_e32 v89, 0xffff0000, v82
	v_lshlrev_b32_e32 v82, 16, v83
	v_and_b32_e32 v83, 0xffff0000, v83
	v_lshlrev_b32_e32 v90, 16, v84
	v_and_b32_e32 v91, 0xffff0000, v84
	v_lshlrev_b32_e32 v84, 16, v85
	v_and_b32_e32 v85, 0xffff0000, v85
	v_pk_add_f32 v[78:79], v[78:79], v[82:83]
	v_pk_add_f32 v[76:77], v[76:77], v[88:89]
	v_pk_add_f32 v[82:83], v[74:75], v[84:85]
	v_pk_add_f32 v[74:75], v[72:73], v[90:91]
	v_cvt_pk_bf16_f32 v72, v76, v77
	v_cvt_pk_bf16_f32 v73, v78, v79
	v_cvt_pk_bf16_f32 v74, v74, v75
	v_cvt_pk_bf16_f32 v75, v82, v83
	global_store_dwordx4 v[86:87], v[72:75], off
	s_waitcnt vmcnt(15)
	s_nop 1
	v_mov_b32_e32 v72, v188
	v_mov_b32_e32 v73, v189
	v_mov_b32_e32 v74, v190
	v_mov_b32_e32 v75, v191
	s_waitcnt lgkmcnt(0)
; DI unsigned pack2(float a, float b) { f32x2 v = {a, b}; hwbf16x2 r = __builtin_convertvector(v, hwbf16x2); return __builtin_bit_cast(unsigned, r); }
; DI float bflo(unsigned w) { return __uint_as_float(w << 16); }
; DI float bfhi(unsigned w) { return __uint_as_float(w & 0xffff0000u); }
;     DI void operator()(const f32x4 (&acc)[2][2][4][2], const Unit& u, int wr, int wc, int fr, int fq) const {
;     ...
;             for (int m = 0; m < 4; ++m) { const size_t ro = (size_t)(row0 + ai * HALF + m * 16) * D + col0;
; #pragma unroll
;                 for (int bj = 0; bj < 2; ++bj) {
;                     f32x4 x0, x1;
;                     if constexpr (IB) { const u32x4 w = *(const u32x4*)((const bf16_t*)Xin + ro + bj * HALF);
;                         x0 = (f32x4){bflo(w[0]), bfhi(w[0]), bflo(w[1]), bfhi(w[1])}; x1 = (f32x4){bflo(w[2]), bfhi(w[2]), bflo(w[3]), bfhi(w[3])}; }
;                     else { x0 = *(const f32x4*)((const float*)Xin + ro + bj * HALF); x1 = *(const f32x4*)((const float*)Xin + ro + bj * HALF + 4); }
;                     x0 += acc[ai][bj][m][0] * sc[bj][0]; x1 += acc[ai][bj][m][1] * sc[bj][1];
;                     if constexpr (OB) { u32x4 o; o[0] = pack2(x0[0], x0[1]); o[1] = pack2(x0[2], x0[3]); o[2] = pack2(x1[0], x1[1]); o[3] = pack2(x1[2], x1[3]);
;                         *(u32x4*)((bf16_t*)Xout + ro + bj * HALF) = o; }
;                     else { *(f32x4*)((float*)Xout + ro + bj * HALF) = x0; *(f32x4*)((float*)Xout + ro + bj * HALF + 4) = x1; } } }
	v_lshlrev_b32_e32 v76, 16, v72
	v_and_b32_e32 v77, 0xffff0000, v72
	v_lshlrev_b32_e32 v72, 16, v73
	v_and_b32_e32 v73, 0xffff0000, v73
	v_lshlrev_b32_e32 v78, 16, v74
	v_and_b32_e32 v79, 0xffff0000, v74
	v_lshlrev_b32_e32 v74, 16, v75
	v_and_b32_e32 v75, 0xffff0000, v75
	v_pk_add_f32 v[70:71], v[70:71], v[72:73]
	v_pk_add_f32 v[68:69], v[68:69], v[76:77]
	v_pk_add_f32 v[72:73], v[66:67], v[74:75]
	v_pk_add_f32 v[66:67], v[64:65], v[78:79]
	v_cvt_pk_bf16_f32 v64, v68, v69
	v_cvt_pk_bf16_f32 v65, v70, v71
	v_cvt_pk_bf16_f32 v66, v66, v67
	v_cvt_pk_bf16_f32 v67, v72, v73
	global_store_dwordx4 v[80:81], v[64:67], off offset:256
	s_nop 1
	v_lshl_add_u64 v[64:65], v[144:145], 0, s[2:3]
	s_mov_b32 s2, 0x80000
	v_add_co_u32_e32 v70, vcc, s2, v144
	s_mov_b64 s[2:3], 0x90000
	s_nop 0
	v_addc_co_u32_e32 v71, vcc, 0, v145, vcc
	s_waitcnt vmcnt(15)
	s_nop 1
	v_mov_b32_e32 v66, v192
	v_mov_b32_e32 v67, v193
	v_mov_b32_e32 v68, v194
	v_mov_b32_e32 v69, v195
	s_waitcnt lgkmcnt(0)
	v_lshlrev_b32_e32 v72, 16, v66
	v_and_b32_e32 v73, 0xffff0000, v66
	v_lshlrev_b32_e32 v66, 16, v67
	v_and_b32_e32 v67, 0xffff0000, v67
	v_lshlrev_b32_e32 v74, 16, v68
	v_and_b32_e32 v75, 0xffff0000, v68
	v_lshlrev_b32_e32 v68, 16, v69
	v_and_b32_e32 v69, 0xffff0000, v69
	v_pk_add_f32 v[62:63], v[62:63], v[66:67]
	v_pk_add_f32 v[60:61], v[60:61], v[72:73]
	v_pk_add_f32 v[66:67], v[58:59], v[68:69]
	v_pk_add_f32 v[58:59], v[56:57], v[74:75]
	v_cvt_pk_bf16_f32 v56, v60, v61
	v_cvt_pk_bf16_f32 v57, v62, v63
	v_cvt_pk_bf16_f32 v58, v58, v59
	v_cvt_pk_bf16_f32 v59, v66, v67
	global_store_dwordx4 v[70:71], v[56:59], off
	s_waitcnt vmcnt(15)
	s_nop 1
	v_mov_b32_e32 v56, v198
	v_mov_b32_e32 v57, v199
	v_mov_b32_e32 v58, v200
	v_mov_b32_e32 v59, v201
	s_waitcnt lgkmcnt(0)
	v_lshlrev_b32_e32 v60, 16, v56
	v_and_b32_e32 v61, 0xffff0000, v56
	v_lshlrev_b32_e32 v56, 16, v57
	v_and_b32_e32 v57, 0xffff0000, v57
	v_lshlrev_b32_e32 v62, 16, v58
	v_and_b32_e32 v63, 0xffff0000, v58
	v_lshlrev_b32_e32 v58, 16, v59
	v_and_b32_e32 v59, 0xffff0000, v59
	v_pk_add_f32 v[54:55], v[54:55], v[56:57]
	v_pk_add_f32 v[52:53], v[52:53], v[60:61]
	v_pk_add_f32 v[56:57], v[50:51], v[58:59]
	v_pk_add_f32 v[50:51], v[48:49], v[62:63]
	v_cvt_pk_bf16_f32 v48, v52, v53
	v_cvt_pk_bf16_f32 v49, v54, v55
	v_cvt_pk_bf16_f32 v50, v50, v51
	v_cvt_pk_bf16_f32 v51, v56, v57
	global_store_dwordx4 v[64:65], v[48:51], off offset:256
	s_nop 1
	v_lshl_add_u64 v[48:49], v[144:145], 0, s[2:3]
	s_mov_b32 s2, 0x90000
	v_add_co_u32_e32 v54, vcc, s2, v144
	s_mov_b64 s[2:3], 0xa0000
	s_nop 0
	v_addc_co_u32_e32 v55, vcc, 0, v145, vcc
	s_waitcnt vmcnt(15)
	s_nop 1
	v_mov_b32_e32 v50, v202
	v_mov_b32_e32 v51, v203
	v_mov_b32_e32 v52, v204
	v_mov_b32_e32 v53, v205
	s_waitcnt lgkmcnt(0)
	v_lshlrev_b32_e32 v56, 16, v50
	v_and_b32_e32 v57, 0xffff0000, v50
	v_lshlrev_b32_e32 v50, 16, v51
	v_and_b32_e32 v51, 0xffff0000, v51
	v_lshlrev_b32_e32 v58, 16, v52
	v_and_b32_e32 v59, 0xffff0000, v52
	v_lshlrev_b32_e32 v52, 16, v53
	v_and_b32_e32 v53, 0xffff0000, v53
	v_pk_add_f32 v[46:47], v[46:47], v[50:51]
	v_pk_add_f32 v[44:45], v[44:45], v[56:57]
	v_pk_add_f32 v[50:51], v[42:43], v[52:53]
	v_pk_add_f32 v[42:43], v[40:41], v[58:59]
	v_cvt_pk_bf16_f32 v40, v44, v45
	v_cvt_pk_bf16_f32 v41, v46, v47
	v_cvt_pk_bf16_f32 v42, v42, v43
	v_cvt_pk_bf16_f32 v43, v50, v51
	global_store_dwordx4 v[54:55], v[40:43], off
	s_waitcnt vmcnt(15)
	s_nop 1
	v_mov_b32_e32 v40, v206
	v_mov_b32_e32 v41, v207
	v_mov_b32_e32 v42, v208
	v_mov_b32_e32 v43, v209
	s_waitcnt lgkmcnt(0)
; DI unsigned pack2(float a, float b) { f32x2 v = {a, b}; hwbf16x2 r = __builtin_convertvector(v, hwbf16x2); return __builtin_bit_cast(unsigned, r); }
; DI float bflo(unsigned w) { return __uint_as_float(w << 16); }
; DI float bfhi(unsigned w) { return __uint_as_float(w & 0xffff0000u); }
; #define PG8_WAIT_V(n) asm volatile("s_waitcnt vmcnt(" #n ")" ::: "memory")
; #define PG8_BAR __builtin_amdgcn_s_barrier()
;     DI void operator()(const f32x4 (&acc)[2][2][4][2], const Unit& u, int wr, int wc, int fr, int fq) const {
;     ...
;             for (int m = 0; m < 4; ++m) { const size_t ro = (size_t)(row0 + ai * HALF + m * 16) * D + col0;
; #pragma unroll
;                 for (int bj = 0; bj < 2; ++bj) {
;                     f32x4 x0, x1;
;                     if constexpr (IB) { const u32x4 w = *(const u32x4*)((const bf16_t*)Xin + ro + bj * HALF);
;                         x0 = (f32x4){bflo(w[0]), bfhi(w[0]), bflo(w[1]), bfhi(w[1])}; x1 = (f32x4){bflo(w[2]), bfhi(w[2]), bflo(w[3]), bfhi(w[3])}; }
;                     else { x0 = *(const f32x4*)((const float*)Xin + ro + bj * HALF); x1 = *(const f32x4*)((const float*)Xin + ro + bj * HALF + 4); }
;                     x0 += acc[ai][bj][m][0] * sc[bj][0]; x1 += acc[ai][bj][m][1] * sc[bj][1];
;                     if constexpr (OB) { u32x4 o; o[0] = pack2(x0[0], x0[1]); o[1] = pack2(x0[2], x0[3]); o[2] = pack2(x1[0], x1[1]); o[3] = pack2(x1[2], x1[3]);
;                         *(u32x4*)((bf16_t*)Xout + ro + bj * HALF) = o; }
;                     else { *(f32x4*)((float*)Xout + ro + bj * HALF) = x0; *(f32x4*)((float*)Xout + ro + bj * HALF + 4) = x1; } } }
; template <class Map, class Epi>
; DI void gemm_phase(LAS unsigned char* lds, const Map& MP, const Epi& E, const int nM, const int nN, const int K, const int lda, const int ldb) {
;     ...
;     PG8_WAIT_V(0);
;     if (wr == 0) PG8_BAR;
;     PG8_BAR;
	v_lshlrev_b32_e32 v44, 16, v40
	v_and_b32_e32 v45, 0xffff0000, v40
	v_lshlrev_b32_e32 v40, 16, v41
	v_and_b32_e32 v41, 0xffff0000, v41
	v_lshlrev_b32_e32 v46, 16, v42
	v_and_b32_e32 v47, 0xffff0000, v42
	v_lshlrev_b32_e32 v42, 16, v43
	v_and_b32_e32 v43, 0xffff0000, v43
	v_pk_add_f32 v[38:39], v[38:39], v[40:41]
	v_pk_add_f32 v[36:37], v[36:37], v[44:45]
	v_pk_add_f32 v[40:41], v[34:35], v[42:43]
	v_pk_add_f32 v[34:35], v[32:33], v[46:47]
	v_cvt_pk_bf16_f32 v32, v36, v37
	v_cvt_pk_bf16_f32 v33, v38, v39
	v_cvt_pk_bf16_f32 v34, v34, v35
	v_cvt_pk_bf16_f32 v35, v40, v41
	global_store_dwordx4 v[48:49], v[32:35], off offset:256
	s_nop 1
	v_lshl_add_u64 v[32:33], v[144:145], 0, s[2:3]
	s_mov_b32 s2, 0xa0000
	v_add_co_u32_e32 v38, vcc, s2, v144
	s_mov_b64 s[2:3], 0xb0000
	s_nop 0
	v_addc_co_u32_e32 v39, vcc, 0, v145, vcc
	s_waitcnt vmcnt(15)
	s_nop 1
	v_mov_b32_e32 v34, v210
	v_mov_b32_e32 v35, v211
	v_mov_b32_e32 v36, v212
	v_mov_b32_e32 v37, v213
	s_waitcnt lgkmcnt(0)
	v_lshlrev_b32_e32 v40, 16, v34
	v_and_b32_e32 v41, 0xffff0000, v34
	v_lshlrev_b32_e32 v34, 16, v35
	v_and_b32_e32 v35, 0xffff0000, v35
	v_lshlrev_b32_e32 v42, 16, v36
	v_and_b32_e32 v43, 0xffff0000, v36
	v_lshlrev_b32_e32 v36, 16, v37
	v_and_b32_e32 v37, 0xffff0000, v37
	v_pk_add_f32 v[30:31], v[30:31], v[34:35]
	v_pk_add_f32 v[28:29], v[28:29], v[40:41]
	v_pk_add_f32 v[34:35], v[26:27], v[36:37]
	v_pk_add_f32 v[26:27], v[24:25], v[42:43]
	v_cvt_pk_bf16_f32 v24, v28, v29
	v_cvt_pk_bf16_f32 v25, v30, v31
	v_cvt_pk_bf16_f32 v26, v26, v27
	v_cvt_pk_bf16_f32 v27, v34, v35
	global_store_dwordx4 v[38:39], v[24:27], off
	s_waitcnt vmcnt(15)
	s_nop 1
	v_mov_b32_e32 v24, v214
	v_mov_b32_e32 v25, v215
	v_mov_b32_e32 v26, v216
	v_mov_b32_e32 v27, v217
	s_waitcnt lgkmcnt(0)
	v_lshlrev_b32_e32 v28, 16, v24
	v_and_b32_e32 v29, 0xffff0000, v24
	v_lshlrev_b32_e32 v24, 16, v25
	v_and_b32_e32 v25, 0xffff0000, v25
	v_lshlrev_b32_e32 v30, 16, v26
	v_and_b32_e32 v31, 0xffff0000, v26
	v_lshlrev_b32_e32 v26, 16, v27
	v_and_b32_e32 v27, 0xffff0000, v27
	v_pk_add_f32 v[22:23], v[22:23], v[24:25]
	v_pk_add_f32 v[20:21], v[20:21], v[28:29]
	v_pk_add_f32 v[24:25], v[18:19], v[26:27]
	v_pk_add_f32 v[18:19], v[16:17], v[30:31]
	v_cvt_pk_bf16_f32 v16, v20, v21
	v_cvt_pk_bf16_f32 v17, v22, v23
	v_cvt_pk_bf16_f32 v18, v18, v19
	v_cvt_pk_bf16_f32 v19, v24, v25
	global_store_dwordx4 v[32:33], v[16:19], off offset:256
	s_nop 1
	v_lshl_add_u64 v[16:17], v[144:145], 0, s[2:3]
	s_mov_b32 s2, 0xb0000
	v_add_co_u32_e32 v22, vcc, s2, v144
	s_mov_b32 s2, s53
	s_nop 0
	v_addc_co_u32_e32 v23, vcc, 0, v145, vcc
	s_waitcnt vmcnt(15)
	s_nop 1
	v_mov_b32_e32 v18, v248
	v_mov_b32_e32 v19, v249
	v_mov_b32_e32 v20, v250
	v_mov_b32_e32 v21, v251
	s_and_b64 vcc, exec, s[40:41]
	s_waitcnt lgkmcnt(0)
	v_lshlrev_b32_e32 v24, 16, v18
	v_and_b32_e32 v25, 0xffff0000, v18
	v_lshlrev_b32_e32 v18, 16, v19
	v_and_b32_e32 v19, 0xffff0000, v19
	v_lshlrev_b32_e32 v26, 16, v20
	v_and_b32_e32 v27, 0xffff0000, v20
	v_lshlrev_b32_e32 v20, 16, v21
	v_and_b32_e32 v21, 0xffff0000, v21
	v_pk_add_f32 v[14:15], v[14:15], v[18:19]
	v_pk_add_f32 v[12:13], v[12:13], v[24:25]
	v_pk_add_f32 v[18:19], v[10:11], v[20:21]
	v_pk_add_f32 v[10:11], v[8:9], v[26:27]
	v_cvt_pk_bf16_f32 v8, v12, v13
	v_cvt_pk_bf16_f32 v9, v14, v15
	v_cvt_pk_bf16_f32 v10, v10, v11
	v_cvt_pk_bf16_f32 v11, v18, v19
	global_store_dwordx4 v[22:23], v[8:11], off
	s_waitcnt vmcnt(15)
	s_nop 1
	v_mov_b32_e32 v8, v252
	v_mov_b32_e32 v9, v253
	v_mov_b32_e32 v10, v254
	v_mov_b32_e32 v11, v255
	s_waitcnt lgkmcnt(0)
	v_lshlrev_b32_e32 v12, 16, v8
	v_and_b32_e32 v13, 0xffff0000, v8
	v_lshlrev_b32_e32 v8, 16, v9
	v_and_b32_e32 v9, 0xffff0000, v9
	v_lshlrev_b32_e32 v14, 16, v10
	v_and_b32_e32 v15, 0xffff0000, v10
	v_lshlrev_b32_e32 v10, 16, v11
	v_and_b32_e32 v11, 0xffff0000, v11
	v_pk_add_f32 v[6:7], v[6:7], v[8:9]
	v_pk_add_f32 v[4:5], v[4:5], v[12:13]
	v_pk_add_f32 v[8:9], v[2:3], v[10:11]
	v_pk_add_f32 v[2:3], v[0:1], v[14:15]
	v_cvt_pk_bf16_f32 v0, v4, v5
	v_cvt_pk_bf16_f32 v1, v6, v7
	v_cvt_pk_bf16_f32 v2, v2, v3
	v_cvt_pk_bf16_f32 v3, v8, v9
	global_store_dwordx4 v[16:17], v[0:3], off offset:256
	s_cbranch_vccz .LBB1_2071
	s_waitcnt vmcnt(0)
	s_cmpk_gt_u32 s17, 0xff
	s_cbranch_scc1 .LBB1_2082
	s_barrier

; #define PG8_STAGE(bufoff, gbase, voff) do { _Pragma("unroll") for (int _i = 0; _i < 2; ++_i) \
;         __builtin_amdgcn_global_load_lds((const unsigned*)((const char*)(gbase) + (voff)[_i]), (LAS unsigned*)(lds + (bufoff) + ldsw + _i * 8192), 16, 0, 0); } while (0)
; #define PG8_LDA(dst, b, h) do { _Pragma("unroll") for (int m = 0; m < 4; ++m) _Pragma("unroll") for (int k = 0; k < 2; ++k) dst[m][k] = *(const LAS bf16x8*)(lds + PG8_SA(b, h) + aoff + m * 2048 + k * 1024); } while (0)
; #define PG8_LDB(dst, b, h) do { _Pragma("unroll") for (int n = 0; n < 2; ++n) _Pragma("unroll") for (int k = 0; k < 2; ++k) dst[n][k] = *(const LAS bf16x8*)(lds + PG8_SB(b, h) + boff + n * 2048 + k * 1024); } while (0)
; #define PG8_MMA(ai, bj, At, Bt) do { __builtin_amdgcn_s_setprio(1); _Pragma("unroll") for (int m = 0; m < 4; ++m) _Pragma("unroll") for (int n = 0; n < 2; ++n) _Pragma("unroll") for (int k = 0; k < 2; ++k) \
;         acc[ai][bj][m][n] = __builtin_amdgcn_mfma_f32_16x16x32_bf16(Bt[n][k], At[m][k], acc[ai][bj][m][n], 0, 0, 0); __builtin_amdgcn_s_setprio(0); } while (0)
; #define PG8_WAIT_V(n) asm volatile("s_waitcnt vmcnt(" #n ")" ::: "memory")
; #define PG8_WAIT_L(n) asm volatile("s_waitcnt lgkmcnt(" #n ")" ::: "memory")
; template <class Map, class Epi>
; DI void gemm_phase(LAS unsigned char* lds, const Map& MP, const Epi& E, const int nM, const int nN, const int K, const int lda, const int ldb) {
;     ...
;         for (int t = 0; t < nt; t += 2) {
;             const bool last = (t == nt - 2);
;             const char* a1 = cA + (size_t)(t + 1) * kstep;
;             const char* a2 = last ? nA : cA + (size_t)(t + 2) * kstep; const char* b2 = last ? nB : cB + (size_t)(t + 2) * kstep;
;             const char* a3 = a2 + kstep; const char* b3 = b2 + kstep;
;             PG8_LDB(B0, 0, 0); PG8_SCHED; PG8_LDA(At, 0, 0); PG8_STAGE(PG8_SA(1, 1), a1 + hstepA, voffA);
;             PG8_WAIT_L(8); PG8_BAR; PG8_WAIT_L(0); PG8_MMA(0, 0, At, B0); PG8_BAR; PG8_SCHED;
;             PG8_LDB(B1, 0, 1); PG8_STAGE(PG8_SB(0, 0), b2, voffB);
;             PG8_BAR; PG8_WAIT_L(0); PG8_MMA(0, 1, At, B1); PG8_BAR;
;             PG8_LDA(At, 0, 1); PG8_STAGE(PG8_SA(0, 0), a2, voffA);
;             PG8_BAR; PG8_WAIT_L(0); PG8_MMA(1, 0, At, B0); PG8_BAR; PG8_SCHED;
;             PG8_STAGE(PG8_SB(0, 1), b2 + hstepB, voffB);
;             PG8_WAIT_V(6); PG8_BAR; PG8_MMA(1, 1, At, B1); PG8_BAR;
.LBB1_2339:
	ds_read_b128 v[168:171], v166
	ds_read_b128 v[172:175], v166 offset:1024
	ds_read_b128 v[176:179], v166 offset:2048
	ds_read_b128 v[180:183], v166 offset:3072
	ds_read_b128 v[184:187], v166 offset:4096
	ds_read_b128 v[188:191], v166 offset:5120
	ds_read_b128 v[192:195], v166 offset:6144
	ds_read_b128 v[198:201], v166 offset:7168
	s_add_u32 s12, s10, 0xfff80080
	s_addc_u32 s13, s11, -1
	s_cmp_eq_u32 s3, 4
	s_cselect_b32 s15, s38, s13
	s_cselect_b32 s14, s39, s12
	s_cselect_b32 s13, s48, s56
	s_cselect_b32 s12, s49, s53
	s_add_i32 m0, s9, 0xc000
	s_nop 0
	global_load_lds_dwordx4 v154, s[10:11]
	s_add_i32 m0, s9, 0xe000
	s_nop 0
	global_load_lds_dwordx4 v152, s[10:11]
	s_waitcnt lgkmcnt(8)
	s_barrier
	s_setprio 1
	s_waitcnt lgkmcnt(7)
	v_mfma_f32_16x16x32_bf16 v[140:143], v[40:43], v[168:171], v[140:143]
	v_mfma_f32_16x16x32_bf16 v[136:139], v[56:59], v[168:171], v[136:139]
	s_waitcnt lgkmcnt(5)
	v_mfma_f32_16x16x32_bf16 v[124:127], v[40:43], v[176:179], v[124:127]
	v_mfma_f32_16x16x32_bf16 v[120:123], v[56:59], v[176:179], v[120:123]
	s_waitcnt lgkmcnt(3)
	v_mfma_f32_16x16x32_bf16 v[108:111], v[40:43], v[184:187], v[108:111]
	v_mfma_f32_16x16x32_bf16 v[104:107], v[56:59], v[184:187], v[104:107]
	s_waitcnt lgkmcnt(1)
	v_mfma_f32_16x16x32_bf16 v[92:95], v[40:43], v[192:195], v[92:95]
	v_mfma_f32_16x16x32_bf16 v[88:91], v[56:59], v[192:195], v[88:91]
	v_mfma_f32_16x16x32_bf16 v[140:143], v[44:47], v[172:175], v[140:143]
	v_mfma_f32_16x16x32_bf16 v[136:139], v[60:63], v[172:175], v[136:139]
	v_mfma_f32_16x16x32_bf16 v[124:127], v[44:47], v[180:183], v[124:127]
	v_mfma_f32_16x16x32_bf16 v[120:123], v[60:63], v[180:183], v[120:123]
	v_mfma_f32_16x16x32_bf16 v[108:111], v[44:47], v[188:191], v[108:111]
	v_mfma_f32_16x16x32_bf16 v[104:107], v[60:63], v[188:191], v[104:107]
	s_waitcnt lgkmcnt(0)
	v_mfma_f32_16x16x32_bf16 v[92:95], v[44:47], v[198:201], v[92:95]
	v_mfma_f32_16x16x32_bf16 v[88:91], v[60:63], v[198:201], v[88:91]
	s_setprio 0
	s_barrier
	ds_read_b128 v[202:205], v167
	ds_read_b128 v[206:209], v167 offset:1024
	ds_read_b128 v[210:213], v167 offset:2048
	ds_read_b128 v[214:217], v167 offset:3072
	s_add_i32 s57, s35, s22
	v_lshl_add_u64 v[160:161], s[12:13], 0, v[148:149]
	s_mov_b32 m0, s57
	s_nop 0
	global_load_lds_dwordx4 v[160:161], off
	v_lshl_add_u64 v[218:219], s[12:13], 0, v[144:145]
	s_add_i32 m0, s57, 0x2000
	s_nop 0
	global_load_lds_dwordx4 v[218:219], off
	s_barrier
	s_setprio 1
	s_waitcnt lgkmcnt(3)
	v_mfma_f32_16x16x32_bf16 v[132:135], v[202:205], v[168:171], v[132:135]
	s_waitcnt lgkmcnt(1)
	v_mfma_f32_16x16x32_bf16 v[128:131], v[210:213], v[168:171], v[128:131]
	v_mfma_f32_16x16x32_bf16 v[116:119], v[202:205], v[176:179], v[116:119]
	v_mfma_f32_16x16x32_bf16 v[112:115], v[210:213], v[176:179], v[112:115]
	v_mfma_f32_16x16x32_bf16 v[100:103], v[202:205], v[184:187], v[100:103]
	v_mfma_f32_16x16x32_bf16 v[96:99], v[210:213], v[184:187], v[96:99]
	v_mfma_f32_16x16x32_bf16 v[84:87], v[202:205], v[192:195], v[84:87]
	v_mfma_f32_16x16x32_bf16 v[80:83], v[210:213], v[192:195], v[80:83]
	v_mfma_f32_16x16x32_bf16 v[132:135], v[206:209], v[172:175], v[132:135]
	s_mov_b32 m0, s9
	s_waitcnt lgkmcnt(0)
	v_mfma_f32_16x16x32_bf16 v[128:131], v[214:217], v[172:175], v[128:131]
	v_lshl_add_u64 v[220:221], s[14:15], 0, v[150:151]
	v_mfma_f32_16x16x32_bf16 v[116:119], v[206:209], v[180:183], v[116:119]
	v_mfma_f32_16x16x32_bf16 v[112:115], v[214:217], v[180:183], v[112:115]
	v_mfma_f32_16x16x32_bf16 v[100:103], v[206:209], v[188:191], v[100:103]
	v_mfma_f32_16x16x32_bf16 v[96:99], v[214:217], v[188:191], v[96:99]
	v_mfma_f32_16x16x32_bf16 v[84:87], v[206:209], v[198:201], v[84:87]
	v_mfma_f32_16x16x32_bf16 v[80:83], v[214:217], v[198:201], v[80:83]
	s_setprio 0
	s_barrier
	ds_read_b128 v[168:171], v166 offset:16384
	ds_read_b128 v[172:175], v166 offset:17408
	ds_read_b128 v[176:179], v166 offset:18432
	ds_read_b128 v[180:183], v166 offset:19456
	ds_read_b128 v[184:187], v166 offset:20480
	ds_read_b128 v[188:191], v166 offset:21504
	ds_read_b128 v[192:195], v166 offset:22528
	ds_read_b128 v[198:201], v166 offset:23552
	global_load_lds_dwordx4 v[220:221], off
	v_lshl_add_u64 v[222:223], s[14:15], 0, v[146:147]
	s_mov_b32 m0, s24
	s_nop 0
	global_load_lds_dwordx4 v[222:223], off
	s_waitcnt vmcnt(10)
	s_barrier
	s_setprio 1
	s_waitcnt lgkmcnt(7)
	v_mfma_f32_16x16x32_bf16 v[76:79], v[40:43], v[168:171], v[76:79]
	v_mfma_f32_16x16x32_bf16 v[72:75], v[56:59], v[168:171], v[72:75]
	s_waitcnt lgkmcnt(5)
	v_mfma_f32_16x16x32_bf16 v[52:55], v[40:43], v[176:179], v[52:55]
	v_mfma_f32_16x16x32_bf16 v[48:51], v[56:59], v[176:179], v[48:51]
	s_waitcnt lgkmcnt(3)
	v_mfma_f32_16x16x32_bf16 v[28:31], v[40:43], v[184:187], v[28:31]
	v_mfma_f32_16x16x32_bf16 v[24:27], v[56:59], v[184:187], v[24:27]
	s_waitcnt lgkmcnt(1)
	v_mfma_f32_16x16x32_bf16 v[12:15], v[40:43], v[192:195], v[12:15]
	v_mfma_f32_16x16x32_bf16 v[8:11], v[56:59], v[192:195], v[8:11]
	v_mfma_f32_16x16x32_bf16 v[76:79], v[44:47], v[172:175], v[76:79]
	v_mfma_f32_16x16x32_bf16 v[72:75], v[60:63], v[172:175], v[72:75]
	v_mfma_f32_16x16x32_bf16 v[52:55], v[44:47], v[180:183], v[52:55]
	v_mfma_f32_16x16x32_bf16 v[48:51], v[60:63], v[180:183], v[48:51]
	v_mfma_f32_16x16x32_bf16 v[28:31], v[44:47], v[188:191], v[28:31]
	v_mfma_f32_16x16x32_bf16 v[24:27], v[60:63], v[188:191], v[24:27]
	s_waitcnt lgkmcnt(0)
	v_mfma_f32_16x16x32_bf16 v[12:15], v[44:47], v[198:201], v[12:15]
	v_mfma_f32_16x16x32_bf16 v[8:11], v[60:63], v[198:201], v[8:11]
	s_setprio 0
	s_barrier
	s_add_u32 s58, s12, 0x20000
	s_addc_u32 s59, s13, 0
	s_add_i32 s57, s36, s22
	s_mov_b32 m0, s57
	s_nop 0
	global_load_lds_dwordx4 v148, s[58:59]
	s_add_i32 m0, s57, 0x2000
	s_nop 0
	global_load_lds_dwordx4 v144, s[58:59]
	s_waitcnt vmcnt(6)
	s_barrier
; #define PG8_STAGE(bufoff, gbase, voff) do { _Pragma("unroll") for (int _i = 0; _i < 2; ++_i) \
;         __builtin_amdgcn_global_load_lds((const unsigned*)((const char*)(gbase) + (voff)[_i]), (LAS unsigned*)(lds + (bufoff) + ldsw + _i * 8192), 16, 0, 0); } while (0)
; #define PG8_LDA(dst, b, h) do { _Pragma("unroll") for (int m = 0; m < 4; ++m) _Pragma("unroll") for (int k = 0; k < 2; ++k) dst[m][k] = *(const LAS bf16x8*)(lds + PG8_SA(b, h) + aoff + m * 2048 + k * 1024); } while (0)
; #define PG8_LDB(dst, b, h) do { _Pragma("unroll") for (int n = 0; n < 2; ++n) _Pragma("unroll") for (int k = 0; k < 2; ++k) dst[n][k] = *(const LAS bf16x8*)(lds + PG8_SB(b, h) + boff + n * 2048 + k * 1024); } while (0)
; #define PG8_MMA(ai, bj, At, Bt) do { __builtin_amdgcn_s_setprio(1); _Pragma("unroll") for (int m = 0; m < 4; ++m) _Pragma("unroll") for (int n = 0; n < 2; ++n) _Pragma("unroll") for (int k = 0; k < 2; ++k) \
;         acc[ai][bj][m][n] = __builtin_amdgcn_mfma_f32_16x16x32_bf16(Bt[n][k], At[m][k], acc[ai][bj][m][n], 0, 0, 0); __builtin_amdgcn_s_setprio(0); } while (0)
; #define PG8_WAIT_V(n) asm volatile("s_waitcnt vmcnt(" #n ")" ::: "memory")
; #define PG8_WAIT_L(n) asm volatile("s_waitcnt lgkmcnt(" #n ")" ::: "memory")
; #define PG8_BAR __builtin_amdgcn_s_barrier()
; #define PG8_SCHED __builtin_amdgcn_sched_barrier(0)
; template <class Map, class Epi>
; DI void gemm_phase(LAS unsigned char* lds, const Map& MP, const Epi& E, const int nM, const int nN, const int K, const int lda, const int ldb) {
;     ...
;             PG8_WAIT_V(6); PG8_BAR; PG8_MMA(1, 1, At, B1); PG8_BAR;
;             PG8_LDB(B0, 1, 0); PG8_SCHED; PG8_LDA(At, 1, 0); PG8_STAGE(PG8_SA(0, 1), a2 + hstepA, voffA);
;             PG8_WAIT_L(8); PG8_BAR; PG8_WAIT_L(0); PG8_MMA(0, 0, At, B0); PG8_BAR; PG8_SCHED;
;             PG8_LDB(B1, 1, 1); PG8_STAGE(PG8_SB(1, 0), b3, voffB);
;             PG8_BAR; PG8_WAIT_L(0); PG8_MMA(0, 1, At, B1); PG8_BAR;
;             PG8_LDA(At, 1, 1); PG8_STAGE(PG8_SA(1, 0), a3, voffA);
;             PG8_BAR; PG8_WAIT_L(0); PG8_MMA(1, 0, At, B0); PG8_BAR; PG8_SCHED;
;             PG8_STAGE(PG8_SB(1, 1), b3 + hstepB, voffB);
	s_setprio 1
	v_mfma_f32_16x16x32_bf16 v[36:39], v[202:205], v[176:179], v[36:39]
	v_mfma_f32_16x16x32_bf16 v[32:35], v[210:213], v[176:179], v[32:35]
	v_mfma_f32_16x16x32_bf16 v[20:23], v[202:205], v[184:187], v[20:23]
	v_mfma_f32_16x16x32_bf16 v[16:19], v[210:213], v[184:187], v[16:19]
	v_mfma_f32_16x16x32_bf16 v[4:7], v[202:205], v[192:195], v[4:7]
	v_mfma_f32_16x16x32_bf16 v[0:3], v[210:213], v[192:195], v[0:3]
	v_mfma_f32_16x16x32_bf16 v[40:43], v[202:205], v[168:171], v[68:71]
	s_add_i32 s57, 0, 0x18000
	v_add_u32_e32 v68, s57, v164
	ds_read_b128 v[56:59], v68
	ds_read_b128 v[60:63], v68 offset:1024
	v_mfma_f32_16x16x32_bf16 v[44:47], v[210:213], v[168:171], v[64:67]
	ds_read_b128 v[64:67], v68 offset:2048
	ds_read_b128 v[68:71], v68 offset:3072
	v_mfma_f32_16x16x32_bf16 v[36:39], v[206:209], v[180:183], v[36:39]
	v_mfma_f32_16x16x32_bf16 v[32:35], v[214:217], v[180:183], v[32:35]
	v_mfma_f32_16x16x32_bf16 v[20:23], v[206:209], v[188:191], v[20:23]
	v_mfma_f32_16x16x32_bf16 v[16:19], v[214:217], v[188:191], v[16:19]
	v_mfma_f32_16x16x32_bf16 v[4:7], v[206:209], v[198:201], v[4:7]
	v_mfma_f32_16x16x32_bf16 v[0:3], v[214:217], v[198:201], v[0:3]
	v_mfma_f32_16x16x32_bf16 v[40:43], v[206:209], v[172:175], v[40:43]
	v_mfma_f32_16x16x32_bf16 v[44:47], v[214:217], v[172:175], v[44:47]
	s_setprio 0
	s_barrier
	ds_read_b128 v[168:171], v166 offset:32768
	ds_read_b128 v[172:175], v166 offset:33792
	ds_read_b128 v[176:179], v166 offset:34816
	ds_read_b128 v[180:183], v166 offset:35840
	ds_read_b128 v[184:187], v166 offset:36864
	ds_read_b128 v[188:191], v166 offset:37888
	ds_read_b128 v[192:195], v166 offset:38912
	ds_read_b128 v[198:201], v166 offset:39936
	s_add_u32 s14, s14, 0x80000
	s_addc_u32 s15, s15, 0
	s_mov_b32 m0, s25
	s_nop 0
	global_load_lds_dwordx4 v150, s[14:15]
	s_mov_b32 m0, s26
	s_nop 0
	global_load_lds_dwordx4 v146, s[14:15]
	s_waitcnt lgkmcnt(8)
	s_barrier
	s_setprio 1
	s_waitcnt lgkmcnt(7)
	v_mfma_f32_16x16x32_bf16 v[140:143], v[56:59], v[168:171], v[140:143]
	v_mfma_f32_16x16x32_bf16 v[136:139], v[64:67], v[168:171], v[136:139]
	s_waitcnt lgkmcnt(5)
	v_mfma_f32_16x16x32_bf16 v[124:127], v[56:59], v[176:179], v[124:127]
	v_mfma_f32_16x16x32_bf16 v[120:123], v[64:67], v[176:179], v[120:123]
	s_waitcnt lgkmcnt(3)
	v_mfma_f32_16x16x32_bf16 v[108:111], v[56:59], v[184:187], v[108:111]
	v_mfma_f32_16x16x32_bf16 v[104:107], v[64:67], v[184:187], v[104:107]
	s_waitcnt lgkmcnt(1)
	v_mfma_f32_16x16x32_bf16 v[92:95], v[56:59], v[192:195], v[92:95]
	v_mfma_f32_16x16x32_bf16 v[88:91], v[64:67], v[192:195], v[88:91]
	v_mfma_f32_16x16x32_bf16 v[140:143], v[60:63], v[172:175], v[140:143]
	v_mfma_f32_16x16x32_bf16 v[136:139], v[68:71], v[172:175], v[136:139]
	v_mfma_f32_16x16x32_bf16 v[124:127], v[60:63], v[180:183], v[124:127]
	v_mfma_f32_16x16x32_bf16 v[120:123], v[68:71], v[180:183], v[120:123]
	v_mfma_f32_16x16x32_bf16 v[108:111], v[60:63], v[188:191], v[108:111]
	v_mfma_f32_16x16x32_bf16 v[104:107], v[68:71], v[188:191], v[104:107]
	s_waitcnt lgkmcnt(0)
	v_mfma_f32_16x16x32_bf16 v[92:95], v[60:63], v[198:201], v[92:95]
	v_mfma_f32_16x16x32_bf16 v[88:91], v[68:71], v[198:201], v[88:91]
	s_setprio 0
	s_barrier
	s_add_i32 s14, 0, 0x1c000
	v_add_u32_e32 v196, s14, v164
	ds_read_b128 v[202:205], v196
	ds_read_b128 v[206:209], v196 offset:1024
	ds_read_b128 v[210:213], v196 offset:2048
	ds_read_b128 v[214:217], v196 offset:3072
	s_add_i32 s15, s57, s22
	v_lshl_add_u64 v[160:161], v[160:161], 0, s[46:47]
	s_mov_b32 m0, s15
	s_nop 0
	global_load_lds_dwordx4 v[160:161], off
	v_lshl_add_u64 v[160:161], v[218:219], 0, s[46:47]
	s_add_i32 m0, s15, 0x2000
	s_nop 0
	global_load_lds_dwordx4 v[160:161], off
	s_barrier
	s_setprio 1
	s_waitcnt lgkmcnt(3)
	v_mfma_f32_16x16x32_bf16 v[132:135], v[202:205], v[168:171], v[132:135]
	s_waitcnt lgkmcnt(1)
	v_mfma_f32_16x16x32_bf16 v[128:131], v[210:213], v[168:171], v[128:131]
	v_mfma_f32_16x16x32_bf16 v[116:119], v[202:205], v[176:179], v[116:119]
	v_mfma_f32_16x16x32_bf16 v[112:115], v[210:213], v[176:179], v[112:115]
	v_mfma_f32_16x16x32_bf16 v[100:103], v[202:205], v[184:187], v[100:103]
	v_mfma_f32_16x16x32_bf16 v[96:99], v[210:213], v[184:187], v[96:99]
	v_mfma_f32_16x16x32_bf16 v[84:87], v[202:205], v[192:195], v[84:87]
	v_mfma_f32_16x16x32_bf16 v[80:83], v[210:213], v[192:195], v[80:83]
	v_mfma_f32_16x16x32_bf16 v[132:135], v[206:209], v[172:175], v[132:135]
	s_mov_b32 m0, s30
	s_waitcnt lgkmcnt(0)
	v_mfma_f32_16x16x32_bf16 v[128:131], v[214:217], v[172:175], v[128:131]
	v_lshl_add_u64 v[160:161], v[220:221], 0, s[46:47]
	v_mfma_f32_16x16x32_bf16 v[116:119], v[206:209], v[180:183], v[116:119]
	v_mfma_f32_16x16x32_bf16 v[112:115], v[214:217], v[180:183], v[112:115]
	v_mfma_f32_16x16x32_bf16 v[100:103], v[206:209], v[188:191], v[100:103]
	v_mfma_f32_16x16x32_bf16 v[96:99], v[214:217], v[188:191], v[96:99]
	v_mfma_f32_16x16x32_bf16 v[84:87], v[206:209], v[198:201], v[84:87]
	v_mfma_f32_16x16x32_bf16 v[80:83], v[214:217], v[198:201], v[80:83]
	s_setprio 0
	s_barrier
	ds_read_b128 v[168:171], v166 offset:49152
	ds_read_b128 v[172:175], v166 offset:50176
	ds_read_b128 v[176:179], v166 offset:51200
	ds_read_b128 v[180:183], v166 offset:52224
	ds_read_b128 v[184:187], v166 offset:53248
	ds_read_b128 v[188:191], v166 offset:54272
	ds_read_b128 v[192:195], v166 offset:55296
	ds_read_b128 v[198:201], v166 offset:56320
	global_load_lds_dwordx4 v[160:161], off
	v_lshl_add_u64 v[160:161], v[222:223], 0, s[46:47]
	s_mov_b32 m0, s31
	s_nop 0
	global_load_lds_dwordx4 v[160:161], off
	s_waitcnt vmcnt(10)
	s_barrier
; DI unsigned pack2(float a, float b) { f32x2 v = {a, b}; hwbf16x2 r = __builtin_convertvector(v, hwbf16x2); return __builtin_bit_cast(unsigned, r); }
; DI float bflo(unsigned w) { return __uint_as_float(w << 16); }
; #define PG8_BAR __builtin_amdgcn_s_barrier()
;     DI void operator()(const f32x4 (&acc)[2][2][4][2], const Unit& u, int wr, int wc, int fr, int fq) const {
;         const int row0 = u.pm * BM + wr * 64 + fr, col0 = u.pn * BM + wc * 32 + 8 * fq;
;         f32x4 sc[2][2];
; #pragma unroll
;         for (int bj = 0; bj < 2; ++bj)
; #pragma unroll
;             for (int n = 0; n < 2; ++n) sc[bj][n] = scale ? *(const f32x4*)(scale + col0 + bj * HALF + 4 * n) : (f32x4){1.f, 1.f, 1.f, 1.f};
; #pragma unroll
;         for (int ai = 0; ai < 2; ++ai)
; #pragma unroll
;             for (int m = 0; m < 4; ++m) { const size_t ro = (size_t)(row0 + ai * HALF + m * 16) * D + col0;
; #pragma unroll
;                 for (int bj = 0; bj < 2; ++bj) {
;                     f32x4 x0, x1;
;                     if constexpr (IB) { const u32x4 w = *(const u32x4*)((const bf16_t*)Xin + ro + bj * HALF);
;                         x0 = (f32x4){bflo(w[0]), bfhi(w[0]), bflo(w[1]), bfhi(w[1])}; x1 = (f32x4){bflo(w[2]), bfhi(w[2]), bflo(w[3]), bfhi(w[3])}; }
;                     else { x0 = *(const f32x4*)((const float*)Xin + ro + bj * HALF); x1 = *(const f32x4*)((const float*)Xin + ro + bj * HALF + 4); }
;                     x0 += acc[ai][bj][m][0] * sc[bj][0]; x1 += acc[ai][bj][m][1] * sc[bj][1];
;                     if constexpr (OB) { u32x4 o; o[0] = pack2(x0[0], x0[1]); o[1] = pack2(x0[2], x0[3]); o[2] = pack2(x1[0], x1[1]); o[3] = pack2(x1[2], x1[3]);
;                         *(u32x4*)((bf16_t*)Xout + ro + bj * HALF) = o; }
;                     else { *(f32x4*)((float*)Xout + ro + bj * HALF) = x0; *(f32x4*)((float*)Xout + ro + bj * HALF + 4) = x1; } } }
; template <class Map, class Epi>
; DI void gemm_phase(LAS unsigned char* lds, const Map& MP, const Epi& E, const int nM, const int nN, const int K, const int lda, const int ldb) {
;     ...
;             PG8_BAR; PG8_WAIT_L(0); PG8_MMA(1, 0, At, B0); PG8_BAR; PG8_SCHED;
;             PG8_STAGE(PG8_SB(1, 1), b3 + hstepB, voffB);
;             PG8_WAIT_V(6); PG8_BAR; PG8_MMA(1, 1, At, B1); PG8_BAR;
;         }
;         { int frr = fr, fqq = fq; asm volatile("" : "+v"(frr), "+v"(fqq)); E(acc, cur, wr, wc, frr, fqq); }
	s_setprio 1
	s_waitcnt lgkmcnt(7)
	v_mfma_f32_16x16x32_bf16 v[76:79], v[56:59], v[168:171], v[76:79]
	v_mfma_f32_16x16x32_bf16 v[72:75], v[64:67], v[168:171], v[72:75]
	s_waitcnt lgkmcnt(5)
	v_mfma_f32_16x16x32_bf16 v[52:55], v[56:59], v[176:179], v[52:55]
	v_mfma_f32_16x16x32_bf16 v[48:51], v[64:67], v[176:179], v[48:51]
	s_waitcnt lgkmcnt(3)
	v_mfma_f32_16x16x32_bf16 v[28:31], v[56:59], v[184:187], v[28:31]
	v_mfma_f32_16x16x32_bf16 v[24:27], v[64:67], v[184:187], v[24:27]
	s_waitcnt lgkmcnt(1)
	v_mfma_f32_16x16x32_bf16 v[12:15], v[56:59], v[192:195], v[12:15]
	v_mfma_f32_16x16x32_bf16 v[8:11], v[64:67], v[192:195], v[8:11]
	v_mfma_f32_16x16x32_bf16 v[76:79], v[60:63], v[172:175], v[76:79]
	v_mfma_f32_16x16x32_bf16 v[72:75], v[68:71], v[172:175], v[72:75]
	v_mfma_f32_16x16x32_bf16 v[52:55], v[60:63], v[180:183], v[52:55]
	v_mfma_f32_16x16x32_bf16 v[48:51], v[68:71], v[180:183], v[48:51]
	v_mfma_f32_16x16x32_bf16 v[28:31], v[60:63], v[188:191], v[28:31]
	v_mfma_f32_16x16x32_bf16 v[24:27], v[68:71], v[188:191], v[24:27]
	s_waitcnt lgkmcnt(0)
	v_mfma_f32_16x16x32_bf16 v[12:15], v[60:63], v[198:201], v[12:15]
	v_mfma_f32_16x16x32_bf16 v[8:11], v[68:71], v[198:201], v[8:11]
	s_setprio 0
	s_barrier
	s_add_u32 s12, s12, 0x20080
	s_addc_u32 s13, s13, 0
	s_add_i32 s14, s14, s22
	s_mov_b32 m0, s14
	s_nop 0
	global_load_lds_dwordx4 v148, s[12:13]
	s_add_i32 m0, s14, 0x2000
	s_nop 0
	global_load_lds_dwordx4 v144, s[12:13]
	s_waitcnt vmcnt(6)
	s_barrier
	s_setprio 1
	v_mfma_f32_16x16x32_bf16 v[40:43], v[202:205], v[168:171], v[40:43]
	v_mfma_f32_16x16x32_bf16 v[68:71], v[206:209], v[172:175], v[40:43]
	v_mfma_f32_16x16x32_bf16 v[40:43], v[210:213], v[168:171], v[44:47]
	v_mfma_f32_16x16x32_bf16 v[36:39], v[202:205], v[176:179], v[36:39]
	v_mfma_f32_16x16x32_bf16 v[32:35], v[210:213], v[176:179], v[32:35]
	v_mfma_f32_16x16x32_bf16 v[20:23], v[202:205], v[184:187], v[20:23]
	v_mfma_f32_16x16x32_bf16 v[16:19], v[210:213], v[184:187], v[16:19]
	v_mfma_f32_16x16x32_bf16 v[4:7], v[202:205], v[192:195], v[4:7]
	v_mfma_f32_16x16x32_bf16 v[0:3], v[210:213], v[192:195], v[0:3]
	s_add_i32 s3, s3, 2
	v_mfma_f32_16x16x32_bf16 v[64:67], v[214:217], v[172:175], v[40:43]
	s_add_u32 s53, s53, 0x100
	s_addc_u32 s56, s56, 0
	ds_read_b128 v[40:43], v165
	ds_read_b128 v[44:47], v165 offset:1024
	ds_read_b128 v[56:59], v165 offset:2048
	ds_read_b128 v[60:63], v165 offset:3072
	v_mfma_f32_16x16x32_bf16 v[36:39], v[206:209], v[180:183], v[36:39]
	s_add_u32 s10, s10, 0x100
	s_addc_u32 s11, s11, 0
	v_mfma_f32_16x16x32_bf16 v[32:35], v[214:217], v[180:183], v[32:35]
	s_cmp_gt_u32 s3, 5
	v_mfma_f32_16x16x32_bf16 v[20:23], v[206:209], v[188:191], v[20:23]
	v_mfma_f32_16x16x32_bf16 v[16:19], v[214:217], v[188:191], v[16:19]
	v_mfma_f32_16x16x32_bf16 v[4:7], v[206:209], v[198:201], v[4:7]
	v_mfma_f32_16x16x32_bf16 v[0:3], v[214:217], v[198:201], v[0:3]
	s_setprio 0
	s_barrier
	s_cbranch_scc0 .LBB1_2339
	s_waitcnt lgkmcnt(0)
	s_lshl_b32 s2, s2, 8
	v_mov_b32_e32 v40, v163
	v_mov_b32_e32 v168, v162
	s_or_b32 s2, s2, s29
	s_and_b64 vcc, exec, s[40:41]
	v_lshl_add_u32 v160, v40, 3, s2
	s_lshl_b32 s2, s8, 8
	s_add_i32 s2, s2, s28
	v_add_u32_e32 v168, s2, v168
	v_ashrrev_i32_e32 v169, 31, v168
	v_ashrrev_i32_e32 v161, 31, v160
	v_lshlrev_b64 v[168:169], 11, v[168:169]
	v_lshl_add_u64 v[44:45], v[160:161], 2, s[44:45]
	v_lshl_add_u64 v[160:161], v[168:169], 0, v[160:161]
	v_lshlrev_b64 v[160:161], 1, v[160:161]
	v_lshl_add_u64 v[172:173], s[4:5], 0, v[160:161]
	global_load_dwordx4 v[56:59], v[44:45], off offset:16
	global_load_dwordx4 v[60:63], v[44:45], off
	global_load_dwordx4 v[40:43], v[44:45], off offset:528
	s_nop 0
	global_load_dwordx4 v[44:47], v[44:45], off offset:512
	s_mov_b64 s[2:3], 0x10000
	global_load_dwordx4 v[178:181], v[172:173], off
	global_load_dwordx4 v[182:185], v[172:173], off offset:256
	s_mov_b64 s[98:99], 0x10000
	v_lshl_add_u64 v[170:171], v[172:173], 0, s[98:99]
	global_load_dwordx4 v[186:189], v[170:171], off
	global_load_dwordx4 v[190:193], v[170:171], off offset:256
	s_mov_b64 s[98:99], 0x20000
	v_lshl_add_u64 v[170:171], v[172:173], 0, s[98:99]
	global_load_dwordx4 v[198:201], v[170:171], off
	global_load_dwordx4 v[202:205], v[170:171], off offset:256
	s_mov_b64 s[98:99], 0x30000
	v_lshl_add_u64 v[170:171], v[172:173], 0, s[98:99]
	global_load_dwordx4 v[206:209], v[170:171], off
	global_load_dwordx4 v[210:213], v[170:171], off offset:256
	s_mov_b64 s[98:99], 0x80000
	v_lshl_add_u64 v[170:171], v[172:173], 0, s[98:99]
	global_load_dwordx4 v[214:217], v[170:171], off
	global_load_dwordx4 v[248:251], v[170:171], off offset:256
	s_mov_b64 s[98:99], 0x90000
	v_lshl_add_u64 v[170:171], v[172:173], 0, s[98:99]
	global_load_dwordx4 v[252:255], v[170:171], off
	s_waitcnt vmcnt(10)
	s_nop 1
	v_mov_b32_e32 v168, v178
	v_mov_b32_e32 v169, v179
	v_mov_b32_e32 v170, v180
	v_mov_b32_e32 v171, v181
	s_mov_b32 s8, s52
	s_mov_b64 s[10:11], s[54:55]
	s_mov_b64 s[12:13], s[6:7]
	s_waitcnt lgkmcnt(0)
	v_lshlrev_b32_e32 v174, 16, v168
	v_and_b32_e32 v175, 0xffff0000, v168
	v_lshlrev_b32_e32 v168, 16, v169
	v_and_b32_e32 v169, 0xffff0000, v169
	v_lshlrev_b32_e32 v176, 16, v170
	v_and_b32_e32 v177, 0xffff0000, v170
	v_lshlrev_b32_e32 v170, 16, v171
	v_and_b32_e32 v171, 0xffff0000, v171
	v_pk_fma_f32 v[142:143], v[142:143], v[62:63], v[168:169]
	v_pk_fma_f32 v[140:141], v[140:141], v[60:61], v[174:175]
	v_pk_fma_f32 v[168:169], v[138:139], v[58:59], v[170:171]
	v_pk_fma_f32 v[138:139], v[136:137], v[56:57], v[176:177]
	v_cvt_pk_bf16_f32 v136, v140, v141
	v_cvt_pk_bf16_f32 v137, v142, v143
	v_cvt_pk_bf16_f32 v138, v138, v139
	v_cvt_pk_bf16_f32 v139, v168, v169
	v_lshl_add_u64 v[140:141], s[42:43], 0, v[160:161]
	global_store_dwordx4 v[140:141], v[136:139], off
	s_waitcnt vmcnt(10)
; DI unsigned pack2(float a, float b) { f32x2 v = {a, b}; hwbf16x2 r = __builtin_convertvector(v, hwbf16x2); return __builtin_bit_cast(unsigned, r); }
; DI float bflo(unsigned w) { return __uint_as_float(w << 16); }
; DI float bfhi(unsigned w) { return __uint_as_float(w & 0xffff0000u); }
;     DI void operator()(const f32x4 (&acc)[2][2][4][2], const Unit& u, int wr, int wc, int fr, int fq) const {
;     ...
;         for (int ai = 0; ai < 2; ++ai)
; #pragma unroll
;             for (int m = 0; m < 4; ++m) { const size_t ro = (size_t)(row0 + ai * HALF + m * 16) * D + col0;
; #pragma unroll
;                 for (int bj = 0; bj < 2; ++bj) {
;                     f32x4 x0, x1;
;                     if constexpr (IB) { const u32x4 w = *(const u32x4*)((const bf16_t*)Xin + ro + bj * HALF);
;                         x0 = (f32x4){bflo(w[0]), bfhi(w[0]), bflo(w[1]), bfhi(w[1])}; x1 = (f32x4){bflo(w[2]), bfhi(w[2]), bflo(w[3]), bfhi(w[3])}; }
;                     else { x0 = *(const f32x4*)((const float*)Xin + ro + bj * HALF); x1 = *(const f32x4*)((const float*)Xin + ro + bj * HALF + 4); }
;                     x0 += acc[ai][bj][m][0] * sc[bj][0]; x1 += acc[ai][bj][m][1] * sc[bj][1];
;                     if constexpr (OB) { u32x4 o; o[0] = pack2(x0[0], x0[1]); o[1] = pack2(x0[2], x0[3]); o[2] = pack2(x1[0], x1[1]); o[3] = pack2(x1[2], x1[3]);
;                         *(u32x4*)((bf16_t*)Xout + ro + bj * HALF) = o; }
;                     else { *(f32x4*)((float*)Xout + ro + bj * HALF) = x0; *(f32x4*)((float*)Xout + ro + bj * HALF + 4) = x1; } } }
	s_nop 1
	v_mov_b32_e32 v136, v182
	v_mov_b32_e32 v137, v183
	v_mov_b32_e32 v138, v184
	v_mov_b32_e32 v139, v185
	s_waitcnt lgkmcnt(0)
	v_lshlrev_b32_e32 v142, 16, v136
	v_and_b32_e32 v143, 0xffff0000, v136
	v_lshlrev_b32_e32 v136, 16, v137
	v_and_b32_e32 v137, 0xffff0000, v137
	v_lshlrev_b32_e32 v168, 16, v138
	v_and_b32_e32 v169, 0xffff0000, v138
	v_lshlrev_b32_e32 v138, 16, v139
	v_and_b32_e32 v139, 0xffff0000, v139
	v_pk_fma_f32 v[134:135], v[134:135], v[46:47], v[136:137]
	v_pk_fma_f32 v[132:133], v[132:133], v[44:45], v[142:143]
	v_pk_fma_f32 v[136:137], v[130:131], v[42:43], v[138:139]
	v_pk_fma_f32 v[130:131], v[128:129], v[40:41], v[168:169]
	v_cvt_pk_bf16_f32 v128, v132, v133
	v_cvt_pk_bf16_f32 v129, v134, v135
	v_cvt_pk_bf16_f32 v130, v130, v131
	v_cvt_pk_bf16_f32 v131, v136, v137
	v_lshl_add_u64 v[132:133], v[160:161], 0, s[2:3]
	global_store_dwordx4 v[140:141], v[128:131], off offset:256
	v_lshl_add_u64 v[134:135], s[4:5], 0, v[132:133]
	s_waitcnt vmcnt(10)
	s_nop 1
	v_mov_b32_e32 v128, v186
	v_mov_b32_e32 v129, v187
	v_mov_b32_e32 v130, v188
	v_mov_b32_e32 v131, v189
	s_mov_b64 s[2:3], 0x20000
	s_waitcnt lgkmcnt(0)
	v_lshlrev_b32_e32 v136, 16, v128
	v_and_b32_e32 v137, 0xffff0000, v128
	v_lshlrev_b32_e32 v128, 16, v129
	v_and_b32_e32 v129, 0xffff0000, v129
	v_lshlrev_b32_e32 v138, 16, v130
	v_and_b32_e32 v139, 0xffff0000, v130
	v_lshlrev_b32_e32 v130, 16, v131
	v_and_b32_e32 v131, 0xffff0000, v131
	v_pk_fma_f32 v[126:127], v[126:127], v[62:63], v[128:129]
	v_pk_fma_f32 v[124:125], v[124:125], v[60:61], v[136:137]
	v_pk_fma_f32 v[128:129], v[122:123], v[58:59], v[130:131]
	v_pk_fma_f32 v[122:123], v[120:121], v[56:57], v[138:139]
	v_cvt_pk_bf16_f32 v120, v124, v125
	v_cvt_pk_bf16_f32 v121, v126, v127
	v_cvt_pk_bf16_f32 v122, v122, v123
	v_cvt_pk_bf16_f32 v123, v128, v129
	v_lshl_add_u64 v[124:125], s[42:43], 0, v[132:133]
	global_store_dwordx4 v[124:125], v[120:123], off
	s_waitcnt vmcnt(10)
	s_nop 1
	v_mov_b32_e32 v120, v190
	v_mov_b32_e32 v121, v191
	v_mov_b32_e32 v122, v192
	v_mov_b32_e32 v123, v193
	s_waitcnt lgkmcnt(0)
	v_lshlrev_b32_e32 v126, 16, v120
	v_and_b32_e32 v127, 0xffff0000, v120
	v_lshlrev_b32_e32 v120, 16, v121
	v_and_b32_e32 v121, 0xffff0000, v121
	v_lshlrev_b32_e32 v128, 16, v122
	v_and_b32_e32 v129, 0xffff0000, v122
	v_lshlrev_b32_e32 v122, 16, v123
	v_and_b32_e32 v123, 0xffff0000, v123
	v_pk_fma_f32 v[118:119], v[118:119], v[46:47], v[120:121]
	v_pk_fma_f32 v[116:117], v[116:117], v[44:45], v[126:127]
	v_pk_fma_f32 v[120:121], v[114:115], v[42:43], v[122:123]
	v_pk_fma_f32 v[114:115], v[112:113], v[40:41], v[128:129]
	v_cvt_pk_bf16_f32 v112, v116, v117
	v_cvt_pk_bf16_f32 v113, v118, v119
	v_cvt_pk_bf16_f32 v114, v114, v115
	v_cvt_pk_bf16_f32 v115, v120, v121
	v_lshl_add_u64 v[116:117], v[160:161], 0, s[2:3]
	global_store_dwordx4 v[124:125], v[112:115], off offset:256
	v_lshl_add_u64 v[118:119], s[4:5], 0, v[116:117]
	s_waitcnt vmcnt(10)
	s_nop 1
	v_mov_b32_e32 v112, v198
	v_mov_b32_e32 v113, v199
	v_mov_b32_e32 v114, v200
	v_mov_b32_e32 v115, v201
	s_mov_b64 s[2:3], 0x30000
	s_waitcnt lgkmcnt(0)
	v_lshlrev_b32_e32 v120, 16, v112
	v_and_b32_e32 v121, 0xffff0000, v112
	v_lshlrev_b32_e32 v112, 16, v113
	v_and_b32_e32 v113, 0xffff0000, v113
	v_lshlrev_b32_e32 v122, 16, v114
	v_and_b32_e32 v123, 0xffff0000, v114
	v_lshlrev_b32_e32 v114, 16, v115
	v_and_b32_e32 v115, 0xffff0000, v115
	v_pk_fma_f32 v[110:111], v[110:111], v[62:63], v[112:113]
	v_pk_fma_f32 v[108:109], v[108:109], v[60:61], v[120:121]
	v_pk_fma_f32 v[112:113], v[106:107], v[58:59], v[114:115]
	v_pk_fma_f32 v[106:107], v[104:105], v[56:57], v[122:123]
	v_cvt_pk_bf16_f32 v104, v108, v109
	v_cvt_pk_bf16_f32 v105, v110, v111
	v_cvt_pk_bf16_f32 v106, v106, v107
	v_cvt_pk_bf16_f32 v107, v112, v113
	v_lshl_add_u64 v[108:109], s[42:43], 0, v[116:117]
	global_store_dwordx4 v[108:109], v[104:107], off
	s_waitcnt vmcnt(10)
	s_nop 1
	v_mov_b32_e32 v104, v202
	v_mov_b32_e32 v105, v203
	v_mov_b32_e32 v106, v204
	v_mov_b32_e32 v107, v205
	s_waitcnt lgkmcnt(0)
	v_lshlrev_b32_e32 v110, 16, v104
	v_and_b32_e32 v111, 0xffff0000, v104
	v_lshlrev_b32_e32 v104, 16, v105
	v_and_b32_e32 v105, 0xffff0000, v105
	v_lshlrev_b32_e32 v112, 16, v106
	v_and_b32_e32 v113, 0xffff0000, v106
	v_lshlrev_b32_e32 v106, 16, v107
	v_and_b32_e32 v107, 0xffff0000, v107
	v_pk_fma_f32 v[102:103], v[102:103], v[46:47], v[104:105]
	v_pk_fma_f32 v[100:101], v[100:101], v[44:45], v[110:111]
	v_pk_fma_f32 v[104:105], v[98:99], v[42:43], v[106:107]
	v_pk_fma_f32 v[98:99], v[96:97], v[40:41], v[112:113]
	v_cvt_pk_bf16_f32 v96, v100, v101
	v_cvt_pk_bf16_f32 v97, v102, v103
	v_cvt_pk_bf16_f32 v98, v98, v99
	v_cvt_pk_bf16_f32 v99, v104, v105
	v_lshl_add_u64 v[100:101], v[160:161], 0, s[2:3]
	global_store_dwordx4 v[108:109], v[96:99], off offset:256
	v_lshl_add_u64 v[102:103], s[4:5], 0, v[100:101]
	s_waitcnt vmcnt(10)
	s_nop 1
	v_mov_b32_e32 v96, v206
	v_mov_b32_e32 v97, v207
	v_mov_b32_e32 v98, v208
	v_mov_b32_e32 v99, v209
	s_mov_b64 s[2:3], 0x80000
	s_waitcnt lgkmcnt(0)
	v_lshlrev_b32_e32 v104, 16, v96
	v_and_b32_e32 v105, 0xffff0000, v96
	v_lshlrev_b32_e32 v96, 16, v97
	v_and_b32_e32 v97, 0xffff0000, v97
	v_lshlrev_b32_e32 v106, 16, v98
	v_and_b32_e32 v107, 0xffff0000, v98
	v_lshlrev_b32_e32 v98, 16, v99
	v_and_b32_e32 v99, 0xffff0000, v99
	v_pk_fma_f32 v[94:95], v[94:95], v[62:63], v[96:97]
	v_pk_fma_f32 v[92:93], v[92:93], v[60:61], v[104:105]
	v_pk_fma_f32 v[96:97], v[90:91], v[58:59], v[98:99]
	v_pk_fma_f32 v[90:91], v[88:89], v[56:57], v[106:107]
	v_cvt_pk_bf16_f32 v88, v92, v93
	v_cvt_pk_bf16_f32 v89, v94, v95
	v_cvt_pk_bf16_f32 v90, v90, v91
	v_cvt_pk_bf16_f32 v91, v96, v97
	v_lshl_add_u64 v[92:93], s[42:43], 0, v[100:101]
	global_store_dwordx4 v[92:93], v[88:91], off
	s_waitcnt vmcnt(10)
; DI unsigned pack2(float a, float b) { f32x2 v = {a, b}; hwbf16x2 r = __builtin_convertvector(v, hwbf16x2); return __builtin_bit_cast(unsigned, r); }
; DI float bflo(unsigned w) { return __uint_as_float(w << 16); }
; DI float bfhi(unsigned w) { return __uint_as_float(w & 0xffff0000u); }
;     DI void operator()(const f32x4 (&acc)[2][2][4][2], const Unit& u, int wr, int wc, int fr, int fq) const {
;     ...
;         for (int ai = 0; ai < 2; ++ai)
; #pragma unroll
;             for (int m = 0; m < 4; ++m) { const size_t ro = (size_t)(row0 + ai * HALF + m * 16) * D + col0;
; #pragma unroll
;                 for (int bj = 0; bj < 2; ++bj) {
;                     f32x4 x0, x1;
;                     if constexpr (IB) { const u32x4 w = *(const u32x4*)((const bf16_t*)Xin + ro + bj * HALF);
;                         x0 = (f32x4){bflo(w[0]), bfhi(w[0]), bflo(w[1]), bfhi(w[1])}; x1 = (f32x4){bflo(w[2]), bfhi(w[2]), bflo(w[3]), bfhi(w[3])}; }
;                     else { x0 = *(const f32x4*)((const float*)Xin + ro + bj * HALF); x1 = *(const f32x4*)((const float*)Xin + ro + bj * HALF + 4); }
;                     x0 += acc[ai][bj][m][0] * sc[bj][0]; x1 += acc[ai][bj][m][1] * sc[bj][1];
;                     if constexpr (OB) { u32x4 o; o[0] = pack2(x0[0], x0[1]); o[1] = pack2(x0[2], x0[3]); o[2] = pack2(x1[0], x1[1]); o[3] = pack2(x1[2], x1[3]);
;                         *(u32x4*)((bf16_t*)Xout + ro + bj * HALF) = o; }
;                     else { *(f32x4*)((float*)Xout + ro + bj * HALF) = x0; *(f32x4*)((float*)Xout + ro + bj * HALF + 4) = x1; } } }
	s_nop 1
	v_mov_b32_e32 v88, v210
	v_mov_b32_e32 v89, v211
	v_mov_b32_e32 v90, v212
	v_mov_b32_e32 v91, v213
	s_waitcnt lgkmcnt(0)
	v_lshlrev_b32_e32 v94, 16, v88
	v_and_b32_e32 v95, 0xffff0000, v88
	v_lshlrev_b32_e32 v88, 16, v89
	v_and_b32_e32 v89, 0xffff0000, v89
	v_lshlrev_b32_e32 v96, 16, v90
	v_and_b32_e32 v97, 0xffff0000, v90
	v_lshlrev_b32_e32 v90, 16, v91
	v_and_b32_e32 v91, 0xffff0000, v91
	v_pk_fma_f32 v[86:87], v[86:87], v[46:47], v[88:89]
	v_pk_fma_f32 v[84:85], v[84:85], v[44:45], v[94:95]
	v_pk_fma_f32 v[88:89], v[82:83], v[42:43], v[90:91]
	v_pk_fma_f32 v[82:83], v[80:81], v[40:41], v[96:97]
	v_cvt_pk_bf16_f32 v80, v84, v85
	v_cvt_pk_bf16_f32 v81, v86, v87
	v_cvt_pk_bf16_f32 v82, v82, v83
	v_cvt_pk_bf16_f32 v83, v88, v89
	v_lshl_add_u64 v[84:85], v[160:161], 0, s[2:3]
	global_store_dwordx4 v[92:93], v[80:83], off offset:256
	v_lshl_add_u64 v[86:87], s[4:5], 0, v[84:85]
	s_waitcnt vmcnt(10)
	s_nop 1
	v_mov_b32_e32 v80, v214
	v_mov_b32_e32 v81, v215
	v_mov_b32_e32 v82, v216
	v_mov_b32_e32 v83, v217
	s_mov_b64 s[2:3], 0x90000
	s_waitcnt lgkmcnt(0)
	v_lshlrev_b32_e32 v88, 16, v80
	v_and_b32_e32 v89, 0xffff0000, v80
	v_lshlrev_b32_e32 v80, 16, v81
	v_and_b32_e32 v81, 0xffff0000, v81
	v_lshlrev_b32_e32 v90, 16, v82
	v_and_b32_e32 v91, 0xffff0000, v82
	v_lshlrev_b32_e32 v82, 16, v83
	v_and_b32_e32 v83, 0xffff0000, v83
	v_pk_fma_f32 v[78:79], v[78:79], v[62:63], v[80:81]
	v_pk_fma_f32 v[76:77], v[76:77], v[60:61], v[88:89]
	v_pk_fma_f32 v[80:81], v[74:75], v[58:59], v[82:83]
	v_pk_fma_f32 v[74:75], v[72:73], v[56:57], v[90:91]
	v_cvt_pk_bf16_f32 v72, v76, v77
	v_cvt_pk_bf16_f32 v73, v78, v79
	v_cvt_pk_bf16_f32 v74, v74, v75
	v_cvt_pk_bf16_f32 v75, v80, v81
	v_lshl_add_u64 v[76:77], s[42:43], 0, v[84:85]
	global_store_dwordx4 v[76:77], v[72:75], off
	s_waitcnt vmcnt(10)
	s_nop 1
	v_mov_b32_e32 v72, v248
	v_mov_b32_e32 v73, v249
	v_mov_b32_e32 v74, v250
	v_mov_b32_e32 v75, v251
	s_waitcnt lgkmcnt(0)
	v_lshlrev_b32_e32 v78, 16, v72
	v_and_b32_e32 v79, 0xffff0000, v72
	v_lshlrev_b32_e32 v72, 16, v73
	v_and_b32_e32 v73, 0xffff0000, v73
	v_lshlrev_b32_e32 v80, 16, v74
	v_and_b32_e32 v81, 0xffff0000, v74
	v_lshlrev_b32_e32 v74, 16, v75
	v_and_b32_e32 v75, 0xffff0000, v75
	v_pk_fma_f32 v[70:71], v[70:71], v[46:47], v[72:73]
	v_pk_fma_f32 v[68:69], v[68:69], v[44:45], v[78:79]
	v_pk_fma_f32 v[72:73], v[66:67], v[42:43], v[74:75]
	v_pk_fma_f32 v[66:67], v[64:65], v[40:41], v[80:81]
	v_cvt_pk_bf16_f32 v64, v68, v69
	v_cvt_pk_bf16_f32 v65, v70, v71
	v_cvt_pk_bf16_f32 v66, v66, v67
	v_cvt_pk_bf16_f32 v67, v72, v73
	v_lshl_add_u64 v[68:69], v[160:161], 0, s[2:3]
	global_store_dwordx4 v[76:77], v[64:67], off offset:256
	v_lshl_add_u64 v[70:71], s[4:5], 0, v[68:69]
	s_waitcnt vmcnt(10)
	s_nop 1
	v_mov_b32_e32 v64, v252
	v_mov_b32_e32 v65, v253
	v_mov_b32_e32 v66, v254
	v_mov_b32_e32 v67, v255
	s_mov_b64 s[2:3], 0xa0000
	s_waitcnt lgkmcnt(0)
	v_lshlrev_b32_e32 v72, 16, v64
	v_and_b32_e32 v73, 0xffff0000, v64
	v_lshlrev_b32_e32 v64, 16, v65
	v_and_b32_e32 v65, 0xffff0000, v65
	v_lshlrev_b32_e32 v74, 16, v66
	v_and_b32_e32 v75, 0xffff0000, v66
	v_lshlrev_b32_e32 v66, 16, v67
	v_and_b32_e32 v67, 0xffff0000, v67
	v_pk_fma_f32 v[54:55], v[54:55], v[62:63], v[64:65]
	v_pk_fma_f32 v[52:53], v[52:53], v[60:61], v[72:73]
	v_pk_fma_f32 v[64:65], v[50:51], v[58:59], v[66:67]
	v_pk_fma_f32 v[50:51], v[48:49], v[56:57], v[74:75]
	v_cvt_pk_bf16_f32 v48, v52, v53
	v_cvt_pk_bf16_f32 v49, v54, v55
	v_cvt_pk_bf16_f32 v50, v50, v51
	v_cvt_pk_bf16_f32 v51, v64, v65
	v_lshl_add_u64 v[52:53], s[42:43], 0, v[68:69]
	global_store_dwordx4 v[52:53], v[48:51], off
	global_load_dwordx4 v[48:51], v[70:71], off offset:256
	s_waitcnt vmcnt(0) lgkmcnt(0)
; DI unsigned pack2(float a, float b) { f32x2 v = {a, b}; hwbf16x2 r = __builtin_convertvector(v, hwbf16x2); return __builtin_bit_cast(unsigned, r); }
; DI float bflo(unsigned w) { return __uint_as_float(w << 16); }
; DI float bfhi(unsigned w) { return __uint_as_float(w & 0xffff0000u); }
;     DI const char* a(const Unit& u) const { return (const char*)(A + (size_t)u.pm * BM * lda); }
;     DI const char* a(const Unit& u) const { return (const char*)(A + (size_t)u.pm * BM * 2048 + (u.pn >> 1) * 512); }
;     DI void operator()(const f32x4 (&acc)[2][2][4][2], const Unit& u, int wr, int wc, int fr, int fq) const {
;     ...
;         for (int ai = 0; ai < 2; ++ai)
; #pragma unroll
;             for (int m = 0; m < 4; ++m) { const size_t ro = (size_t)(row0 + ai * HALF + m * 16) * D + col0;
; #pragma unroll
;                 for (int bj = 0; bj < 2; ++bj) {
;                     f32x4 x0, x1;
;                     if constexpr (IB) { const u32x4 w = *(const u32x4*)((const bf16_t*)Xin + ro + bj * HALF);
;                         x0 = (f32x4){bflo(w[0]), bfhi(w[0]), bflo(w[1]), bfhi(w[1])}; x1 = (f32x4){bflo(w[2]), bfhi(w[2]), bflo(w[3]), bfhi(w[3])}; }
;                     else { x0 = *(const f32x4*)((const float*)Xin + ro + bj * HALF); x1 = *(const f32x4*)((const float*)Xin + ro + bj * HALF + 4); }
;                     x0 += acc[ai][bj][m][0] * sc[bj][0]; x1 += acc[ai][bj][m][1] * sc[bj][1];
;                     if constexpr (OB) { u32x4 o; o[0] = pack2(x0[0], x0[1]); o[1] = pack2(x0[2], x0[3]); o[2] = pack2(x1[0], x1[1]); o[3] = pack2(x1[2], x1[3]);
;                         *(u32x4*)((bf16_t*)Xout + ro + bj * HALF) = o; }
;                     else { *(f32x4*)((float*)Xout + ro + bj * HALF) = x0; *(f32x4*)((float*)Xout + ro + bj * HALF + 4) = x1; } } }
; template <class Map, class Epi>
; DI void gemm_phase(LAS unsigned char* lds, const Map& MP, const Epi& E, const int nM, const int nN, const int K, const int lda, const int ldb) {
;     ...
;         if (!has_next) break;
; #pragma unroll
;         for (int a = 0; a < 2; ++a)
; #pragma unroll
;             for (int b = 0; b < 2; ++b)
; #pragma unroll
;                 for (int m = 0; m < 4; ++m)
; #pragma unroll
;                     for (int n = 0; n < 2; ++n) acc[a][b][m][n] = (f32x4){0.f, 0.f, 0.f, 0.f};
;         cur = nxt; cA = nA; cB = nB; ++ui;
;     }
;     PG8_WAIT_V(0);
;     if (wr == 0) PG8_BAR;
;     PG8_BAR;
	v_lshlrev_b32_e32 v54, 16, v48
	v_and_b32_e32 v55, 0xffff0000, v48
	v_lshlrev_b32_e32 v48, 16, v49
	v_and_b32_e32 v49, 0xffff0000, v49
	v_lshlrev_b32_e32 v64, 16, v50
	v_and_b32_e32 v65, 0xffff0000, v50
	v_lshlrev_b32_e32 v50, 16, v51
	v_and_b32_e32 v51, 0xffff0000, v51
	v_pk_fma_f32 v[38:39], v[38:39], v[46:47], v[48:49]
	v_pk_fma_f32 v[36:37], v[36:37], v[44:45], v[54:55]
	v_pk_fma_f32 v[48:49], v[34:35], v[42:43], v[50:51]
	v_pk_fma_f32 v[34:35], v[32:33], v[40:41], v[64:65]
	v_cvt_pk_bf16_f32 v32, v36, v37
	v_cvt_pk_bf16_f32 v33, v38, v39
	v_cvt_pk_bf16_f32 v34, v34, v35
	v_cvt_pk_bf16_f32 v35, v48, v49
	v_lshl_add_u64 v[36:37], v[160:161], 0, s[2:3]
	global_store_dwordx4 v[52:53], v[32:35], off offset:256
	v_lshl_add_u64 v[38:39], s[4:5], 0, v[36:37]
	global_load_dwordx4 v[32:35], v[38:39], off
	s_mov_b64 s[2:3], 0xb0000
	s_waitcnt vmcnt(0) lgkmcnt(0)
	v_lshlrev_b32_e32 v48, 16, v32
	v_and_b32_e32 v49, 0xffff0000, v32
	v_lshlrev_b32_e32 v32, 16, v33
	v_and_b32_e32 v33, 0xffff0000, v33
	v_lshlrev_b32_e32 v50, 16, v34
	v_and_b32_e32 v51, 0xffff0000, v34
	v_lshlrev_b32_e32 v34, 16, v35
	v_and_b32_e32 v35, 0xffff0000, v35
	v_pk_fma_f32 v[30:31], v[30:31], v[62:63], v[32:33]
	v_pk_fma_f32 v[28:29], v[28:29], v[60:61], v[48:49]
	v_pk_fma_f32 v[32:33], v[26:27], v[58:59], v[34:35]
	v_pk_fma_f32 v[26:27], v[24:25], v[56:57], v[50:51]
	v_cvt_pk_bf16_f32 v24, v28, v29
	v_cvt_pk_bf16_f32 v25, v30, v31
	v_cvt_pk_bf16_f32 v26, v26, v27
	v_cvt_pk_bf16_f32 v27, v32, v33
	v_lshl_add_u64 v[28:29], s[42:43], 0, v[36:37]
	global_store_dwordx4 v[28:29], v[24:27], off
	global_load_dwordx4 v[24:27], v[38:39], off offset:256
	s_waitcnt vmcnt(0) lgkmcnt(0)
	v_lshlrev_b32_e32 v30, 16, v24
	v_and_b32_e32 v31, 0xffff0000, v24
	v_lshlrev_b32_e32 v24, 16, v25
	v_and_b32_e32 v25, 0xffff0000, v25
	v_lshlrev_b32_e32 v32, 16, v26
	v_and_b32_e32 v33, 0xffff0000, v26
	v_lshlrev_b32_e32 v26, 16, v27
	v_and_b32_e32 v27, 0xffff0000, v27
	v_pk_fma_f32 v[22:23], v[22:23], v[46:47], v[24:25]
	v_pk_fma_f32 v[20:21], v[20:21], v[44:45], v[30:31]
	v_pk_fma_f32 v[24:25], v[18:19], v[42:43], v[26:27]
	v_pk_fma_f32 v[18:19], v[16:17], v[40:41], v[32:33]
	v_cvt_pk_bf16_f32 v16, v20, v21
	v_cvt_pk_bf16_f32 v17, v22, v23
	v_cvt_pk_bf16_f32 v18, v18, v19
	v_cvt_pk_bf16_f32 v19, v24, v25
	v_lshl_add_u64 v[20:21], v[160:161], 0, s[2:3]
	global_store_dwordx4 v[28:29], v[16:19], off offset:256
	v_lshl_add_u64 v[22:23], s[4:5], 0, v[20:21]
	global_load_dwordx4 v[16:19], v[22:23], off
	s_mov_b32 s2, s37
	s_waitcnt vmcnt(0) lgkmcnt(0)
	v_lshlrev_b32_e32 v24, 16, v16
	v_and_b32_e32 v25, 0xffff0000, v16
	v_lshlrev_b32_e32 v16, 16, v17
	v_and_b32_e32 v17, 0xffff0000, v17
	v_lshlrev_b32_e32 v26, 16, v18
	v_and_b32_e32 v27, 0xffff0000, v18
	v_lshlrev_b32_e32 v18, 16, v19
	v_and_b32_e32 v19, 0xffff0000, v19
	v_pk_fma_f32 v[14:15], v[14:15], v[62:63], v[16:17]
	v_pk_fma_f32 v[12:13], v[12:13], v[60:61], v[24:25]
	v_pk_fma_f32 v[16:17], v[10:11], v[58:59], v[18:19]
	v_pk_fma_f32 v[10:11], v[8:9], v[56:57], v[26:27]
	v_cvt_pk_bf16_f32 v8, v12, v13
	v_cvt_pk_bf16_f32 v9, v14, v15
	v_cvt_pk_bf16_f32 v10, v10, v11
	v_cvt_pk_bf16_f32 v11, v16, v17
	v_lshl_add_u64 v[12:13], s[42:43], 0, v[20:21]
	global_store_dwordx4 v[12:13], v[8:11], off
	global_load_dwordx4 v[8:11], v[22:23], off offset:256
	s_waitcnt vmcnt(0) lgkmcnt(0)
	v_lshlrev_b32_e32 v14, 16, v8
	v_and_b32_e32 v15, 0xffff0000, v8
	v_lshlrev_b32_e32 v8, 16, v9
	v_and_b32_e32 v9, 0xffff0000, v9
	v_lshlrev_b32_e32 v16, 16, v10
	v_and_b32_e32 v17, 0xffff0000, v10
	v_lshlrev_b32_e32 v10, 16, v11
	v_and_b32_e32 v11, 0xffff0000, v11
	v_pk_fma_f32 v[6:7], v[6:7], v[46:47], v[8:9]
	v_pk_fma_f32 v[4:5], v[4:5], v[44:45], v[14:15]
	v_pk_fma_f32 v[8:9], v[2:3], v[42:43], v[10:11]
	v_pk_fma_f32 v[2:3], v[0:1], v[40:41], v[16:17]
	v_cvt_pk_bf16_f32 v0, v4, v5
	v_cvt_pk_bf16_f32 v1, v6, v7
	v_cvt_pk_bf16_f32 v2, v2, v3
	v_cvt_pk_bf16_f32 v3, v8, v9
	global_store_dwordx4 v[12:13], v[0:3], off offset:256
	s_cbranch_vccz .LBB1_2336
	s_waitcnt vmcnt(0)
	s_cmpk_gt_u32 s17, 0xff
	s_cbranch_scc1 .LBB1_2343
	s_barrier

; #define PG8_STAGE(bufoff, gbase, voff) do { _Pragma("unroll") for (int _i = 0; _i < 2; ++_i) \
;         __builtin_amdgcn_global_load_lds((const unsigned*)((const char*)(gbase) + (voff)[_i]), (LAS unsigned*)(lds + (bufoff) + ldsw + _i * 8192), 16, 0, 0); } while (0)
; #define PG8_LDA(dst, b, h) do { _Pragma("unroll") for (int m = 0; m < 4; ++m) _Pragma("unroll") for (int k = 0; k < 2; ++k) dst[m][k] = *(const LAS bf16x8*)(lds + PG8_SA(b, h) + aoff + m * 2048 + k * 1024); } while (0)
; #define PG8_LDB(dst, b, h) do { _Pragma("unroll") for (int n = 0; n < 2; ++n) _Pragma("unroll") for (int k = 0; k < 2; ++k) dst[n][k] = *(const LAS bf16x8*)(lds + PG8_SB(b, h) + boff + n * 2048 + k * 1024); } while (0)
; #define PG8_MMA(ai, bj, At, Bt) do { __builtin_amdgcn_s_setprio(1); _Pragma("unroll") for (int m = 0; m < 4; ++m) _Pragma("unroll") for (int n = 0; n < 2; ++n) _Pragma("unroll") for (int k = 0; k < 2; ++k) \
;         acc[ai][bj][m][n] = __builtin_amdgcn_mfma_f32_16x16x32_bf16(Bt[n][k], At[m][k], acc[ai][bj][m][n], 0, 0, 0); __builtin_amdgcn_s_setprio(0); } while (0)
; #define PG8_WAIT_V(n) asm volatile("s_waitcnt vmcnt(" #n ")" ::: "memory")
; #define PG8_WAIT_L(n) asm volatile("s_waitcnt lgkmcnt(" #n ")" ::: "memory")
; template <class Map, class Epi>
; DI void gemm_phase(LAS unsigned char* lds, const Map& MP, const Epi& E, const int nM, const int nN, const int K, const int lda, const int ldb) {
;     ...
;         for (int t = 0; t < nt; t += 2) {
;             const bool last = (t == nt - 2);
;             const char* a1 = cA + (size_t)(t + 1) * kstep;
;             const char* a2 = last ? nA : cA + (size_t)(t + 2) * kstep; const char* b2 = last ? nB : cB + (size_t)(t + 2) * kstep;
;             const char* a3 = a2 + kstep; const char* b3 = b2 + kstep;
;             PG8_LDB(B0, 0, 0); PG8_SCHED; PG8_LDA(At, 0, 0); PG8_STAGE(PG8_SA(1, 1), a1 + hstepA, voffA);
;             PG8_WAIT_L(8); PG8_BAR; PG8_WAIT_L(0); PG8_MMA(0, 0, At, B0); PG8_BAR; PG8_SCHED;
;             PG8_LDB(B1, 0, 1); PG8_STAGE(PG8_SB(0, 0), b2, voffB);
;             PG8_BAR; PG8_WAIT_L(0); PG8_MMA(0, 1, At, B1); PG8_BAR;
;             PG8_LDA(At, 0, 1); PG8_STAGE(PG8_SA(0, 0), a2, voffA);
;             PG8_BAR; PG8_WAIT_L(0); PG8_MMA(1, 0, At, B0); PG8_BAR; PG8_SCHED;
;             PG8_STAGE(PG8_SB(0, 1), b2 + hstepB, voffB);
;             PG8_WAIT_V(6); PG8_BAR; PG8_MMA(1, 1, At, B1); PG8_BAR;
.LBB1_2483:
	ds_read_b128 v[96:99], v190
	ds_read_b128 v[100:103], v190 offset:1024
	ds_read_b128 v[108:111], v190 offset:2048
	ds_read_b128 v[112:115], v190 offset:3072
	ds_read_b128 v[160:163], v190 offset:4096
	ds_read_b128 v[164:167], v190 offset:5120
	ds_read_b128 v[198:201], v190 offset:6144
	ds_read_b128 v[202:205], v190 offset:7168
	s_add_u32 s28, s42, 0xfff80080
	s_addc_u32 s29, s43, -1
	s_cmp_eq_u32 s3, 28
	s_cselect_b32 s47, s23, s29
	s_cselect_b32 s46, s58, s28
	s_cselect_b32 s29, s21, vcc_hi
	s_cselect_b32 s28, s59, vcc_lo
	s_add_i32 m0, s38, 0xc000
	s_nop 0
	global_load_lds_dwordx4 v178, s[42:43]
	s_add_i32 m0, s38, 0xe000
	s_nop 0
	global_load_lds_dwordx4 v176, s[42:43]
	s_waitcnt lgkmcnt(8)
	s_barrier
	s_setprio 1
	s_waitcnt lgkmcnt(7)
	v_mfma_f32_16x16x32_bf16 v[148:151], v[80:83], v[96:99], v[148:151]
	v_mfma_f32_16x16x32_bf16 v[144:147], v[88:91], v[96:99], v[144:147]
	s_waitcnt lgkmcnt(5)
	v_mfma_f32_16x16x32_bf16 v[136:139], v[80:83], v[108:111], v[136:139]
	v_mfma_f32_16x16x32_bf16 v[128:131], v[88:91], v[108:111], v[128:131]
	s_waitcnt lgkmcnt(3)
	v_mfma_f32_16x16x32_bf16 v[120:123], v[80:83], v[160:163], v[120:123]
	v_mfma_f32_16x16x32_bf16 v[104:107], v[88:91], v[160:163], v[104:107]
	s_waitcnt lgkmcnt(1)
	v_mfma_f32_16x16x32_bf16 v[76:79], v[80:83], v[198:201], v[76:79]
	v_mfma_f32_16x16x32_bf16 v[72:75], v[88:91], v[198:201], v[72:75]
	v_mfma_f32_16x16x32_bf16 v[148:151], v[84:87], v[100:103], v[148:151]
	v_mfma_f32_16x16x32_bf16 v[144:147], v[92:95], v[100:103], v[144:147]
	v_mfma_f32_16x16x32_bf16 v[136:139], v[84:87], v[112:115], v[136:139]
	v_mfma_f32_16x16x32_bf16 v[128:131], v[92:95], v[112:115], v[128:131]
	v_mfma_f32_16x16x32_bf16 v[120:123], v[84:87], v[164:167], v[120:123]
	v_mfma_f32_16x16x32_bf16 v[104:107], v[92:95], v[164:167], v[104:107]
	s_waitcnt lgkmcnt(0)
	v_mfma_f32_16x16x32_bf16 v[76:79], v[84:87], v[202:205], v[76:79]
	v_mfma_f32_16x16x32_bf16 v[72:75], v[92:95], v[202:205], v[72:75]
	s_setprio 0
	s_barrier
	ds_read_b128 v[206:209], v191
	ds_read_b128 v[210:213], v191 offset:1024
	ds_read_b128 v[214:217], v191 offset:2048
	ds_read_b128 v[218:221], v191 offset:3072
	s_add_i32 s68, s2, s37
	v_lshl_add_u64 v[184:185], s[28:29], 0, v[172:173]
	s_mov_b32 m0, s68
	s_nop 0
	global_load_lds_dwordx4 v[184:185], off
	v_lshl_add_u64 v[194:195], s[28:29], 0, v[168:169]
	s_add_i32 m0, s68, 0x2000
	s_nop 0
	global_load_lds_dwordx4 v[194:195], off
	s_barrier
	s_setprio 1
	s_waitcnt lgkmcnt(3)
	v_mfma_f32_16x16x32_bf16 v[156:159], v[206:209], v[96:99], v[156:159]
	s_waitcnt lgkmcnt(1)
	v_mfma_f32_16x16x32_bf16 v[96:99], v[214:217], v[96:99], v[152:155]
	v_mfma_f32_16x16x32_bf16 v[156:159], v[210:213], v[100:103], v[156:159]
	s_waitcnt lgkmcnt(0)
	v_mfma_f32_16x16x32_bf16 v[96:99], v[218:221], v[100:103], v[96:99]
	v_mfma_f32_16x16x32_bf16 v[100:103], v[206:209], v[108:111], v[140:143]
	v_mfma_f32_16x16x32_bf16 v[108:111], v[214:217], v[108:111], v[132:135]
	v_mfma_f32_16x16x32_bf16 v[116:119], v[214:217], v[160:163], v[116:119]
	v_mfma_f32_16x16x32_bf16 v[68:71], v[206:209], v[198:201], v[68:71]
	v_mfma_f32_16x16x32_bf16 v[64:67], v[214:217], v[198:201], v[64:67]
	s_mov_b32 m0, s38
	v_mfma_f32_16x16x32_bf16 v[100:103], v[210:213], v[112:115], v[100:103]
	v_lshl_add_u64 v[230:231], s[46:47], 0, v[174:175]
	v_mfma_f32_16x16x32_bf16 v[108:111], v[218:221], v[112:115], v[108:111]
	v_mfma_f32_16x16x32_bf16 v[112:115], v[206:209], v[160:163], v[124:127]
	v_mfma_f32_16x16x32_bf16 v[116:119], v[218:221], v[164:167], v[116:119]
	v_mfma_f32_16x16x32_bf16 v[68:71], v[210:213], v[202:205], v[68:71]
	v_mfma_f32_16x16x32_bf16 v[64:67], v[218:221], v[202:205], v[64:67]
	v_mfma_f32_16x16x32_bf16 v[112:115], v[210:213], v[164:167], v[112:115]
	s_setprio 0
	s_barrier
	ds_read_b128 v[124:127], v190 offset:16384
	ds_read_b128 v[132:135], v190 offset:17408
	ds_read_b128 v[140:143], v190 offset:18432
	ds_read_b128 v[152:155], v190 offset:19456
	ds_read_b128 v[160:163], v190 offset:20480
	ds_read_b128 v[164:167], v190 offset:21504
	ds_read_b128 v[198:201], v190 offset:22528
	ds_read_b128 v[202:205], v190 offset:23552
	global_load_lds_dwordx4 v[230:231], off
	v_lshl_add_u64 v[232:233], s[46:47], 0, v[170:171]
	s_mov_b32 m0, s39
	s_nop 0
	global_load_lds_dwordx4 v[232:233], off
	s_waitcnt vmcnt(10)
	s_barrier
	s_setprio 1
	s_waitcnt lgkmcnt(7)
	v_mfma_f32_16x16x32_bf16 v[60:63], v[80:83], v[124:127], v[60:63]
	v_mfma_f32_16x16x32_bf16 v[48:51], v[88:91], v[124:127], v[48:51]
	s_waitcnt lgkmcnt(5)
	v_mfma_f32_16x16x32_bf16 v[40:43], v[80:83], v[140:143], v[40:43]
	v_mfma_f32_16x16x32_bf16 v[32:35], v[88:91], v[140:143], v[32:35]
	s_waitcnt lgkmcnt(3)
	v_mfma_f32_16x16x32_bf16 v[24:27], v[80:83], v[160:163], v[24:27]
	v_mfma_f32_16x16x32_bf16 v[16:19], v[88:91], v[160:163], v[16:19]
	s_waitcnt lgkmcnt(1)
	v_mfma_f32_16x16x32_bf16 v[12:15], v[80:83], v[198:201], v[12:15]
	v_mfma_f32_16x16x32_bf16 v[8:11], v[88:91], v[198:201], v[8:11]
	v_mfma_f32_16x16x32_bf16 v[60:63], v[84:87], v[132:135], v[60:63]
	v_mfma_f32_16x16x32_bf16 v[48:51], v[92:95], v[132:135], v[48:51]
	v_mfma_f32_16x16x32_bf16 v[40:43], v[84:87], v[152:155], v[40:43]
	v_mfma_f32_16x16x32_bf16 v[32:35], v[92:95], v[152:155], v[32:35]
	v_mfma_f32_16x16x32_bf16 v[24:27], v[84:87], v[164:167], v[24:27]
	v_mfma_f32_16x16x32_bf16 v[16:19], v[92:95], v[164:167], v[16:19]
	s_waitcnt lgkmcnt(0)
	v_mfma_f32_16x16x32_bf16 v[12:15], v[84:87], v[202:205], v[12:15]
	v_mfma_f32_16x16x32_bf16 v[8:11], v[92:95], v[202:205], v[8:11]
	s_setprio 0
	s_barrier
	s_add_u32 s68, s28, 0x80000
	s_addc_u32 s69, s29, 0
	s_add_i32 s70, s67, s37
	s_mov_b32 m0, s70
	s_nop 0
	global_load_lds_dwordx4 v172, s[68:69]
	s_add_i32 m0, s70, 0x2000
	s_nop 0
	global_load_lds_dwordx4 v168, s[68:69]
	s_waitcnt vmcnt(6)
	s_barrier
; #define PG8_STAGE(bufoff, gbase, voff) do { _Pragma("unroll") for (int _i = 0; _i < 2; ++_i) \
;         __builtin_amdgcn_global_load_lds((const unsigned*)((const char*)(gbase) + (voff)[_i]), (LAS unsigned*)(lds + (bufoff) + ldsw + _i * 8192), 16, 0, 0); } while (0)
; #define PG8_LDA(dst, b, h) do { _Pragma("unroll") for (int m = 0; m < 4; ++m) _Pragma("unroll") for (int k = 0; k < 2; ++k) dst[m][k] = *(const LAS bf16x8*)(lds + PG8_SA(b, h) + aoff + m * 2048 + k * 1024); } while (0)
; #define PG8_LDB(dst, b, h) do { _Pragma("unroll") for (int n = 0; n < 2; ++n) _Pragma("unroll") for (int k = 0; k < 2; ++k) dst[n][k] = *(const LAS bf16x8*)(lds + PG8_SB(b, h) + boff + n * 2048 + k * 1024); } while (0)
; #define PG8_MMA(ai, bj, At, Bt) do { __builtin_amdgcn_s_setprio(1); _Pragma("unroll") for (int m = 0; m < 4; ++m) _Pragma("unroll") for (int n = 0; n < 2; ++n) _Pragma("unroll") for (int k = 0; k < 2; ++k) \
;         acc[ai][bj][m][n] = __builtin_amdgcn_mfma_f32_16x16x32_bf16(Bt[n][k], At[m][k], acc[ai][bj][m][n], 0, 0, 0); __builtin_amdgcn_s_setprio(0); } while (0)
; #define PG8_WAIT_V(n) asm volatile("s_waitcnt vmcnt(" #n ")" ::: "memory")
; #define PG8_WAIT_L(n) asm volatile("s_waitcnt lgkmcnt(" #n ")" ::: "memory")
; #define PG8_BAR __builtin_amdgcn_s_barrier()
; #define PG8_SCHED __builtin_amdgcn_sched_barrier(0)
; template <class Map, class Epi>
; DI void gemm_phase(LAS unsigned char* lds, const Map& MP, const Epi& E, const int nM, const int nN, const int K, const int lda, const int ldb) {
;     ...
;             PG8_WAIT_V(6); PG8_BAR; PG8_MMA(1, 1, At, B1); PG8_BAR;
;             PG8_LDB(B0, 1, 0); PG8_SCHED; PG8_LDA(At, 1, 0); PG8_STAGE(PG8_SA(0, 1), a2 + hstepA, voffA);
;             PG8_WAIT_L(8); PG8_BAR; PG8_WAIT_L(0); PG8_MMA(0, 0, At, B0); PG8_BAR; PG8_SCHED;
;             PG8_LDB(B1, 1, 1); PG8_STAGE(PG8_SB(1, 0), b3, voffB);
;             PG8_BAR; PG8_WAIT_L(0); PG8_MMA(0, 1, At, B1); PG8_BAR;
;             PG8_LDA(At, 1, 1); PG8_STAGE(PG8_SA(1, 0), a3, voffA);
;             PG8_BAR; PG8_WAIT_L(0); PG8_MMA(1, 0, At, B0); PG8_BAR; PG8_SCHED;
;             PG8_STAGE(PG8_SB(1, 1), b3 + hstepB, voffB);
	s_setprio 1
	v_mfma_f32_16x16x32_bf16 v[56:59], v[206:209], v[124:127], v[56:59]
	v_mfma_f32_16x16x32_bf16 v[52:55], v[214:217], v[124:127], v[52:55]
	s_add_i32 s68, 0, 0x18000
	v_add_u32_e32 v92, s68, v188
	ds_read_b128 v[80:83], v92
	v_mfma_f32_16x16x32_bf16 v[44:47], v[206:209], v[140:143], v[44:47]
	v_mfma_f32_16x16x32_bf16 v[36:39], v[214:217], v[140:143], v[36:39]
	ds_read_b128 v[84:87], v92 offset:1024
	v_mfma_f32_16x16x32_bf16 v[28:31], v[206:209], v[160:163], v[28:31]
	v_mfma_f32_16x16x32_bf16 v[20:23], v[214:217], v[160:163], v[20:23]
	ds_read_b128 v[88:91], v92 offset:2048
	v_mfma_f32_16x16x32_bf16 v[4:7], v[206:209], v[198:201], v[4:7]
	v_mfma_f32_16x16x32_bf16 v[0:3], v[214:217], v[198:201], v[0:3]
	ds_read_b128 v[92:95], v92 offset:3072
	v_mfma_f32_16x16x32_bf16 v[56:59], v[210:213], v[132:135], v[56:59]
	v_mfma_f32_16x16x32_bf16 v[52:55], v[218:221], v[132:135], v[52:55]
	v_mfma_f32_16x16x32_bf16 v[44:47], v[210:213], v[152:155], v[44:47]
	v_mfma_f32_16x16x32_bf16 v[36:39], v[218:221], v[152:155], v[36:39]
	v_mfma_f32_16x16x32_bf16 v[28:31], v[210:213], v[164:167], v[28:31]
	v_mfma_f32_16x16x32_bf16 v[20:23], v[218:221], v[164:167], v[20:23]
	v_mfma_f32_16x16x32_bf16 v[4:7], v[210:213], v[202:205], v[4:7]
	v_mfma_f32_16x16x32_bf16 v[0:3], v[218:221], v[202:205], v[0:3]
	s_setprio 0
	s_barrier
	ds_read_b128 v[124:127], v190 offset:32768
	ds_read_b128 v[132:135], v190 offset:33792
	ds_read_b128 v[160:163], v190 offset:34816
	ds_read_b128 v[164:167], v190 offset:35840
	ds_read_b128 v[198:201], v190 offset:36864
	ds_read_b128 v[202:205], v190 offset:37888
	ds_read_b128 v[206:209], v190 offset:38912
	ds_read_b128 v[210:213], v190 offset:39936
	s_add_u32 s46, s46, 0x80000
	s_addc_u32 s47, s47, 0
	s_mov_b32 m0, s55
	s_nop 0
	global_load_lds_dwordx4 v174, s[46:47]
	s_mov_b32 m0, s56
	s_nop 0
	global_load_lds_dwordx4 v170, s[46:47]
	s_waitcnt lgkmcnt(8)
	s_barrier
	s_setprio 1
	s_waitcnt lgkmcnt(7)
	v_mfma_f32_16x16x32_bf16 v[140:143], v[80:83], v[124:127], v[148:151]
	s_waitcnt lgkmcnt(6)
	v_mfma_f32_16x16x32_bf16 v[148:151], v[84:87], v[132:135], v[140:143]
	v_mfma_f32_16x16x32_bf16 v[140:143], v[88:91], v[124:127], v[144:147]
	s_waitcnt lgkmcnt(5)
	v_mfma_f32_16x16x32_bf16 v[136:139], v[80:83], v[160:163], v[136:139]
	v_mfma_f32_16x16x32_bf16 v[128:131], v[88:91], v[160:163], v[128:131]
	s_waitcnt lgkmcnt(3)
	v_mfma_f32_16x16x32_bf16 v[120:123], v[80:83], v[198:201], v[120:123]
	v_mfma_f32_16x16x32_bf16 v[104:107], v[88:91], v[198:201], v[104:107]
	s_waitcnt lgkmcnt(1)
	v_mfma_f32_16x16x32_bf16 v[76:79], v[80:83], v[206:209], v[76:79]
	v_mfma_f32_16x16x32_bf16 v[72:75], v[88:91], v[206:209], v[72:75]
	v_mfma_f32_16x16x32_bf16 v[144:147], v[92:95], v[132:135], v[140:143]
	v_mfma_f32_16x16x32_bf16 v[136:139], v[84:87], v[164:167], v[136:139]
	v_mfma_f32_16x16x32_bf16 v[128:131], v[92:95], v[164:167], v[128:131]
	v_mfma_f32_16x16x32_bf16 v[120:123], v[84:87], v[202:205], v[120:123]
	v_mfma_f32_16x16x32_bf16 v[104:107], v[92:95], v[202:205], v[104:107]
	s_waitcnt lgkmcnt(0)
	v_mfma_f32_16x16x32_bf16 v[76:79], v[84:87], v[210:213], v[76:79]
	v_mfma_f32_16x16x32_bf16 v[72:75], v[92:95], v[210:213], v[72:75]
	s_setprio 0
	s_barrier
	s_add_i32 s46, 0, 0x1c000
	v_add_u32_e32 v140, s46, v188
	ds_read_b128 v[214:217], v140
	ds_read_b128 v[218:221], v140 offset:1024
	ds_read_b128 v[222:225], v140 offset:2048
	ds_read_b128 v[226:229], v140 offset:3072
	s_add_i32 s47, s68, s37
	v_lshl_add_u64 v[140:141], v[184:185], 0, s[14:15]
	s_mov_b32 m0, s47
	s_nop 0
	global_load_lds_dwordx4 v[140:141], off
	v_lshl_add_u64 v[140:141], v[194:195], 0, s[14:15]
	s_add_i32 m0, s47, 0x2000
	s_nop 0
	global_load_lds_dwordx4 v[140:141], off
	s_barrier
	s_setprio 1
	s_waitcnt lgkmcnt(1)
	v_mfma_f32_16x16x32_bf16 v[96:99], v[222:225], v[124:127], v[96:99]
	v_mfma_f32_16x16x32_bf16 v[140:143], v[214:217], v[124:127], v[156:159]
	s_waitcnt lgkmcnt(0)
	v_mfma_f32_16x16x32_bf16 v[152:155], v[226:229], v[132:135], v[96:99]
	v_mfma_f32_16x16x32_bf16 v[96:99], v[214:217], v[160:163], v[100:103]
	v_mfma_f32_16x16x32_bf16 v[156:159], v[218:221], v[132:135], v[140:143]
	v_mfma_f32_16x16x32_bf16 v[140:143], v[218:221], v[164:167], v[96:99]
	v_mfma_f32_16x16x32_bf16 v[96:99], v[222:225], v[160:163], v[108:111]
	v_mfma_f32_16x16x32_bf16 v[132:135], v[226:229], v[164:167], v[96:99]
	v_mfma_f32_16x16x32_bf16 v[96:99], v[214:217], v[198:201], v[112:115]
	s_mov_b32 m0, s62
	v_mfma_f32_16x16x32_bf16 v[124:127], v[218:221], v[202:205], v[96:99]
	v_lshl_add_u64 v[184:185], v[230:231], 0, s[14:15]
	v_mfma_f32_16x16x32_bf16 v[96:99], v[222:225], v[198:201], v[116:119]
	v_mfma_f32_16x16x32_bf16 v[68:71], v[214:217], v[206:209], v[68:71]
	v_mfma_f32_16x16x32_bf16 v[64:67], v[222:225], v[206:209], v[64:67]
	v_mfma_f32_16x16x32_bf16 v[116:119], v[226:229], v[202:205], v[96:99]
	v_mfma_f32_16x16x32_bf16 v[68:71], v[218:221], v[210:213], v[68:71]
	v_mfma_f32_16x16x32_bf16 v[64:67], v[226:229], v[210:213], v[64:67]
	s_setprio 0
	s_barrier
	ds_read_b128 v[96:99], v190 offset:49152
	ds_read_b128 v[100:103], v190 offset:50176
	ds_read_b128 v[108:111], v190 offset:51200
	ds_read_b128 v[112:115], v190 offset:52224
	ds_read_b128 v[160:163], v190 offset:53248
	ds_read_b128 v[164:167], v190 offset:54272
	ds_read_b128 v[198:201], v190 offset:55296
	ds_read_b128 v[202:205], v190 offset:56320
	global_load_lds_dwordx4 v[184:185], off
	v_lshl_add_u64 v[184:185], v[232:233], 0, s[14:15]
	s_mov_b32 m0, s63
	s_nop 0
	global_load_lds_dwordx4 v[184:185], off
	s_waitcnt vmcnt(10)
	s_barrier
; #define PG8_STAGE(bufoff, gbase, voff) do { _Pragma("unroll") for (int _i = 0; _i < 2; ++_i) \
;         __builtin_amdgcn_global_load_lds((const unsigned*)((const char*)(gbase) + (voff)[_i]), (LAS unsigned*)(lds + (bufoff) + ldsw + _i * 8192), 16, 0, 0); } while (0)
; #define PG8_MMA(ai, bj, At, Bt) do { __builtin_amdgcn_s_setprio(1); _Pragma("unroll") for (int m = 0; m < 4; ++m) _Pragma("unroll") for (int n = 0; n < 2; ++n) _Pragma("unroll") for (int k = 0; k < 2; ++k) \
;         acc[ai][bj][m][n] = __builtin_amdgcn_mfma_f32_16x16x32_bf16(Bt[n][k], At[m][k], acc[ai][bj][m][n], 0, 0, 0); __builtin_amdgcn_s_setprio(0); } while (0)
; #define PG8_WAIT_V(n) asm volatile("s_waitcnt vmcnt(" #n ")" ::: "memory")
; #define PG8_WAIT_L(n) asm volatile("s_waitcnt lgkmcnt(" #n ")" ::: "memory")
; #define PG8_BAR __builtin_amdgcn_s_barrier()
; #define PG8_SCHED __builtin_amdgcn_sched_barrier(0)
; template <class Map, class Epi>
; DI void gemm_phase(LAS unsigned char* lds, const Map& MP, const Epi& E, const int nM, const int nN, const int K, const int lda, const int ldb) {
;     ...
;             PG8_BAR; PG8_WAIT_L(0); PG8_MMA(1, 0, At, B0); PG8_BAR; PG8_SCHED;
;             PG8_STAGE(PG8_SB(1, 1), b3 + hstepB, voffB);
;             PG8_WAIT_V(6); PG8_BAR; PG8_MMA(1, 1, At, B1); PG8_BAR;
;         }
	s_setprio 1
	s_waitcnt lgkmcnt(7)
	v_mfma_f32_16x16x32_bf16 v[60:63], v[80:83], v[96:99], v[60:63]
	v_mfma_f32_16x16x32_bf16 v[48:51], v[88:91], v[96:99], v[48:51]
	s_waitcnt lgkmcnt(5)
	v_mfma_f32_16x16x32_bf16 v[40:43], v[80:83], v[108:111], v[40:43]
	v_mfma_f32_16x16x32_bf16 v[32:35], v[88:91], v[108:111], v[32:35]
	s_waitcnt lgkmcnt(3)
	v_mfma_f32_16x16x32_bf16 v[24:27], v[80:83], v[160:163], v[24:27]
	v_mfma_f32_16x16x32_bf16 v[16:19], v[88:91], v[160:163], v[16:19]
	s_waitcnt lgkmcnt(1)
	v_mfma_f32_16x16x32_bf16 v[12:15], v[80:83], v[198:201], v[12:15]
	v_mfma_f32_16x16x32_bf16 v[8:11], v[88:91], v[198:201], v[8:11]
	v_mfma_f32_16x16x32_bf16 v[60:63], v[84:87], v[100:103], v[60:63]
	v_mfma_f32_16x16x32_bf16 v[48:51], v[92:95], v[100:103], v[48:51]
	v_mfma_f32_16x16x32_bf16 v[40:43], v[84:87], v[112:115], v[40:43]
	v_mfma_f32_16x16x32_bf16 v[32:35], v[92:95], v[112:115], v[32:35]
	v_mfma_f32_16x16x32_bf16 v[24:27], v[84:87], v[164:167], v[24:27]
	v_mfma_f32_16x16x32_bf16 v[16:19], v[92:95], v[164:167], v[16:19]
	s_waitcnt lgkmcnt(0)
	v_mfma_f32_16x16x32_bf16 v[12:15], v[84:87], v[202:205], v[12:15]
	v_mfma_f32_16x16x32_bf16 v[8:11], v[92:95], v[202:205], v[8:11]
	s_setprio 0
	s_barrier
	s_add_u32 s28, s28, 0x80080
	s_addc_u32 s29, s29, 0
	s_add_i32 s46, s46, s37
	s_mov_b32 m0, s46
	s_nop 0
	global_load_lds_dwordx4 v172, s[28:29]
	s_add_i32 m0, s46, 0x2000
	s_nop 0
	global_load_lds_dwordx4 v168, s[28:29]
	s_waitcnt vmcnt(6)
	s_barrier
	s_setprio 1
	v_mfma_f32_16x16x32_bf16 v[56:59], v[214:217], v[96:99], v[56:59]
	v_mfma_f32_16x16x32_bf16 v[52:55], v[222:225], v[96:99], v[52:55]
	ds_read_b128 v[80:83], v189
	v_mfma_f32_16x16x32_bf16 v[44:47], v[214:217], v[108:111], v[44:47]
	v_mfma_f32_16x16x32_bf16 v[36:39], v[222:225], v[108:111], v[36:39]
	ds_read_b128 v[84:87], v189 offset:1024
	v_mfma_f32_16x16x32_bf16 v[28:31], v[214:217], v[160:163], v[28:31]
	v_mfma_f32_16x16x32_bf16 v[20:23], v[222:225], v[160:163], v[20:23]
	ds_read_b128 v[88:91], v189 offset:2048
	v_mfma_f32_16x16x32_bf16 v[4:7], v[214:217], v[198:201], v[4:7]
	v_mfma_f32_16x16x32_bf16 v[0:3], v[222:225], v[198:201], v[0:3]
	ds_read_b128 v[92:95], v189 offset:3072
	v_mfma_f32_16x16x32_bf16 v[56:59], v[218:221], v[100:103], v[56:59]
	s_add_i32 s3, s3, 2
	v_mfma_f32_16x16x32_bf16 v[52:55], v[226:229], v[100:103], v[52:55]
	s_add_u32 vcc_lo, vcc_lo, 0x100
	s_addc_u32 vcc_hi, vcc_hi, 0
	v_mfma_f32_16x16x32_bf16 v[44:47], v[218:221], v[112:115], v[44:47]
	s_add_u32 s42, s42, 0x100
	s_addc_u32 s43, s43, 0
	v_mfma_f32_16x16x32_bf16 v[36:39], v[226:229], v[112:115], v[36:39]
	s_cmp_gt_u32 s3, 29
	v_mfma_f32_16x16x32_bf16 v[28:31], v[218:221], v[164:167], v[28:31]
	v_mfma_f32_16x16x32_bf16 v[20:23], v[226:229], v[164:167], v[20:23]
	v_mfma_f32_16x16x32_bf16 v[4:7], v[218:221], v[202:205], v[4:7]
	v_mfma_f32_16x16x32_bf16 v[0:3], v[226:229], v[202:205], v[0:3]
	s_setprio 0
	s_barrier
	s_cbranch_scc0 .LBB1_2483
; DI float silu_mul(float g, float v) { return g * v * __builtin_amdgcn_rcpf(1.0f + __builtin_amdgcn_exp2f(-LOG2E * g)); }
;     DI void operator()(const f32x4 (&acc)[2][2][4][2], const Unit& u, int wr, int wc, int fr, int fq) const {
;         const int row0 = u.pm * BM + wr * 64 + fr, ch0 = u.pn * 128 + wc * 32 + 8 * fq;
;         f32x4 w0[2], w1[2], w2[2], bb[2];
; #pragma unroll
;         for (int n = 0; n < 2; ++n) { w0[n] = *(const f32x4*)(cw + ch0 + 4 * n); w1[n] = *(const f32x4*)(cw + DFF + ch0 + 4 * n); w2[n] = *(const f32x4*)(cw + 2 * DFF + ch0 + 4 * n); bb[n] = *(const f32x4*)(cb + ch0 + 4 * n); }
; #pragma unroll
;         for (int ai = 0; ai < 2; ++ai)
; #pragma unroll
;             for (int m = 0; m < 4; ++m) {
;                 const bool efirst = (m == 0) && (fr == 0), elast = (m == 3) && (fr == 15);
;                 const int row = row0 + ai * HALF + m * 16;
;                 f32x4 gc[2];
; #pragma unroll
;                 for (int n = 0; n < 2; ++n) {
;                     const f32x4 g = acc[ai][0][m][n];
;                     const f32x4 gprev = acc[ai][0][m > 0 ? m - 1 : 0][n], gnext = acc[ai][0][m < 3 ? m + 1 : 3][n];
;                     f32x4 up, dn;
; #pragma unroll
;                     for (int e = 0; e < 4; ++e) {
;                         const float pu = (m > 0 && fr == 15) ? gprev[e] : g[e];
;                         const float pd = (m < 3 && fr == 0) ? gnext[e] : g[e];
;                         up[e] = dpp_ror1(pu); dn[e] = dpp_ror15(pd);
;                     }
;                     if (efirst) up = (f32x4){0.f, 0.f, 0.f, 0.f};
;                     if (elast) dn = (f32x4){0.f, 0.f, 0.f, 0.f};
;                     gc[n] = w0[n] * up + w1[n] * g + w2[n] * dn + bb[n];
;                 }
;                 if (efirst || elast) {
;                     const size_t eo = (size_t)((row >> 6) * 2 + (elast ? 1 : 0)) * DFF + ch0;
; #pragma unroll
;                     for (int n = 0; n < 2; ++n) { *(f32x4*)(EP + eo + 4 * n) = gc[n]; *(f32x4*)(ER + eo + 4 * n) = acc[ai][0][m][n]; *(f32x4*)(EV + eo + 4 * n) = acc[ai][1][m][n]; }
;                 } else {
;                     const f32x4 v0 = acc[ai][1][m][0], v1 = acc[ai][1][m][1];
;                     u32x4 o;
;                     o[0] = pack2(silu_mul(gc[0][0], v0[0]), silu_mul(gc[0][1], v0[1])); o[1] = pack2(silu_mul(gc[0][2], v0[2]), silu_mul(gc[0][3], v0[3]));
	s_waitcnt lgkmcnt(0)
	s_lshl_b32 s21, s45, 7
	v_mov_b32_e32 v80, v187
	v_mov_b32_e32 v194, v186
	s_or_b32 s21, s21, s57
	v_mov_b32_e32 v160, 0
	v_lshl_add_u32 v184, v80, 3, s21
	v_ashrrev_i32_e32 v185, 31, v184
	v_lshlrev_b64 v[80:81], 2, v[184:185]
	v_lshl_add_u64 v[84:85], s[4:5], 0, v[80:81]
	v_lshl_add_u64 v[88:89], s[16:17], 0, v[80:81]
	v_lshl_add_u64 v[92:93], s[18:19], 0, v[80:81]
	v_lshl_add_u64 v[112:113], s[6:7], 0, v[80:81]
	global_load_dwordx4 v[80:83], v[84:85], off offset:16
	global_load_dwordx4 v[96:99], v[84:85], off
	s_nop 0
	global_load_dwordx4 v[84:87], v[88:89], off offset:16
	global_load_dwordx4 v[100:103], v[88:89], off
	s_nop 0
	global_load_dwordx4 v[88:91], v[92:93], off offset:16
	global_load_dwordx4 v[108:111], v[92:93], off
	s_nop 0
	global_load_dwordx4 v[92:95], v[112:113], off offset:16
	s_nop 0
	global_load_dwordx4 v[112:115], v[112:113], off
	v_cmp_eq_u32_e32 vcc, 0, v194
	v_mov_b32_e32 v164, 0
	v_mov_b32_e32 v195, 0
	v_cndmask_b32_e32 v161, v148, v136, vcc
	v_cndmask_b32_e32 v162, v149, v137, vcc
	v_cndmask_b32_e32 v163, v150, v138, vcc
	v_mov_b32_dpp v160, v161 row_ror:15 row_mask:0xf bank_mask:0xf
	v_mov_b32_e32 v161, 0
	v_mov_b32_e32 v166, 0
	v_mov_b32_e32 v167, 0
	v_mov_b32_dpp v161, v162 row_ror:15 row_mask:0xf bank_mask:0xf
	v_mov_b32_e32 v162, 0
	v_mov_b32_dpp v164, v150 row_ror:1 row_mask:0xf bank_mask:0xf
	v_cndmask_b32_e32 v165, v151, v139, vcc
	v_mov_b32_dpp v162, v163 row_ror:15 row_mask:0xf bank_mask:0xf
	v_mov_b32_dpp v195, v151 row_ror:1 row_mask:0xf bank_mask:0xf
	v_mov_b32_e32 v163, 0
	v_mov_b32_dpp v166, v148 row_ror:1 row_mask:0xf bank_mask:0xf
	v_mov_b32_dpp v167, v149 row_ror:1 row_mask:0xf bank_mask:0xf
	v_mov_b32_dpp v163, v165 row_ror:15 row_mask:0xf bank_mask:0xf
	v_cndmask_b32_e64 v165, v195, 0, vcc
	v_cndmask_b32_e64 v164, v164, 0, vcc
	v_cndmask_b32_e64 v167, v167, 0, vcc
	v_cndmask_b32_e64 v166, v166, 0, vcc
	v_mov_b32_e32 v195, 0
	v_mov_b32_e32 v196, 0
	v_mov_b32_e32 v198, 0
	v_mov_b32_e32 v200, 0
	v_mov_b32_dpp v195, v144 row_ror:1 row_mask:0xf bank_mask:0xf
	v_mov_b32_dpp v196, v145 row_ror:1 row_mask:0xf bank_mask:0xf
	v_mov_b32_dpp v198, v146 row_ror:1 row_mask:0xf bank_mask:0xf
	v_cndmask_b32_e32 v199, v147, v131, vcc
	v_mov_b32_dpp v200, v147 row_ror:1 row_mask:0xf bank_mask:0xf
	v_cndmask_b32_e64 v198, v198, 0, vcc
	v_cndmask_b32_e64 v201, v196, 0, vcc
	s_lshl_b32 s3, s44, 8
	s_add_i32 s3, s3, s49
	v_add_u32_e32 v193, s3, v194
	v_cmp_ne_u32_e64 s[46:47], 0, v194
	s_waitcnt vmcnt(0)
	v_pk_mul_f32 v[164:165], v[98:99], v[164:165]
	v_pk_mul_f32 v[166:167], v[96:97], v[166:167]
	v_pk_fma_f32 v[164:165], v[150:151], v[102:103], v[164:165]
	v_pk_fma_f32 v[166:167], v[148:149], v[100:101], v[166:167]
	v_pk_fma_f32 v[162:163], v[110:111], v[162:163], v[164:165]
	v_cndmask_b32_e32 v165, v144, v128, vcc
	v_mov_b32_e32 v164, 0
	v_pk_fma_f32 v[160:161], v[108:109], v[160:161], v[166:167]
	v_cndmask_b32_e32 v166, v145, v129, vcc
	v_mov_b32_dpp v164, v165 row_ror:15 row_mask:0xf bank_mask:0xf
	v_mov_b32_e32 v165, 0
	v_cndmask_b32_e32 v167, v146, v130, vcc
	v_pk_add_f32 v[162:163], v[114:115], v[162:163]
	v_mov_b32_dpp v165, v166 row_ror:15 row_mask:0xf bank_mask:0xf
	v_mov_b32_e32 v166, 0
	v_pk_add_f32 v[160:161], v[112:113], v[160:161]
	s_nop 0
	v_mov_b32_dpp v166, v167 row_ror:15 row_mask:0xf bank_mask:0xf
	v_mov_b32_e32 v167, 0
	s_nop 1
	v_mov_b32_dpp v167, v199 row_ror:15 row_mask:0xf bank_mask:0xf
	v_cndmask_b32_e64 v199, v200, 0, vcc
	v_cndmask_b32_e64 v200, v195, 0, vcc
	v_pk_mul_f32 v[200:201], v[80:81], v[200:201]
	v_pk_mul_f32 v[198:199], v[82:83], v[198:199]
	v_pk_fma_f32 v[200:201], v[144:145], v[84:85], v[200:201]
	v_pk_fma_f32 v[198:199], v[146:147], v[86:87], v[198:199]
	v_pk_fma_f32 v[164:165], v[88:89], v[164:165], v[200:201]
	v_pk_fma_f32 v[166:167], v[90:91], v[166:167], v[198:199]
	v_pk_add_f32 v[164:165], v[92:93], v[164:165]
	v_pk_add_f32 v[166:167], v[94:95], v[166:167]
	s_and_saveexec_b64 s[28:29], s[46:47]
	s_xor_b64 s[28:29], exec, s[28:29]
	s_cbranch_execz .LBB1_2486
	v_mul_f32_e32 v195, 0xbfb8aa3b, v160
	v_exp_f32_e32 v195, v195
	v_mul_f32_e32 v196, 0xbfb8aa3b, v161
	v_exp_f32_e32 v196, v196
	v_pk_mul_f32 v[160:161], v[156:157], v[160:161]
	v_add_f32_e32 v195, 1.0, v195
	v_rcp_f32_e32 v198, v195
	v_add_f32_e32 v196, 1.0, v196
	v_mul_f32_e32 v195, 0xbfb8aa3b, v162
	v_rcp_f32_e32 v199, v196
	v_exp_f32_e32 v195, v195
	v_mul_f32_e32 v196, 0xbfb8aa3b, v163
	v_exp_f32_e32 v196, v196
	v_pk_mul_f32 v[160:161], v[160:161], v[198:199]
	v_add_f32_e32 v195, 1.0, v195
	v_rcp_f32_e32 v200, v195
	v_add_f32_e32 v195, 1.0, v196
	v_rcp_f32_e32 v201, v195
	v_cvt_pk_bf16_f32 v160, v160, v161
	v_mul_f32_e32 v161, 0xbfb8aa3b, v164
	v_exp_f32_e32 v195, v161
	v_mul_f32_e32 v161, 0xbfb8aa3b, v165
	v_exp_f32_e32 v196, v161
	v_pk_mul_f32 v[162:163], v[158:159], v[162:163]
	v_pk_mul_f32 v[164:165], v[152:153], v[164:165]
	v_pk_mul_f32 v[162:163], v[162:163], v[200:201]
	s_nop 0
	v_cvt_pk_bf16_f32 v161, v162, v163
	v_add_f32_e32 v162, 1.0, v195
	v_mul_f32_e32 v195, 0xbfb8aa3b, v166
	v_add_f32_e32 v163, 1.0, v196
	v_exp_f32_e32 v195, v195
	v_mul_f32_e32 v196, 0xbfb8aa3b, v167
	v_exp_f32_e32 v196, v196
	v_rcp_f32_e32 v162, v162
	v_add_f32_e32 v195, 1.0, v195
	v_rcp_f32_e32 v198, v195
	v_add_f32_e32 v195, 1.0, v196
	v_rcp_f32_e32 v163, v163
	v_rcp_f32_e32 v199, v195
	v_pk_mul_f32 v[166:167], v[154:155], v[166:167]
	v_pk_mul_f32 v[162:163], v[164:165], v[162:163]
	v_pk_mul_f32 v[164:165], v[166:167], v[198:199]
	v_cvt_pk_bf16_f32 v162, v162, v163
	v_cvt_pk_bf16_f32 v163, v164, v165
	v_mov_b64_e32 v[164:165], s[52:53]
	v_mad_i64_i32 v[164:165], s[42:43], v193, s60, v[164:165]
	v_lshl_add_u64 v[164:165], v[184:185], 1, v[164:165]
	global_store_dwordx4 v[164:165], v[160:163], off

; #define PG8_STAGE(bufoff, gbase, voff) do { _Pragma("unroll") for (int _i = 0; _i < 2; ++_i) \
;         __builtin_amdgcn_global_load_lds((const unsigned*)((const char*)(gbase) + (voff)[_i]), (LAS unsigned*)(lds + (bufoff) + ldsw + _i * 8192), 16, 0, 0); } while (0)
; #define PG8_LDA(dst, b, h) do { _Pragma("unroll") for (int m = 0; m < 4; ++m) _Pragma("unroll") for (int k = 0; k < 2; ++k) dst[m][k] = *(const LAS bf16x8*)(lds + PG8_SA(b, h) + aoff + m * 2048 + k * 1024); } while (0)
; #define PG8_LDB(dst, b, h) do { _Pragma("unroll") for (int n = 0; n < 2; ++n) _Pragma("unroll") for (int k = 0; k < 2; ++k) dst[n][k] = *(const LAS bf16x8*)(lds + PG8_SB(b, h) + boff + n * 2048 + k * 1024); } while (0)
; #define PG8_MMA(ai, bj, At, Bt) do { __builtin_amdgcn_s_setprio(1); _Pragma("unroll") for (int m = 0; m < 4; ++m) _Pragma("unroll") for (int n = 0; n < 2; ++n) _Pragma("unroll") for (int k = 0; k < 2; ++k) \
;         acc[ai][bj][m][n] = __builtin_amdgcn_mfma_f32_16x16x32_bf16(Bt[n][k], At[m][k], acc[ai][bj][m][n], 0, 0, 0); __builtin_amdgcn_s_setprio(0); } while (0)
; #define PG8_WAIT_V(n) asm volatile("s_waitcnt vmcnt(" #n ")" ::: "memory")
; #define PG8_WAIT_L(n) asm volatile("s_waitcnt lgkmcnt(" #n ")" ::: "memory")
; template <class Map, class Epi>
; DI void gemm_phase(LAS unsigned char* lds, const Map& MP, const Epi& E, const int nM, const int nN, const int K, const int lda, const int ldb) {
;     ...
;         for (int t = 0; t < nt; t += 2) {
;             const bool last = (t == nt - 2);
;             const char* a1 = cA + (size_t)(t + 1) * kstep;
;             const char* a2 = last ? nA : cA + (size_t)(t + 2) * kstep; const char* b2 = last ? nB : cB + (size_t)(t + 2) * kstep;
;             const char* a3 = a2 + kstep; const char* b3 = b2 + kstep;
;             PG8_LDB(B0, 0, 0); PG8_SCHED; PG8_LDA(At, 0, 0); PG8_STAGE(PG8_SA(1, 1), a1 + hstepA, voffA);
;             PG8_WAIT_L(8); PG8_BAR; PG8_WAIT_L(0); PG8_MMA(0, 0, At, B0); PG8_BAR; PG8_SCHED;
;             PG8_LDB(B1, 0, 1); PG8_STAGE(PG8_SB(0, 0), b2, voffB);
;             PG8_BAR; PG8_WAIT_L(0); PG8_MMA(0, 1, At, B1); PG8_BAR;
;             PG8_LDA(At, 0, 1); PG8_STAGE(PG8_SA(0, 0), a2, voffA);
;             PG8_BAR; PG8_WAIT_L(0); PG8_MMA(1, 0, At, B0); PG8_BAR; PG8_SCHED;
;             PG8_STAGE(PG8_SB(0, 1), b2 + hstepB, voffB);
;             PG8_WAIT_V(6); PG8_BAR; PG8_MMA(1, 1, At, B1); PG8_BAR;
.LBB1_2653:
	ds_read_b128 v[168:171], v150
	ds_read_b128 v[172:175], v150 offset:1024
	ds_read_b128 v[176:179], v150 offset:2048
	ds_read_b128 v[180:183], v150 offset:3072
	ds_read_b128 v[184:187], v150 offset:4096
	ds_read_b128 v[188:191], v150 offset:5120
	ds_read_b128 v[192:195], v150 offset:6144
	ds_read_b128 v[196:199], v150 offset:7168
	s_add_u32 s10, s8, 0x100
	s_addc_u32 s11, s9, 0
	s_cmpk_eq_i32 s48, 0x54
	s_cselect_b32 s15, s43, s11
	s_cselect_b32 s14, s42, s10
	s_cselect_b32 s13, s45, s39
	s_cselect_b32 s12, s44, s38
	s_add_i32 m0, s22, 0xc000
	s_nop 0
	global_load_lds_dwordx4 v138, s[8:9]
	s_add_i32 m0, s22, 0xe000
	s_nop 0
	global_load_lds_dwordx4 v136, s[8:9]
	s_waitcnt lgkmcnt(8)
	s_barrier
	s_setprio 1
	s_waitcnt lgkmcnt(7)
	v_mfma_f32_16x16x32_bf16 v[124:127], v[152:155], v[168:171], v[124:127]
	v_mfma_f32_16x16x32_bf16 v[120:123], v[160:163], v[168:171], v[120:123]
	s_waitcnt lgkmcnt(5)
	v_mfma_f32_16x16x32_bf16 v[108:111], v[152:155], v[176:179], v[108:111]
	v_mfma_f32_16x16x32_bf16 v[104:107], v[160:163], v[176:179], v[104:107]
	s_waitcnt lgkmcnt(3)
	v_mfma_f32_16x16x32_bf16 v[92:95], v[152:155], v[184:187], v[92:95]
	v_mfma_f32_16x16x32_bf16 v[88:91], v[160:163], v[184:187], v[88:91]
	s_waitcnt lgkmcnt(1)
	v_mfma_f32_16x16x32_bf16 v[76:79], v[152:155], v[192:195], v[76:79]
	v_mfma_f32_16x16x32_bf16 v[72:75], v[160:163], v[192:195], v[72:75]
	v_mfma_f32_16x16x32_bf16 v[124:127], v[156:159], v[172:175], v[124:127]
	v_mfma_f32_16x16x32_bf16 v[120:123], v[164:167], v[172:175], v[120:123]
	v_mfma_f32_16x16x32_bf16 v[108:111], v[156:159], v[180:183], v[108:111]
	v_mfma_f32_16x16x32_bf16 v[104:107], v[164:167], v[180:183], v[104:107]
	v_mfma_f32_16x16x32_bf16 v[92:95], v[156:159], v[188:191], v[92:95]
	v_mfma_f32_16x16x32_bf16 v[88:91], v[164:167], v[188:191], v[88:91]
	s_waitcnt lgkmcnt(0)
	v_mfma_f32_16x16x32_bf16 v[76:79], v[156:159], v[196:199], v[76:79]
	v_mfma_f32_16x16x32_bf16 v[72:75], v[164:167], v[196:199], v[72:75]
	s_setprio 0
	s_barrier
	ds_read_b128 v[200:203], v151
	ds_read_b128 v[204:207], v151 offset:1024
	ds_read_b128 v[208:211], v151 offset:2048
	ds_read_b128 v[212:215], v151 offset:3072
	s_add_i32 s8, s33, s20
	v_lshl_add_u64 v[144:145], s[12:13], 0, v[132:133]
	s_mov_b32 m0, s8
	s_nop 0
	global_load_lds_dwordx4 v[144:145], off
	v_lshl_add_u64 v[216:217], s[12:13], 0, v[128:129]
	s_add_i32 m0, s8, 0x2000
	s_nop 0
	global_load_lds_dwordx4 v[216:217], off
	s_barrier
	s_setprio 1
	s_waitcnt lgkmcnt(3)
	v_mfma_f32_16x16x32_bf16 v[116:119], v[200:203], v[168:171], v[116:119]
	s_waitcnt lgkmcnt(1)
	v_mfma_f32_16x16x32_bf16 v[112:115], v[208:211], v[168:171], v[112:115]
	v_mfma_f32_16x16x32_bf16 v[100:103], v[200:203], v[176:179], v[100:103]
	v_mfma_f32_16x16x32_bf16 v[96:99], v[208:211], v[176:179], v[96:99]
	v_mfma_f32_16x16x32_bf16 v[84:87], v[200:203], v[184:187], v[84:87]
	v_mfma_f32_16x16x32_bf16 v[80:83], v[208:211], v[184:187], v[80:83]
	v_mfma_f32_16x16x32_bf16 v[68:71], v[200:203], v[192:195], v[68:71]
	v_mfma_f32_16x16x32_bf16 v[64:67], v[208:211], v[192:195], v[64:67]
	v_mfma_f32_16x16x32_bf16 v[116:119], v[204:207], v[172:175], v[116:119]
	s_mov_b32 m0, s22
	s_waitcnt lgkmcnt(0)
	v_mfma_f32_16x16x32_bf16 v[112:115], v[212:215], v[172:175], v[112:115]
	v_lshl_add_u64 v[218:219], s[14:15], 0, v[134:135]
	v_mfma_f32_16x16x32_bf16 v[100:103], v[204:207], v[180:183], v[100:103]
	v_mfma_f32_16x16x32_bf16 v[96:99], v[212:215], v[180:183], v[96:99]
	v_mfma_f32_16x16x32_bf16 v[84:87], v[204:207], v[188:191], v[84:87]
	v_mfma_f32_16x16x32_bf16 v[80:83], v[212:215], v[188:191], v[80:83]
	v_mfma_f32_16x16x32_bf16 v[68:71], v[204:207], v[196:199], v[68:71]
	v_mfma_f32_16x16x32_bf16 v[64:67], v[212:215], v[196:199], v[64:67]
	s_setprio 0
	s_barrier
	ds_read_b128 v[168:171], v150 offset:16384
	ds_read_b128 v[172:175], v150 offset:17408
	ds_read_b128 v[176:179], v150 offset:18432
	ds_read_b128 v[180:183], v150 offset:19456
	ds_read_b128 v[184:187], v150 offset:20480
	ds_read_b128 v[188:191], v150 offset:21504
	ds_read_b128 v[192:195], v150 offset:22528
	ds_read_b128 v[196:199], v150 offset:23552
	global_load_lds_dwordx4 v[218:219], off
	v_lshl_add_u64 v[220:221], s[14:15], 0, v[130:131]
	s_mov_b32 m0, s23
	s_nop 0
	global_load_lds_dwordx4 v[220:221], off
	s_waitcnt vmcnt(10)
	s_barrier
	s_setprio 1
	s_waitcnt lgkmcnt(7)
	v_mfma_f32_16x16x32_bf16 v[60:63], v[152:155], v[168:171], v[60:63]
	v_mfma_f32_16x16x32_bf16 v[56:59], v[160:163], v[168:171], v[56:59]
	s_waitcnt lgkmcnt(5)
	v_mfma_f32_16x16x32_bf16 v[44:47], v[152:155], v[176:179], v[44:47]
	v_mfma_f32_16x16x32_bf16 v[40:43], v[160:163], v[176:179], v[40:43]
	s_waitcnt lgkmcnt(3)
	v_mfma_f32_16x16x32_bf16 v[28:31], v[152:155], v[184:187], v[28:31]
	v_mfma_f32_16x16x32_bf16 v[24:27], v[160:163], v[184:187], v[24:27]
	s_waitcnt lgkmcnt(1)
	v_mfma_f32_16x16x32_bf16 v[12:15], v[152:155], v[192:195], v[12:15]
	v_mfma_f32_16x16x32_bf16 v[8:11], v[160:163], v[192:195], v[8:11]
	v_mfma_f32_16x16x32_bf16 v[60:63], v[156:159], v[172:175], v[60:63]
	v_mfma_f32_16x16x32_bf16 v[56:59], v[164:167], v[172:175], v[56:59]
	v_mfma_f32_16x16x32_bf16 v[44:47], v[156:159], v[180:183], v[44:47]
	v_mfma_f32_16x16x32_bf16 v[40:43], v[164:167], v[180:183], v[40:43]
	v_mfma_f32_16x16x32_bf16 v[28:31], v[156:159], v[188:191], v[28:31]
	v_mfma_f32_16x16x32_bf16 v[24:27], v[164:167], v[188:191], v[24:27]
	s_waitcnt lgkmcnt(0)
	v_mfma_f32_16x16x32_bf16 v[12:15], v[156:159], v[196:199], v[12:15]
	v_mfma_f32_16x16x32_bf16 v[8:11], v[164:167], v[196:199], v[8:11]
	s_setprio 0
	s_barrier
; #define PG8_STAGE(bufoff, gbase, voff) do { _Pragma("unroll") for (int _i = 0; _i < 2; ++_i) \
;         __builtin_amdgcn_global_load_lds((const unsigned*)((const char*)(gbase) + (voff)[_i]), (LAS unsigned*)(lds + (bufoff) + ldsw + _i * 8192), 16, 0, 0); } while (0)
; #define PG8_LDA(dst, b, h) do { _Pragma("unroll") for (int m = 0; m < 4; ++m) _Pragma("unroll") for (int k = 0; k < 2; ++k) dst[m][k] = *(const LAS bf16x8*)(lds + PG8_SA(b, h) + aoff + m * 2048 + k * 1024); } while (0)
; #define PG8_LDB(dst, b, h) do { _Pragma("unroll") for (int n = 0; n < 2; ++n) _Pragma("unroll") for (int k = 0; k < 2; ++k) dst[n][k] = *(const LAS bf16x8*)(lds + PG8_SB(b, h) + boff + n * 2048 + k * 1024); } while (0)
; #define PG8_MMA(ai, bj, At, Bt) do { __builtin_amdgcn_s_setprio(1); _Pragma("unroll") for (int m = 0; m < 4; ++m) _Pragma("unroll") for (int n = 0; n < 2; ++n) _Pragma("unroll") for (int k = 0; k < 2; ++k) \
;         acc[ai][bj][m][n] = __builtin_amdgcn_mfma_f32_16x16x32_bf16(Bt[n][k], At[m][k], acc[ai][bj][m][n], 0, 0, 0); __builtin_amdgcn_s_setprio(0); } while (0)
; #define PG8_WAIT_V(n) asm volatile("s_waitcnt vmcnt(" #n ")" ::: "memory")
; #define PG8_WAIT_L(n) asm volatile("s_waitcnt lgkmcnt(" #n ")" ::: "memory")
; #define PG8_BAR __builtin_amdgcn_s_barrier()
; #define PG8_SCHED __builtin_amdgcn_sched_barrier(0)
; template <class Map, class Epi>
; DI void gemm_phase(LAS unsigned char* lds, const Map& MP, const Epi& E, const int nM, const int nN, const int K, const int lda, const int ldb) {
;     ...
;             PG8_STAGE(PG8_SB(0, 1), b2 + hstepB, voffB);
;             PG8_WAIT_V(6); PG8_BAR; PG8_MMA(1, 1, At, B1); PG8_BAR;
;             PG8_LDB(B0, 1, 0); PG8_SCHED; PG8_LDA(At, 1, 0); PG8_STAGE(PG8_SA(0, 1), a2 + hstepA, voffA);
;             PG8_WAIT_L(8); PG8_BAR; PG8_WAIT_L(0); PG8_MMA(0, 0, At, B0); PG8_BAR; PG8_SCHED;
;             PG8_LDB(B1, 1, 1); PG8_STAGE(PG8_SB(1, 0), b3, voffB);
;             PG8_BAR; PG8_WAIT_L(0); PG8_MMA(0, 1, At, B1); PG8_BAR;
;             PG8_LDA(At, 1, 1); PG8_STAGE(PG8_SA(1, 0), a3, voffA);
;             PG8_BAR; PG8_WAIT_L(0); PG8_MMA(1, 0, At, B0); PG8_BAR; PG8_SCHED;
;             PG8_STAGE(PG8_SB(1, 1), b3 + hstepB, voffB);
	s_add_u32 s8, s12, 0x160000
	s_addc_u32 s9, s13, 0
	s_add_i32 s49, s34, s20
	s_mov_b32 m0, s49
	s_nop 0
	global_load_lds_dwordx4 v132, s[8:9]
	s_add_i32 m0, s49, 0x2000
	s_nop 0
	global_load_lds_dwordx4 v128, s[8:9]
	s_waitcnt vmcnt(6)
	s_barrier
	s_setprio 1
	v_mfma_f32_16x16x32_bf16 v[52:55], v[200:203], v[168:171], v[52:55]
	v_mfma_f32_16x16x32_bf16 v[48:51], v[208:211], v[168:171], v[48:51]
	s_add_i32 s49, 0, 0x18000
	v_add_u32_e32 v164, s49, v148
	ds_read_b128 v[152:155], v164
	v_mfma_f32_16x16x32_bf16 v[36:39], v[200:203], v[176:179], v[36:39]
	v_mfma_f32_16x16x32_bf16 v[32:35], v[208:211], v[176:179], v[32:35]
	ds_read_b128 v[156:159], v164 offset:1024
	v_mfma_f32_16x16x32_bf16 v[20:23], v[200:203], v[184:187], v[20:23]
	v_mfma_f32_16x16x32_bf16 v[16:19], v[208:211], v[184:187], v[16:19]
	ds_read_b128 v[160:163], v164 offset:2048
	v_mfma_f32_16x16x32_bf16 v[4:7], v[200:203], v[192:195], v[4:7]
	v_mfma_f32_16x16x32_bf16 v[0:3], v[208:211], v[192:195], v[0:3]
	ds_read_b128 v[164:167], v164 offset:3072
	v_mfma_f32_16x16x32_bf16 v[52:55], v[204:207], v[172:175], v[52:55]
	v_mfma_f32_16x16x32_bf16 v[48:51], v[212:215], v[172:175], v[48:51]
	v_mfma_f32_16x16x32_bf16 v[36:39], v[204:207], v[180:183], v[36:39]
	v_mfma_f32_16x16x32_bf16 v[32:35], v[212:215], v[180:183], v[32:35]
	v_mfma_f32_16x16x32_bf16 v[20:23], v[204:207], v[188:191], v[20:23]
	v_mfma_f32_16x16x32_bf16 v[16:19], v[212:215], v[188:191], v[16:19]
	v_mfma_f32_16x16x32_bf16 v[4:7], v[204:207], v[196:199], v[4:7]
	v_mfma_f32_16x16x32_bf16 v[0:3], v[212:215], v[196:199], v[0:3]
	s_setprio 0
	s_barrier
	ds_read_b128 v[168:171], v150 offset:32768
	ds_read_b128 v[172:175], v150 offset:33792
	ds_read_b128 v[176:179], v150 offset:34816
	ds_read_b128 v[180:183], v150 offset:35840
	ds_read_b128 v[184:187], v150 offset:36864
	ds_read_b128 v[188:191], v150 offset:37888
	ds_read_b128 v[192:195], v150 offset:38912
	ds_read_b128 v[196:199], v150 offset:39936
	s_add_u32 s8, s14, 0x160000
	s_addc_u32 s9, s15, 0
	s_mov_b32 m0, s24
	s_nop 0
	global_load_lds_dwordx4 v134, s[8:9]
	s_mov_b32 m0, s25
	s_nop 0
	global_load_lds_dwordx4 v130, s[8:9]
	s_waitcnt lgkmcnt(8)
	s_barrier
	s_setprio 1
	s_waitcnt lgkmcnt(7)
	v_mfma_f32_16x16x32_bf16 v[124:127], v[152:155], v[168:171], v[124:127]
	v_mfma_f32_16x16x32_bf16 v[120:123], v[160:163], v[168:171], v[120:123]
	s_waitcnt lgkmcnt(5)
	v_mfma_f32_16x16x32_bf16 v[108:111], v[152:155], v[176:179], v[108:111]
	v_mfma_f32_16x16x32_bf16 v[104:107], v[160:163], v[176:179], v[104:107]
	s_waitcnt lgkmcnt(3)
	v_mfma_f32_16x16x32_bf16 v[92:95], v[152:155], v[184:187], v[92:95]
	v_mfma_f32_16x16x32_bf16 v[88:91], v[160:163], v[184:187], v[88:91]
	s_waitcnt lgkmcnt(1)
	v_mfma_f32_16x16x32_bf16 v[76:79], v[152:155], v[192:195], v[76:79]
	v_mfma_f32_16x16x32_bf16 v[72:75], v[160:163], v[192:195], v[72:75]
	v_mfma_f32_16x16x32_bf16 v[124:127], v[156:159], v[172:175], v[124:127]
	v_mfma_f32_16x16x32_bf16 v[120:123], v[164:167], v[172:175], v[120:123]
	v_mfma_f32_16x16x32_bf16 v[108:111], v[156:159], v[180:183], v[108:111]
	v_mfma_f32_16x16x32_bf16 v[104:107], v[164:167], v[180:183], v[104:107]
	v_mfma_f32_16x16x32_bf16 v[92:95], v[156:159], v[188:191], v[92:95]
	v_mfma_f32_16x16x32_bf16 v[88:91], v[164:167], v[188:191], v[88:91]
	s_waitcnt lgkmcnt(0)
	v_mfma_f32_16x16x32_bf16 v[76:79], v[156:159], v[196:199], v[76:79]
	v_mfma_f32_16x16x32_bf16 v[72:75], v[164:167], v[196:199], v[72:75]
	s_setprio 0
	s_barrier
	s_add_i32 s14, 0, 0x1c000
	v_add_u32_e32 v212, s14, v148
	ds_read_b128 v[200:203], v212
	ds_read_b128 v[204:207], v212 offset:1024
	ds_read_b128 v[208:211], v212 offset:2048
	ds_read_b128 v[212:215], v212 offset:3072
	s_add_i32 s8, s49, s20
	v_lshl_add_u64 v[144:145], v[144:145], 0, s[46:47]
	s_mov_b32 m0, s8
	s_nop 0
	global_load_lds_dwordx4 v[144:145], off
	v_lshl_add_u64 v[144:145], v[216:217], 0, s[46:47]
	s_add_i32 m0, s8, 0x2000
	s_nop 0
	global_load_lds_dwordx4 v[144:145], off
	s_barrier
	s_setprio 1
	s_waitcnt lgkmcnt(3)
	v_mfma_f32_16x16x32_bf16 v[116:119], v[200:203], v[168:171], v[116:119]
	s_waitcnt lgkmcnt(1)
	v_mfma_f32_16x16x32_bf16 v[112:115], v[208:211], v[168:171], v[112:115]
	v_mfma_f32_16x16x32_bf16 v[100:103], v[200:203], v[176:179], v[100:103]
	v_mfma_f32_16x16x32_bf16 v[96:99], v[208:211], v[176:179], v[96:99]
	v_mfma_f32_16x16x32_bf16 v[84:87], v[200:203], v[184:187], v[84:87]
	v_mfma_f32_16x16x32_bf16 v[80:83], v[208:211], v[184:187], v[80:83]
	v_mfma_f32_16x16x32_bf16 v[68:71], v[200:203], v[192:195], v[68:71]
	v_mfma_f32_16x16x32_bf16 v[64:67], v[208:211], v[192:195], v[64:67]
	v_mfma_f32_16x16x32_bf16 v[116:119], v[204:207], v[172:175], v[116:119]
	s_mov_b32 m0, s29
	s_waitcnt lgkmcnt(0)
	v_mfma_f32_16x16x32_bf16 v[112:115], v[212:215], v[172:175], v[112:115]
	v_lshl_add_u64 v[144:145], v[218:219], 0, s[46:47]
	v_mfma_f32_16x16x32_bf16 v[100:103], v[204:207], v[180:183], v[100:103]
	v_mfma_f32_16x16x32_bf16 v[96:99], v[212:215], v[180:183], v[96:99]
	v_mfma_f32_16x16x32_bf16 v[84:87], v[204:207], v[188:191], v[84:87]
	v_mfma_f32_16x16x32_bf16 v[80:83], v[212:215], v[188:191], v[80:83]
	v_mfma_f32_16x16x32_bf16 v[68:71], v[204:207], v[196:199], v[68:71]
	v_mfma_f32_16x16x32_bf16 v[64:67], v[212:215], v[196:199], v[64:67]
	s_setprio 0
	s_barrier
	ds_read_b128 v[168:171], v150 offset:49152
	ds_read_b128 v[172:175], v150 offset:50176
	ds_read_b128 v[176:179], v150 offset:51200
	ds_read_b128 v[180:183], v150 offset:52224
	ds_read_b128 v[184:187], v150 offset:53248
	ds_read_b128 v[188:191], v150 offset:54272
	ds_read_b128 v[192:195], v150 offset:55296
	ds_read_b128 v[196:199], v150 offset:56320
	global_load_lds_dwordx4 v[144:145], off
	v_lshl_add_u64 v[144:145], v[220:221], 0, s[46:47]
	s_mov_b32 m0, s30
	s_nop 0
	global_load_lds_dwordx4 v[144:145], off
	s_waitcnt vmcnt(10)
	s_barrier
; DI unsigned pack2(float a, float b) { f32x2 v = {a, b}; hwbf16x2 r = __builtin_convertvector(v, hwbf16x2); return __builtin_bit_cast(unsigned, r); }
; DI float bflo(unsigned w) { return __uint_as_float(w << 16); }
; DI float bfhi(unsigned w) { return __uint_as_float(w & 0xffff0000u); }
; #define PG8_STAGE(bufoff, gbase, voff) do { _Pragma("unroll") for (int _i = 0; _i < 2; ++_i) \
;         __builtin_amdgcn_global_load_lds((const unsigned*)((const char*)(gbase) + (voff)[_i]), (LAS unsigned*)(lds + (bufoff) + ldsw + _i * 8192), 16, 0, 0); } while (0)
; #define PG8_BAR __builtin_amdgcn_s_barrier()
;     DI void operator()(const f32x4 (&acc)[2][2][4][2], const Unit& u, int wr, int wc, int fr, int fq) const {
;     ...
;         for (int ai = 0; ai < 2; ++ai)
; #pragma unroll
;             for (int m = 0; m < 4; ++m) { const size_t ro = (size_t)(row0 + ai * HALF + m * 16) * D + col0;
; #pragma unroll
;                 for (int bj = 0; bj < 2; ++bj) {
;                     f32x4 x0, x1;
;                     if constexpr (IB) { const u32x4 w = *(const u32x4*)((const bf16_t*)Xin + ro + bj * HALF);
;                         x0 = (f32x4){bflo(w[0]), bfhi(w[0]), bflo(w[1]), bfhi(w[1])}; x1 = (f32x4){bflo(w[2]), bfhi(w[2]), bflo(w[3]), bfhi(w[3])}; }
;                     else { x0 = *(const f32x4*)((const float*)Xin + ro + bj * HALF); x1 = *(const f32x4*)((const float*)Xin + ro + bj * HALF + 4); }
;                     x0 += acc[ai][bj][m][0] * sc[bj][0]; x1 += acc[ai][bj][m][1] * sc[bj][1];
;                     if constexpr (OB) { u32x4 o; o[0] = pack2(x0[0], x0[1]); o[1] = pack2(x0[2], x0[3]); o[2] = pack2(x1[0], x1[1]); o[3] = pack2(x1[2], x1[3]);
;                         *(u32x4*)((bf16_t*)Xout + ro + bj * HALF) = o; }
;                     else { *(f32x4*)((float*)Xout + ro + bj * HALF) = x0; *(f32x4*)((float*)Xout + ro + bj * HALF + 4) = x1; } } }
; template <class Map, class Epi>
; DI void gemm_phase(LAS unsigned char* lds, const Map& MP, const Epi& E, const int nM, const int nN, const int K, const int lda, const int ldb) {
;     ...
;             PG8_BAR; PG8_WAIT_L(0); PG8_MMA(1, 0, At, B0); PG8_BAR; PG8_SCHED;
;             PG8_STAGE(PG8_SB(1, 1), b3 + hstepB, voffB);
;             PG8_WAIT_V(6); PG8_BAR; PG8_MMA(1, 1, At, B1); PG8_BAR;
;         }
;         { int frr = fr, fqq = fq; asm volatile("" : "+v"(frr), "+v"(fqq)); E(acc, cur, wr, wc, frr, fqq); }
	s_setprio 1
	s_waitcnt lgkmcnt(7)
	v_mfma_f32_16x16x32_bf16 v[60:63], v[152:155], v[168:171], v[60:63]
	v_mfma_f32_16x16x32_bf16 v[56:59], v[160:163], v[168:171], v[56:59]
	s_waitcnt lgkmcnt(5)
	v_mfma_f32_16x16x32_bf16 v[44:47], v[152:155], v[176:179], v[44:47]
	v_mfma_f32_16x16x32_bf16 v[40:43], v[160:163], v[176:179], v[40:43]
	s_waitcnt lgkmcnt(3)
	v_mfma_f32_16x16x32_bf16 v[28:31], v[152:155], v[184:187], v[28:31]
	v_mfma_f32_16x16x32_bf16 v[24:27], v[160:163], v[184:187], v[24:27]
	s_waitcnt lgkmcnt(1)
	v_mfma_f32_16x16x32_bf16 v[12:15], v[152:155], v[192:195], v[12:15]
	v_mfma_f32_16x16x32_bf16 v[8:11], v[160:163], v[192:195], v[8:11]
	v_mfma_f32_16x16x32_bf16 v[60:63], v[156:159], v[172:175], v[60:63]
	v_mfma_f32_16x16x32_bf16 v[56:59], v[164:167], v[172:175], v[56:59]
	v_mfma_f32_16x16x32_bf16 v[44:47], v[156:159], v[180:183], v[44:47]
	v_mfma_f32_16x16x32_bf16 v[40:43], v[164:167], v[180:183], v[40:43]
	v_mfma_f32_16x16x32_bf16 v[28:31], v[156:159], v[188:191], v[28:31]
	v_mfma_f32_16x16x32_bf16 v[24:27], v[164:167], v[188:191], v[24:27]
	s_waitcnt lgkmcnt(0)
	v_mfma_f32_16x16x32_bf16 v[12:15], v[156:159], v[196:199], v[12:15]
	v_mfma_f32_16x16x32_bf16 v[8:11], v[164:167], v[196:199], v[8:11]
	s_setprio 0
	s_barrier
	s_add_u32 s8, s12, 0x160080
	s_addc_u32 s9, s13, 0
	s_add_i32 s12, s14, s20
	s_mov_b32 m0, s12
	s_nop 0
	global_load_lds_dwordx4 v132, s[8:9]
	s_add_i32 m0, s12, 0x2000
	s_nop 0
	global_load_lds_dwordx4 v128, s[8:9]
	s_waitcnt vmcnt(6)
	s_barrier
	s_setprio 1
	v_mfma_f32_16x16x32_bf16 v[52:55], v[200:203], v[168:171], v[52:55]
	v_mfma_f32_16x16x32_bf16 v[48:51], v[208:211], v[168:171], v[48:51]
	ds_read_b128 v[152:155], v149
	v_mfma_f32_16x16x32_bf16 v[36:39], v[200:203], v[176:179], v[36:39]
	v_mfma_f32_16x16x32_bf16 v[32:35], v[208:211], v[176:179], v[32:35]
	ds_read_b128 v[156:159], v149 offset:1024
	v_mfma_f32_16x16x32_bf16 v[20:23], v[200:203], v[184:187], v[20:23]
	v_mfma_f32_16x16x32_bf16 v[16:19], v[208:211], v[184:187], v[16:19]
	ds_read_b128 v[160:163], v149 offset:2048
	v_mfma_f32_16x16x32_bf16 v[4:7], v[200:203], v[192:195], v[4:7]
	v_mfma_f32_16x16x32_bf16 v[0:3], v[208:211], v[192:195], v[0:3]
	ds_read_b128 v[164:167], v149 offset:3072
	v_mfma_f32_16x16x32_bf16 v[52:55], v[204:207], v[172:175], v[52:55]
	s_add_i32 s48, s48, 2
	v_mfma_f32_16x16x32_bf16 v[48:51], v[212:215], v[172:175], v[48:51]
	s_add_u32 s38, s38, 0x100
	s_addc_u32 s39, s39, 0
	v_mfma_f32_16x16x32_bf16 v[36:39], v[204:207], v[180:183], v[36:39]
	s_cmpk_gt_u32 s48, 0x55
	v_mfma_f32_16x16x32_bf16 v[32:35], v[212:215], v[180:183], v[32:35]
	s_mov_b64 s[8:9], s[10:11]
	v_mfma_f32_16x16x32_bf16 v[20:23], v[204:207], v[188:191], v[20:23]
	v_mfma_f32_16x16x32_bf16 v[16:19], v[212:215], v[188:191], v[16:19]
	v_mfma_f32_16x16x32_bf16 v[4:7], v[204:207], v[196:199], v[4:7]
	v_mfma_f32_16x16x32_bf16 v[0:3], v[212:215], v[196:199], v[0:3]
	s_setprio 0
	s_barrier
	s_cbranch_scc0 .LBB1_2653
	s_waitcnt lgkmcnt(0)
	v_mov_b32_e32 v144, v147
	v_mov_b32_e32 v152, v146
	s_lshl_b32 s2, s2, 8
	s_lshl_b32 s8, s37, 8
	s_add_i32 s2, s2, s27
	s_or_b32 s8, s8, s28
	v_add_u32_e32 v152, s2, v152
	v_lshl_add_u32 v144, v144, 3, s8
	v_ashrrev_i32_e32 v153, 31, v152
	v_ashrrev_i32_e32 v145, 31, v144
	v_lshlrev_b64 v[152:153], 11, v[152:153]
	v_lshl_add_u64 v[144:145], v[152:153], 0, v[144:145]
	v_lshl_add_u64 v[156:157], v[144:145], 1, s[6:7]
	global_load_dwordx4 v[162:165], v[156:157], off
	global_load_dwordx4 v[166:169], v[156:157], off offset:256
	s_mov_b64 s[98:99], 0x10000
	v_lshl_add_u64 v[154:155], v[156:157], 0, s[98:99]
	global_load_dwordx4 v[170:173], v[154:155], off
	global_load_dwordx4 v[174:177], v[154:155], off offset:256
	s_mov_b64 s[98:99], 0x20000
	v_lshl_add_u64 v[154:155], v[156:157], 0, s[98:99]
	global_load_dwordx4 v[178:181], v[154:155], off
	global_load_dwordx4 v[182:185], v[154:155], off offset:256
	s_mov_b64 s[98:99], 0x30000
	v_lshl_add_u64 v[154:155], v[156:157], 0, s[98:99]
	global_load_dwordx4 v[186:189], v[154:155], off
	global_load_dwordx4 v[190:193], v[154:155], off offset:256
	s_mov_b64 s[98:99], 0x80000
	v_lshl_add_u64 v[154:155], v[156:157], 0, s[98:99]
	global_load_dwordx4 v[194:197], v[154:155], off
	global_load_dwordx4 v[198:201], v[154:155], off offset:256
	s_mov_b64 s[98:99], 0x90000
	v_lshl_add_u64 v[154:155], v[156:157], 0, s[98:99]
	global_load_dwordx4 v[202:205], v[154:155], off
	global_load_dwordx4 v[206:209], v[154:155], off offset:256
	s_mov_b64 s[98:99], 0xa0000
	v_lshl_add_u64 v[154:155], v[156:157], 0, s[98:99]
	global_load_dwordx4 v[210:213], v[154:155], off
	global_load_dwordx4 v[248:251], v[154:155], off offset:256
	s_mov_b64 s[98:99], 0xb0000
	v_lshl_add_u64 v[154:155], v[156:157], 0, s[98:99]
	global_load_dwordx4 v[252:255], v[154:155], off
	s_waitcnt vmcnt(14)
	s_nop 1
	v_mov_b32_e32 v152, v162
	v_mov_b32_e32 v153, v163
	v_mov_b32_e32 v154, v164
	v_mov_b32_e32 v155, v165
	s_mov_b64 s[8:9], 0x8000
	s_and_b64 vcc, exec, s[40:41]
	s_mov_b32 s37, s35
	s_mov_b32 s2, s36
	s_mov_b64 s[10:11], s[44:45]
	s_waitcnt lgkmcnt(0)
	v_lshlrev_b32_e32 v158, 16, v152
	v_and_b32_e32 v159, 0xffff0000, v152
	v_lshlrev_b32_e32 v152, 16, v153
	v_and_b32_e32 v153, 0xffff0000, v153
	v_lshlrev_b32_e32 v160, 16, v154
	v_and_b32_e32 v161, 0xffff0000, v154
	v_lshlrev_b32_e32 v154, 16, v155
	v_and_b32_e32 v155, 0xffff0000, v155
	v_pk_add_f32 v[126:127], v[126:127], v[152:153]
	v_pk_add_f32 v[124:125], v[124:125], v[158:159]
	v_lshl_add_u64 v[152:153], v[144:145], 2, s[4:5]
	v_pk_add_f32 v[122:123], v[122:123], v[154:155]
	v_pk_add_f32 v[120:121], v[120:121], v[160:161]
	global_store_dwordx4 v[152:153], v[124:127], off
	global_store_dwordx4 v[152:153], v[120:123], off offset:16
	s_waitcnt vmcnt(15)
; DI unsigned pack2(float a, float b) { f32x2 v = {a, b}; hwbf16x2 r = __builtin_convertvector(v, hwbf16x2); return __builtin_bit_cast(unsigned, r); }
; DI float bflo(unsigned w) { return __uint_as_float(w << 16); }
; DI float bfhi(unsigned w) { return __uint_as_float(w & 0xffff0000u); }
;     DI void operator()(const f32x4 (&acc)[2][2][4][2], const Unit& u, int wr, int wc, int fr, int fq) const {
;     ...
;         for (int ai = 0; ai < 2; ++ai)
; #pragma unroll
;             for (int m = 0; m < 4; ++m) { const size_t ro = (size_t)(row0 + ai * HALF + m * 16) * D + col0;
; #pragma unroll
;                 for (int bj = 0; bj < 2; ++bj) {
;                     f32x4 x0, x1;
;                     if constexpr (IB) { const u32x4 w = *(const u32x4*)((const bf16_t*)Xin + ro + bj * HALF);
;                         x0 = (f32x4){bflo(w[0]), bfhi(w[0]), bflo(w[1]), bfhi(w[1])}; x1 = (f32x4){bflo(w[2]), bfhi(w[2]), bflo(w[3]), bfhi(w[3])}; }
;                     else { x0 = *(const f32x4*)((const float*)Xin + ro + bj * HALF); x1 = *(const f32x4*)((const float*)Xin + ro + bj * HALF + 4); }
;                     x0 += acc[ai][bj][m][0] * sc[bj][0]; x1 += acc[ai][bj][m][1] * sc[bj][1];
;                     if constexpr (OB) { u32x4 o; o[0] = pack2(x0[0], x0[1]); o[1] = pack2(x0[2], x0[3]); o[2] = pack2(x1[0], x1[1]); o[3] = pack2(x1[2], x1[3]);
;                         *(u32x4*)((bf16_t*)Xout + ro + bj * HALF) = o; }
;                     else { *(f32x4*)((float*)Xout + ro + bj * HALF) = x0; *(f32x4*)((float*)Xout + ro + bj * HALF + 4) = x1; } } }
	s_nop 1
	v_mov_b32_e32 v120, v166
	v_mov_b32_e32 v121, v167
	v_mov_b32_e32 v122, v168
	v_mov_b32_e32 v123, v169
	s_waitcnt lgkmcnt(0)
	v_lshlrev_b32_e32 v124, 16, v120
	v_and_b32_e32 v125, 0xffff0000, v120
	v_lshlrev_b32_e32 v120, 16, v121
	v_and_b32_e32 v121, 0xffff0000, v121
	v_lshlrev_b32_e32 v126, 16, v122
	v_and_b32_e32 v127, 0xffff0000, v122
	v_lshlrev_b32_e32 v122, 16, v123
	v_and_b32_e32 v123, 0xffff0000, v123
	v_pk_add_f32 v[118:119], v[118:119], v[120:121]
	v_pk_add_f32 v[116:117], v[116:117], v[124:125]
	v_pk_add_f32 v[114:115], v[114:115], v[122:123]
	v_pk_add_f32 v[112:113], v[112:113], v[126:127]
	global_store_dwordx4 v[152:153], v[116:119], off offset:512
	global_store_dwordx4 v[152:153], v[112:115], off offset:528
	s_nop 0
	v_lshl_add_u64 v[116:117], v[144:145], 0, s[8:9]
	v_lshl_add_u64 v[118:119], v[116:117], 1, s[6:7]
	s_waitcnt vmcnt(16)
	s_nop 1
	v_mov_b32_e32 v112, v170
	v_mov_b32_e32 v113, v171
	v_mov_b32_e32 v114, v172
	v_mov_b32_e32 v115, v173
	s_mov_b64 s[8:9], 0x10000
	s_waitcnt lgkmcnt(0)
	v_lshlrev_b32_e32 v120, 16, v112
	v_and_b32_e32 v121, 0xffff0000, v112
	v_lshlrev_b32_e32 v112, 16, v113
	v_and_b32_e32 v113, 0xffff0000, v113
	v_lshlrev_b32_e32 v122, 16, v114
	v_and_b32_e32 v123, 0xffff0000, v114
	v_lshlrev_b32_e32 v114, 16, v115
	v_and_b32_e32 v115, 0xffff0000, v115
	v_pk_add_f32 v[110:111], v[110:111], v[112:113]
	v_pk_add_f32 v[108:109], v[108:109], v[120:121]
	v_lshl_add_u64 v[112:113], v[116:117], 2, s[4:5]
	v_pk_add_f32 v[106:107], v[106:107], v[114:115]
	v_pk_add_f32 v[104:105], v[104:105], v[122:123]
	global_store_dwordx4 v[112:113], v[108:111], off
	global_store_dwordx4 v[112:113], v[104:107], off offset:16
	s_waitcnt vmcnt(17)
	s_nop 1
	v_mov_b32_e32 v104, v174
	v_mov_b32_e32 v105, v175
	v_mov_b32_e32 v106, v176
	v_mov_b32_e32 v107, v177
	s_waitcnt lgkmcnt(0)
	v_lshlrev_b32_e32 v108, 16, v104
	v_and_b32_e32 v109, 0xffff0000, v104
	v_lshlrev_b32_e32 v104, 16, v105
	v_and_b32_e32 v105, 0xffff0000, v105
	v_lshlrev_b32_e32 v110, 16, v106
	v_and_b32_e32 v111, 0xffff0000, v106
	v_lshlrev_b32_e32 v106, 16, v107
	v_and_b32_e32 v107, 0xffff0000, v107
	v_pk_add_f32 v[102:103], v[102:103], v[104:105]
	v_pk_add_f32 v[100:101], v[100:101], v[108:109]
	v_pk_add_f32 v[98:99], v[98:99], v[106:107]
	v_pk_add_f32 v[96:97], v[96:97], v[110:111]
	global_store_dwordx4 v[112:113], v[100:103], off offset:512
	global_store_dwordx4 v[112:113], v[96:99], off offset:528
	s_nop 0
	v_lshl_add_u64 v[100:101], v[144:145], 0, s[8:9]
	v_lshl_add_u64 v[102:103], v[100:101], 1, s[6:7]
	s_waitcnt vmcnt(18)
	s_nop 1
	v_mov_b32_e32 v96, v178
	v_mov_b32_e32 v97, v179
	v_mov_b32_e32 v98, v180
	v_mov_b32_e32 v99, v181
	s_mov_b64 s[8:9], 0x18000
	s_waitcnt lgkmcnt(0)
	v_lshlrev_b32_e32 v104, 16, v96
	v_and_b32_e32 v105, 0xffff0000, v96
	v_lshlrev_b32_e32 v96, 16, v97
	v_and_b32_e32 v97, 0xffff0000, v97
	v_lshlrev_b32_e32 v106, 16, v98
	v_and_b32_e32 v107, 0xffff0000, v98
	v_lshlrev_b32_e32 v98, 16, v99
	v_and_b32_e32 v99, 0xffff0000, v99
	v_pk_add_f32 v[94:95], v[94:95], v[96:97]
	v_pk_add_f32 v[92:93], v[92:93], v[104:105]
	v_lshl_add_u64 v[96:97], v[100:101], 2, s[4:5]
	v_pk_add_f32 v[90:91], v[90:91], v[98:99]
	v_pk_add_f32 v[88:89], v[88:89], v[106:107]
	global_store_dwordx4 v[96:97], v[92:95], off
	global_store_dwordx4 v[96:97], v[88:91], off offset:16
	s_waitcnt vmcnt(19)
	s_nop 1
	v_mov_b32_e32 v88, v182
	v_mov_b32_e32 v89, v183
	v_mov_b32_e32 v90, v184
	v_mov_b32_e32 v91, v185
	s_waitcnt lgkmcnt(0)
	v_lshlrev_b32_e32 v92, 16, v88
	v_and_b32_e32 v93, 0xffff0000, v88
	v_lshlrev_b32_e32 v88, 16, v89
	v_and_b32_e32 v89, 0xffff0000, v89
	v_lshlrev_b32_e32 v94, 16, v90
	v_and_b32_e32 v95, 0xffff0000, v90
	v_lshlrev_b32_e32 v90, 16, v91
	v_and_b32_e32 v91, 0xffff0000, v91
	v_pk_add_f32 v[86:87], v[86:87], v[88:89]
	v_pk_add_f32 v[84:85], v[84:85], v[92:93]
	v_pk_add_f32 v[82:83], v[82:83], v[90:91]
	v_pk_add_f32 v[80:81], v[80:81], v[94:95]
	global_store_dwordx4 v[96:97], v[84:87], off offset:512
	global_store_dwordx4 v[96:97], v[80:83], off offset:528
	s_nop 0
	v_lshl_add_u64 v[84:85], v[144:145], 0, s[8:9]
	v_lshl_add_u64 v[86:87], v[84:85], 1, s[6:7]
	s_waitcnt vmcnt(20)
	s_nop 1
	v_mov_b32_e32 v80, v186
	v_mov_b32_e32 v81, v187
	v_mov_b32_e32 v82, v188
	v_mov_b32_e32 v83, v189
	s_mov_b64 s[8:9], 0x40000
	s_waitcnt lgkmcnt(0)
	v_lshlrev_b32_e32 v88, 16, v80
	v_and_b32_e32 v89, 0xffff0000, v80
	v_lshlrev_b32_e32 v80, 16, v81
	v_and_b32_e32 v81, 0xffff0000, v81
	v_lshlrev_b32_e32 v90, 16, v82
	v_and_b32_e32 v91, 0xffff0000, v82
	v_lshlrev_b32_e32 v82, 16, v83
	v_and_b32_e32 v83, 0xffff0000, v83
	v_pk_add_f32 v[78:79], v[78:79], v[80:81]
	v_pk_add_f32 v[76:77], v[76:77], v[88:89]
	v_lshl_add_u64 v[80:81], v[84:85], 2, s[4:5]
	v_pk_add_f32 v[74:75], v[74:75], v[82:83]
	v_pk_add_f32 v[72:73], v[72:73], v[90:91]
	global_store_dwordx4 v[80:81], v[76:79], off
	global_store_dwordx4 v[80:81], v[72:75], off offset:16
	s_waitcnt vmcnt(21)
	s_nop 1
	v_mov_b32_e32 v72, v190
	v_mov_b32_e32 v73, v191
	v_mov_b32_e32 v74, v192
	v_mov_b32_e32 v75, v193
	s_waitcnt lgkmcnt(0)
	v_lshlrev_b32_e32 v76, 16, v72
	v_and_b32_e32 v77, 0xffff0000, v72
	v_lshlrev_b32_e32 v72, 16, v73
	v_and_b32_e32 v73, 0xffff0000, v73
	v_lshlrev_b32_e32 v78, 16, v74
	v_and_b32_e32 v79, 0xffff0000, v74
	v_lshlrev_b32_e32 v74, 16, v75
	v_and_b32_e32 v75, 0xffff0000, v75
	v_pk_add_f32 v[70:71], v[70:71], v[72:73]
	v_pk_add_f32 v[68:69], v[68:69], v[76:77]
	v_pk_add_f32 v[66:67], v[66:67], v[74:75]
	v_pk_add_f32 v[64:65], v[64:65], v[78:79]
	global_store_dwordx4 v[80:81], v[68:71], off offset:512
	global_store_dwordx4 v[80:81], v[64:67], off offset:528
	s_nop 0
	v_lshl_add_u64 v[68:69], v[144:145], 0, s[8:9]
	v_lshl_add_u64 v[70:71], v[68:69], 1, s[6:7]
	s_waitcnt vmcnt(22)
; DI unsigned pack2(float a, float b) { f32x2 v = {a, b}; hwbf16x2 r = __builtin_convertvector(v, hwbf16x2); return __builtin_bit_cast(unsigned, r); }
; DI float bflo(unsigned w) { return __uint_as_float(w << 16); }
; DI float bfhi(unsigned w) { return __uint_as_float(w & 0xffff0000u); }
;     DI const char* a(const Unit& u) const { return (const char*)(A + (size_t)u.pm * BM * lda); }
;     DI const char* a(const Unit& u) const { return (const char*)(A + (size_t)u.pm * BM * 2048 + (u.pn >> 1) * 512); }
;     DI void operator()(const f32x4 (&acc)[2][2][4][2], const Unit& u, int wr, int wc, int fr, int fq) const {
;     ...
;         for (int ai = 0; ai < 2; ++ai)
; #pragma unroll
;             for (int m = 0; m < 4; ++m) { const size_t ro = (size_t)(row0 + ai * HALF + m * 16) * D + col0;
; #pragma unroll
;                 for (int bj = 0; bj < 2; ++bj) {
;                     f32x4 x0, x1;
;                     if constexpr (IB) { const u32x4 w = *(const u32x4*)((const bf16_t*)Xin + ro + bj * HALF);
;                         x0 = (f32x4){bflo(w[0]), bfhi(w[0]), bflo(w[1]), bfhi(w[1])}; x1 = (f32x4){bflo(w[2]), bfhi(w[2]), bflo(w[3]), bfhi(w[3])}; }
;                     else { x0 = *(const f32x4*)((const float*)Xin + ro + bj * HALF); x1 = *(const f32x4*)((const float*)Xin + ro + bj * HALF + 4); }
;                     x0 += acc[ai][bj][m][0] * sc[bj][0]; x1 += acc[ai][bj][m][1] * sc[bj][1];
;                     if constexpr (OB) { u32x4 o; o[0] = pack2(x0[0], x0[1]); o[1] = pack2(x0[2], x0[3]); o[2] = pack2(x1[0], x1[1]); o[3] = pack2(x1[2], x1[3]);
;                         *(u32x4*)((bf16_t*)Xout + ro + bj * HALF) = o; }
;                     else { *(f32x4*)((float*)Xout + ro + bj * HALF) = x0; *(f32x4*)((float*)Xout + ro + bj * HALF + 4) = x1; } } }
; template <class Map, class Epi>
; DI void gemm_phase(LAS unsigned char* lds, const Map& MP, const Epi& E, const int nM, const int nN, const int K, const int lda, const int ldb) {
;     ...
;         if (!has_next) break;
; #pragma unroll
;         for (int a = 0; a < 2; ++a)
; #pragma unroll
;             for (int b = 0; b < 2; ++b)
; #pragma unroll
;                 for (int m = 0; m < 4; ++m)
; #pragma unroll
;                     for (int n = 0; n < 2; ++n) acc[a][b][m][n] = (f32x4){0.f, 0.f, 0.f, 0.f};
;         cur = nxt; cA = nA; cB = nB; ++ui;
;     }
;     PG8_WAIT_V(0);
;     if (wr == 0) PG8_BAR;
;     PG8_BAR;
	s_nop 1
	v_mov_b32_e32 v64, v194
	v_mov_b32_e32 v65, v195
	v_mov_b32_e32 v66, v196
	v_mov_b32_e32 v67, v197
	s_mov_b64 s[8:9], 0x48000
	s_waitcnt lgkmcnt(0)
	v_lshlrev_b32_e32 v72, 16, v64
	v_and_b32_e32 v73, 0xffff0000, v64
	v_lshlrev_b32_e32 v64, 16, v65
	v_and_b32_e32 v65, 0xffff0000, v65
	v_lshlrev_b32_e32 v74, 16, v66
	v_and_b32_e32 v75, 0xffff0000, v66
	v_lshlrev_b32_e32 v66, 16, v67
	v_and_b32_e32 v67, 0xffff0000, v67
	v_pk_add_f32 v[62:63], v[62:63], v[64:65]
	v_pk_add_f32 v[60:61], v[60:61], v[72:73]
	v_lshl_add_u64 v[64:65], v[68:69], 2, s[4:5]
	v_pk_add_f32 v[58:59], v[58:59], v[66:67]
	v_pk_add_f32 v[56:57], v[56:57], v[74:75]
	global_store_dwordx4 v[64:65], v[60:63], off
	global_store_dwordx4 v[64:65], v[56:59], off offset:16
	s_waitcnt vmcnt(23)
	s_nop 1
	v_mov_b32_e32 v56, v198
	v_mov_b32_e32 v57, v199
	v_mov_b32_e32 v58, v200
	v_mov_b32_e32 v59, v201
	s_waitcnt lgkmcnt(0)
	v_lshlrev_b32_e32 v60, 16, v56
	v_and_b32_e32 v61, 0xffff0000, v56
	v_lshlrev_b32_e32 v56, 16, v57
	v_and_b32_e32 v57, 0xffff0000, v57
	v_lshlrev_b32_e32 v62, 16, v58
	v_and_b32_e32 v63, 0xffff0000, v58
	v_lshlrev_b32_e32 v58, 16, v59
	v_and_b32_e32 v59, 0xffff0000, v59
	v_pk_add_f32 v[54:55], v[54:55], v[56:57]
	v_pk_add_f32 v[52:53], v[52:53], v[60:61]
	v_pk_add_f32 v[50:51], v[50:51], v[58:59]
	v_pk_add_f32 v[48:49], v[48:49], v[62:63]
	global_store_dwordx4 v[64:65], v[52:55], off offset:512
	global_store_dwordx4 v[64:65], v[48:51], off offset:528
	s_nop 0
	v_lshl_add_u64 v[52:53], v[144:145], 0, s[8:9]
	v_lshl_add_u64 v[54:55], v[52:53], 1, s[6:7]
	s_waitcnt vmcnt(24)
	s_nop 1
	v_mov_b32_e32 v48, v202
	v_mov_b32_e32 v49, v203
	v_mov_b32_e32 v50, v204
	v_mov_b32_e32 v51, v205
	s_mov_b64 s[8:9], 0x50000
	s_waitcnt lgkmcnt(0)
	v_lshlrev_b32_e32 v56, 16, v48
	v_and_b32_e32 v57, 0xffff0000, v48
	v_lshlrev_b32_e32 v48, 16, v49
	v_and_b32_e32 v49, 0xffff0000, v49
	v_lshlrev_b32_e32 v58, 16, v50
	v_and_b32_e32 v59, 0xffff0000, v50
	v_lshlrev_b32_e32 v50, 16, v51
	v_and_b32_e32 v51, 0xffff0000, v51
	v_pk_add_f32 v[46:47], v[46:47], v[48:49]
	v_pk_add_f32 v[44:45], v[44:45], v[56:57]
	v_lshl_add_u64 v[48:49], v[52:53], 2, s[4:5]
	v_pk_add_f32 v[42:43], v[42:43], v[50:51]
	v_pk_add_f32 v[40:41], v[40:41], v[58:59]
	global_store_dwordx4 v[48:49], v[44:47], off
	global_store_dwordx4 v[48:49], v[40:43], off offset:16
	s_waitcnt vmcnt(25)
	s_nop 1
	v_mov_b32_e32 v40, v206
	v_mov_b32_e32 v41, v207
	v_mov_b32_e32 v42, v208
	v_mov_b32_e32 v43, v209
	s_waitcnt lgkmcnt(0)
	v_lshlrev_b32_e32 v44, 16, v40
	v_and_b32_e32 v45, 0xffff0000, v40
	v_lshlrev_b32_e32 v40, 16, v41
	v_and_b32_e32 v41, 0xffff0000, v41
	v_lshlrev_b32_e32 v46, 16, v42
	v_and_b32_e32 v47, 0xffff0000, v42
	v_lshlrev_b32_e32 v42, 16, v43
	v_and_b32_e32 v43, 0xffff0000, v43
	v_pk_add_f32 v[38:39], v[38:39], v[40:41]
	v_pk_add_f32 v[36:37], v[36:37], v[44:45]
	v_pk_add_f32 v[34:35], v[34:35], v[42:43]
	v_pk_add_f32 v[32:33], v[32:33], v[46:47]
	global_store_dwordx4 v[48:49], v[36:39], off offset:512
	global_store_dwordx4 v[48:49], v[32:35], off offset:528
	s_nop 0
	v_lshl_add_u64 v[36:37], v[144:145], 0, s[8:9]
	v_lshl_add_u64 v[38:39], v[36:37], 1, s[6:7]
	s_waitcnt vmcnt(26)
	s_nop 1
	v_mov_b32_e32 v32, v210
	v_mov_b32_e32 v33, v211
	v_mov_b32_e32 v34, v212
	v_mov_b32_e32 v35, v213
	s_mov_b64 s[8:9], 0x58000
	s_waitcnt lgkmcnt(0)
	v_lshlrev_b32_e32 v40, 16, v32
	v_and_b32_e32 v41, 0xffff0000, v32
	v_lshlrev_b32_e32 v32, 16, v33
	v_and_b32_e32 v33, 0xffff0000, v33
	v_lshlrev_b32_e32 v42, 16, v34
	v_and_b32_e32 v43, 0xffff0000, v34
	v_lshlrev_b32_e32 v34, 16, v35
	v_and_b32_e32 v35, 0xffff0000, v35
	v_pk_add_f32 v[30:31], v[30:31], v[32:33]
	v_pk_add_f32 v[28:29], v[28:29], v[40:41]
	v_lshl_add_u64 v[32:33], v[36:37], 2, s[4:5]
	v_pk_add_f32 v[26:27], v[26:27], v[34:35]
	v_pk_add_f32 v[24:25], v[24:25], v[42:43]
	global_store_dwordx4 v[32:33], v[28:31], off
	global_store_dwordx4 v[32:33], v[24:27], off offset:16
	s_waitcnt vmcnt(27)
	s_nop 1
	v_mov_b32_e32 v24, v248
	v_mov_b32_e32 v25, v249
	v_mov_b32_e32 v26, v250
	v_mov_b32_e32 v27, v251
	s_waitcnt lgkmcnt(0)
	v_lshlrev_b32_e32 v28, 16, v24
	v_and_b32_e32 v29, 0xffff0000, v24
	v_lshlrev_b32_e32 v24, 16, v25
	v_and_b32_e32 v25, 0xffff0000, v25
	v_lshlrev_b32_e32 v30, 16, v26
	v_and_b32_e32 v31, 0xffff0000, v26
	v_lshlrev_b32_e32 v26, 16, v27
	v_and_b32_e32 v27, 0xffff0000, v27
	v_pk_add_f32 v[22:23], v[22:23], v[24:25]
	v_pk_add_f32 v[20:21], v[20:21], v[28:29]
	v_pk_add_f32 v[18:19], v[18:19], v[26:27]
	v_pk_add_f32 v[16:17], v[16:17], v[30:31]
	global_store_dwordx4 v[32:33], v[20:23], off offset:512
	global_store_dwordx4 v[32:33], v[16:19], off offset:528
	s_nop 0
	v_lshl_add_u64 v[20:21], v[144:145], 0, s[8:9]
	v_lshl_add_u64 v[22:23], v[20:21], 1, s[6:7]
	s_waitcnt vmcnt(28)
	s_nop 1
	v_mov_b32_e32 v16, v252
	v_mov_b32_e32 v17, v253
	v_mov_b32_e32 v18, v254
	v_mov_b32_e32 v19, v255
	s_mov_b64 s[8:9], s[42:43]
	s_waitcnt lgkmcnt(0)
	v_lshlrev_b32_e32 v24, 16, v16
	v_and_b32_e32 v25, 0xffff0000, v16
	v_lshlrev_b32_e32 v16, 16, v17
	v_and_b32_e32 v17, 0xffff0000, v17
	v_lshlrev_b32_e32 v26, 16, v18
	v_and_b32_e32 v27, 0xffff0000, v18
	v_lshlrev_b32_e32 v18, 16, v19
	v_and_b32_e32 v19, 0xffff0000, v19
	v_pk_add_f32 v[14:15], v[14:15], v[16:17]
	v_pk_add_f32 v[12:13], v[12:13], v[24:25]
	v_lshl_add_u64 v[16:17], v[20:21], 2, s[4:5]
	v_pk_add_f32 v[10:11], v[10:11], v[18:19]
	v_pk_add_f32 v[8:9], v[8:9], v[26:27]
	global_store_dwordx4 v[16:17], v[12:15], off
	global_store_dwordx4 v[16:17], v[8:11], off offset:16
	global_load_dwordx4 v[8:11], v[22:23], off offset:256
	s_waitcnt vmcnt(0) lgkmcnt(0)
	v_lshlrev_b32_e32 v12, 16, v8
	v_and_b32_e32 v13, 0xffff0000, v8
	v_lshlrev_b32_e32 v8, 16, v9
	v_and_b32_e32 v9, 0xffff0000, v9
	v_lshlrev_b32_e32 v14, 16, v10
	v_and_b32_e32 v15, 0xffff0000, v10
	v_lshlrev_b32_e32 v10, 16, v11
	v_and_b32_e32 v11, 0xffff0000, v11
	v_pk_add_f32 v[6:7], v[6:7], v[8:9]
	v_pk_add_f32 v[4:5], v[4:5], v[12:13]
	v_pk_add_f32 v[2:3], v[2:3], v[10:11]
	v_pk_add_f32 v[0:1], v[0:1], v[14:15]
	global_store_dwordx4 v[16:17], v[4:7], off offset:512
	global_store_dwordx4 v[16:17], v[0:3], off offset:528
	s_cbranch_vccz .LBB1_2646
	s_waitcnt vmcnt(0)
	s_cmpk_gt_u32 s3, 0xff
	s_cbranch_scc1 .LBB1_2657
	s_barrier
